# phase 2 rewritten by hand: all 18 rows of each column walk loaded up front, next walk prefetched, a_up kept in registers for the forget gate
# speedup vs baseline: 1.1020x; 1.0154x over previous
; __device__ __forceinline__ void unpack8(const u32x4 w, float (&f)[8]) { f[0] = bflo(w.x); f[1] = bfhi(w.x); f[2] = bflo(w.y); f[3] = bfhi(w.y); f[4] = bflo(w.z); f[5] = bfhi(w.z); f[6] = bflo(w.w); f[7] = bfhi(w.w); }
; __device__ __forceinline__ u32x4 pack8(const float (&f)[8]) { u32x4 o; o.x = pk2(f[0], f[1]); o.y = pk2(f[2], f[3]); o.z = pk2(f[4], f[5]); o.w = pk2(f[6], f[7]); return o; }
; template <int CH> __device__ __forceinline__ void p2_rwkv_chunk(const Params& p, int t0, int lane) {
;     ...
;     const bf16_t* zc = (const bf16_t*)(ws + WS_Z) + (size_t)t0 * ZLD + c;
;     float mu[8], kq[8];
;     { const f32x4 m0 = *(const f32x4*)(p.in[8] + c), m1 = *(const f32x4*)(p.in[8] + c + 4);
; #pragma unroll
;       for (int i = 0; i < 4; ++i) { mu[i] = m0[i]; mu[4 + i] = m1[i]; } }
;     if (CH == 1) { const f32x4 q0 = *(const f32x4*)(p.in[14] + c - 512), q1 = *(const f32x4*)(p.in[14] + c - 512 + 4);
; #pragma unroll
;         for (int i = 0; i < 4; ++i) { kq[i] = q0[i]; kq[4 + i] = q1[i]; } }
;     float P[8], C[8], N[8];
;     if ((t0 & (T_SEQ - 1)) != 0) unpack8(__builtin_nontemporal_load((const u32x4*)(zc - ZLD)), P); else {
; #pragma unroll
;         for (int i = 0; i < 8; ++i) P[i] = 0.f; }
;     unpack8(__builtin_nontemporal_load((const u32x4*)(zc)), C);
;     u32x4 raw = __builtin_nontemporal_load((const u32x4*)(zc + ZLD));
; #pragma unroll 2
;     for (int i = 0; i < 16; ++i) {
;         const int t = t0 + i; const bool hasn = (t & (T_SEQ - 1)) != T_SEQ - 1;
;         if (hasn) unpack8(raw, N); else {
; #pragma unroll
;             for (int q = 0; q < 8; ++q) N[q] = 0.f; }
;         if (i < 15 && ((t + 1) & (T_SEQ - 1)) != T_SEQ - 1) raw = __builtin_nontemporal_load((const u32x4*)(zc + (size_t)(i + 2) * ZLD));
;         float zs[8];
; #pragma unroll
;         for (int q = 0; q < 8; ++q) zs[q] = C[q] + mu[q] * (0.5f * (P[q] + N[q]) - C[q]);
;         if (CH < 3) {
;             *(u32x4*)(RKV + (size_t)t * 1536 + c) = pack8(zs);
; __device__ __forceinline__ void phase2(const Params& p, LAS unsigned char* lds, int wid, int lane) {
;     ...
;     const int gw = blockIdx.x * 8 + wid, NGW = gridDim.x * 8;
;     for (int grp = gw; grp < M_TOK / 16; grp += NGW) {
;         const int t0 = grp * 16;
;         p2_rwkv_chunk<0>(p, t0, lane); p2_rwkv_chunk<1>(p, t0, lane); p2_rwkv_chunk<2>(p, t0, lane); p2_rwkv_chunk<3>(p, t0, lane);
.LBB0_236:
	v_and_b32_e32 v0, 63, v244
	v_mov_b32_e32 v250, v140
	v_mov_b32_e32 v251, v141
	v_readfirstlane_b32 s0, v244
	s_nop 0
	s_lshr_b32 s0, s0, 6
	s_lshl_b32 s60, s2, 3
	s_add_i32 s60, s60, s0
	s_lshl_b32 s61, s96, 3
.Lp2_grp_1:
	s_cmpk_lt_i32 s60, 0x800
	s_cbranch_scc0 .Lp2_done_2
	s_waitcnt vmcnt(0)
	s_lshl_b32 s62, s60, 4
	s_and_b32 s63, s62, 0xfff
	s_cmp_eq_u32 s63, 0
	s_cselect_b32 s66, 1, 0
	s_cmpk_eq_i32 s63, 0xff0
	s_cselect_b32 s67, 1, 0
	s_mul_i32 s63, s62, 0x1c00
	s_add_u32 s63, s63, 0x7000000
	v_lshl_add_u32 v4, v0, 4, s63
	v_add_u32_e32 v1, 0xffffe400, v4
	s_cmp_lg_u32 s66, 0
	s_cselect_b64 vcc, -1, 0
	s_nop 1
	v_cndmask_b32_e32 v1, v1, v4, vcc
	global_load_dwordx4 v[8:11], v1, s[58:59] nt
	global_load_dwordx4 v[12:15], v4, s[58:59] nt
	v_mov_b32_e32 v1, v4
	v_add_u32_e32 v1, 0x1c00, v1
	global_load_dwordx4 v[16:19], v1, s[58:59] nt
	v_add_u32_e32 v1, 0x1c00, v1
	global_load_dwordx4 v[20:23], v1, s[58:59] nt
	v_add_u32_e32 v1, 0x1c00, v1
	global_load_dwordx4 v[24:27], v1, s[58:59] nt
	v_add_u32_e32 v1, 0x1c00, v1
	global_load_dwordx4 v[28:31], v1, s[58:59] nt
	v_add_u32_e32 v1, 0x1c00, v1
	global_load_dwordx4 v[32:35], v1, s[58:59] nt
	v_add_u32_e32 v1, 0x1c00, v1
	global_load_dwordx4 v[36:39], v1, s[58:59] nt
	v_add_u32_e32 v1, 0x1c00, v1
	global_load_dwordx4 v[40:43], v1, s[58:59] nt
	v_add_u32_e32 v1, 0x1c00, v1
	global_load_dwordx4 v[44:47], v1, s[58:59] nt
	v_add_u32_e32 v1, 0x1c00, v1
	global_load_dwordx4 v[48:51], v1, s[58:59] nt
	v_add_u32_e32 v1, 0x1c00, v1
	global_load_dwordx4 v[52:55], v1, s[58:59] nt
	v_add_u32_e32 v1, 0x1c00, v1
	global_load_dwordx4 v[56:59], v1, s[58:59] nt
	v_add_u32_e32 v1, 0x1c00, v1
	global_load_dwordx4 v[60:63], v1, s[58:59] nt
	v_add_u32_e32 v1, 0x1c00, v1
	global_load_dwordx4 v[64:67], v1, s[58:59] nt
	v_add_u32_e32 v1, 0x1c00, v1
	global_load_dwordx4 v[68:71], v1, s[58:59] nt
	v_add_u32_e32 v1, 0x1c00, v1
	global_load_dwordx4 v[72:75], v1, s[58:59] nt
	v_add_u32_e32 v1, 0x1c00, v1
	s_cmp_lg_u32 s67, 0
	s_cselect_b64 vcc, -1, 0
	s_nop 1
	v_cndmask_b32_e32 v1, v1, v4, vcc
	global_load_dwordx4 v[76:79], v1, s[58:59] nt
	v_mov_b32_e32 v2, v250
	v_mov_b32_e32 v3, v251
	global_load_dwordx4 v[104:107], v[2:3], off
	global_load_dwordx4 v[108:111], v[2:3], off offset:16
	s_mul_i32 s63, s62, 0x1c00
	s_add_u32 s63, s63, 0x7000400
	v_lshl_add_u32 v4, v0, 4, s63
	v_add_u32_e32 v1, 0xffffe400, v4
	s_cmp_lg_u32 s66, 0
	s_cselect_b64 vcc, -1, 0
	s_nop 1
	v_cndmask_b32_e32 v1, v1, v4, vcc
	global_load_dwordx4 v[168:171], v1, s[58:59] nt
	global_load_dwordx4 v[172:175], v4, s[58:59] nt
	v_mov_b32_e32 v1, v4
	v_add_u32_e32 v1, 0x1c00, v1
	global_load_dwordx4 v[176:179], v1, s[58:59] nt
	v_add_u32_e32 v1, 0x1c00, v1
	global_load_dwordx4 v[180:183], v1, s[58:59] nt
	v_add_u32_e32 v1, 0x1c00, v1
	global_load_dwordx4 v[184:187], v1, s[58:59] nt
	v_add_u32_e32 v1, 0x1c00, v1
	global_load_dwordx4 v[188:191], v1, s[58:59] nt
	v_add_u32_e32 v1, 0x1c00, v1
	global_load_dwordx4 v[192:195], v1, s[58:59] nt
	v_add_u32_e32 v1, 0x1c00, v1
	global_load_dwordx4 v[196:199], v1, s[58:59] nt
	v_add_u32_e32 v1, 0x1c00, v1
	global_load_dwordx4 v[200:203], v1, s[58:59] nt
	v_add_u32_e32 v1, 0x1c00, v1
	global_load_dwordx4 v[204:207], v1, s[58:59] nt
	v_add_u32_e32 v1, 0x1c00, v1
	global_load_dwordx4 v[208:211], v1, s[58:59] nt
	v_add_u32_e32 v1, 0x1c00, v1
	global_load_dwordx4 v[212:215], v1, s[58:59] nt
	v_add_u32_e32 v1, 0x1c00, v1
	global_load_dwordx4 v[216:219], v1, s[58:59] nt
	v_add_u32_e32 v1, 0x1c00, v1
	global_load_dwordx4 v[220:223], v1, s[58:59] nt
	v_add_u32_e32 v1, 0x1c00, v1
	global_load_dwordx4 v[224:227], v1, s[58:59] nt
	v_add_u32_e32 v1, 0x1c00, v1
	global_load_dwordx4 v[228:231], v1, s[58:59] nt
	v_add_u32_e32 v1, 0x1c00, v1
	global_load_dwordx4 v[232:235], v1, s[58:59] nt
	v_add_u32_e32 v1, 0x1c00, v1
	s_cmp_lg_u32 s67, 0
	s_cselect_b64 vcc, -1, 0
	s_nop 1
	v_cndmask_b32_e32 v1, v1, v4, vcc
	global_load_dwordx4 v[236:239], v1, s[58:59] nt
	s_mul_i32 s63, s62, 0xc00
	s_add_u32 s63, s63, 0x15000000
	v_lshl_add_u32 v5, v0, 4, s63
	s_waitcnt vmcnt(18)
	s_cmp_eq_u32 s66, 0
	s_cbranch_scc1 .Lp2_nz_3
	v_mov_b32_e32 v8, 0
	v_mov_b32_e32 v9, 0
	v_mov_b32_e32 v10, 0
	v_mov_b32_e32 v11, 0
.Lp2_nz_3:
	v_lshlrev_b32_e32 v80, 16, v8
	v_and_b32_e32 v81, 0xffff0000, v8
	v_lshlrev_b32_e32 v82, 16, v9
	v_and_b32_e32 v83, 0xffff0000, v9
	v_lshlrev_b32_e32 v84, 16, v10
	v_and_b32_e32 v85, 0xffff0000, v10
	v_lshlrev_b32_e32 v86, 16, v11
	v_and_b32_e32 v87, 0xffff0000, v11
	v_lshlrev_b32_e32 v88, 16, v12
	v_and_b32_e32 v89, 0xffff0000, v12
	v_lshlrev_b32_e32 v90, 16, v13
	v_and_b32_e32 v91, 0xffff0000, v13
	v_lshlrev_b32_e32 v92, 16, v14
	v_and_b32_e32 v93, 0xffff0000, v14
	v_lshlrev_b32_e32 v94, 16, v15
	v_and_b32_e32 v95, 0xffff0000, v15
	v_lshlrev_b32_e32 v96, 16, v16
	v_and_b32_e32 v97, 0xffff0000, v16
	v_lshlrev_b32_e32 v98, 16, v17
	v_and_b32_e32 v99, 0xffff0000, v17
	v_lshlrev_b32_e32 v100, 16, v18
	v_and_b32_e32 v101, 0xffff0000, v18
	v_lshlrev_b32_e32 v102, 16, v19
	v_and_b32_e32 v103, 0xffff0000, v19
	v_add_f32_e32 v136, v80, v96
	v_add_f32_e32 v137, v81, v97
	v_add_f32_e32 v138, v82, v98
	v_add_f32_e32 v139, v83, v99
	v_add_f32_e32 v140, v84, v100
	v_add_f32_e32 v141, v85, v101
	v_add_f32_e32 v142, v86, v102
	v_add_f32_e32 v143, v87, v103
	v_fma_f32 v136, v136, 0.5, -v88
	v_fma_f32 v137, v137, 0.5, -v89
	v_fma_f32 v138, v138, 0.5, -v90
	v_fma_f32 v139, v139, 0.5, -v91
	v_fma_f32 v140, v140, 0.5, -v92
	v_fma_f32 v141, v141, 0.5, -v93
	v_fma_f32 v142, v142, 0.5, -v94
	v_fma_f32 v143, v143, 0.5, -v95
	v_fma_f32 v128, v104, v136, v88
	v_fma_f32 v129, v105, v137, v89
	v_fma_f32 v130, v106, v138, v90
; __device__ __forceinline__ void unpack8(const u32x4 w, float (&f)[8]) { f[0] = bflo(w.x); f[1] = bfhi(w.x); f[2] = bflo(w.y); f[3] = bfhi(w.y); f[4] = bflo(w.z); f[5] = bfhi(w.z); f[6] = bflo(w.w); f[7] = bfhi(w.w); }
; __device__ __forceinline__ u32x4 pack8(const float (&f)[8]) { u32x4 o; o.x = pk2(f[0], f[1]); o.y = pk2(f[2], f[3]); o.z = pk2(f[4], f[5]); o.w = pk2(f[6], f[7]); return o; }
; __device__ __forceinline__ float sigmoidf_(float x) { return __builtin_amdgcn_rcpf(1.0f + __expf(-x)); }
; __device__ __forceinline__ float tanhf_(float x) { return 1.0f - 2.0f * __builtin_amdgcn_rcpf(__expf(2.0f * x) + 1.0f); }
; template <int CH> __device__ __forceinline__ void p2_rwkv_chunk(const Params& p, int t0, int lane) {
;     ...
;     for (int i = 0; i < 16; ++i) {
;         const int t = t0 + i; const bool hasn = (t & (T_SEQ - 1)) != T_SEQ - 1;
;         if (hasn) unpack8(raw, N); else {
; #pragma unroll
;             for (int q = 0; q < 8; ++q) N[q] = 0.f; }
;         if (i < 15 && ((t + 1) & (T_SEQ - 1)) != T_SEQ - 1) raw = __builtin_nontemporal_load((const u32x4*)(zc + (size_t)(i + 2) * ZLD));
;         float zs[8];
; #pragma unroll
;         for (int q = 0; q < 8; ++q) zs[q] = C[q] + mu[q] * (0.5f * (P[q] + N[q]) - C[q]);
;         if (CH < 3) {
;             *(u32x4*)(RKV + (size_t)t * 1536 + c) = pack8(zs);
;             if (CH == 1) { float s2 = 0.f;
; #pragma unroll
;                 for (int q = 0; q < 8; ++q) { const float v = zs[q] * kq[q]; s2 += v * v; }
;                 s2 = red8s(s2);
;                 if ((lane & 7) == 0) RINV[t * 8 + (lane >> 3)] = rsqrtf(fmaxf(s2, 1e-24f)); }
;         } else {
;             const int cc = c - 1536; float o[8];
; #pragma unroll
;             for (int q = 0; q < 8; ++q) o[q] = cc < 128 ? tanhf_(zs[q]) : (cc < 192 ? zs[q] : sigmoidf_(zs[q]));
;             *(u32x4*)(AP + (size_t)t * KLORA + cc) = pack8(o);
;         }
; #pragma unroll
;         for (int q = 0; q < 8; ++q) { P[q] = C[q]; C[q] = N[q]; }
	v_fma_f32 v131, v107, v139, v91
	v_fma_f32 v132, v108, v140, v92
	v_fma_f32 v133, v109, v141, v93
	v_fma_f32 v134, v110, v142, v94
	v_fma_f32 v135, v111, v143, v95
	v_cvt_pk_bf16_f32 v246, v128, v129
	v_cvt_pk_bf16_f32 v247, v130, v131
	v_cvt_pk_bf16_f32 v248, v132, v133
	v_cvt_pk_bf16_f32 v249, v134, v135
	global_store_dwordx4 v5, v[246:249], s[58:59] nt
	v_add_u32_e32 v5, 0xc00, v5
	v_lshlrev_b32_e32 v80, 16, v20
	v_and_b32_e32 v81, 0xffff0000, v20
	v_lshlrev_b32_e32 v82, 16, v21
	v_and_b32_e32 v83, 0xffff0000, v21
	v_lshlrev_b32_e32 v84, 16, v22
	v_and_b32_e32 v85, 0xffff0000, v22
	v_lshlrev_b32_e32 v86, 16, v23
	v_and_b32_e32 v87, 0xffff0000, v23
	v_add_f32_e32 v136, v88, v80
	v_add_f32_e32 v137, v89, v81
	v_add_f32_e32 v138, v90, v82
	v_add_f32_e32 v139, v91, v83
	v_add_f32_e32 v140, v92, v84
	v_add_f32_e32 v141, v93, v85
	v_add_f32_e32 v142, v94, v86
	v_add_f32_e32 v143, v95, v87
	v_fma_f32 v136, v136, 0.5, -v96
	v_fma_f32 v137, v137, 0.5, -v97
	v_fma_f32 v138, v138, 0.5, -v98
	v_fma_f32 v139, v139, 0.5, -v99
	v_fma_f32 v140, v140, 0.5, -v100
	v_fma_f32 v141, v141, 0.5, -v101
	v_fma_f32 v142, v142, 0.5, -v102
	v_fma_f32 v143, v143, 0.5, -v103
	v_fma_f32 v128, v104, v136, v96
	v_fma_f32 v129, v105, v137, v97
	v_fma_f32 v130, v106, v138, v98
	v_fma_f32 v131, v107, v139, v99
	v_fma_f32 v132, v108, v140, v100
	v_fma_f32 v133, v109, v141, v101
	v_fma_f32 v134, v110, v142, v102
	v_fma_f32 v135, v111, v143, v103
	v_cvt_pk_bf16_f32 v246, v128, v129
	v_cvt_pk_bf16_f32 v247, v130, v131
	v_cvt_pk_bf16_f32 v248, v132, v133
	v_cvt_pk_bf16_f32 v249, v134, v135
	global_store_dwordx4 v5, v[246:249], s[58:59] nt
	v_add_u32_e32 v5, 0xc00, v5
	v_lshlrev_b32_e32 v88, 16, v24
	v_and_b32_e32 v89, 0xffff0000, v24
	v_lshlrev_b32_e32 v90, 16, v25
	v_and_b32_e32 v91, 0xffff0000, v25
	v_lshlrev_b32_e32 v92, 16, v26
	v_and_b32_e32 v93, 0xffff0000, v26
	v_lshlrev_b32_e32 v94, 16, v27
	v_and_b32_e32 v95, 0xffff0000, v27
	v_add_f32_e32 v136, v96, v88
	v_add_f32_e32 v137, v97, v89
	v_add_f32_e32 v138, v98, v90
	v_add_f32_e32 v139, v99, v91
	v_add_f32_e32 v140, v100, v92
	v_add_f32_e32 v141, v101, v93
	v_add_f32_e32 v142, v102, v94
	v_add_f32_e32 v143, v103, v95
	v_fma_f32 v136, v136, 0.5, -v80
	v_fma_f32 v137, v137, 0.5, -v81
	v_fma_f32 v138, v138, 0.5, -v82
	v_fma_f32 v139, v139, 0.5, -v83
	v_fma_f32 v140, v140, 0.5, -v84
	v_fma_f32 v141, v141, 0.5, -v85
	v_fma_f32 v142, v142, 0.5, -v86
	v_fma_f32 v143, v143, 0.5, -v87
	v_fma_f32 v128, v104, v136, v80
	v_fma_f32 v129, v105, v137, v81
	v_fma_f32 v130, v106, v138, v82
	v_fma_f32 v131, v107, v139, v83
	v_fma_f32 v132, v108, v140, v84
	v_fma_f32 v133, v109, v141, v85
	v_fma_f32 v134, v110, v142, v86
	v_fma_f32 v135, v111, v143, v87
	v_cvt_pk_bf16_f32 v246, v128, v129
	v_cvt_pk_bf16_f32 v247, v130, v131
	v_cvt_pk_bf16_f32 v248, v132, v133
	v_cvt_pk_bf16_f32 v249, v134, v135
	global_store_dwordx4 v5, v[246:249], s[58:59] nt
	v_add_u32_e32 v5, 0xc00, v5
	v_lshlrev_b32_e32 v96, 16, v28
	v_and_b32_e32 v97, 0xffff0000, v28
	v_lshlrev_b32_e32 v98, 16, v29
	v_and_b32_e32 v99, 0xffff0000, v29
	v_lshlrev_b32_e32 v100, 16, v30
	v_and_b32_e32 v101, 0xffff0000, v30
	v_lshlrev_b32_e32 v102, 16, v31
	v_and_b32_e32 v103, 0xffff0000, v31
	v_add_f32_e32 v136, v80, v96
	v_add_f32_e32 v137, v81, v97
	v_add_f32_e32 v138, v82, v98
	v_add_f32_e32 v139, v83, v99
	v_add_f32_e32 v140, v84, v100
	v_add_f32_e32 v141, v85, v101
	v_add_f32_e32 v142, v86, v102
	v_add_f32_e32 v143, v87, v103
	v_fma_f32 v136, v136, 0.5, -v88
	v_fma_f32 v137, v137, 0.5, -v89
	v_fma_f32 v138, v138, 0.5, -v90
	v_fma_f32 v139, v139, 0.5, -v91
	v_fma_f32 v140, v140, 0.5, -v92
	v_fma_f32 v141, v141, 0.5, -v93
	v_fma_f32 v142, v142, 0.5, -v94
	v_fma_f32 v143, v143, 0.5, -v95
	v_fma_f32 v128, v104, v136, v88
	v_fma_f32 v129, v105, v137, v89
	v_fma_f32 v130, v106, v138, v90
	v_fma_f32 v131, v107, v139, v91
	v_fma_f32 v132, v108, v140, v92
	v_fma_f32 v133, v109, v141, v93
	v_fma_f32 v134, v110, v142, v94
	v_fma_f32 v135, v111, v143, v95
	v_cvt_pk_bf16_f32 v246, v128, v129
	v_cvt_pk_bf16_f32 v247, v130, v131
	v_cvt_pk_bf16_f32 v248, v132, v133
	v_cvt_pk_bf16_f32 v249, v134, v135
	global_store_dwordx4 v5, v[246:249], s[58:59] nt
	v_add_u32_e32 v5, 0xc00, v5
	v_lshlrev_b32_e32 v80, 16, v32
	v_and_b32_e32 v81, 0xffff0000, v32
	v_lshlrev_b32_e32 v82, 16, v33
	v_and_b32_e32 v83, 0xffff0000, v33
	v_lshlrev_b32_e32 v84, 16, v34
	v_and_b32_e32 v85, 0xffff0000, v34
	v_lshlrev_b32_e32 v86, 16, v35
	v_and_b32_e32 v87, 0xffff0000, v35
	v_add_f32_e32 v136, v88, v80
	v_add_f32_e32 v137, v89, v81
	v_add_f32_e32 v138, v90, v82
	v_add_f32_e32 v139, v91, v83
	v_add_f32_e32 v140, v92, v84
	v_add_f32_e32 v141, v93, v85
	v_add_f32_e32 v142, v94, v86
	v_add_f32_e32 v143, v95, v87
	v_fma_f32 v136, v136, 0.5, -v96
	v_fma_f32 v137, v137, 0.5, -v97
	v_fma_f32 v138, v138, 0.5, -v98
	v_fma_f32 v139, v139, 0.5, -v99
	v_fma_f32 v140, v140, 0.5, -v100
	v_fma_f32 v141, v141, 0.5, -v101
	v_fma_f32 v142, v142, 0.5, -v102
	v_fma_f32 v143, v143, 0.5, -v103
	v_fma_f32 v128, v104, v136, v96
	v_fma_f32 v129, v105, v137, v97
	v_fma_f32 v130, v106, v138, v98
	v_fma_f32 v131, v107, v139, v99
	v_fma_f32 v132, v108, v140, v100
	v_fma_f32 v133, v109, v141, v101
	v_fma_f32 v134, v110, v142, v102
	v_fma_f32 v135, v111, v143, v103
	v_cvt_pk_bf16_f32 v246, v128, v129
	v_cvt_pk_bf16_f32 v247, v130, v131
	v_cvt_pk_bf16_f32 v248, v132, v133
	v_cvt_pk_bf16_f32 v249, v134, v135
	global_store_dwordx4 v5, v[246:249], s[58:59] nt
	v_add_u32_e32 v5, 0xc00, v5
	v_lshlrev_b32_e32 v88, 16, v36
	v_and_b32_e32 v89, 0xffff0000, v36
	v_lshlrev_b32_e32 v90, 16, v37
	v_and_b32_e32 v91, 0xffff0000, v37
	v_lshlrev_b32_e32 v92, 16, v38
; __device__ __forceinline__ void unpack8(const u32x4 w, float (&f)[8]) { f[0] = bflo(w.x); f[1] = bfhi(w.x); f[2] = bflo(w.y); f[3] = bfhi(w.y); f[4] = bflo(w.z); f[5] = bfhi(w.z); f[6] = bflo(w.w); f[7] = bfhi(w.w); }
; __device__ __forceinline__ u32x4 pack8(const float (&f)[8]) { u32x4 o; o.x = pk2(f[0], f[1]); o.y = pk2(f[2], f[3]); o.z = pk2(f[4], f[5]); o.w = pk2(f[6], f[7]); return o; }
; __device__ __forceinline__ float sigmoidf_(float x) { return __builtin_amdgcn_rcpf(1.0f + __expf(-x)); }
; __device__ __forceinline__ float tanhf_(float x) { return 1.0f - 2.0f * __builtin_amdgcn_rcpf(__expf(2.0f * x) + 1.0f); }
; template <int CH> __device__ __forceinline__ void p2_rwkv_chunk(const Params& p, int t0, int lane) {
;     ...
;     for (int i = 0; i < 16; ++i) {
;         const int t = t0 + i; const bool hasn = (t & (T_SEQ - 1)) != T_SEQ - 1;
;         if (hasn) unpack8(raw, N); else {
; #pragma unroll
;             for (int q = 0; q < 8; ++q) N[q] = 0.f; }
;         if (i < 15 && ((t + 1) & (T_SEQ - 1)) != T_SEQ - 1) raw = __builtin_nontemporal_load((const u32x4*)(zc + (size_t)(i + 2) * ZLD));
;         float zs[8];
; #pragma unroll
;         for (int q = 0; q < 8; ++q) zs[q] = C[q] + mu[q] * (0.5f * (P[q] + N[q]) - C[q]);
;         if (CH < 3) {
;             *(u32x4*)(RKV + (size_t)t * 1536 + c) = pack8(zs);
;             if (CH == 1) { float s2 = 0.f;
; #pragma unroll
;                 for (int q = 0; q < 8; ++q) { const float v = zs[q] * kq[q]; s2 += v * v; }
;                 s2 = red8s(s2);
;                 if ((lane & 7) == 0) RINV[t * 8 + (lane >> 3)] = rsqrtf(fmaxf(s2, 1e-24f)); }
;         } else {
;             const int cc = c - 1536; float o[8];
; #pragma unroll
;             for (int q = 0; q < 8; ++q) o[q] = cc < 128 ? tanhf_(zs[q]) : (cc < 192 ? zs[q] : sigmoidf_(zs[q]));
;             *(u32x4*)(AP + (size_t)t * KLORA + cc) = pack8(o);
;         }
; #pragma unroll
;         for (int q = 0; q < 8; ++q) { P[q] = C[q]; C[q] = N[q]; }
	v_and_b32_e32 v93, 0xffff0000, v38
	v_lshlrev_b32_e32 v94, 16, v39
	v_and_b32_e32 v95, 0xffff0000, v39
	v_add_f32_e32 v136, v96, v88
	v_add_f32_e32 v137, v97, v89
	v_add_f32_e32 v138, v98, v90
	v_add_f32_e32 v139, v99, v91
	v_add_f32_e32 v140, v100, v92
	v_add_f32_e32 v141, v101, v93
	v_add_f32_e32 v142, v102, v94
	v_add_f32_e32 v143, v103, v95
	v_fma_f32 v136, v136, 0.5, -v80
	v_fma_f32 v137, v137, 0.5, -v81
	v_fma_f32 v138, v138, 0.5, -v82
	v_fma_f32 v139, v139, 0.5, -v83
	v_fma_f32 v140, v140, 0.5, -v84
	v_fma_f32 v141, v141, 0.5, -v85
	v_fma_f32 v142, v142, 0.5, -v86
	v_fma_f32 v143, v143, 0.5, -v87
	v_fma_f32 v128, v104, v136, v80
	v_fma_f32 v129, v105, v137, v81
	v_fma_f32 v130, v106, v138, v82
	v_fma_f32 v131, v107, v139, v83
	v_fma_f32 v132, v108, v140, v84
	v_fma_f32 v133, v109, v141, v85
	v_fma_f32 v134, v110, v142, v86
	v_fma_f32 v135, v111, v143, v87
	v_cvt_pk_bf16_f32 v246, v128, v129
	v_cvt_pk_bf16_f32 v247, v130, v131
	v_cvt_pk_bf16_f32 v248, v132, v133
	v_cvt_pk_bf16_f32 v249, v134, v135
	global_store_dwordx4 v5, v[246:249], s[58:59] nt
	v_add_u32_e32 v5, 0xc00, v5
	v_lshlrev_b32_e32 v96, 16, v40
	v_and_b32_e32 v97, 0xffff0000, v40
	v_lshlrev_b32_e32 v98, 16, v41
	v_and_b32_e32 v99, 0xffff0000, v41
	v_lshlrev_b32_e32 v100, 16, v42
	v_and_b32_e32 v101, 0xffff0000, v42
	v_lshlrev_b32_e32 v102, 16, v43
	v_and_b32_e32 v103, 0xffff0000, v43
	v_add_f32_e32 v136, v80, v96
	v_add_f32_e32 v137, v81, v97
	v_add_f32_e32 v138, v82, v98
	v_add_f32_e32 v139, v83, v99
	v_add_f32_e32 v140, v84, v100
	v_add_f32_e32 v141, v85, v101
	v_add_f32_e32 v142, v86, v102
	v_add_f32_e32 v143, v87, v103
	v_fma_f32 v136, v136, 0.5, -v88
	v_fma_f32 v137, v137, 0.5, -v89
	v_fma_f32 v138, v138, 0.5, -v90
	v_fma_f32 v139, v139, 0.5, -v91
	v_fma_f32 v140, v140, 0.5, -v92
	v_fma_f32 v141, v141, 0.5, -v93
	v_fma_f32 v142, v142, 0.5, -v94
	v_fma_f32 v143, v143, 0.5, -v95
	v_fma_f32 v128, v104, v136, v88
	v_fma_f32 v129, v105, v137, v89
	v_fma_f32 v130, v106, v138, v90
	v_fma_f32 v131, v107, v139, v91
	v_fma_f32 v132, v108, v140, v92
	v_fma_f32 v133, v109, v141, v93
	v_fma_f32 v134, v110, v142, v94
	v_fma_f32 v135, v111, v143, v95
	v_cvt_pk_bf16_f32 v246, v128, v129
	v_cvt_pk_bf16_f32 v247, v130, v131
	v_cvt_pk_bf16_f32 v248, v132, v133
	v_cvt_pk_bf16_f32 v249, v134, v135
	global_store_dwordx4 v5, v[246:249], s[58:59] nt
	v_add_u32_e32 v5, 0xc00, v5
	v_lshlrev_b32_e32 v80, 16, v44
	v_and_b32_e32 v81, 0xffff0000, v44
	v_lshlrev_b32_e32 v82, 16, v45
	v_and_b32_e32 v83, 0xffff0000, v45
	v_lshlrev_b32_e32 v84, 16, v46
	v_and_b32_e32 v85, 0xffff0000, v46
	v_lshlrev_b32_e32 v86, 16, v47
	v_and_b32_e32 v87, 0xffff0000, v47
	v_add_f32_e32 v136, v88, v80
	v_add_f32_e32 v137, v89, v81
	v_add_f32_e32 v138, v90, v82
	v_add_f32_e32 v139, v91, v83
	v_add_f32_e32 v140, v92, v84
	v_add_f32_e32 v141, v93, v85
	v_add_f32_e32 v142, v94, v86
	v_add_f32_e32 v143, v95, v87
	v_fma_f32 v136, v136, 0.5, -v96
	v_fma_f32 v137, v137, 0.5, -v97
	v_fma_f32 v138, v138, 0.5, -v98
	v_fma_f32 v139, v139, 0.5, -v99
	v_fma_f32 v140, v140, 0.5, -v100
	v_fma_f32 v141, v141, 0.5, -v101
	v_fma_f32 v142, v142, 0.5, -v102
	v_fma_f32 v143, v143, 0.5, -v103
	v_fma_f32 v128, v104, v136, v96
	v_fma_f32 v129, v105, v137, v97
	v_fma_f32 v130, v106, v138, v98
	v_fma_f32 v131, v107, v139, v99
	v_fma_f32 v132, v108, v140, v100
	v_fma_f32 v133, v109, v141, v101
	v_fma_f32 v134, v110, v142, v102
	v_fma_f32 v135, v111, v143, v103
	v_cvt_pk_bf16_f32 v246, v128, v129
	v_cvt_pk_bf16_f32 v247, v130, v131
	v_cvt_pk_bf16_f32 v248, v132, v133
	v_cvt_pk_bf16_f32 v249, v134, v135
	global_store_dwordx4 v5, v[246:249], s[58:59] nt
	v_add_u32_e32 v5, 0xc00, v5
	v_lshlrev_b32_e32 v88, 16, v48
	v_and_b32_e32 v89, 0xffff0000, v48
	v_lshlrev_b32_e32 v90, 16, v49
	v_and_b32_e32 v91, 0xffff0000, v49
	v_lshlrev_b32_e32 v92, 16, v50
	v_and_b32_e32 v93, 0xffff0000, v50
	v_lshlrev_b32_e32 v94, 16, v51
	v_and_b32_e32 v95, 0xffff0000, v51
	v_add_f32_e32 v136, v96, v88
	v_add_f32_e32 v137, v97, v89
	v_add_f32_e32 v138, v98, v90
	v_add_f32_e32 v139, v99, v91
	v_add_f32_e32 v140, v100, v92
	v_add_f32_e32 v141, v101, v93
	v_add_f32_e32 v142, v102, v94
	v_add_f32_e32 v143, v103, v95
	v_fma_f32 v136, v136, 0.5, -v80
	v_fma_f32 v137, v137, 0.5, -v81
	v_fma_f32 v138, v138, 0.5, -v82
	v_fma_f32 v139, v139, 0.5, -v83
	v_fma_f32 v140, v140, 0.5, -v84
	v_fma_f32 v141, v141, 0.5, -v85
	v_fma_f32 v142, v142, 0.5, -v86
	v_fma_f32 v143, v143, 0.5, -v87
	v_fma_f32 v128, v104, v136, v80
	v_fma_f32 v129, v105, v137, v81
	v_fma_f32 v130, v106, v138, v82
	v_fma_f32 v131, v107, v139, v83
	v_fma_f32 v132, v108, v140, v84
	v_fma_f32 v133, v109, v141, v85
	v_fma_f32 v134, v110, v142, v86
	v_fma_f32 v135, v111, v143, v87
	v_cvt_pk_bf16_f32 v246, v128, v129
	v_cvt_pk_bf16_f32 v247, v130, v131
	v_cvt_pk_bf16_f32 v248, v132, v133
	v_cvt_pk_bf16_f32 v249, v134, v135
	global_store_dwordx4 v5, v[246:249], s[58:59] nt
	v_add_u32_e32 v5, 0xc00, v5
	v_lshlrev_b32_e32 v96, 16, v52
	v_and_b32_e32 v97, 0xffff0000, v52
	v_lshlrev_b32_e32 v98, 16, v53
	v_and_b32_e32 v99, 0xffff0000, v53
	v_lshlrev_b32_e32 v100, 16, v54
	v_and_b32_e32 v101, 0xffff0000, v54
	v_lshlrev_b32_e32 v102, 16, v55
	v_and_b32_e32 v103, 0xffff0000, v55
	v_add_f32_e32 v136, v80, v96
	v_add_f32_e32 v137, v81, v97
	v_add_f32_e32 v138, v82, v98
	v_add_f32_e32 v139, v83, v99
	v_add_f32_e32 v140, v84, v100
	v_add_f32_e32 v141, v85, v101
	v_add_f32_e32 v142, v86, v102
	v_add_f32_e32 v143, v87, v103
	v_fma_f32 v136, v136, 0.5, -v88
	v_fma_f32 v137, v137, 0.5, -v89
	v_fma_f32 v138, v138, 0.5, -v90
	v_fma_f32 v139, v139, 0.5, -v91
	v_fma_f32 v140, v140, 0.5, -v92
	v_fma_f32 v141, v141, 0.5, -v93
; __device__ __forceinline__ void unpack8(const u32x4 w, float (&f)[8]) { f[0] = bflo(w.x); f[1] = bfhi(w.x); f[2] = bflo(w.y); f[3] = bfhi(w.y); f[4] = bflo(w.z); f[5] = bfhi(w.z); f[6] = bflo(w.w); f[7] = bfhi(w.w); }
; __device__ __forceinline__ u32x4 pack8(const float (&f)[8]) { u32x4 o; o.x = pk2(f[0], f[1]); o.y = pk2(f[2], f[3]); o.z = pk2(f[4], f[5]); o.w = pk2(f[6], f[7]); return o; }
; __device__ __forceinline__ float sigmoidf_(float x) { return __builtin_amdgcn_rcpf(1.0f + __expf(-x)); }
; __device__ __forceinline__ float tanhf_(float x) { return 1.0f - 2.0f * __builtin_amdgcn_rcpf(__expf(2.0f * x) + 1.0f); }
; template <int CH> __device__ __forceinline__ void p2_rwkv_chunk(const Params& p, int t0, int lane) {
;     ...
;     for (int i = 0; i < 16; ++i) {
;         const int t = t0 + i; const bool hasn = (t & (T_SEQ - 1)) != T_SEQ - 1;
;         if (hasn) unpack8(raw, N); else {
; #pragma unroll
;             for (int q = 0; q < 8; ++q) N[q] = 0.f; }
;         if (i < 15 && ((t + 1) & (T_SEQ - 1)) != T_SEQ - 1) raw = __builtin_nontemporal_load((const u32x4*)(zc + (size_t)(i + 2) * ZLD));
;         float zs[8];
; #pragma unroll
;         for (int q = 0; q < 8; ++q) zs[q] = C[q] + mu[q] * (0.5f * (P[q] + N[q]) - C[q]);
;         if (CH < 3) {
;             *(u32x4*)(RKV + (size_t)t * 1536 + c) = pack8(zs);
;             if (CH == 1) { float s2 = 0.f;
; #pragma unroll
;                 for (int q = 0; q < 8; ++q) { const float v = zs[q] * kq[q]; s2 += v * v; }
;                 s2 = red8s(s2);
;                 if ((lane & 7) == 0) RINV[t * 8 + (lane >> 3)] = rsqrtf(fmaxf(s2, 1e-24f)); }
;         } else {
;             const int cc = c - 1536; float o[8];
; #pragma unroll
;             for (int q = 0; q < 8; ++q) o[q] = cc < 128 ? tanhf_(zs[q]) : (cc < 192 ? zs[q] : sigmoidf_(zs[q]));
;             *(u32x4*)(AP + (size_t)t * KLORA + cc) = pack8(o);
;         }
; #pragma unroll
;         for (int q = 0; q < 8; ++q) { P[q] = C[q]; C[q] = N[q]; }
	v_fma_f32 v142, v142, 0.5, -v94
	v_fma_f32 v143, v143, 0.5, -v95
	v_fma_f32 v128, v104, v136, v88
	v_fma_f32 v129, v105, v137, v89
	v_fma_f32 v130, v106, v138, v90
	v_fma_f32 v131, v107, v139, v91
	v_fma_f32 v132, v108, v140, v92
	v_fma_f32 v133, v109, v141, v93
	v_fma_f32 v134, v110, v142, v94
	v_fma_f32 v135, v111, v143, v95
	v_cvt_pk_bf16_f32 v246, v128, v129
	v_cvt_pk_bf16_f32 v247, v130, v131
	v_cvt_pk_bf16_f32 v248, v132, v133
	v_cvt_pk_bf16_f32 v249, v134, v135
	global_store_dwordx4 v5, v[246:249], s[58:59] nt
	v_add_u32_e32 v5, 0xc00, v5
	v_lshlrev_b32_e32 v80, 16, v56
	v_and_b32_e32 v81, 0xffff0000, v56
	v_lshlrev_b32_e32 v82, 16, v57
	v_and_b32_e32 v83, 0xffff0000, v57
	v_lshlrev_b32_e32 v84, 16, v58
	v_and_b32_e32 v85, 0xffff0000, v58
	v_lshlrev_b32_e32 v86, 16, v59
	v_and_b32_e32 v87, 0xffff0000, v59
	v_add_f32_e32 v136, v88, v80
	v_add_f32_e32 v137, v89, v81
	v_add_f32_e32 v138, v90, v82
	v_add_f32_e32 v139, v91, v83
	v_add_f32_e32 v140, v92, v84
	v_add_f32_e32 v141, v93, v85
	v_add_f32_e32 v142, v94, v86
	v_add_f32_e32 v143, v95, v87
	v_fma_f32 v136, v136, 0.5, -v96
	v_fma_f32 v137, v137, 0.5, -v97
	v_fma_f32 v138, v138, 0.5, -v98
	v_fma_f32 v139, v139, 0.5, -v99
	v_fma_f32 v140, v140, 0.5, -v100
	v_fma_f32 v141, v141, 0.5, -v101
	v_fma_f32 v142, v142, 0.5, -v102
	v_fma_f32 v143, v143, 0.5, -v103
	v_fma_f32 v128, v104, v136, v96
	v_fma_f32 v129, v105, v137, v97
	v_fma_f32 v130, v106, v138, v98
	v_fma_f32 v131, v107, v139, v99
	v_fma_f32 v132, v108, v140, v100
	v_fma_f32 v133, v109, v141, v101
	v_fma_f32 v134, v110, v142, v102
	v_fma_f32 v135, v111, v143, v103
	v_cvt_pk_bf16_f32 v246, v128, v129
	v_cvt_pk_bf16_f32 v247, v130, v131
	v_cvt_pk_bf16_f32 v248, v132, v133
	v_cvt_pk_bf16_f32 v249, v134, v135
	global_store_dwordx4 v5, v[246:249], s[58:59] nt
	v_add_u32_e32 v5, 0xc00, v5
	v_lshlrev_b32_e32 v88, 16, v60
	v_and_b32_e32 v89, 0xffff0000, v60
	v_lshlrev_b32_e32 v90, 16, v61
	v_and_b32_e32 v91, 0xffff0000, v61
	v_lshlrev_b32_e32 v92, 16, v62
	v_and_b32_e32 v93, 0xffff0000, v62
	v_lshlrev_b32_e32 v94, 16, v63
	v_and_b32_e32 v95, 0xffff0000, v63
	v_add_f32_e32 v136, v96, v88
	v_add_f32_e32 v137, v97, v89
	v_add_f32_e32 v138, v98, v90
	v_add_f32_e32 v139, v99, v91
	v_add_f32_e32 v140, v100, v92
	v_add_f32_e32 v141, v101, v93
	v_add_f32_e32 v142, v102, v94
	v_add_f32_e32 v143, v103, v95
	v_fma_f32 v136, v136, 0.5, -v80
	v_fma_f32 v137, v137, 0.5, -v81
	v_fma_f32 v138, v138, 0.5, -v82
	v_fma_f32 v139, v139, 0.5, -v83
	v_fma_f32 v140, v140, 0.5, -v84
	v_fma_f32 v141, v141, 0.5, -v85
	v_fma_f32 v142, v142, 0.5, -v86
	v_fma_f32 v143, v143, 0.5, -v87
	v_fma_f32 v128, v104, v136, v80
	v_fma_f32 v129, v105, v137, v81
	v_fma_f32 v130, v106, v138, v82
	v_fma_f32 v131, v107, v139, v83
	v_fma_f32 v132, v108, v140, v84
	v_fma_f32 v133, v109, v141, v85
	v_fma_f32 v134, v110, v142, v86
	v_fma_f32 v135, v111, v143, v87
	v_cvt_pk_bf16_f32 v246, v128, v129
	v_cvt_pk_bf16_f32 v247, v130, v131
	v_cvt_pk_bf16_f32 v248, v132, v133
	v_cvt_pk_bf16_f32 v249, v134, v135
	global_store_dwordx4 v5, v[246:249], s[58:59] nt
	v_add_u32_e32 v5, 0xc00, v5
	v_lshlrev_b32_e32 v96, 16, v64
	v_and_b32_e32 v97, 0xffff0000, v64
	v_lshlrev_b32_e32 v98, 16, v65
	v_and_b32_e32 v99, 0xffff0000, v65
	v_lshlrev_b32_e32 v100, 16, v66
	v_and_b32_e32 v101, 0xffff0000, v66
	v_lshlrev_b32_e32 v102, 16, v67
	v_and_b32_e32 v103, 0xffff0000, v67
	v_add_f32_e32 v136, v80, v96
	v_add_f32_e32 v137, v81, v97
	v_add_f32_e32 v138, v82, v98
	v_add_f32_e32 v139, v83, v99
	v_add_f32_e32 v140, v84, v100
	v_add_f32_e32 v141, v85, v101
	v_add_f32_e32 v142, v86, v102
	v_add_f32_e32 v143, v87, v103
	v_fma_f32 v136, v136, 0.5, -v88
	v_fma_f32 v137, v137, 0.5, -v89
	v_fma_f32 v138, v138, 0.5, -v90
	v_fma_f32 v139, v139, 0.5, -v91
	v_fma_f32 v140, v140, 0.5, -v92
	v_fma_f32 v141, v141, 0.5, -v93
	v_fma_f32 v142, v142, 0.5, -v94
	v_fma_f32 v143, v143, 0.5, -v95
	v_fma_f32 v128, v104, v136, v88
	v_fma_f32 v129, v105, v137, v89
	v_fma_f32 v130, v106, v138, v90
	v_fma_f32 v131, v107, v139, v91
	v_fma_f32 v132, v108, v140, v92
	v_fma_f32 v133, v109, v141, v93
	v_fma_f32 v134, v110, v142, v94
	v_fma_f32 v135, v111, v143, v95
	v_cvt_pk_bf16_f32 v246, v128, v129
	v_cvt_pk_bf16_f32 v247, v130, v131
	v_cvt_pk_bf16_f32 v248, v132, v133
	v_cvt_pk_bf16_f32 v249, v134, v135
	global_store_dwordx4 v5, v[246:249], s[58:59] nt
	v_add_u32_e32 v5, 0xc00, v5
	v_lshlrev_b32_e32 v80, 16, v68
	v_and_b32_e32 v81, 0xffff0000, v68
	v_lshlrev_b32_e32 v82, 16, v69
	v_and_b32_e32 v83, 0xffff0000, v69
	v_lshlrev_b32_e32 v84, 16, v70
	v_and_b32_e32 v85, 0xffff0000, v70
	v_lshlrev_b32_e32 v86, 16, v71
	v_and_b32_e32 v87, 0xffff0000, v71
	v_add_f32_e32 v136, v88, v80
	v_add_f32_e32 v137, v89, v81
	v_add_f32_e32 v138, v90, v82
	v_add_f32_e32 v139, v91, v83
	v_add_f32_e32 v140, v92, v84
	v_add_f32_e32 v141, v93, v85
	v_add_f32_e32 v142, v94, v86
	v_add_f32_e32 v143, v95, v87
	v_fma_f32 v136, v136, 0.5, -v96
	v_fma_f32 v137, v137, 0.5, -v97
	v_fma_f32 v138, v138, 0.5, -v98
	v_fma_f32 v139, v139, 0.5, -v99
	v_fma_f32 v140, v140, 0.5, -v100
	v_fma_f32 v141, v141, 0.5, -v101
	v_fma_f32 v142, v142, 0.5, -v102
	v_fma_f32 v143, v143, 0.5, -v103
	v_fma_f32 v128, v104, v136, v96
	v_fma_f32 v129, v105, v137, v97
	v_fma_f32 v130, v106, v138, v98
	v_fma_f32 v131, v107, v139, v99
	v_fma_f32 v132, v108, v140, v100
	v_fma_f32 v133, v109, v141, v101
	v_fma_f32 v134, v110, v142, v102
	v_fma_f32 v135, v111, v143, v103
	v_cvt_pk_bf16_f32 v246, v128, v129
	v_cvt_pk_bf16_f32 v247, v130, v131
	v_cvt_pk_bf16_f32 v248, v132, v133
	v_cvt_pk_bf16_f32 v249, v134, v135
	global_store_dwordx4 v5, v[246:249], s[58:59] nt
	v_add_u32_e32 v5, 0xc00, v5
	v_lshlrev_b32_e32 v88, 16, v72
	v_and_b32_e32 v89, 0xffff0000, v72
	v_lshlrev_b32_e32 v90, 16, v73
	v_and_b32_e32 v91, 0xffff0000, v73
	v_lshlrev_b32_e32 v92, 16, v74
	v_and_b32_e32 v93, 0xffff0000, v74
	v_lshlrev_b32_e32 v94, 16, v75
	v_and_b32_e32 v95, 0xffff0000, v75
	v_add_f32_e32 v136, v96, v88
	v_add_f32_e32 v137, v97, v89
	v_add_f32_e32 v138, v98, v90
	v_add_f32_e32 v139, v99, v91
	v_add_f32_e32 v140, v100, v92
	v_add_f32_e32 v141, v101, v93
	v_add_f32_e32 v142, v102, v94
	v_add_f32_e32 v143, v103, v95
	v_fma_f32 v136, v136, 0.5, -v80
	v_fma_f32 v137, v137, 0.5, -v81
	v_fma_f32 v138, v138, 0.5, -v82
	v_fma_f32 v139, v139, 0.5, -v83
	v_fma_f32 v140, v140, 0.5, -v84
	v_fma_f32 v141, v141, 0.5, -v85
	v_fma_f32 v142, v142, 0.5, -v86
	v_fma_f32 v143, v143, 0.5, -v87
	v_fma_f32 v128, v104, v136, v80
	v_fma_f32 v129, v105, v137, v81
	v_fma_f32 v130, v106, v138, v82
	v_fma_f32 v131, v107, v139, v83
	v_fma_f32 v132, v108, v140, v84
	v_fma_f32 v133, v109, v141, v85
	v_fma_f32 v134, v110, v142, v86
	v_fma_f32 v135, v111, v143, v87
	v_cvt_pk_bf16_f32 v246, v128, v129
	v_cvt_pk_bf16_f32 v247, v130, v131
	v_cvt_pk_bf16_f32 v248, v132, v133
	v_cvt_pk_bf16_f32 v249, v134, v135
	global_store_dwordx4 v5, v[246:249], s[58:59] nt
	v_add_u32_e32 v5, 0xc00, v5
	s_cmp_eq_u32 s67, 0
	s_cbranch_scc1 .Lp2_nz_4
	v_mov_b32_e32 v76, 0
	v_mov_b32_e32 v77, 0
	v_mov_b32_e32 v78, 0
	v_mov_b32_e32 v79, 0
; __device__ __forceinline__ void unpack8(const u32x4 w, float (&f)[8]) { f[0] = bflo(w.x); f[1] = bfhi(w.x); f[2] = bflo(w.y); f[3] = bfhi(w.y); f[4] = bflo(w.z); f[5] = bfhi(w.z); f[6] = bflo(w.w); f[7] = bfhi(w.w); }
; __device__ __forceinline__ u32x4 pack8(const float (&f)[8]) { u32x4 o; o.x = pk2(f[0], f[1]); o.y = pk2(f[2], f[3]); o.z = pk2(f[4], f[5]); o.w = pk2(f[6], f[7]); return o; }
; template <int CH> __device__ __forceinline__ void p2_rwkv_chunk(const Params& p, int t0, int lane) {
;     ...
;     const bf16_t* zc = (const bf16_t*)(ws + WS_Z) + (size_t)t0 * ZLD + c;
;     float mu[8], kq[8];
;     { const f32x4 m0 = *(const f32x4*)(p.in[8] + c), m1 = *(const f32x4*)(p.in[8] + c + 4);
; #pragma unroll
;       for (int i = 0; i < 4; ++i) { mu[i] = m0[i]; mu[4 + i] = m1[i]; } }
;     if (CH == 1) { const f32x4 q0 = *(const f32x4*)(p.in[14] + c - 512), q1 = *(const f32x4*)(p.in[14] + c - 512 + 4);
; #pragma unroll
;         for (int i = 0; i < 4; ++i) { kq[i] = q0[i]; kq[4 + i] = q1[i]; } }
;     float P[8], C[8], N[8];
;     if ((t0 & (T_SEQ - 1)) != 0) unpack8(__builtin_nontemporal_load((const u32x4*)(zc - ZLD)), P); else {
; #pragma unroll
;         for (int i = 0; i < 8; ++i) P[i] = 0.f; }
;     unpack8(__builtin_nontemporal_load((const u32x4*)(zc)), C);
;     u32x4 raw = __builtin_nontemporal_load((const u32x4*)(zc + ZLD));
; #pragma unroll 2
;     for (int i = 0; i < 16; ++i) {
;         const int t = t0 + i; const bool hasn = (t & (T_SEQ - 1)) != T_SEQ - 1;
;         if (hasn) unpack8(raw, N); else {
; #pragma unroll
;             for (int q = 0; q < 8; ++q) N[q] = 0.f; }
;         if (i < 15 && ((t + 1) & (T_SEQ - 1)) != T_SEQ - 1) raw = __builtin_nontemporal_load((const u32x4*)(zc + (size_t)(i + 2) * ZLD));
;         float zs[8];
; #pragma unroll
;         for (int q = 0; q < 8; ++q) zs[q] = C[q] + mu[q] * (0.5f * (P[q] + N[q]) - C[q]);
;         if (CH < 3) {
;             *(u32x4*)(RKV + (size_t)t * 1536 + c) = pack8(zs);
;             if (CH == 1) { float s2 = 0.f;
; #pragma unroll
;                 for (int q = 0; q < 8; ++q) { const float v = zs[q] * kq[q]; s2 += v * v; }
;                 s2 = red8s(s2);
;                 if ((lane & 7) == 0) RINV[t * 8 + (lane >> 3)] = rsqrtf(fmaxf(s2, 1e-24f)); }
.Lp2_nz_4:
	v_lshlrev_b32_e32 v96, 16, v76
	v_and_b32_e32 v97, 0xffff0000, v76
	v_lshlrev_b32_e32 v98, 16, v77
	v_and_b32_e32 v99, 0xffff0000, v77
	v_lshlrev_b32_e32 v100, 16, v78
	v_and_b32_e32 v101, 0xffff0000, v78
	v_lshlrev_b32_e32 v102, 16, v79
	v_and_b32_e32 v103, 0xffff0000, v79
	v_add_f32_e32 v136, v80, v96
	v_add_f32_e32 v137, v81, v97
	v_add_f32_e32 v138, v82, v98
	v_add_f32_e32 v139, v83, v99
	v_add_f32_e32 v140, v84, v100
	v_add_f32_e32 v141, v85, v101
	v_add_f32_e32 v142, v86, v102
	v_add_f32_e32 v143, v87, v103
	v_fma_f32 v136, v136, 0.5, -v88
	v_fma_f32 v137, v137, 0.5, -v89
	v_fma_f32 v138, v138, 0.5, -v90
	v_fma_f32 v139, v139, 0.5, -v91
	v_fma_f32 v140, v140, 0.5, -v92
	v_fma_f32 v141, v141, 0.5, -v93
	v_fma_f32 v142, v142, 0.5, -v94
	v_fma_f32 v143, v143, 0.5, -v95
	v_fma_f32 v128, v104, v136, v88
	v_fma_f32 v129, v105, v137, v89
	v_fma_f32 v130, v106, v138, v90
	v_fma_f32 v131, v107, v139, v91
	v_fma_f32 v132, v108, v140, v92
	v_fma_f32 v133, v109, v141, v93
	v_fma_f32 v134, v110, v142, v94
	v_fma_f32 v135, v111, v143, v95
	v_cvt_pk_bf16_f32 v246, v128, v129
	v_cvt_pk_bf16_f32 v247, v130, v131
	v_cvt_pk_bf16_f32 v248, v132, v133
	v_cvt_pk_bf16_f32 v249, v134, v135
	global_store_dwordx4 v5, v[246:249], s[58:59] nt
	v_add_u32_e32 v5, 0xc00, v5
	s_mov_b32 s98, 0x800
	s_mov_b32 s99, 0
	v_lshl_add_u64 v[2:3], v[250:251], 0, s[98:99]
	global_load_dwordx4 v[104:107], v[2:3], off
	global_load_dwordx4 v[108:111], v[2:3], off offset:16
	v_lshlrev_b32_e32 v1, 5, v0
	global_load_dwordx4 v[112:115], v1, s[28:29]
	global_load_dwordx4 v[116:119], v1, s[28:29] offset:16
	s_mul_i32 s63, s62, 0x1c00
	s_add_u32 s63, s63, 0x7000800
	v_lshl_add_u32 v4, v0, 4, s63
	v_add_u32_e32 v1, 0xffffe400, v4
	s_cmp_lg_u32 s66, 0
	s_cselect_b64 vcc, -1, 0
	s_nop 1
	v_cndmask_b32_e32 v1, v1, v4, vcc
	global_load_dwordx4 v[8:11], v1, s[58:59] nt
	global_load_dwordx4 v[12:15], v4, s[58:59] nt
	v_mov_b32_e32 v1, v4
	v_add_u32_e32 v1, 0x1c00, v1
	global_load_dwordx4 v[16:19], v1, s[58:59] nt
	v_add_u32_e32 v1, 0x1c00, v1
	global_load_dwordx4 v[20:23], v1, s[58:59] nt
	v_add_u32_e32 v1, 0x1c00, v1
	global_load_dwordx4 v[24:27], v1, s[58:59] nt
	v_add_u32_e32 v1, 0x1c00, v1
	global_load_dwordx4 v[28:31], v1, s[58:59] nt
	v_add_u32_e32 v1, 0x1c00, v1
	global_load_dwordx4 v[32:35], v1, s[58:59] nt
	v_add_u32_e32 v1, 0x1c00, v1
	global_load_dwordx4 v[36:39], v1, s[58:59] nt
	v_add_u32_e32 v1, 0x1c00, v1
	global_load_dwordx4 v[40:43], v1, s[58:59] nt
	v_add_u32_e32 v1, 0x1c00, v1
	global_load_dwordx4 v[44:47], v1, s[58:59] nt
	v_add_u32_e32 v1, 0x1c00, v1
	global_load_dwordx4 v[48:51], v1, s[58:59] nt
	v_add_u32_e32 v1, 0x1c00, v1
	global_load_dwordx4 v[52:55], v1, s[58:59] nt
	v_add_u32_e32 v1, 0x1c00, v1
	global_load_dwordx4 v[56:59], v1, s[58:59] nt
	v_add_u32_e32 v1, 0x1c00, v1
	global_load_dwordx4 v[60:63], v1, s[58:59] nt
	v_add_u32_e32 v1, 0x1c00, v1
	global_load_dwordx4 v[64:67], v1, s[58:59] nt
	v_add_u32_e32 v1, 0x1c00, v1
	global_load_dwordx4 v[68:71], v1, s[58:59] nt
	v_add_u32_e32 v1, 0x1c00, v1
	global_load_dwordx4 v[72:75], v1, s[58:59] nt
	v_add_u32_e32 v1, 0x1c00, v1
	s_cmp_lg_u32 s67, 0
	s_cselect_b64 vcc, -1, 0
	s_nop 1
	v_cndmask_b32_e32 v1, v1, v4, vcc
	global_load_dwordx4 v[76:79], v1, s[58:59] nt
	s_mul_i32 s63, s62, 0xc00
	s_add_u32 s63, s63, 0x15000400
	v_lshl_add_u32 v5, v0, 4, s63
	s_lshl_b32 s63, s62, 5
	s_add_u32 s63, s63, 0x2e00000
	v_lshrrev_b32_e32 v6, 3, v0
	v_lshl_add_u32 v6, v6, 2, s63
	v_and_b32_e32 v151, 7, v0
	v_cmp_eq_u32_e64 s[64:65], 0, v151
	s_waitcnt vmcnt(18)
	s_cmp_eq_u32 s66, 0
	s_cbranch_scc1 .Lp2_nz_5
	v_mov_b32_e32 v168, 0
	v_mov_b32_e32 v169, 0
	v_mov_b32_e32 v170, 0
	v_mov_b32_e32 v171, 0
.Lp2_nz_5:
	v_lshlrev_b32_e32 v80, 16, v168
	v_and_b32_e32 v81, 0xffff0000, v168
	v_lshlrev_b32_e32 v82, 16, v169
	v_and_b32_e32 v83, 0xffff0000, v169
	v_lshlrev_b32_e32 v84, 16, v170
	v_and_b32_e32 v85, 0xffff0000, v170
	v_lshlrev_b32_e32 v86, 16, v171
	v_and_b32_e32 v87, 0xffff0000, v171
	v_lshlrev_b32_e32 v88, 16, v172
	v_and_b32_e32 v89, 0xffff0000, v172
	v_lshlrev_b32_e32 v90, 16, v173
	v_and_b32_e32 v91, 0xffff0000, v173
	v_lshlrev_b32_e32 v92, 16, v174
	v_and_b32_e32 v93, 0xffff0000, v174
	v_lshlrev_b32_e32 v94, 16, v175
	v_and_b32_e32 v95, 0xffff0000, v175
	v_lshlrev_b32_e32 v96, 16, v176
	v_and_b32_e32 v97, 0xffff0000, v176
	v_lshlrev_b32_e32 v98, 16, v177
	v_and_b32_e32 v99, 0xffff0000, v177
	v_lshlrev_b32_e32 v100, 16, v178
	v_and_b32_e32 v101, 0xffff0000, v178
	v_lshlrev_b32_e32 v102, 16, v179
	v_and_b32_e32 v103, 0xffff0000, v179
	v_add_f32_e32 v136, v80, v96
	v_add_f32_e32 v137, v81, v97
	v_add_f32_e32 v138, v82, v98
	v_add_f32_e32 v139, v83, v99
	v_add_f32_e32 v140, v84, v100
	v_add_f32_e32 v141, v85, v101
	v_add_f32_e32 v142, v86, v102
	v_add_f32_e32 v143, v87, v103
	v_fma_f32 v136, v136, 0.5, -v88
	v_fma_f32 v137, v137, 0.5, -v89
	v_fma_f32 v138, v138, 0.5, -v90
	v_fma_f32 v139, v139, 0.5, -v91
	v_fma_f32 v140, v140, 0.5, -v92
	v_fma_f32 v141, v141, 0.5, -v93
	v_fma_f32 v142, v142, 0.5, -v94
	v_fma_f32 v143, v143, 0.5, -v95
	v_fma_f32 v128, v104, v136, v88
	v_fma_f32 v129, v105, v137, v89
	v_fma_f32 v130, v106, v138, v90
	v_fma_f32 v131, v107, v139, v91
	v_fma_f32 v132, v108, v140, v92
	v_fma_f32 v133, v109, v141, v93
	v_fma_f32 v134, v110, v142, v94
	v_fma_f32 v135, v111, v143, v95
	v_cvt_pk_bf16_f32 v246, v128, v129
	v_cvt_pk_bf16_f32 v247, v130, v131
	v_cvt_pk_bf16_f32 v248, v132, v133
	v_cvt_pk_bf16_f32 v249, v134, v135
	global_store_dwordx4 v5, v[246:249], s[58:59] nt
	v_add_u32_e32 v5, 0xc00, v5
	v_mul_f32_e32 v136, v128, v112
	v_mul_f32_e32 v137, v129, v113
	v_mul_f32_e32 v138, v130, v114
; __device__ __forceinline__ void unpack8(const u32x4 w, float (&f)[8]) { f[0] = bflo(w.x); f[1] = bfhi(w.x); f[2] = bflo(w.y); f[3] = bfhi(w.y); f[4] = bflo(w.z); f[5] = bfhi(w.z); f[6] = bflo(w.w); f[7] = bfhi(w.w); }
; __device__ __forceinline__ u32x4 pack8(const float (&f)[8]) { u32x4 o; o.x = pk2(f[0], f[1]); o.y = pk2(f[2], f[3]); o.z = pk2(f[4], f[5]); o.w = pk2(f[6], f[7]); return o; }
; template <int CH> __device__ __forceinline__ void p2_rwkv_chunk(const Params& p, int t0, int lane) {
;     ...
;     for (int i = 0; i < 16; ++i) {
;         const int t = t0 + i; const bool hasn = (t & (T_SEQ - 1)) != T_SEQ - 1;
;         if (hasn) unpack8(raw, N); else {
; #pragma unroll
;             for (int q = 0; q < 8; ++q) N[q] = 0.f; }
;         if (i < 15 && ((t + 1) & (T_SEQ - 1)) != T_SEQ - 1) raw = __builtin_nontemporal_load((const u32x4*)(zc + (size_t)(i + 2) * ZLD));
;         float zs[8];
; #pragma unroll
;         for (int q = 0; q < 8; ++q) zs[q] = C[q] + mu[q] * (0.5f * (P[q] + N[q]) - C[q]);
;         if (CH < 3) {
;             *(u32x4*)(RKV + (size_t)t * 1536 + c) = pack8(zs);
;             if (CH == 1) { float s2 = 0.f;
; #pragma unroll
;                 for (int q = 0; q < 8; ++q) { const float v = zs[q] * kq[q]; s2 += v * v; }
;                 s2 = red8s(s2);
;                 if ((lane & 7) == 0) RINV[t * 8 + (lane >> 3)] = rsqrtf(fmaxf(s2, 1e-24f)); }
	v_mul_f32_e32 v139, v131, v115
	v_mul_f32_e32 v140, v132, v116
	v_mul_f32_e32 v141, v133, v117
	v_mul_f32_e32 v142, v134, v118
	v_mul_f32_e32 v143, v135, v119
	v_mul_f32_e32 v144, v136, v136
	v_fmac_f32_e32 v144, v137, v137
	v_fmac_f32_e32 v144, v138, v138
	v_fmac_f32_e32 v144, v139, v139
	v_fmac_f32_e32 v144, v140, v140
	v_fmac_f32_e32 v144, v141, v141
	v_fmac_f32_e32 v144, v142, v142
	v_fmac_f32_e32 v144, v143, v143
	s_nop 1
	v_add_f32_dpp v144, v144, v144 quad_perm:[1,0,3,2] row_mask:0xf bank_mask:0xf bound_ctrl:1
	s_nop 1
	v_add_f32_dpp v144, v144, v144 quad_perm:[2,3,0,1] row_mask:0xf bank_mask:0xf bound_ctrl:1
	s_nop 1
	v_add_f32_dpp v144, v144, v144 row_half_mirror row_mask:0xf bank_mask:0xf bound_ctrl:1
	v_max_f32_e32 v144, 0x179abe15, v144
	v_rsq_f32_e32 v144, v144
	s_mov_b64 s[42:43], exec
	s_and_b64 exec, exec, s[64:65]
	global_store_dword v6, v144, s[58:59]
	s_mov_b64 exec, s[42:43]
	v_add_u32_e32 v6, 32, v6
	v_lshlrev_b32_e32 v80, 16, v180
	v_and_b32_e32 v81, 0xffff0000, v180
	v_lshlrev_b32_e32 v82, 16, v181
	v_and_b32_e32 v83, 0xffff0000, v181
	v_lshlrev_b32_e32 v84, 16, v182
	v_and_b32_e32 v85, 0xffff0000, v182
	v_lshlrev_b32_e32 v86, 16, v183
	v_and_b32_e32 v87, 0xffff0000, v183
	v_add_f32_e32 v136, v88, v80
	v_add_f32_e32 v137, v89, v81
	v_add_f32_e32 v138, v90, v82
	v_add_f32_e32 v139, v91, v83
	v_add_f32_e32 v140, v92, v84
	v_add_f32_e32 v141, v93, v85
	v_add_f32_e32 v142, v94, v86
	v_add_f32_e32 v143, v95, v87
	v_fma_f32 v136, v136, 0.5, -v96
	v_fma_f32 v137, v137, 0.5, -v97
	v_fma_f32 v138, v138, 0.5, -v98
	v_fma_f32 v139, v139, 0.5, -v99
	v_fma_f32 v140, v140, 0.5, -v100
	v_fma_f32 v141, v141, 0.5, -v101
	v_fma_f32 v142, v142, 0.5, -v102
	v_fma_f32 v143, v143, 0.5, -v103
	v_fma_f32 v128, v104, v136, v96
	v_fma_f32 v129, v105, v137, v97
	v_fma_f32 v130, v106, v138, v98
	v_fma_f32 v131, v107, v139, v99
	v_fma_f32 v132, v108, v140, v100
	v_fma_f32 v133, v109, v141, v101
	v_fma_f32 v134, v110, v142, v102
	v_fma_f32 v135, v111, v143, v103
	v_cvt_pk_bf16_f32 v246, v128, v129
	v_cvt_pk_bf16_f32 v247, v130, v131
	v_cvt_pk_bf16_f32 v248, v132, v133
	v_cvt_pk_bf16_f32 v249, v134, v135
	global_store_dwordx4 v5, v[246:249], s[58:59] nt
	v_add_u32_e32 v5, 0xc00, v5
	v_mul_f32_e32 v136, v128, v112
	v_mul_f32_e32 v137, v129, v113
	v_mul_f32_e32 v138, v130, v114
	v_mul_f32_e32 v139, v131, v115
	v_mul_f32_e32 v140, v132, v116
	v_mul_f32_e32 v141, v133, v117
	v_mul_f32_e32 v142, v134, v118
	v_mul_f32_e32 v143, v135, v119
	v_mul_f32_e32 v144, v136, v136
	v_fmac_f32_e32 v144, v137, v137
	v_fmac_f32_e32 v144, v138, v138
	v_fmac_f32_e32 v144, v139, v139
	v_fmac_f32_e32 v144, v140, v140
	v_fmac_f32_e32 v144, v141, v141
	v_fmac_f32_e32 v144, v142, v142
	v_fmac_f32_e32 v144, v143, v143
	s_nop 1
	v_add_f32_dpp v144, v144, v144 quad_perm:[1,0,3,2] row_mask:0xf bank_mask:0xf bound_ctrl:1
	s_nop 1
	v_add_f32_dpp v144, v144, v144 quad_perm:[2,3,0,1] row_mask:0xf bank_mask:0xf bound_ctrl:1
	s_nop 1
	v_add_f32_dpp v144, v144, v144 row_half_mirror row_mask:0xf bank_mask:0xf bound_ctrl:1
	v_max_f32_e32 v144, 0x179abe15, v144
	v_rsq_f32_e32 v144, v144
	s_mov_b64 s[42:43], exec
	s_and_b64 exec, exec, s[64:65]
	global_store_dword v6, v144, s[58:59]
	s_mov_b64 exec, s[42:43]
	v_add_u32_e32 v6, 32, v6
	v_lshlrev_b32_e32 v88, 16, v184
	v_and_b32_e32 v89, 0xffff0000, v184
	v_lshlrev_b32_e32 v90, 16, v185
	v_and_b32_e32 v91, 0xffff0000, v185
	v_lshlrev_b32_e32 v92, 16, v186
	v_and_b32_e32 v93, 0xffff0000, v186
	v_lshlrev_b32_e32 v94, 16, v187
	v_and_b32_e32 v95, 0xffff0000, v187
	v_add_f32_e32 v136, v96, v88
	v_add_f32_e32 v137, v97, v89
	v_add_f32_e32 v138, v98, v90
	v_add_f32_e32 v139, v99, v91
	v_add_f32_e32 v140, v100, v92
	v_add_f32_e32 v141, v101, v93
	v_add_f32_e32 v142, v102, v94
	v_add_f32_e32 v143, v103, v95
	v_fma_f32 v136, v136, 0.5, -v80
	v_fma_f32 v137, v137, 0.5, -v81
	v_fma_f32 v138, v138, 0.5, -v82
	v_fma_f32 v139, v139, 0.5, -v83
	v_fma_f32 v140, v140, 0.5, -v84
	v_fma_f32 v141, v141, 0.5, -v85
	v_fma_f32 v142, v142, 0.5, -v86
	v_fma_f32 v143, v143, 0.5, -v87
	v_fma_f32 v128, v104, v136, v80
	v_fma_f32 v129, v105, v137, v81
	v_fma_f32 v130, v106, v138, v82
	v_fma_f32 v131, v107, v139, v83
	v_fma_f32 v132, v108, v140, v84
	v_fma_f32 v133, v109, v141, v85
	v_fma_f32 v134, v110, v142, v86
	v_fma_f32 v135, v111, v143, v87
	v_cvt_pk_bf16_f32 v246, v128, v129
	v_cvt_pk_bf16_f32 v247, v130, v131
	v_cvt_pk_bf16_f32 v248, v132, v133
	v_cvt_pk_bf16_f32 v249, v134, v135
	global_store_dwordx4 v5, v[246:249], s[58:59] nt
	v_add_u32_e32 v5, 0xc00, v5
	v_mul_f32_e32 v136, v128, v112
	v_mul_f32_e32 v137, v129, v113
	v_mul_f32_e32 v138, v130, v114
	v_mul_f32_e32 v139, v131, v115
	v_mul_f32_e32 v140, v132, v116
	v_mul_f32_e32 v141, v133, v117
	v_mul_f32_e32 v142, v134, v118
	v_mul_f32_e32 v143, v135, v119
	v_mul_f32_e32 v144, v136, v136
	v_fmac_f32_e32 v144, v137, v137
	v_fmac_f32_e32 v144, v138, v138
	v_fmac_f32_e32 v144, v139, v139
	v_fmac_f32_e32 v144, v140, v140
	v_fmac_f32_e32 v144, v141, v141
	v_fmac_f32_e32 v144, v142, v142
	v_fmac_f32_e32 v144, v143, v143
	s_nop 1
	v_add_f32_dpp v144, v144, v144 quad_perm:[1,0,3,2] row_mask:0xf bank_mask:0xf bound_ctrl:1
	s_nop 1
	v_add_f32_dpp v144, v144, v144 quad_perm:[2,3,0,1] row_mask:0xf bank_mask:0xf bound_ctrl:1
	s_nop 1
	v_add_f32_dpp v144, v144, v144 row_half_mirror row_mask:0xf bank_mask:0xf bound_ctrl:1
	v_max_f32_e32 v144, 0x179abe15, v144
	v_rsq_f32_e32 v144, v144
	s_mov_b64 s[42:43], exec
	s_and_b64 exec, exec, s[64:65]
	global_store_dword v6, v144, s[58:59]
	s_mov_b64 exec, s[42:43]
	v_add_u32_e32 v6, 32, v6
	v_lshlrev_b32_e32 v96, 16, v188
	v_and_b32_e32 v97, 0xffff0000, v188
	v_lshlrev_b32_e32 v98, 16, v189
; __device__ __forceinline__ void unpack8(const u32x4 w, float (&f)[8]) { f[0] = bflo(w.x); f[1] = bfhi(w.x); f[2] = bflo(w.y); f[3] = bfhi(w.y); f[4] = bflo(w.z); f[5] = bfhi(w.z); f[6] = bflo(w.w); f[7] = bfhi(w.w); }
; __device__ __forceinline__ u32x4 pack8(const float (&f)[8]) { u32x4 o; o.x = pk2(f[0], f[1]); o.y = pk2(f[2], f[3]); o.z = pk2(f[4], f[5]); o.w = pk2(f[6], f[7]); return o; }
; template <int CH> __device__ __forceinline__ void p2_rwkv_chunk(const Params& p, int t0, int lane) {
;     ...
;     for (int i = 0; i < 16; ++i) {
;         const int t = t0 + i; const bool hasn = (t & (T_SEQ - 1)) != T_SEQ - 1;
;         if (hasn) unpack8(raw, N); else {
; #pragma unroll
;             for (int q = 0; q < 8; ++q) N[q] = 0.f; }
;         if (i < 15 && ((t + 1) & (T_SEQ - 1)) != T_SEQ - 1) raw = __builtin_nontemporal_load((const u32x4*)(zc + (size_t)(i + 2) * ZLD));
;         float zs[8];
; #pragma unroll
;         for (int q = 0; q < 8; ++q) zs[q] = C[q] + mu[q] * (0.5f * (P[q] + N[q]) - C[q]);
;         if (CH < 3) {
;             *(u32x4*)(RKV + (size_t)t * 1536 + c) = pack8(zs);
;             if (CH == 1) { float s2 = 0.f;
; #pragma unroll
;                 for (int q = 0; q < 8; ++q) { const float v = zs[q] * kq[q]; s2 += v * v; }
;                 s2 = red8s(s2);
;                 if ((lane & 7) == 0) RINV[t * 8 + (lane >> 3)] = rsqrtf(fmaxf(s2, 1e-24f)); }
	v_and_b32_e32 v99, 0xffff0000, v189
	v_lshlrev_b32_e32 v100, 16, v190
	v_and_b32_e32 v101, 0xffff0000, v190
	v_lshlrev_b32_e32 v102, 16, v191
	v_and_b32_e32 v103, 0xffff0000, v191
	v_add_f32_e32 v136, v80, v96
	v_add_f32_e32 v137, v81, v97
	v_add_f32_e32 v138, v82, v98
	v_add_f32_e32 v139, v83, v99
	v_add_f32_e32 v140, v84, v100
	v_add_f32_e32 v141, v85, v101
	v_add_f32_e32 v142, v86, v102
	v_add_f32_e32 v143, v87, v103
	v_fma_f32 v136, v136, 0.5, -v88
	v_fma_f32 v137, v137, 0.5, -v89
	v_fma_f32 v138, v138, 0.5, -v90
	v_fma_f32 v139, v139, 0.5, -v91
	v_fma_f32 v140, v140, 0.5, -v92
	v_fma_f32 v141, v141, 0.5, -v93
	v_fma_f32 v142, v142, 0.5, -v94
	v_fma_f32 v143, v143, 0.5, -v95
	v_fma_f32 v128, v104, v136, v88
	v_fma_f32 v129, v105, v137, v89
	v_fma_f32 v130, v106, v138, v90
	v_fma_f32 v131, v107, v139, v91
	v_fma_f32 v132, v108, v140, v92
	v_fma_f32 v133, v109, v141, v93
	v_fma_f32 v134, v110, v142, v94
	v_fma_f32 v135, v111, v143, v95
	v_cvt_pk_bf16_f32 v246, v128, v129
	v_cvt_pk_bf16_f32 v247, v130, v131
	v_cvt_pk_bf16_f32 v248, v132, v133
	v_cvt_pk_bf16_f32 v249, v134, v135
	global_store_dwordx4 v5, v[246:249], s[58:59] nt
	v_add_u32_e32 v5, 0xc00, v5
	v_mul_f32_e32 v136, v128, v112
	v_mul_f32_e32 v137, v129, v113
	v_mul_f32_e32 v138, v130, v114
	v_mul_f32_e32 v139, v131, v115
	v_mul_f32_e32 v140, v132, v116
	v_mul_f32_e32 v141, v133, v117
	v_mul_f32_e32 v142, v134, v118
	v_mul_f32_e32 v143, v135, v119
	v_mul_f32_e32 v144, v136, v136
	v_fmac_f32_e32 v144, v137, v137
	v_fmac_f32_e32 v144, v138, v138
	v_fmac_f32_e32 v144, v139, v139
	v_fmac_f32_e32 v144, v140, v140
	v_fmac_f32_e32 v144, v141, v141
	v_fmac_f32_e32 v144, v142, v142
	v_fmac_f32_e32 v144, v143, v143
	s_nop 1
	v_add_f32_dpp v144, v144, v144 quad_perm:[1,0,3,2] row_mask:0xf bank_mask:0xf bound_ctrl:1
	s_nop 1
	v_add_f32_dpp v144, v144, v144 quad_perm:[2,3,0,1] row_mask:0xf bank_mask:0xf bound_ctrl:1
	s_nop 1
	v_add_f32_dpp v144, v144, v144 row_half_mirror row_mask:0xf bank_mask:0xf bound_ctrl:1
	v_max_f32_e32 v144, 0x179abe15, v144
	v_rsq_f32_e32 v144, v144
	s_mov_b64 s[42:43], exec
	s_and_b64 exec, exec, s[64:65]
	global_store_dword v6, v144, s[58:59]
	s_mov_b64 exec, s[42:43]
	v_add_u32_e32 v6, 32, v6
	v_lshlrev_b32_e32 v80, 16, v192
	v_and_b32_e32 v81, 0xffff0000, v192
	v_lshlrev_b32_e32 v82, 16, v193
	v_and_b32_e32 v83, 0xffff0000, v193
	v_lshlrev_b32_e32 v84, 16, v194
	v_and_b32_e32 v85, 0xffff0000, v194
	v_lshlrev_b32_e32 v86, 16, v195
	v_and_b32_e32 v87, 0xffff0000, v195
	v_add_f32_e32 v136, v88, v80
	v_add_f32_e32 v137, v89, v81
	v_add_f32_e32 v138, v90, v82
	v_add_f32_e32 v139, v91, v83
	v_add_f32_e32 v140, v92, v84
	v_add_f32_e32 v141, v93, v85
	v_add_f32_e32 v142, v94, v86
	v_add_f32_e32 v143, v95, v87
	v_fma_f32 v136, v136, 0.5, -v96
	v_fma_f32 v137, v137, 0.5, -v97
	v_fma_f32 v138, v138, 0.5, -v98
	v_fma_f32 v139, v139, 0.5, -v99
	v_fma_f32 v140, v140, 0.5, -v100
	v_fma_f32 v141, v141, 0.5, -v101
	v_fma_f32 v142, v142, 0.5, -v102
	v_fma_f32 v143, v143, 0.5, -v103
	v_fma_f32 v128, v104, v136, v96
	v_fma_f32 v129, v105, v137, v97
	v_fma_f32 v130, v106, v138, v98
	v_fma_f32 v131, v107, v139, v99
	v_fma_f32 v132, v108, v140, v100
	v_fma_f32 v133, v109, v141, v101
	v_fma_f32 v134, v110, v142, v102
	v_fma_f32 v135, v111, v143, v103
	v_cvt_pk_bf16_f32 v246, v128, v129
	v_cvt_pk_bf16_f32 v247, v130, v131
	v_cvt_pk_bf16_f32 v248, v132, v133
	v_cvt_pk_bf16_f32 v249, v134, v135
	global_store_dwordx4 v5, v[246:249], s[58:59] nt
	v_add_u32_e32 v5, 0xc00, v5
	v_mul_f32_e32 v136, v128, v112
	v_mul_f32_e32 v137, v129, v113
	v_mul_f32_e32 v138, v130, v114
	v_mul_f32_e32 v139, v131, v115
	v_mul_f32_e32 v140, v132, v116
	v_mul_f32_e32 v141, v133, v117
	v_mul_f32_e32 v142, v134, v118
	v_mul_f32_e32 v143, v135, v119
	v_mul_f32_e32 v144, v136, v136
	v_fmac_f32_e32 v144, v137, v137
	v_fmac_f32_e32 v144, v138, v138
	v_fmac_f32_e32 v144, v139, v139
	v_fmac_f32_e32 v144, v140, v140
	v_fmac_f32_e32 v144, v141, v141
	v_fmac_f32_e32 v144, v142, v142
	v_fmac_f32_e32 v144, v143, v143
	s_nop 1
	v_add_f32_dpp v144, v144, v144 quad_perm:[1,0,3,2] row_mask:0xf bank_mask:0xf bound_ctrl:1
	s_nop 1
	v_add_f32_dpp v144, v144, v144 quad_perm:[2,3,0,1] row_mask:0xf bank_mask:0xf bound_ctrl:1
	s_nop 1
	v_add_f32_dpp v144, v144, v144 row_half_mirror row_mask:0xf bank_mask:0xf bound_ctrl:1
	v_max_f32_e32 v144, 0x179abe15, v144
	v_rsq_f32_e32 v144, v144
	s_mov_b64 s[42:43], exec
	s_and_b64 exec, exec, s[64:65]
	global_store_dword v6, v144, s[58:59]
	s_mov_b64 exec, s[42:43]
	v_add_u32_e32 v6, 32, v6
	v_lshlrev_b32_e32 v88, 16, v196
	v_and_b32_e32 v89, 0xffff0000, v196
	v_lshlrev_b32_e32 v90, 16, v197
	v_and_b32_e32 v91, 0xffff0000, v197
	v_lshlrev_b32_e32 v92, 16, v198
	v_and_b32_e32 v93, 0xffff0000, v198
	v_lshlrev_b32_e32 v94, 16, v199
	v_and_b32_e32 v95, 0xffff0000, v199
	v_add_f32_e32 v136, v96, v88
	v_add_f32_e32 v137, v97, v89
	v_add_f32_e32 v138, v98, v90
	v_add_f32_e32 v139, v99, v91
	v_add_f32_e32 v140, v100, v92
	v_add_f32_e32 v141, v101, v93
	v_add_f32_e32 v142, v102, v94
	v_add_f32_e32 v143, v103, v95
	v_fma_f32 v136, v136, 0.5, -v80
	v_fma_f32 v137, v137, 0.5, -v81
	v_fma_f32 v138, v138, 0.5, -v82
	v_fma_f32 v139, v139, 0.5, -v83
	v_fma_f32 v140, v140, 0.5, -v84
	v_fma_f32 v141, v141, 0.5, -v85
	v_fma_f32 v142, v142, 0.5, -v86
	v_fma_f32 v143, v143, 0.5, -v87
	v_fma_f32 v128, v104, v136, v80
	v_fma_f32 v129, v105, v137, v81
	v_fma_f32 v130, v106, v138, v82
	v_fma_f32 v131, v107, v139, v83
	v_fma_f32 v132, v108, v140, v84
	v_fma_f32 v133, v109, v141, v85
	v_fma_f32 v134, v110, v142, v86
	v_fma_f32 v135, v111, v143, v87
	v_cvt_pk_bf16_f32 v246, v128, v129
	v_cvt_pk_bf16_f32 v247, v130, v131
; __device__ __forceinline__ void unpack8(const u32x4 w, float (&f)[8]) { f[0] = bflo(w.x); f[1] = bfhi(w.x); f[2] = bflo(w.y); f[3] = bfhi(w.y); f[4] = bflo(w.z); f[5] = bfhi(w.z); f[6] = bflo(w.w); f[7] = bfhi(w.w); }
; __device__ __forceinline__ u32x4 pack8(const float (&f)[8]) { u32x4 o; o.x = pk2(f[0], f[1]); o.y = pk2(f[2], f[3]); o.z = pk2(f[4], f[5]); o.w = pk2(f[6], f[7]); return o; }
; template <int CH> __device__ __forceinline__ void p2_rwkv_chunk(const Params& p, int t0, int lane) {
;     ...
;     for (int i = 0; i < 16; ++i) {
;         const int t = t0 + i; const bool hasn = (t & (T_SEQ - 1)) != T_SEQ - 1;
;         if (hasn) unpack8(raw, N); else {
; #pragma unroll
;             for (int q = 0; q < 8; ++q) N[q] = 0.f; }
;         if (i < 15 && ((t + 1) & (T_SEQ - 1)) != T_SEQ - 1) raw = __builtin_nontemporal_load((const u32x4*)(zc + (size_t)(i + 2) * ZLD));
;         float zs[8];
; #pragma unroll
;         for (int q = 0; q < 8; ++q) zs[q] = C[q] + mu[q] * (0.5f * (P[q] + N[q]) - C[q]);
;         if (CH < 3) {
;             *(u32x4*)(RKV + (size_t)t * 1536 + c) = pack8(zs);
;             if (CH == 1) { float s2 = 0.f;
; #pragma unroll
;                 for (int q = 0; q < 8; ++q) { const float v = zs[q] * kq[q]; s2 += v * v; }
;                 s2 = red8s(s2);
;                 if ((lane & 7) == 0) RINV[t * 8 + (lane >> 3)] = rsqrtf(fmaxf(s2, 1e-24f)); }
	v_cvt_pk_bf16_f32 v248, v132, v133
	v_cvt_pk_bf16_f32 v249, v134, v135
	global_store_dwordx4 v5, v[246:249], s[58:59] nt
	v_add_u32_e32 v5, 0xc00, v5
	v_mul_f32_e32 v136, v128, v112
	v_mul_f32_e32 v137, v129, v113
	v_mul_f32_e32 v138, v130, v114
	v_mul_f32_e32 v139, v131, v115
	v_mul_f32_e32 v140, v132, v116
	v_mul_f32_e32 v141, v133, v117
	v_mul_f32_e32 v142, v134, v118
	v_mul_f32_e32 v143, v135, v119
	v_mul_f32_e32 v144, v136, v136
	v_fmac_f32_e32 v144, v137, v137
	v_fmac_f32_e32 v144, v138, v138
	v_fmac_f32_e32 v144, v139, v139
	v_fmac_f32_e32 v144, v140, v140
	v_fmac_f32_e32 v144, v141, v141
	v_fmac_f32_e32 v144, v142, v142
	v_fmac_f32_e32 v144, v143, v143
	s_nop 1
	v_add_f32_dpp v144, v144, v144 quad_perm:[1,0,3,2] row_mask:0xf bank_mask:0xf bound_ctrl:1
	s_nop 1
	v_add_f32_dpp v144, v144, v144 quad_perm:[2,3,0,1] row_mask:0xf bank_mask:0xf bound_ctrl:1
	s_nop 1
	v_add_f32_dpp v144, v144, v144 row_half_mirror row_mask:0xf bank_mask:0xf bound_ctrl:1
	v_max_f32_e32 v144, 0x179abe15, v144
	v_rsq_f32_e32 v144, v144
	s_mov_b64 s[42:43], exec
	s_and_b64 exec, exec, s[64:65]
	global_store_dword v6, v144, s[58:59]
	s_mov_b64 exec, s[42:43]
	v_add_u32_e32 v6, 32, v6
	v_lshlrev_b32_e32 v96, 16, v200
	v_and_b32_e32 v97, 0xffff0000, v200
	v_lshlrev_b32_e32 v98, 16, v201
	v_and_b32_e32 v99, 0xffff0000, v201
	v_lshlrev_b32_e32 v100, 16, v202
	v_and_b32_e32 v101, 0xffff0000, v202
	v_lshlrev_b32_e32 v102, 16, v203
	v_and_b32_e32 v103, 0xffff0000, v203
	v_add_f32_e32 v136, v80, v96
	v_add_f32_e32 v137, v81, v97
	v_add_f32_e32 v138, v82, v98
	v_add_f32_e32 v139, v83, v99
	v_add_f32_e32 v140, v84, v100
	v_add_f32_e32 v141, v85, v101
	v_add_f32_e32 v142, v86, v102
	v_add_f32_e32 v143, v87, v103
	v_fma_f32 v136, v136, 0.5, -v88
	v_fma_f32 v137, v137, 0.5, -v89
	v_fma_f32 v138, v138, 0.5, -v90
	v_fma_f32 v139, v139, 0.5, -v91
	v_fma_f32 v140, v140, 0.5, -v92
	v_fma_f32 v141, v141, 0.5, -v93
	v_fma_f32 v142, v142, 0.5, -v94
	v_fma_f32 v143, v143, 0.5, -v95
	v_fma_f32 v128, v104, v136, v88
	v_fma_f32 v129, v105, v137, v89
	v_fma_f32 v130, v106, v138, v90
	v_fma_f32 v131, v107, v139, v91
	v_fma_f32 v132, v108, v140, v92
	v_fma_f32 v133, v109, v141, v93
	v_fma_f32 v134, v110, v142, v94
	v_fma_f32 v135, v111, v143, v95
	v_cvt_pk_bf16_f32 v246, v128, v129
	v_cvt_pk_bf16_f32 v247, v130, v131
	v_cvt_pk_bf16_f32 v248, v132, v133
	v_cvt_pk_bf16_f32 v249, v134, v135
	global_store_dwordx4 v5, v[246:249], s[58:59] nt
	v_add_u32_e32 v5, 0xc00, v5
	v_mul_f32_e32 v136, v128, v112
	v_mul_f32_e32 v137, v129, v113
	v_mul_f32_e32 v138, v130, v114
	v_mul_f32_e32 v139, v131, v115
	v_mul_f32_e32 v140, v132, v116
	v_mul_f32_e32 v141, v133, v117
	v_mul_f32_e32 v142, v134, v118
	v_mul_f32_e32 v143, v135, v119
	v_mul_f32_e32 v144, v136, v136
	v_fmac_f32_e32 v144, v137, v137
	v_fmac_f32_e32 v144, v138, v138
	v_fmac_f32_e32 v144, v139, v139
	v_fmac_f32_e32 v144, v140, v140
	v_fmac_f32_e32 v144, v141, v141
	v_fmac_f32_e32 v144, v142, v142
	v_fmac_f32_e32 v144, v143, v143
	s_nop 1
	v_add_f32_dpp v144, v144, v144 quad_perm:[1,0,3,2] row_mask:0xf bank_mask:0xf bound_ctrl:1
	s_nop 1
	v_add_f32_dpp v144, v144, v144 quad_perm:[2,3,0,1] row_mask:0xf bank_mask:0xf bound_ctrl:1
	s_nop 1
	v_add_f32_dpp v144, v144, v144 row_half_mirror row_mask:0xf bank_mask:0xf bound_ctrl:1
	v_max_f32_e32 v144, 0x179abe15, v144
	v_rsq_f32_e32 v144, v144
	s_mov_b64 s[42:43], exec
	s_and_b64 exec, exec, s[64:65]
	global_store_dword v6, v144, s[58:59]
	s_mov_b64 exec, s[42:43]
	v_add_u32_e32 v6, 32, v6
	v_lshlrev_b32_e32 v80, 16, v204
	v_and_b32_e32 v81, 0xffff0000, v204
	v_lshlrev_b32_e32 v82, 16, v205
	v_and_b32_e32 v83, 0xffff0000, v205
	v_lshlrev_b32_e32 v84, 16, v206
	v_and_b32_e32 v85, 0xffff0000, v206
	v_lshlrev_b32_e32 v86, 16, v207
	v_and_b32_e32 v87, 0xffff0000, v207
	v_add_f32_e32 v136, v88, v80
	v_add_f32_e32 v137, v89, v81
	v_add_f32_e32 v138, v90, v82
	v_add_f32_e32 v139, v91, v83
	v_add_f32_e32 v140, v92, v84
	v_add_f32_e32 v141, v93, v85
	v_add_f32_e32 v142, v94, v86
	v_add_f32_e32 v143, v95, v87
	v_fma_f32 v136, v136, 0.5, -v96
	v_fma_f32 v137, v137, 0.5, -v97
	v_fma_f32 v138, v138, 0.5, -v98
	v_fma_f32 v139, v139, 0.5, -v99
	v_fma_f32 v140, v140, 0.5, -v100
	v_fma_f32 v141, v141, 0.5, -v101
	v_fma_f32 v142, v142, 0.5, -v102
	v_fma_f32 v143, v143, 0.5, -v103
	v_fma_f32 v128, v104, v136, v96
	v_fma_f32 v129, v105, v137, v97
	v_fma_f32 v130, v106, v138, v98
	v_fma_f32 v131, v107, v139, v99
	v_fma_f32 v132, v108, v140, v100
	v_fma_f32 v133, v109, v141, v101
	v_fma_f32 v134, v110, v142, v102
	v_fma_f32 v135, v111, v143, v103
	v_cvt_pk_bf16_f32 v246, v128, v129
	v_cvt_pk_bf16_f32 v247, v130, v131
	v_cvt_pk_bf16_f32 v248, v132, v133
	v_cvt_pk_bf16_f32 v249, v134, v135
	global_store_dwordx4 v5, v[246:249], s[58:59] nt
	v_add_u32_e32 v5, 0xc00, v5
	v_mul_f32_e32 v136, v128, v112
	v_mul_f32_e32 v137, v129, v113
	v_mul_f32_e32 v138, v130, v114
	v_mul_f32_e32 v139, v131, v115
	v_mul_f32_e32 v140, v132, v116
	v_mul_f32_e32 v141, v133, v117
	v_mul_f32_e32 v142, v134, v118
	v_mul_f32_e32 v143, v135, v119
	v_mul_f32_e32 v144, v136, v136
	v_fmac_f32_e32 v144, v137, v137
	v_fmac_f32_e32 v144, v138, v138
	v_fmac_f32_e32 v144, v139, v139
	v_fmac_f32_e32 v144, v140, v140
	v_fmac_f32_e32 v144, v141, v141
	v_fmac_f32_e32 v144, v142, v142
	v_fmac_f32_e32 v144, v143, v143
	s_nop 1
	v_add_f32_dpp v144, v144, v144 quad_perm:[1,0,3,2] row_mask:0xf bank_mask:0xf bound_ctrl:1
	s_nop 1
	v_add_f32_dpp v144, v144, v144 quad_perm:[2,3,0,1] row_mask:0xf bank_mask:0xf bound_ctrl:1
	s_nop 1
	v_add_f32_dpp v144, v144, v144 row_half_mirror row_mask:0xf bank_mask:0xf bound_ctrl:1
	v_max_f32_e32 v144, 0x179abe15, v144
; __device__ __forceinline__ void unpack8(const u32x4 w, float (&f)[8]) { f[0] = bflo(w.x); f[1] = bfhi(w.x); f[2] = bflo(w.y); f[3] = bfhi(w.y); f[4] = bflo(w.z); f[5] = bfhi(w.z); f[6] = bflo(w.w); f[7] = bfhi(w.w); }
; __device__ __forceinline__ u32x4 pack8(const float (&f)[8]) { u32x4 o; o.x = pk2(f[0], f[1]); o.y = pk2(f[2], f[3]); o.z = pk2(f[4], f[5]); o.w = pk2(f[6], f[7]); return o; }
; template <int CH> __device__ __forceinline__ void p2_rwkv_chunk(const Params& p, int t0, int lane) {
;     ...
;     for (int i = 0; i < 16; ++i) {
;         const int t = t0 + i; const bool hasn = (t & (T_SEQ - 1)) != T_SEQ - 1;
;         if (hasn) unpack8(raw, N); else {
; #pragma unroll
;             for (int q = 0; q < 8; ++q) N[q] = 0.f; }
;         if (i < 15 && ((t + 1) & (T_SEQ - 1)) != T_SEQ - 1) raw = __builtin_nontemporal_load((const u32x4*)(zc + (size_t)(i + 2) * ZLD));
;         float zs[8];
; #pragma unroll
;         for (int q = 0; q < 8; ++q) zs[q] = C[q] + mu[q] * (0.5f * (P[q] + N[q]) - C[q]);
;         if (CH < 3) {
;             *(u32x4*)(RKV + (size_t)t * 1536 + c) = pack8(zs);
;             if (CH == 1) { float s2 = 0.f;
; #pragma unroll
;                 for (int q = 0; q < 8; ++q) { const float v = zs[q] * kq[q]; s2 += v * v; }
;                 s2 = red8s(s2);
;                 if ((lane & 7) == 0) RINV[t * 8 + (lane >> 3)] = rsqrtf(fmaxf(s2, 1e-24f)); }
	v_rsq_f32_e32 v144, v144
	s_mov_b64 s[42:43], exec
	s_and_b64 exec, exec, s[64:65]
	global_store_dword v6, v144, s[58:59]
	s_mov_b64 exec, s[42:43]
	v_add_u32_e32 v6, 32, v6
	v_lshlrev_b32_e32 v88, 16, v208
	v_and_b32_e32 v89, 0xffff0000, v208
	v_lshlrev_b32_e32 v90, 16, v209
	v_and_b32_e32 v91, 0xffff0000, v209
	v_lshlrev_b32_e32 v92, 16, v210
	v_and_b32_e32 v93, 0xffff0000, v210
	v_lshlrev_b32_e32 v94, 16, v211
	v_and_b32_e32 v95, 0xffff0000, v211
	v_add_f32_e32 v136, v96, v88
	v_add_f32_e32 v137, v97, v89
	v_add_f32_e32 v138, v98, v90
	v_add_f32_e32 v139, v99, v91
	v_add_f32_e32 v140, v100, v92
	v_add_f32_e32 v141, v101, v93
	v_add_f32_e32 v142, v102, v94
	v_add_f32_e32 v143, v103, v95
	v_fma_f32 v136, v136, 0.5, -v80
	v_fma_f32 v137, v137, 0.5, -v81
	v_fma_f32 v138, v138, 0.5, -v82
	v_fma_f32 v139, v139, 0.5, -v83
	v_fma_f32 v140, v140, 0.5, -v84
	v_fma_f32 v141, v141, 0.5, -v85
	v_fma_f32 v142, v142, 0.5, -v86
	v_fma_f32 v143, v143, 0.5, -v87
	v_fma_f32 v128, v104, v136, v80
	v_fma_f32 v129, v105, v137, v81
	v_fma_f32 v130, v106, v138, v82
	v_fma_f32 v131, v107, v139, v83
	v_fma_f32 v132, v108, v140, v84
	v_fma_f32 v133, v109, v141, v85
	v_fma_f32 v134, v110, v142, v86
	v_fma_f32 v135, v111, v143, v87
	v_cvt_pk_bf16_f32 v246, v128, v129
	v_cvt_pk_bf16_f32 v247, v130, v131
	v_cvt_pk_bf16_f32 v248, v132, v133
	v_cvt_pk_bf16_f32 v249, v134, v135
	global_store_dwordx4 v5, v[246:249], s[58:59] nt
	v_add_u32_e32 v5, 0xc00, v5
	v_mul_f32_e32 v136, v128, v112
	v_mul_f32_e32 v137, v129, v113
	v_mul_f32_e32 v138, v130, v114
	v_mul_f32_e32 v139, v131, v115
	v_mul_f32_e32 v140, v132, v116
	v_mul_f32_e32 v141, v133, v117
	v_mul_f32_e32 v142, v134, v118
	v_mul_f32_e32 v143, v135, v119
	v_mul_f32_e32 v144, v136, v136
	v_fmac_f32_e32 v144, v137, v137
	v_fmac_f32_e32 v144, v138, v138
	v_fmac_f32_e32 v144, v139, v139
	v_fmac_f32_e32 v144, v140, v140
	v_fmac_f32_e32 v144, v141, v141
	v_fmac_f32_e32 v144, v142, v142
	v_fmac_f32_e32 v144, v143, v143
	s_nop 1
	v_add_f32_dpp v144, v144, v144 quad_perm:[1,0,3,2] row_mask:0xf bank_mask:0xf bound_ctrl:1
	s_nop 1
	v_add_f32_dpp v144, v144, v144 quad_perm:[2,3,0,1] row_mask:0xf bank_mask:0xf bound_ctrl:1
	s_nop 1
	v_add_f32_dpp v144, v144, v144 row_half_mirror row_mask:0xf bank_mask:0xf bound_ctrl:1
	v_max_f32_e32 v144, 0x179abe15, v144
	v_rsq_f32_e32 v144, v144
	s_mov_b64 s[42:43], exec
	s_and_b64 exec, exec, s[64:65]
	global_store_dword v6, v144, s[58:59]
	s_mov_b64 exec, s[42:43]
	v_add_u32_e32 v6, 32, v6
	v_lshlrev_b32_e32 v96, 16, v212
	v_and_b32_e32 v97, 0xffff0000, v212
	v_lshlrev_b32_e32 v98, 16, v213
	v_and_b32_e32 v99, 0xffff0000, v213
	v_lshlrev_b32_e32 v100, 16, v214
	v_and_b32_e32 v101, 0xffff0000, v214
	v_lshlrev_b32_e32 v102, 16, v215
	v_and_b32_e32 v103, 0xffff0000, v215
	v_add_f32_e32 v136, v80, v96
	v_add_f32_e32 v137, v81, v97
	v_add_f32_e32 v138, v82, v98
	v_add_f32_e32 v139, v83, v99
	v_add_f32_e32 v140, v84, v100
	v_add_f32_e32 v141, v85, v101
	v_add_f32_e32 v142, v86, v102
	v_add_f32_e32 v143, v87, v103
	v_fma_f32 v136, v136, 0.5, -v88
	v_fma_f32 v137, v137, 0.5, -v89
	v_fma_f32 v138, v138, 0.5, -v90
	v_fma_f32 v139, v139, 0.5, -v91
	v_fma_f32 v140, v140, 0.5, -v92
	v_fma_f32 v141, v141, 0.5, -v93
	v_fma_f32 v142, v142, 0.5, -v94
	v_fma_f32 v143, v143, 0.5, -v95
	v_fma_f32 v128, v104, v136, v88
	v_fma_f32 v129, v105, v137, v89
	v_fma_f32 v130, v106, v138, v90
	v_fma_f32 v131, v107, v139, v91
	v_fma_f32 v132, v108, v140, v92
	v_fma_f32 v133, v109, v141, v93
	v_fma_f32 v134, v110, v142, v94
	v_fma_f32 v135, v111, v143, v95
	v_cvt_pk_bf16_f32 v246, v128, v129
	v_cvt_pk_bf16_f32 v247, v130, v131
	v_cvt_pk_bf16_f32 v248, v132, v133
	v_cvt_pk_bf16_f32 v249, v134, v135
	global_store_dwordx4 v5, v[246:249], s[58:59] nt
	v_add_u32_e32 v5, 0xc00, v5
	v_mul_f32_e32 v136, v128, v112
	v_mul_f32_e32 v137, v129, v113
	v_mul_f32_e32 v138, v130, v114
	v_mul_f32_e32 v139, v131, v115
	v_mul_f32_e32 v140, v132, v116
	v_mul_f32_e32 v141, v133, v117
	v_mul_f32_e32 v142, v134, v118
	v_mul_f32_e32 v143, v135, v119
	v_mul_f32_e32 v144, v136, v136
	v_fmac_f32_e32 v144, v137, v137
	v_fmac_f32_e32 v144, v138, v138
	v_fmac_f32_e32 v144, v139, v139
	v_fmac_f32_e32 v144, v140, v140
	v_fmac_f32_e32 v144, v141, v141
	v_fmac_f32_e32 v144, v142, v142
	v_fmac_f32_e32 v144, v143, v143
	s_nop 1
	v_add_f32_dpp v144, v144, v144 quad_perm:[1,0,3,2] row_mask:0xf bank_mask:0xf bound_ctrl:1
	s_nop 1
	v_add_f32_dpp v144, v144, v144 quad_perm:[2,3,0,1] row_mask:0xf bank_mask:0xf bound_ctrl:1
	s_nop 1
	v_add_f32_dpp v144, v144, v144 row_half_mirror row_mask:0xf bank_mask:0xf bound_ctrl:1
	v_max_f32_e32 v144, 0x179abe15, v144
	v_rsq_f32_e32 v144, v144
	s_mov_b64 s[42:43], exec
	s_and_b64 exec, exec, s[64:65]
	global_store_dword v6, v144, s[58:59]
	s_mov_b64 exec, s[42:43]
	v_add_u32_e32 v6, 32, v6
	v_lshlrev_b32_e32 v80, 16, v216
	v_and_b32_e32 v81, 0xffff0000, v216
	v_lshlrev_b32_e32 v82, 16, v217
	v_and_b32_e32 v83, 0xffff0000, v217
	v_lshlrev_b32_e32 v84, 16, v218
	v_and_b32_e32 v85, 0xffff0000, v218
	v_lshlrev_b32_e32 v86, 16, v219
	v_and_b32_e32 v87, 0xffff0000, v219
	v_add_f32_e32 v136, v88, v80
	v_add_f32_e32 v137, v89, v81
	v_add_f32_e32 v138, v90, v82
	v_add_f32_e32 v139, v91, v83
	v_add_f32_e32 v140, v92, v84
	v_add_f32_e32 v141, v93, v85
	v_add_f32_e32 v142, v94, v86
	v_add_f32_e32 v143, v95, v87
	v_fma_f32 v136, v136, 0.5, -v96
	v_fma_f32 v137, v137, 0.5, -v97
	v_fma_f32 v138, v138, 0.5, -v98
	v_fma_f32 v139, v139, 0.5, -v99
	v_fma_f32 v140, v140, 0.5, -v100
	v_fma_f32 v141, v141, 0.5, -v101
	v_fma_f32 v142, v142, 0.5, -v102
	v_fma_f32 v143, v143, 0.5, -v103
	v_fma_f32 v128, v104, v136, v96
	v_fma_f32 v129, v105, v137, v97
; __device__ __forceinline__ void unpack8(const u32x4 w, float (&f)[8]) { f[0] = bflo(w.x); f[1] = bfhi(w.x); f[2] = bflo(w.y); f[3] = bfhi(w.y); f[4] = bflo(w.z); f[5] = bfhi(w.z); f[6] = bflo(w.w); f[7] = bfhi(w.w); }
; __device__ __forceinline__ u32x4 pack8(const float (&f)[8]) { u32x4 o; o.x = pk2(f[0], f[1]); o.y = pk2(f[2], f[3]); o.z = pk2(f[4], f[5]); o.w = pk2(f[6], f[7]); return o; }
; template <int CH> __device__ __forceinline__ void p2_rwkv_chunk(const Params& p, int t0, int lane) {
;     ...
;     for (int i = 0; i < 16; ++i) {
;         const int t = t0 + i; const bool hasn = (t & (T_SEQ - 1)) != T_SEQ - 1;
;         if (hasn) unpack8(raw, N); else {
; #pragma unroll
;             for (int q = 0; q < 8; ++q) N[q] = 0.f; }
;         if (i < 15 && ((t + 1) & (T_SEQ - 1)) != T_SEQ - 1) raw = __builtin_nontemporal_load((const u32x4*)(zc + (size_t)(i + 2) * ZLD));
;         float zs[8];
; #pragma unroll
;         for (int q = 0; q < 8; ++q) zs[q] = C[q] + mu[q] * (0.5f * (P[q] + N[q]) - C[q]);
;         if (CH < 3) {
;             *(u32x4*)(RKV + (size_t)t * 1536 + c) = pack8(zs);
;             if (CH == 1) { float s2 = 0.f;
; #pragma unroll
;                 for (int q = 0; q < 8; ++q) { const float v = zs[q] * kq[q]; s2 += v * v; }
;                 s2 = red8s(s2);
;                 if ((lane & 7) == 0) RINV[t * 8 + (lane >> 3)] = rsqrtf(fmaxf(s2, 1e-24f)); }
	v_fma_f32 v130, v106, v138, v98
	v_fma_f32 v131, v107, v139, v99
	v_fma_f32 v132, v108, v140, v100
	v_fma_f32 v133, v109, v141, v101
	v_fma_f32 v134, v110, v142, v102
	v_fma_f32 v135, v111, v143, v103
	v_cvt_pk_bf16_f32 v246, v128, v129
	v_cvt_pk_bf16_f32 v247, v130, v131
	v_cvt_pk_bf16_f32 v248, v132, v133
	v_cvt_pk_bf16_f32 v249, v134, v135
	global_store_dwordx4 v5, v[246:249], s[58:59] nt
	v_add_u32_e32 v5, 0xc00, v5
	v_mul_f32_e32 v136, v128, v112
	v_mul_f32_e32 v137, v129, v113
	v_mul_f32_e32 v138, v130, v114
	v_mul_f32_e32 v139, v131, v115
	v_mul_f32_e32 v140, v132, v116
	v_mul_f32_e32 v141, v133, v117
	v_mul_f32_e32 v142, v134, v118
	v_mul_f32_e32 v143, v135, v119
	v_mul_f32_e32 v144, v136, v136
	v_fmac_f32_e32 v144, v137, v137
	v_fmac_f32_e32 v144, v138, v138
	v_fmac_f32_e32 v144, v139, v139
	v_fmac_f32_e32 v144, v140, v140
	v_fmac_f32_e32 v144, v141, v141
	v_fmac_f32_e32 v144, v142, v142
	v_fmac_f32_e32 v144, v143, v143
	s_nop 1
	v_add_f32_dpp v144, v144, v144 quad_perm:[1,0,3,2] row_mask:0xf bank_mask:0xf bound_ctrl:1
	s_nop 1
	v_add_f32_dpp v144, v144, v144 quad_perm:[2,3,0,1] row_mask:0xf bank_mask:0xf bound_ctrl:1
	s_nop 1
	v_add_f32_dpp v144, v144, v144 row_half_mirror row_mask:0xf bank_mask:0xf bound_ctrl:1
	v_max_f32_e32 v144, 0x179abe15, v144
	v_rsq_f32_e32 v144, v144
	s_mov_b64 s[42:43], exec
	s_and_b64 exec, exec, s[64:65]
	global_store_dword v6, v144, s[58:59]
	s_mov_b64 exec, s[42:43]
	v_add_u32_e32 v6, 32, v6
	v_lshlrev_b32_e32 v88, 16, v220
	v_and_b32_e32 v89, 0xffff0000, v220
	v_lshlrev_b32_e32 v90, 16, v221
	v_and_b32_e32 v91, 0xffff0000, v221
	v_lshlrev_b32_e32 v92, 16, v222
	v_and_b32_e32 v93, 0xffff0000, v222
	v_lshlrev_b32_e32 v94, 16, v223
	v_and_b32_e32 v95, 0xffff0000, v223
	v_add_f32_e32 v136, v96, v88
	v_add_f32_e32 v137, v97, v89
	v_add_f32_e32 v138, v98, v90
	v_add_f32_e32 v139, v99, v91
	v_add_f32_e32 v140, v100, v92
	v_add_f32_e32 v141, v101, v93
	v_add_f32_e32 v142, v102, v94
	v_add_f32_e32 v143, v103, v95
	v_fma_f32 v136, v136, 0.5, -v80
	v_fma_f32 v137, v137, 0.5, -v81
	v_fma_f32 v138, v138, 0.5, -v82
	v_fma_f32 v139, v139, 0.5, -v83
	v_fma_f32 v140, v140, 0.5, -v84
	v_fma_f32 v141, v141, 0.5, -v85
	v_fma_f32 v142, v142, 0.5, -v86
	v_fma_f32 v143, v143, 0.5, -v87
	v_fma_f32 v128, v104, v136, v80
	v_fma_f32 v129, v105, v137, v81
	v_fma_f32 v130, v106, v138, v82
	v_fma_f32 v131, v107, v139, v83
	v_fma_f32 v132, v108, v140, v84
	v_fma_f32 v133, v109, v141, v85
	v_fma_f32 v134, v110, v142, v86
	v_fma_f32 v135, v111, v143, v87
	v_cvt_pk_bf16_f32 v246, v128, v129
	v_cvt_pk_bf16_f32 v247, v130, v131
	v_cvt_pk_bf16_f32 v248, v132, v133
	v_cvt_pk_bf16_f32 v249, v134, v135
	global_store_dwordx4 v5, v[246:249], s[58:59] nt
	v_add_u32_e32 v5, 0xc00, v5
	v_mul_f32_e32 v136, v128, v112
	v_mul_f32_e32 v137, v129, v113
	v_mul_f32_e32 v138, v130, v114
	v_mul_f32_e32 v139, v131, v115
	v_mul_f32_e32 v140, v132, v116
	v_mul_f32_e32 v141, v133, v117
	v_mul_f32_e32 v142, v134, v118
	v_mul_f32_e32 v143, v135, v119
	v_mul_f32_e32 v144, v136, v136
	v_fmac_f32_e32 v144, v137, v137
	v_fmac_f32_e32 v144, v138, v138
	v_fmac_f32_e32 v144, v139, v139
	v_fmac_f32_e32 v144, v140, v140
	v_fmac_f32_e32 v144, v141, v141
	v_fmac_f32_e32 v144, v142, v142
	v_fmac_f32_e32 v144, v143, v143
	s_nop 1
	v_add_f32_dpp v144, v144, v144 quad_perm:[1,0,3,2] row_mask:0xf bank_mask:0xf bound_ctrl:1
	s_nop 1
	v_add_f32_dpp v144, v144, v144 quad_perm:[2,3,0,1] row_mask:0xf bank_mask:0xf bound_ctrl:1
	s_nop 1
	v_add_f32_dpp v144, v144, v144 row_half_mirror row_mask:0xf bank_mask:0xf bound_ctrl:1
	v_max_f32_e32 v144, 0x179abe15, v144
	v_rsq_f32_e32 v144, v144
	s_mov_b64 s[42:43], exec
	s_and_b64 exec, exec, s[64:65]
	global_store_dword v6, v144, s[58:59]
	s_mov_b64 exec, s[42:43]
	v_add_u32_e32 v6, 32, v6
	v_lshlrev_b32_e32 v96, 16, v224
	v_and_b32_e32 v97, 0xffff0000, v224
	v_lshlrev_b32_e32 v98, 16, v225
	v_and_b32_e32 v99, 0xffff0000, v225
	v_lshlrev_b32_e32 v100, 16, v226
	v_and_b32_e32 v101, 0xffff0000, v226
	v_lshlrev_b32_e32 v102, 16, v227
	v_and_b32_e32 v103, 0xffff0000, v227
	v_add_f32_e32 v136, v80, v96
	v_add_f32_e32 v137, v81, v97
	v_add_f32_e32 v138, v82, v98
	v_add_f32_e32 v139, v83, v99
	v_add_f32_e32 v140, v84, v100
	v_add_f32_e32 v141, v85, v101
	v_add_f32_e32 v142, v86, v102
	v_add_f32_e32 v143, v87, v103
	v_fma_f32 v136, v136, 0.5, -v88
	v_fma_f32 v137, v137, 0.5, -v89
	v_fma_f32 v138, v138, 0.5, -v90
	v_fma_f32 v139, v139, 0.5, -v91
	v_fma_f32 v140, v140, 0.5, -v92
	v_fma_f32 v141, v141, 0.5, -v93
	v_fma_f32 v142, v142, 0.5, -v94
	v_fma_f32 v143, v143, 0.5, -v95
	v_fma_f32 v128, v104, v136, v88
	v_fma_f32 v129, v105, v137, v89
	v_fma_f32 v130, v106, v138, v90
	v_fma_f32 v131, v107, v139, v91
	v_fma_f32 v132, v108, v140, v92
	v_fma_f32 v133, v109, v141, v93
	v_fma_f32 v134, v110, v142, v94
	v_fma_f32 v135, v111, v143, v95
	v_cvt_pk_bf16_f32 v246, v128, v129
	v_cvt_pk_bf16_f32 v247, v130, v131
	v_cvt_pk_bf16_f32 v248, v132, v133
	v_cvt_pk_bf16_f32 v249, v134, v135
	global_store_dwordx4 v5, v[246:249], s[58:59] nt
	v_add_u32_e32 v5, 0xc00, v5
	v_mul_f32_e32 v136, v128, v112
	v_mul_f32_e32 v137, v129, v113
	v_mul_f32_e32 v138, v130, v114
	v_mul_f32_e32 v139, v131, v115
	v_mul_f32_e32 v140, v132, v116
	v_mul_f32_e32 v141, v133, v117
	v_mul_f32_e32 v142, v134, v118
	v_mul_f32_e32 v143, v135, v119
	v_mul_f32_e32 v144, v136, v136
	v_fmac_f32_e32 v144, v137, v137
	v_fmac_f32_e32 v144, v138, v138
	v_fmac_f32_e32 v144, v139, v139
	v_fmac_f32_e32 v144, v140, v140
	v_fmac_f32_e32 v144, v141, v141
	v_fmac_f32_e32 v144, v142, v142
	v_fmac_f32_e32 v144, v143, v143
	s_nop 1
	v_add_f32_dpp v144, v144, v144 quad_perm:[1,0,3,2] row_mask:0xf bank_mask:0xf bound_ctrl:1
; __device__ __forceinline__ void unpack8(const u32x4 w, float (&f)[8]) { f[0] = bflo(w.x); f[1] = bfhi(w.x); f[2] = bflo(w.y); f[3] = bfhi(w.y); f[4] = bflo(w.z); f[5] = bfhi(w.z); f[6] = bflo(w.w); f[7] = bfhi(w.w); }
; __device__ __forceinline__ u32x4 pack8(const float (&f)[8]) { u32x4 o; o.x = pk2(f[0], f[1]); o.y = pk2(f[2], f[3]); o.z = pk2(f[4], f[5]); o.w = pk2(f[6], f[7]); return o; }
; template <int CH> __device__ __forceinline__ void p2_rwkv_chunk(const Params& p, int t0, int lane) {
;     ...
;     for (int i = 0; i < 16; ++i) {
;         const int t = t0 + i; const bool hasn = (t & (T_SEQ - 1)) != T_SEQ - 1;
;         if (hasn) unpack8(raw, N); else {
; #pragma unroll
;             for (int q = 0; q < 8; ++q) N[q] = 0.f; }
;         if (i < 15 && ((t + 1) & (T_SEQ - 1)) != T_SEQ - 1) raw = __builtin_nontemporal_load((const u32x4*)(zc + (size_t)(i + 2) * ZLD));
;         float zs[8];
; #pragma unroll
;         for (int q = 0; q < 8; ++q) zs[q] = C[q] + mu[q] * (0.5f * (P[q] + N[q]) - C[q]);
;         if (CH < 3) {
;             *(u32x4*)(RKV + (size_t)t * 1536 + c) = pack8(zs);
;             if (CH == 1) { float s2 = 0.f;
; #pragma unroll
;                 for (int q = 0; q < 8; ++q) { const float v = zs[q] * kq[q]; s2 += v * v; }
;                 s2 = red8s(s2);
;                 if ((lane & 7) == 0) RINV[t * 8 + (lane >> 3)] = rsqrtf(fmaxf(s2, 1e-24f)); }
	s_nop 1
	v_add_f32_dpp v144, v144, v144 quad_perm:[2,3,0,1] row_mask:0xf bank_mask:0xf bound_ctrl:1
	s_nop 1
	v_add_f32_dpp v144, v144, v144 row_half_mirror row_mask:0xf bank_mask:0xf bound_ctrl:1
	v_max_f32_e32 v144, 0x179abe15, v144
	v_rsq_f32_e32 v144, v144
	s_mov_b64 s[42:43], exec
	s_and_b64 exec, exec, s[64:65]
	global_store_dword v6, v144, s[58:59]
	s_mov_b64 exec, s[42:43]
	v_add_u32_e32 v6, 32, v6
	v_lshlrev_b32_e32 v80, 16, v228
	v_and_b32_e32 v81, 0xffff0000, v228
	v_lshlrev_b32_e32 v82, 16, v229
	v_and_b32_e32 v83, 0xffff0000, v229
	v_lshlrev_b32_e32 v84, 16, v230
	v_and_b32_e32 v85, 0xffff0000, v230
	v_lshlrev_b32_e32 v86, 16, v231
	v_and_b32_e32 v87, 0xffff0000, v231
	v_add_f32_e32 v136, v88, v80
	v_add_f32_e32 v137, v89, v81
	v_add_f32_e32 v138, v90, v82
	v_add_f32_e32 v139, v91, v83
	v_add_f32_e32 v140, v92, v84
	v_add_f32_e32 v141, v93, v85
	v_add_f32_e32 v142, v94, v86
	v_add_f32_e32 v143, v95, v87
	v_fma_f32 v136, v136, 0.5, -v96
	v_fma_f32 v137, v137, 0.5, -v97
	v_fma_f32 v138, v138, 0.5, -v98
	v_fma_f32 v139, v139, 0.5, -v99
	v_fma_f32 v140, v140, 0.5, -v100
	v_fma_f32 v141, v141, 0.5, -v101
	v_fma_f32 v142, v142, 0.5, -v102
	v_fma_f32 v143, v143, 0.5, -v103
	v_fma_f32 v128, v104, v136, v96
	v_fma_f32 v129, v105, v137, v97
	v_fma_f32 v130, v106, v138, v98
	v_fma_f32 v131, v107, v139, v99
	v_fma_f32 v132, v108, v140, v100
	v_fma_f32 v133, v109, v141, v101
	v_fma_f32 v134, v110, v142, v102
	v_fma_f32 v135, v111, v143, v103
	v_cvt_pk_bf16_f32 v246, v128, v129
	v_cvt_pk_bf16_f32 v247, v130, v131
	v_cvt_pk_bf16_f32 v248, v132, v133
	v_cvt_pk_bf16_f32 v249, v134, v135
	global_store_dwordx4 v5, v[246:249], s[58:59] nt
	v_add_u32_e32 v5, 0xc00, v5
	v_mul_f32_e32 v136, v128, v112
	v_mul_f32_e32 v137, v129, v113
	v_mul_f32_e32 v138, v130, v114
	v_mul_f32_e32 v139, v131, v115
	v_mul_f32_e32 v140, v132, v116
	v_mul_f32_e32 v141, v133, v117
	v_mul_f32_e32 v142, v134, v118
	v_mul_f32_e32 v143, v135, v119
	v_mul_f32_e32 v144, v136, v136
	v_fmac_f32_e32 v144, v137, v137
	v_fmac_f32_e32 v144, v138, v138
	v_fmac_f32_e32 v144, v139, v139
	v_fmac_f32_e32 v144, v140, v140
	v_fmac_f32_e32 v144, v141, v141
	v_fmac_f32_e32 v144, v142, v142
	v_fmac_f32_e32 v144, v143, v143
	s_nop 1
	v_add_f32_dpp v144, v144, v144 quad_perm:[1,0,3,2] row_mask:0xf bank_mask:0xf bound_ctrl:1
	s_nop 1
	v_add_f32_dpp v144, v144, v144 quad_perm:[2,3,0,1] row_mask:0xf bank_mask:0xf bound_ctrl:1
	s_nop 1
	v_add_f32_dpp v144, v144, v144 row_half_mirror row_mask:0xf bank_mask:0xf bound_ctrl:1
	v_max_f32_e32 v144, 0x179abe15, v144
	v_rsq_f32_e32 v144, v144
	s_mov_b64 s[42:43], exec
	s_and_b64 exec, exec, s[64:65]
	global_store_dword v6, v144, s[58:59]
	s_mov_b64 exec, s[42:43]
	v_add_u32_e32 v6, 32, v6
	v_lshlrev_b32_e32 v88, 16, v232
	v_and_b32_e32 v89, 0xffff0000, v232
	v_lshlrev_b32_e32 v90, 16, v233
	v_and_b32_e32 v91, 0xffff0000, v233
	v_lshlrev_b32_e32 v92, 16, v234
	v_and_b32_e32 v93, 0xffff0000, v234
	v_lshlrev_b32_e32 v94, 16, v235
	v_and_b32_e32 v95, 0xffff0000, v235
	v_add_f32_e32 v136, v96, v88
	v_add_f32_e32 v137, v97, v89
	v_add_f32_e32 v138, v98, v90
	v_add_f32_e32 v139, v99, v91
	v_add_f32_e32 v140, v100, v92
	v_add_f32_e32 v141, v101, v93
	v_add_f32_e32 v142, v102, v94
	v_add_f32_e32 v143, v103, v95
	v_fma_f32 v136, v136, 0.5, -v80
	v_fma_f32 v137, v137, 0.5, -v81
	v_fma_f32 v138, v138, 0.5, -v82
	v_fma_f32 v139, v139, 0.5, -v83
	v_fma_f32 v140, v140, 0.5, -v84
	v_fma_f32 v141, v141, 0.5, -v85
	v_fma_f32 v142, v142, 0.5, -v86
	v_fma_f32 v143, v143, 0.5, -v87
	v_fma_f32 v128, v104, v136, v80
	v_fma_f32 v129, v105, v137, v81
	v_fma_f32 v130, v106, v138, v82
	v_fma_f32 v131, v107, v139, v83
	v_fma_f32 v132, v108, v140, v84
	v_fma_f32 v133, v109, v141, v85
	v_fma_f32 v134, v110, v142, v86
	v_fma_f32 v135, v111, v143, v87
	v_cvt_pk_bf16_f32 v246, v128, v129
	v_cvt_pk_bf16_f32 v247, v130, v131
	v_cvt_pk_bf16_f32 v248, v132, v133
	v_cvt_pk_bf16_f32 v249, v134, v135
	global_store_dwordx4 v5, v[246:249], s[58:59] nt
	v_add_u32_e32 v5, 0xc00, v5
	v_mul_f32_e32 v136, v128, v112
	v_mul_f32_e32 v137, v129, v113
	v_mul_f32_e32 v138, v130, v114
	v_mul_f32_e32 v139, v131, v115
	v_mul_f32_e32 v140, v132, v116
	v_mul_f32_e32 v141, v133, v117
	v_mul_f32_e32 v142, v134, v118
	v_mul_f32_e32 v143, v135, v119
	v_mul_f32_e32 v144, v136, v136
	v_fmac_f32_e32 v144, v137, v137
	v_fmac_f32_e32 v144, v138, v138
	v_fmac_f32_e32 v144, v139, v139
	v_fmac_f32_e32 v144, v140, v140
	v_fmac_f32_e32 v144, v141, v141
	v_fmac_f32_e32 v144, v142, v142
	v_fmac_f32_e32 v144, v143, v143
	s_nop 1
	v_add_f32_dpp v144, v144, v144 quad_perm:[1,0,3,2] row_mask:0xf bank_mask:0xf bound_ctrl:1
	s_nop 1
	v_add_f32_dpp v144, v144, v144 quad_perm:[2,3,0,1] row_mask:0xf bank_mask:0xf bound_ctrl:1
	s_nop 1
	v_add_f32_dpp v144, v144, v144 row_half_mirror row_mask:0xf bank_mask:0xf bound_ctrl:1
	v_max_f32_e32 v144, 0x179abe15, v144
	v_rsq_f32_e32 v144, v144
	s_mov_b64 s[42:43], exec
	s_and_b64 exec, exec, s[64:65]
	global_store_dword v6, v144, s[58:59]
	s_mov_b64 exec, s[42:43]
	v_add_u32_e32 v6, 32, v6
	s_cmp_eq_u32 s67, 0
	s_cbranch_scc1 .Lp2_nz_6
	v_mov_b32_e32 v236, 0
	v_mov_b32_e32 v237, 0
	v_mov_b32_e32 v238, 0
	v_mov_b32_e32 v239, 0
; __device__ __forceinline__ void unpack8(const u32x4 w, float (&f)[8]) { f[0] = bflo(w.x); f[1] = bfhi(w.x); f[2] = bflo(w.y); f[3] = bfhi(w.y); f[4] = bflo(w.z); f[5] = bfhi(w.z); f[6] = bflo(w.w); f[7] = bfhi(w.w); }
; __device__ __forceinline__ u32x4 pack8(const float (&f)[8]) { u32x4 o; o.x = pk2(f[0], f[1]); o.y = pk2(f[2], f[3]); o.z = pk2(f[4], f[5]); o.w = pk2(f[6], f[7]); return o; }
; template <int CH> __device__ __forceinline__ void p2_rwkv_chunk(const Params& p, int t0, int lane) {
;     ...
;     const bf16_t* zc = (const bf16_t*)(ws + WS_Z) + (size_t)t0 * ZLD + c;
;     float mu[8], kq[8];
;     { const f32x4 m0 = *(const f32x4*)(p.in[8] + c), m1 = *(const f32x4*)(p.in[8] + c + 4);
; #pragma unroll
;       for (int i = 0; i < 4; ++i) { mu[i] = m0[i]; mu[4 + i] = m1[i]; } }
;     if (CH == 1) { const f32x4 q0 = *(const f32x4*)(p.in[14] + c - 512), q1 = *(const f32x4*)(p.in[14] + c - 512 + 4);
; #pragma unroll
;         for (int i = 0; i < 4; ++i) { kq[i] = q0[i]; kq[4 + i] = q1[i]; } }
;     float P[8], C[8], N[8];
;     if ((t0 & (T_SEQ - 1)) != 0) unpack8(__builtin_nontemporal_load((const u32x4*)(zc - ZLD)), P); else {
; #pragma unroll
;         for (int i = 0; i < 8; ++i) P[i] = 0.f; }
;     unpack8(__builtin_nontemporal_load((const u32x4*)(zc)), C);
;     u32x4 raw = __builtin_nontemporal_load((const u32x4*)(zc + ZLD));
; #pragma unroll 2
;     for (int i = 0; i < 16; ++i) {
;         const int t = t0 + i; const bool hasn = (t & (T_SEQ - 1)) != T_SEQ - 1;
;         if (hasn) unpack8(raw, N); else {
; #pragma unroll
;             for (int q = 0; q < 8; ++q) N[q] = 0.f; }
;         if (i < 15 && ((t + 1) & (T_SEQ - 1)) != T_SEQ - 1) raw = __builtin_nontemporal_load((const u32x4*)(zc + (size_t)(i + 2) * ZLD));
;         float zs[8];
; #pragma unroll
;         for (int q = 0; q < 8; ++q) zs[q] = C[q] + mu[q] * (0.5f * (P[q] + N[q]) - C[q]);
;         if (CH < 3) {
;             *(u32x4*)(RKV + (size_t)t * 1536 + c) = pack8(zs);
.Lp2_nz_6:
	v_lshlrev_b32_e32 v96, 16, v236
	v_and_b32_e32 v97, 0xffff0000, v236
	v_lshlrev_b32_e32 v98, 16, v237
	v_and_b32_e32 v99, 0xffff0000, v237
	v_lshlrev_b32_e32 v100, 16, v238
	v_and_b32_e32 v101, 0xffff0000, v238
	v_lshlrev_b32_e32 v102, 16, v239
	v_and_b32_e32 v103, 0xffff0000, v239
	v_add_f32_e32 v136, v80, v96
	v_add_f32_e32 v137, v81, v97
	v_add_f32_e32 v138, v82, v98
	v_add_f32_e32 v139, v83, v99
	v_add_f32_e32 v140, v84, v100
	v_add_f32_e32 v141, v85, v101
	v_add_f32_e32 v142, v86, v102
	v_add_f32_e32 v143, v87, v103
	v_fma_f32 v136, v136, 0.5, -v88
	v_fma_f32 v137, v137, 0.5, -v89
	v_fma_f32 v138, v138, 0.5, -v90
	v_fma_f32 v139, v139, 0.5, -v91
	v_fma_f32 v140, v140, 0.5, -v92
	v_fma_f32 v141, v141, 0.5, -v93
	v_fma_f32 v142, v142, 0.5, -v94
	v_fma_f32 v143, v143, 0.5, -v95
	v_fma_f32 v128, v104, v136, v88
	v_fma_f32 v129, v105, v137, v89
	v_fma_f32 v130, v106, v138, v90
	v_fma_f32 v131, v107, v139, v91
	v_fma_f32 v132, v108, v140, v92
	v_fma_f32 v133, v109, v141, v93
	v_fma_f32 v134, v110, v142, v94
	v_fma_f32 v135, v111, v143, v95
	v_cvt_pk_bf16_f32 v246, v128, v129
	v_cvt_pk_bf16_f32 v247, v130, v131
	v_cvt_pk_bf16_f32 v248, v132, v133
	v_cvt_pk_bf16_f32 v249, v134, v135
	global_store_dwordx4 v5, v[246:249], s[58:59] nt
	v_add_u32_e32 v5, 0xc00, v5
	v_mul_f32_e32 v136, v128, v112
	v_mul_f32_e32 v137, v129, v113
	v_mul_f32_e32 v138, v130, v114
	v_mul_f32_e32 v139, v131, v115
	v_mul_f32_e32 v140, v132, v116
	v_mul_f32_e32 v141, v133, v117
	v_mul_f32_e32 v142, v134, v118
	v_mul_f32_e32 v143, v135, v119
	v_mul_f32_e32 v144, v136, v136
	v_fmac_f32_e32 v144, v137, v137
	v_fmac_f32_e32 v144, v138, v138
	v_fmac_f32_e32 v144, v139, v139
	v_fmac_f32_e32 v144, v140, v140
	v_fmac_f32_e32 v144, v141, v141
	v_fmac_f32_e32 v144, v142, v142
	v_fmac_f32_e32 v144, v143, v143
	s_nop 1
	v_add_f32_dpp v144, v144, v144 quad_perm:[1,0,3,2] row_mask:0xf bank_mask:0xf bound_ctrl:1
	s_nop 1
	v_add_f32_dpp v144, v144, v144 quad_perm:[2,3,0,1] row_mask:0xf bank_mask:0xf bound_ctrl:1
	s_nop 1
	v_add_f32_dpp v144, v144, v144 row_half_mirror row_mask:0xf bank_mask:0xf bound_ctrl:1
	v_max_f32_e32 v144, 0x179abe15, v144
	v_rsq_f32_e32 v144, v144
	s_mov_b64 s[42:43], exec
	s_and_b64 exec, exec, s[64:65]
	global_store_dword v6, v144, s[58:59]
	s_mov_b64 exec, s[42:43]
	v_add_u32_e32 v6, 32, v6
	s_mov_b32 s98, 0x1000
	s_mov_b32 s99, 0
	v_lshl_add_u64 v[2:3], v[250:251], 0, s[98:99]
	global_load_dwordx4 v[104:107], v[2:3], off
	global_load_dwordx4 v[108:111], v[2:3], off offset:16
	s_mul_i32 s63, s62, 0x1c00
	s_add_u32 s63, s63, 0x7000c00
	v_lshl_add_u32 v4, v0, 4, s63
	v_add_u32_e32 v1, 0xffffe400, v4
	s_cmp_lg_u32 s66, 0
	s_cselect_b64 vcc, -1, 0
	s_nop 1
	v_cndmask_b32_e32 v1, v1, v4, vcc
	global_load_dwordx4 v[168:171], v1, s[58:59] nt
	global_load_dwordx4 v[172:175], v4, s[58:59] nt
	v_mov_b32_e32 v1, v4
	v_add_u32_e32 v1, 0x1c00, v1
	global_load_dwordx4 v[176:179], v1, s[58:59] nt
	v_add_u32_e32 v1, 0x1c00, v1
	global_load_dwordx4 v[180:183], v1, s[58:59] nt
	v_add_u32_e32 v1, 0x1c00, v1
	global_load_dwordx4 v[184:187], v1, s[58:59] nt
	v_add_u32_e32 v1, 0x1c00, v1
	global_load_dwordx4 v[188:191], v1, s[58:59] nt
	v_add_u32_e32 v1, 0x1c00, v1
	global_load_dwordx4 v[192:195], v1, s[58:59] nt
	v_add_u32_e32 v1, 0x1c00, v1
	global_load_dwordx4 v[196:199], v1, s[58:59] nt
	v_add_u32_e32 v1, 0x1c00, v1
	global_load_dwordx4 v[200:203], v1, s[58:59] nt
	v_add_u32_e32 v1, 0x1c00, v1
	global_load_dwordx4 v[204:207], v1, s[58:59] nt
	v_add_u32_e32 v1, 0x1c00, v1
	global_load_dwordx4 v[208:211], v1, s[58:59] nt
	v_add_u32_e32 v1, 0x1c00, v1
	global_load_dwordx4 v[212:215], v1, s[58:59] nt
	v_add_u32_e32 v1, 0x1c00, v1
	global_load_dwordx4 v[216:219], v1, s[58:59] nt
	v_add_u32_e32 v1, 0x1c00, v1
	global_load_dwordx4 v[220:223], v1, s[58:59] nt
	v_add_u32_e32 v1, 0x1c00, v1
	global_load_dwordx4 v[224:227], v1, s[58:59] nt
	v_add_u32_e32 v1, 0x1c00, v1
	global_load_dwordx4 v[228:231], v1, s[58:59] nt
	v_add_u32_e32 v1, 0x1c00, v1
	global_load_dwordx4 v[232:235], v1, s[58:59] nt
	v_add_u32_e32 v1, 0x1c00, v1
	s_cmp_lg_u32 s67, 0
	s_cselect_b64 vcc, -1, 0
	s_nop 1
	v_cndmask_b32_e32 v1, v1, v4, vcc
	global_load_dwordx4 v[236:239], v1, s[58:59] nt
	s_mul_i32 s63, s62, 0xc00
	s_add_u32 s63, s63, 0x15000800
	v_lshl_add_u32 v5, v0, 4, s63
	s_waitcnt vmcnt(18)
	s_cmp_eq_u32 s66, 0
	s_cbranch_scc1 .Lp2_nz_7
	v_mov_b32_e32 v8, 0
	v_mov_b32_e32 v9, 0
	v_mov_b32_e32 v10, 0
	v_mov_b32_e32 v11, 0

; template <int CH> __device__ __forceinline__ void p2_rwkv_chunk(const Params& p, int t0, int lane) {
;     ...
;     const bf16_t* zc = (const bf16_t*)(ws + WS_Z) + (size_t)t0 * ZLD + c;
;     float mu[8], kq[8];
;     { const f32x4 m0 = *(const f32x4*)(p.in[8] + c), m1 = *(const f32x4*)(p.in[8] + c + 4);
; #pragma unroll
;       for (int i = 0; i < 4; ++i) { mu[i] = m0[i]; mu[4 + i] = m1[i]; } }
;     if (CH == 1) { const f32x4 q0 = *(const f32x4*)(p.in[14] + c - 512), q1 = *(const f32x4*)(p.in[14] + c - 512 + 4);
; #pragma unroll
;         for (int i = 0; i < 4; ++i) { kq[i] = q0[i]; kq[4 + i] = q1[i]; } }
;     float P[8], C[8], N[8];
;     if ((t0 & (T_SEQ - 1)) != 0) unpack8(__builtin_nontemporal_load((const u32x4*)(zc - ZLD)), P); else {
; #pragma unroll
;         for (int i = 0; i < 8; ++i) P[i] = 0.f; }
;     unpack8(__builtin_nontemporal_load((const u32x4*)(zc)), C);
;     u32x4 raw = __builtin_nontemporal_load((const u32x4*)(zc + ZLD));
; #pragma unroll 2
;     for (int i = 0; i < 16; ++i) {
;         const int t = t0 + i; const bool hasn = (t & (T_SEQ - 1)) != T_SEQ - 1;
;         if (hasn) unpack8(raw, N); else {
; #pragma unroll
;             for (int q = 0; q < 8; ++q) N[q] = 0.f; }
;         if (i < 15 && ((t + 1) & (T_SEQ - 1)) != T_SEQ - 1) raw = __builtin_nontemporal_load((const u32x4*)(zc + (size_t)(i + 2) * ZLD));
;         float zs[8];
; #pragma unroll
;         for (int q = 0; q < 8; ++q) zs[q] = C[q] + mu[q] * (0.5f * (P[q] + N[q]) - C[q]);
;         if (CH < 3) {
;             *(u32x4*)(RKV + (size_t)t * 1536 + c) = pack8(zs);
;             if (CH == 1) { float s2 = 0.f;
; #pragma unroll
;                 for (int q = 0; q < 8; ++q) { const float v = zs[q] * kq[q]; s2 += v * v; }
;                 s2 = red8s(s2);
;                 if ((lane & 7) == 0) RINV[t * 8 + (lane >> 3)] = rsqrtf(fmaxf(s2, 1e-24f)); }
;         } else {
;             const int cc = c - 1536; float o[8];
; #pragma unroll
;             for (int q = 0; q < 8; ++q) o[q] = cc < 128 ? tanhf_(zs[q]) : (cc < 192 ? zs[q] : sigmoidf_(zs[q]));
;             *(u32x4*)(AP + (size_t)t * KLORA + cc) = pack8(o);
; template <int CH> __device__ __forceinline__ void p2_gla_chunk(const Params& p, int t0, int lane) {
;     ...
;     const bf16_t* zc = (const bf16_t*)(ws + WS_Z) + (size_t)t0 * ZLD + NRW + c;
;     float w0[8], w1[8], w2[8];
; #pragma unroll
.Lp2_nz_8:
	v_lshlrev_b32_e32 v96, 16, v76
	v_and_b32_e32 v97, 0xffff0000, v76
	v_lshlrev_b32_e32 v98, 16, v77
	v_and_b32_e32 v99, 0xffff0000, v77
	v_lshlrev_b32_e32 v100, 16, v78
	v_and_b32_e32 v101, 0xffff0000, v78
	v_lshlrev_b32_e32 v102, 16, v79
	v_and_b32_e32 v103, 0xffff0000, v79
	v_add_f32_e32 v136, v80, v96
	v_add_f32_e32 v137, v81, v97
	v_add_f32_e32 v138, v82, v98
	v_add_f32_e32 v139, v83, v99
	v_add_f32_e32 v140, v84, v100
	v_add_f32_e32 v141, v85, v101
	v_add_f32_e32 v142, v86, v102
	v_add_f32_e32 v143, v87, v103
	v_fma_f32 v136, v136, 0.5, -v88
	v_fma_f32 v137, v137, 0.5, -v89
	v_fma_f32 v138, v138, 0.5, -v90
	v_fma_f32 v139, v139, 0.5, -v91
	v_fma_f32 v140, v140, 0.5, -v92
	v_fma_f32 v141, v141, 0.5, -v93
	v_fma_f32 v142, v142, 0.5, -v94
	v_fma_f32 v143, v143, 0.5, -v95
	v_fma_f32 v128, v104, v136, v88
	v_fma_f32 v129, v105, v137, v89
	v_fma_f32 v130, v106, v138, v90
	v_fma_f32 v131, v107, v139, v91
	v_fma_f32 v132, v108, v140, v92
	v_fma_f32 v133, v109, v141, v93
	v_fma_f32 v134, v110, v142, v94
	v_fma_f32 v135, v111, v143, v95
	v_cvt_pk_bf16_f32 v246, v128, v129
	v_cvt_pk_bf16_f32 v247, v130, v131
	v_cvt_pk_bf16_f32 v248, v132, v133
	v_cvt_pk_bf16_f32 v249, v134, v135
	global_store_dwordx4 v5, v[246:249], s[58:59] nt
	v_add_u32_e32 v5, 0xc00, v5
	s_mov_b32 s98, 0x1800
	s_mov_b32 s99, 0
	v_lshl_add_u64 v[2:3], v[250:251], 0, s[98:99]
	v_mov_b32_e32 v104, 0
	v_mov_b32_e32 v105, 0
	v_mov_b32_e32 v106, 0
	v_mov_b32_e32 v107, 0
	v_mov_b32_e32 v108, 0
	v_mov_b32_e32 v109, 0
	v_mov_b32_e32 v110, 0
	v_mov_b32_e32 v111, 0
	v_cmp_gt_u32_e64 s[64:65], 40, v0
	s_mov_b64 s[42:43], exec
	s_nop 0
	s_and_b64 exec, exec, s[64:65]
	global_load_dwordx4 v[104:107], v[2:3], off
	global_load_dwordx4 v[108:111], v[2:3], off offset:16
	s_mov_b64 exec, s[42:43]
	s_mul_i32 s63, s62, 0x1c00
	s_add_u32 s63, s63, 0x7000e80
	v_lshl_add_u32 v4, v0, 4, s63
	v_add_u32_e32 v1, 0xffffe400, v4
	s_cmp_lg_u32 s66, 0
	s_cselect_b64 vcc, -1, 0
	s_nop 1
	v_cndmask_b32_e32 v1, v1, v4, vcc
	global_load_dwordx4 v[8:11], v1, s[58:59] nt
	global_load_dwordx4 v[12:15], v4, s[58:59] nt
	v_mov_b32_e32 v1, v4
	v_add_u32_e32 v1, 0x1c00, v1
	global_load_dwordx4 v[16:19], v1, s[58:59] nt
	v_add_u32_e32 v1, 0x1c00, v1
	global_load_dwordx4 v[20:23], v1, s[58:59] nt
	v_add_u32_e32 v1, 0x1c00, v1
	global_load_dwordx4 v[24:27], v1, s[58:59] nt
	v_add_u32_e32 v1, 0x1c00, v1
	global_load_dwordx4 v[28:31], v1, s[58:59] nt
	v_add_u32_e32 v1, 0x1c00, v1
	global_load_dwordx4 v[32:35], v1, s[58:59] nt
	v_add_u32_e32 v1, 0x1c00, v1
	global_load_dwordx4 v[36:39], v1, s[58:59] nt
	v_add_u32_e32 v1, 0x1c00, v1
	global_load_dwordx4 v[40:43], v1, s[58:59] nt
	v_add_u32_e32 v1, 0x1c00, v1
	global_load_dwordx4 v[44:47], v1, s[58:59] nt
	v_add_u32_e32 v1, 0x1c00, v1
	global_load_dwordx4 v[48:51], v1, s[58:59] nt
	v_add_u32_e32 v1, 0x1c00, v1
	global_load_dwordx4 v[52:55], v1, s[58:59] nt
	v_add_u32_e32 v1, 0x1c00, v1
	global_load_dwordx4 v[56:59], v1, s[58:59] nt
	v_add_u32_e32 v1, 0x1c00, v1
	global_load_dwordx4 v[60:63], v1, s[58:59] nt
	v_add_u32_e32 v1, 0x1c00, v1
	global_load_dwordx4 v[64:67], v1, s[58:59] nt
	v_add_u32_e32 v1, 0x1c00, v1
	global_load_dwordx4 v[68:71], v1, s[58:59] nt
	v_add_u32_e32 v1, 0x1c00, v1
	global_load_dwordx4 v[72:75], v1, s[58:59] nt
	v_add_u32_e32 v1, 0x1c00, v1
	s_cmp_lg_u32 s67, 0
	s_cselect_b64 vcc, -1, 0
	s_nop 1
	v_cndmask_b32_e32 v1, v1, v4, vcc
	global_load_dwordx4 v[76:79], v1, s[58:59] nt
	v_cmp_gt_u32_e64 s[64:65], 40, v0
	v_cmp_gt_u32_e64 s[74:75], 16, v0
	v_cmp_gt_u32_e64 s[76:77], 24, v0
	v_cmp_gt_u32_e64 s[36:37], 48, v0
	s_mul_i32 s63, s62, 0x300
	v_lshl_add_u32 v5, v0, 4, s63
	s_waitcnt vmcnt(18)
	s_cmp_eq_u32 s66, 0
	s_cbranch_scc1 .Lp2_nz_9
	v_mov_b32_e32 v168, 0
	v_mov_b32_e32 v169, 0
	v_mov_b32_e32 v170, 0
	v_mov_b32_e32 v171, 0
.Lp2_nz_9:
	v_lshlrev_b32_e32 v80, 16, v168
	v_and_b32_e32 v81, 0xffff0000, v168
	v_lshlrev_b32_e32 v82, 16, v169
	v_and_b32_e32 v83, 0xffff0000, v169
	v_lshlrev_b32_e32 v84, 16, v170
	v_and_b32_e32 v85, 0xffff0000, v170
	v_lshlrev_b32_e32 v86, 16, v171
	v_and_b32_e32 v87, 0xffff0000, v171
	v_lshlrev_b32_e32 v88, 16, v172
	v_and_b32_e32 v89, 0xffff0000, v172
	v_lshlrev_b32_e32 v90, 16, v173
	v_and_b32_e32 v91, 0xffff0000, v173
	v_lshlrev_b32_e32 v92, 16, v174
	v_and_b32_e32 v93, 0xffff0000, v174
	v_lshlrev_b32_e32 v94, 16, v175
	v_and_b32_e32 v95, 0xffff0000, v175
	v_lshlrev_b32_e32 v96, 16, v176
	v_and_b32_e32 v97, 0xffff0000, v176
	v_lshlrev_b32_e32 v98, 16, v177
	v_and_b32_e32 v99, 0xffff0000, v177
	v_lshlrev_b32_e32 v100, 16, v178
	v_and_b32_e32 v101, 0xffff0000, v178
	v_lshlrev_b32_e32 v102, 16, v179
	v_and_b32_e32 v103, 0xffff0000, v179
	v_add_f32_e32 v136, v80, v96
	v_add_f32_e32 v137, v81, v97
	v_add_f32_e32 v138, v82, v98
	v_add_f32_e32 v139, v83, v99
	v_add_f32_e32 v140, v84, v100
	v_add_f32_e32 v141, v85, v101
	v_add_f32_e32 v142, v86, v102
	v_add_f32_e32 v143, v87, v103
	v_fma_f32 v136, v136, 0.5, -v88
	v_fma_f32 v137, v137, 0.5, -v89
	v_fma_f32 v138, v138, 0.5, -v90
	v_fma_f32 v139, v139, 0.5, -v91
	v_fma_f32 v140, v140, 0.5, -v92
	v_fma_f32 v141, v141, 0.5, -v93
	v_fma_f32 v142, v142, 0.5, -v94
	v_fma_f32 v143, v143, 0.5, -v95
	v_fma_f32 v128, v104, v136, v88
	v_fma_f32 v129, v105, v137, v89
	v_fma_f32 v130, v106, v138, v90
	v_fma_f32 v131, v107, v139, v91
	v_fma_f32 v132, v108, v140, v92
	v_fma_f32 v133, v109, v141, v93
	v_fma_f32 v134, v110, v142, v94
	v_fma_f32 v135, v111, v143, v95
	v_mul_f32_e32 v136, 0x4038aa3b, v128
	v_mul_f32_e32 v137, 0x4038aa3b, v129
	v_mul_f32_e32 v138, 0x4038aa3b, v130
	v_mul_f32_e32 v139, 0x4038aa3b, v131
	v_mul_f32_e32 v140, 0x4038aa3b, v132
	v_mul_f32_e32 v141, 0x4038aa3b, v133
; __device__ __forceinline__ u32x4 pack8(const float (&f)[8]) { u32x4 o; o.x = pk2(f[0], f[1]); o.y = pk2(f[2], f[3]); o.z = pk2(f[4], f[5]); o.w = pk2(f[6], f[7]); return o; }
; __device__ __forceinline__ float sigmoidf_(float x) { return __builtin_amdgcn_rcpf(1.0f + __expf(-x)); }
; __device__ __forceinline__ float tanhf_(float x) { return 1.0f - 2.0f * __builtin_amdgcn_rcpf(__expf(2.0f * x) + 1.0f); }
; template <int CH> __device__ __forceinline__ void p2_rwkv_chunk(const Params& p, int t0, int lane) {
;     ...
;         for (int q = 0; q < 8; ++q) zs[q] = C[q] + mu[q] * (0.5f * (P[q] + N[q]) - C[q]);
;         if (CH < 3) {
;             *(u32x4*)(RKV + (size_t)t * 1536 + c) = pack8(zs);
;             if (CH == 1) { float s2 = 0.f;
; #pragma unroll
;                 for (int q = 0; q < 8; ++q) { const float v = zs[q] * kq[q]; s2 += v * v; }
;                 s2 = red8s(s2);
;                 if ((lane & 7) == 0) RINV[t * 8 + (lane >> 3)] = rsqrtf(fmaxf(s2, 1e-24f)); }
;         } else {
;             const int cc = c - 1536; float o[8];
; #pragma unroll
;             for (int q = 0; q < 8; ++q) o[q] = cc < 128 ? tanhf_(zs[q]) : (cc < 192 ? zs[q] : sigmoidf_(zs[q]));
;             *(u32x4*)(AP + (size_t)t * KLORA + cc) = pack8(o);
	v_mul_f32_e32 v142, 0x4038aa3b, v134
	v_mul_f32_e32 v143, 0x4038aa3b, v135
	v_mul_f32_e32 v144, 0xbfb8aa3b, v128
	v_mul_f32_e32 v145, 0xbfb8aa3b, v129
	v_mul_f32_e32 v146, 0xbfb8aa3b, v130
	v_mul_f32_e32 v147, 0xbfb8aa3b, v131
	v_mul_f32_e32 v148, 0xbfb8aa3b, v132
	v_mul_f32_e32 v149, 0xbfb8aa3b, v133
	v_mul_f32_e32 v150, 0xbfb8aa3b, v134
	v_mul_f32_e32 v151, 0xbfb8aa3b, v135
	v_exp_f32_e32 v136, v136
	v_exp_f32_e32 v137, v137
	v_exp_f32_e32 v138, v138
	v_exp_f32_e32 v139, v139
	v_exp_f32_e32 v140, v140
	v_exp_f32_e32 v141, v141
	v_exp_f32_e32 v142, v142
	v_exp_f32_e32 v143, v143
	v_exp_f32_e32 v144, v144
	v_exp_f32_e32 v145, v145
	v_exp_f32_e32 v146, v146
	v_exp_f32_e32 v147, v147
	v_exp_f32_e32 v148, v148
	v_exp_f32_e32 v149, v149
	v_exp_f32_e32 v150, v150
	v_exp_f32_e32 v151, v151
	v_add_f32_e32 v136, 1.0, v136
	v_add_f32_e32 v137, 1.0, v137
	v_add_f32_e32 v138, 1.0, v138
	v_add_f32_e32 v139, 1.0, v139
	v_add_f32_e32 v140, 1.0, v140
	v_add_f32_e32 v141, 1.0, v141
	v_add_f32_e32 v142, 1.0, v142
	v_add_f32_e32 v143, 1.0, v143
	v_add_f32_e32 v144, 1.0, v144
	v_add_f32_e32 v145, 1.0, v145
	v_add_f32_e32 v146, 1.0, v146
	v_add_f32_e32 v147, 1.0, v147
	v_add_f32_e32 v148, 1.0, v148
	v_add_f32_e32 v149, 1.0, v149
	v_add_f32_e32 v150, 1.0, v150
	v_add_f32_e32 v151, 1.0, v151
	v_rcp_f32_e32 v136, v136
	v_rcp_f32_e32 v137, v137
	v_rcp_f32_e32 v138, v138
	v_rcp_f32_e32 v139, v139
	v_rcp_f32_e32 v140, v140
	v_rcp_f32_e32 v141, v141
	v_rcp_f32_e32 v142, v142
	v_rcp_f32_e32 v143, v143
	v_rcp_f32_e32 v144, v144
	v_rcp_f32_e32 v145, v145
	v_rcp_f32_e32 v146, v146
	v_rcp_f32_e32 v147, v147
	v_rcp_f32_e32 v148, v148
	v_rcp_f32_e32 v149, v149
	v_rcp_f32_e32 v150, v150
	v_rcp_f32_e32 v151, v151
	v_fma_f32 v136, v136, -2.0, 1.0
	v_fma_f32 v137, v137, -2.0, 1.0
	v_fma_f32 v138, v138, -2.0, 1.0
	v_fma_f32 v139, v139, -2.0, 1.0
	v_fma_f32 v140, v140, -2.0, 1.0
	v_fma_f32 v141, v141, -2.0, 1.0
	v_fma_f32 v142, v142, -2.0, 1.0
	v_fma_f32 v143, v143, -2.0, 1.0
	v_cndmask_b32_e64 v144, v144, v128, s[76:77]
	v_cndmask_b32_e64 v145, v145, v129, s[76:77]
	v_cndmask_b32_e64 v146, v146, v130, s[76:77]
	v_cndmask_b32_e64 v147, v147, v131, s[76:77]
	v_cndmask_b32_e64 v148, v148, v132, s[76:77]
	v_cndmask_b32_e64 v149, v149, v133, s[76:77]
	v_cndmask_b32_e64 v150, v150, v134, s[76:77]
	v_cndmask_b32_e64 v151, v151, v135, s[76:77]
	v_cndmask_b32_e64 v144, v144, v136, s[74:75]
	v_cndmask_b32_e64 v145, v145, v137, s[74:75]
	v_cndmask_b32_e64 v146, v146, v138, s[74:75]
	v_cndmask_b32_e64 v147, v147, v139, s[74:75]
	v_cndmask_b32_e64 v148, v148, v140, s[74:75]
	v_cndmask_b32_e64 v149, v149, v141, s[74:75]
	v_cndmask_b32_e64 v150, v150, v142, s[74:75]
	v_cndmask_b32_e64 v151, v151, v143, s[74:75]
	v_cndmask_b32_e64 v144, 0, v144, s[64:65]
	v_cndmask_b32_e64 v145, 0, v145, s[64:65]
	v_cndmask_b32_e64 v146, 0, v146, s[64:65]
	v_cndmask_b32_e64 v147, 0, v147, s[64:65]
	v_cndmask_b32_e64 v148, 0, v148, s[64:65]
	v_cndmask_b32_e64 v149, 0, v149, s[64:65]
	v_cndmask_b32_e64 v150, 0, v150, s[64:65]
	v_cndmask_b32_e64 v151, 0, v151, s[64:65]
	v_cvt_pk_bf16_f32 v246, v144, v145
	v_cvt_pk_bf16_f32 v247, v146, v147
	v_cvt_pk_bf16_f32 v248, v148, v149
	v_cvt_pk_bf16_f32 v249, v150, v151
	s_mov_b64 s[42:43], exec
	s_and_b64 exec, exec, s[36:37]
	global_store_dwordx4 v5, v[246:249], s[56:57] nt
	s_mov_b64 exec, s[42:43]
	v_add_u32_e32 v5, 0x300, v5
	v_lshlrev_b32_e32 v80, 16, v180
	v_and_b32_e32 v81, 0xffff0000, v180
	v_lshlrev_b32_e32 v82, 16, v181
	v_and_b32_e32 v83, 0xffff0000, v181
	v_lshlrev_b32_e32 v84, 16, v182
	v_and_b32_e32 v85, 0xffff0000, v182
	v_lshlrev_b32_e32 v86, 16, v183
	v_and_b32_e32 v87, 0xffff0000, v183
	v_add_f32_e32 v136, v88, v80
	v_add_f32_e32 v137, v89, v81
	v_add_f32_e32 v138, v90, v82
	v_add_f32_e32 v139, v91, v83
	v_add_f32_e32 v140, v92, v84
	v_add_f32_e32 v141, v93, v85
	v_add_f32_e32 v142, v94, v86
	v_add_f32_e32 v143, v95, v87
	v_fma_f32 v136, v136, 0.5, -v96
	v_fma_f32 v137, v137, 0.5, -v97
	v_fma_f32 v138, v138, 0.5, -v98
	v_fma_f32 v139, v139, 0.5, -v99
	v_fma_f32 v140, v140, 0.5, -v100
	v_fma_f32 v141, v141, 0.5, -v101
	v_fma_f32 v142, v142, 0.5, -v102
	v_fma_f32 v143, v143, 0.5, -v103
	v_fma_f32 v128, v104, v136, v96
	v_fma_f32 v129, v105, v137, v97
	v_fma_f32 v130, v106, v138, v98
	v_fma_f32 v131, v107, v139, v99
	v_fma_f32 v132, v108, v140, v100
	v_fma_f32 v133, v109, v141, v101
	v_fma_f32 v134, v110, v142, v102
	v_fma_f32 v135, v111, v143, v103
	v_mul_f32_e32 v136, 0x4038aa3b, v128
	v_mul_f32_e32 v137, 0x4038aa3b, v129
	v_mul_f32_e32 v138, 0x4038aa3b, v130
	v_mul_f32_e32 v139, 0x4038aa3b, v131
	v_mul_f32_e32 v140, 0x4038aa3b, v132
	v_mul_f32_e32 v141, 0x4038aa3b, v133
	v_mul_f32_e32 v142, 0x4038aa3b, v134
	v_mul_f32_e32 v143, 0x4038aa3b, v135
	v_mul_f32_e32 v144, 0xbfb8aa3b, v128
	v_mul_f32_e32 v145, 0xbfb8aa3b, v129
	v_mul_f32_e32 v146, 0xbfb8aa3b, v130
	v_mul_f32_e32 v147, 0xbfb8aa3b, v131
	v_mul_f32_e32 v148, 0xbfb8aa3b, v132
	v_mul_f32_e32 v149, 0xbfb8aa3b, v133
	v_mul_f32_e32 v150, 0xbfb8aa3b, v134
	v_mul_f32_e32 v151, 0xbfb8aa3b, v135
	v_exp_f32_e32 v136, v136
	v_exp_f32_e32 v137, v137
	v_exp_f32_e32 v138, v138
	v_exp_f32_e32 v139, v139
	v_exp_f32_e32 v140, v140
	v_exp_f32_e32 v141, v141
	v_exp_f32_e32 v142, v142
	v_exp_f32_e32 v143, v143
	v_exp_f32_e32 v144, v144
	v_exp_f32_e32 v145, v145
	v_exp_f32_e32 v146, v146
	v_exp_f32_e32 v147, v147
	v_exp_f32_e32 v148, v148
	v_exp_f32_e32 v149, v149
	v_exp_f32_e32 v150, v150
	v_exp_f32_e32 v151, v151
	v_add_f32_e32 v136, 1.0, v136
	v_add_f32_e32 v137, 1.0, v137
	v_add_f32_e32 v138, 1.0, v138
	v_add_f32_e32 v139, 1.0, v139
	v_add_f32_e32 v140, 1.0, v140
	v_add_f32_e32 v141, 1.0, v141
; __device__ __forceinline__ u32x4 pack8(const float (&f)[8]) { u32x4 o; o.x = pk2(f[0], f[1]); o.y = pk2(f[2], f[3]); o.z = pk2(f[4], f[5]); o.w = pk2(f[6], f[7]); return o; }
; __device__ __forceinline__ float sigmoidf_(float x) { return __builtin_amdgcn_rcpf(1.0f + __expf(-x)); }
; __device__ __forceinline__ float tanhf_(float x) { return 1.0f - 2.0f * __builtin_amdgcn_rcpf(__expf(2.0f * x) + 1.0f); }
; template <int CH> __device__ __forceinline__ void p2_rwkv_chunk(const Params& p, int t0, int lane) {
;     ...
;         for (int q = 0; q < 8; ++q) zs[q] = C[q] + mu[q] * (0.5f * (P[q] + N[q]) - C[q]);
;         if (CH < 3) {
;             *(u32x4*)(RKV + (size_t)t * 1536 + c) = pack8(zs);
;             if (CH == 1) { float s2 = 0.f;
; #pragma unroll
;                 for (int q = 0; q < 8; ++q) { const float v = zs[q] * kq[q]; s2 += v * v; }
;                 s2 = red8s(s2);
;                 if ((lane & 7) == 0) RINV[t * 8 + (lane >> 3)] = rsqrtf(fmaxf(s2, 1e-24f)); }
;         } else {
;             const int cc = c - 1536; float o[8];
; #pragma unroll
;             for (int q = 0; q < 8; ++q) o[q] = cc < 128 ? tanhf_(zs[q]) : (cc < 192 ? zs[q] : sigmoidf_(zs[q]));
;             *(u32x4*)(AP + (size_t)t * KLORA + cc) = pack8(o);
	v_add_f32_e32 v142, 1.0, v142
	v_add_f32_e32 v143, 1.0, v143
	v_add_f32_e32 v144, 1.0, v144
	v_add_f32_e32 v145, 1.0, v145
	v_add_f32_e32 v146, 1.0, v146
	v_add_f32_e32 v147, 1.0, v147
	v_add_f32_e32 v148, 1.0, v148
	v_add_f32_e32 v149, 1.0, v149
	v_add_f32_e32 v150, 1.0, v150
	v_add_f32_e32 v151, 1.0, v151
	v_rcp_f32_e32 v136, v136
	v_rcp_f32_e32 v137, v137
	v_rcp_f32_e32 v138, v138
	v_rcp_f32_e32 v139, v139
	v_rcp_f32_e32 v140, v140
	v_rcp_f32_e32 v141, v141
	v_rcp_f32_e32 v142, v142
	v_rcp_f32_e32 v143, v143
	v_rcp_f32_e32 v144, v144
	v_rcp_f32_e32 v145, v145
	v_rcp_f32_e32 v146, v146
	v_rcp_f32_e32 v147, v147
	v_rcp_f32_e32 v148, v148
	v_rcp_f32_e32 v149, v149
	v_rcp_f32_e32 v150, v150
	v_rcp_f32_e32 v151, v151
	v_fma_f32 v136, v136, -2.0, 1.0
	v_fma_f32 v137, v137, -2.0, 1.0
	v_fma_f32 v138, v138, -2.0, 1.0
	v_fma_f32 v139, v139, -2.0, 1.0
	v_fma_f32 v140, v140, -2.0, 1.0
	v_fma_f32 v141, v141, -2.0, 1.0
	v_fma_f32 v142, v142, -2.0, 1.0
	v_fma_f32 v143, v143, -2.0, 1.0
	v_cndmask_b32_e64 v144, v144, v128, s[76:77]
	v_cndmask_b32_e64 v145, v145, v129, s[76:77]
	v_cndmask_b32_e64 v146, v146, v130, s[76:77]
	v_cndmask_b32_e64 v147, v147, v131, s[76:77]
	v_cndmask_b32_e64 v148, v148, v132, s[76:77]
	v_cndmask_b32_e64 v149, v149, v133, s[76:77]
	v_cndmask_b32_e64 v150, v150, v134, s[76:77]
	v_cndmask_b32_e64 v151, v151, v135, s[76:77]
	v_cndmask_b32_e64 v144, v144, v136, s[74:75]
	v_cndmask_b32_e64 v145, v145, v137, s[74:75]
	v_cndmask_b32_e64 v146, v146, v138, s[74:75]
	v_cndmask_b32_e64 v147, v147, v139, s[74:75]
	v_cndmask_b32_e64 v148, v148, v140, s[74:75]
	v_cndmask_b32_e64 v149, v149, v141, s[74:75]
	v_cndmask_b32_e64 v150, v150, v142, s[74:75]
	v_cndmask_b32_e64 v151, v151, v143, s[74:75]
	v_cndmask_b32_e64 v144, 0, v144, s[64:65]
	v_cndmask_b32_e64 v145, 0, v145, s[64:65]
	v_cndmask_b32_e64 v146, 0, v146, s[64:65]
	v_cndmask_b32_e64 v147, 0, v147, s[64:65]
	v_cndmask_b32_e64 v148, 0, v148, s[64:65]
	v_cndmask_b32_e64 v149, 0, v149, s[64:65]
	v_cndmask_b32_e64 v150, 0, v150, s[64:65]
	v_cndmask_b32_e64 v151, 0, v151, s[64:65]
	v_cvt_pk_bf16_f32 v246, v144, v145
	v_cvt_pk_bf16_f32 v247, v146, v147
	v_cvt_pk_bf16_f32 v248, v148, v149
	v_cvt_pk_bf16_f32 v249, v150, v151
	s_mov_b64 s[42:43], exec
	s_and_b64 exec, exec, s[36:37]
	global_store_dwordx4 v5, v[246:249], s[56:57] nt
	s_mov_b64 exec, s[42:43]
	v_add_u32_e32 v5, 0x300, v5
	v_lshlrev_b32_e32 v88, 16, v184
	v_and_b32_e32 v89, 0xffff0000, v184
	v_lshlrev_b32_e32 v90, 16, v185
	v_and_b32_e32 v91, 0xffff0000, v185
	v_lshlrev_b32_e32 v92, 16, v186
	v_and_b32_e32 v93, 0xffff0000, v186
	v_lshlrev_b32_e32 v94, 16, v187
	v_and_b32_e32 v95, 0xffff0000, v187
	v_add_f32_e32 v136, v96, v88
	v_add_f32_e32 v137, v97, v89
	v_add_f32_e32 v138, v98, v90
	v_add_f32_e32 v139, v99, v91
	v_add_f32_e32 v140, v100, v92
	v_add_f32_e32 v141, v101, v93
	v_add_f32_e32 v142, v102, v94
	v_add_f32_e32 v143, v103, v95
	v_fma_f32 v136, v136, 0.5, -v80
	v_fma_f32 v137, v137, 0.5, -v81
	v_fma_f32 v138, v138, 0.5, -v82
	v_fma_f32 v139, v139, 0.5, -v83
	v_fma_f32 v140, v140, 0.5, -v84
	v_fma_f32 v141, v141, 0.5, -v85
	v_fma_f32 v142, v142, 0.5, -v86
	v_fma_f32 v143, v143, 0.5, -v87
	v_fma_f32 v128, v104, v136, v80
	v_fma_f32 v129, v105, v137, v81
	v_fma_f32 v130, v106, v138, v82
	v_fma_f32 v131, v107, v139, v83
	v_fma_f32 v132, v108, v140, v84
	v_fma_f32 v133, v109, v141, v85
	v_fma_f32 v134, v110, v142, v86
	v_fma_f32 v135, v111, v143, v87
	v_mul_f32_e32 v136, 0x4038aa3b, v128
	v_mul_f32_e32 v137, 0x4038aa3b, v129
	v_mul_f32_e32 v138, 0x4038aa3b, v130
	v_mul_f32_e32 v139, 0x4038aa3b, v131
	v_mul_f32_e32 v140, 0x4038aa3b, v132
	v_mul_f32_e32 v141, 0x4038aa3b, v133
	v_mul_f32_e32 v142, 0x4038aa3b, v134
	v_mul_f32_e32 v143, 0x4038aa3b, v135
	v_mul_f32_e32 v144, 0xbfb8aa3b, v128
	v_mul_f32_e32 v145, 0xbfb8aa3b, v129
	v_mul_f32_e32 v146, 0xbfb8aa3b, v130
	v_mul_f32_e32 v147, 0xbfb8aa3b, v131
	v_mul_f32_e32 v148, 0xbfb8aa3b, v132
	v_mul_f32_e32 v149, 0xbfb8aa3b, v133
	v_mul_f32_e32 v150, 0xbfb8aa3b, v134
	v_mul_f32_e32 v151, 0xbfb8aa3b, v135
	v_exp_f32_e32 v136, v136
	v_exp_f32_e32 v137, v137
	v_exp_f32_e32 v138, v138
	v_exp_f32_e32 v139, v139
	v_exp_f32_e32 v140, v140
	v_exp_f32_e32 v141, v141
	v_exp_f32_e32 v142, v142
	v_exp_f32_e32 v143, v143
	v_exp_f32_e32 v144, v144
	v_exp_f32_e32 v145, v145
	v_exp_f32_e32 v146, v146
	v_exp_f32_e32 v147, v147
	v_exp_f32_e32 v148, v148
	v_exp_f32_e32 v149, v149
	v_exp_f32_e32 v150, v150
	v_exp_f32_e32 v151, v151
	v_add_f32_e32 v136, 1.0, v136
	v_add_f32_e32 v137, 1.0, v137
	v_add_f32_e32 v138, 1.0, v138
	v_add_f32_e32 v139, 1.0, v139
	v_add_f32_e32 v140, 1.0, v140
	v_add_f32_e32 v141, 1.0, v141
	v_add_f32_e32 v142, 1.0, v142
	v_add_f32_e32 v143, 1.0, v143
	v_add_f32_e32 v144, 1.0, v144
	v_add_f32_e32 v145, 1.0, v145
	v_add_f32_e32 v146, 1.0, v146
	v_add_f32_e32 v147, 1.0, v147
	v_add_f32_e32 v148, 1.0, v148
	v_add_f32_e32 v149, 1.0, v149
	v_add_f32_e32 v150, 1.0, v150
	v_add_f32_e32 v151, 1.0, v151
	v_rcp_f32_e32 v136, v136
	v_rcp_f32_e32 v137, v137
	v_rcp_f32_e32 v138, v138
	v_rcp_f32_e32 v139, v139
	v_rcp_f32_e32 v140, v140
	v_rcp_f32_e32 v141, v141
	v_rcp_f32_e32 v142, v142
	v_rcp_f32_e32 v143, v143
	v_rcp_f32_e32 v144, v144
	v_rcp_f32_e32 v145, v145
	v_rcp_f32_e32 v146, v146
	v_rcp_f32_e32 v147, v147
	v_rcp_f32_e32 v148, v148
	v_rcp_f32_e32 v149, v149
	v_rcp_f32_e32 v150, v150
	v_rcp_f32_e32 v151, v151
	v_fma_f32 v136, v136, -2.0, 1.0
	v_fma_f32 v137, v137, -2.0, 1.0
	v_fma_f32 v138, v138, -2.0, 1.0
	v_fma_f32 v139, v139, -2.0, 1.0
	v_fma_f32 v140, v140, -2.0, 1.0
	v_fma_f32 v141, v141, -2.0, 1.0
	v_fma_f32 v142, v142, -2.0, 1.0
	v_fma_f32 v143, v143, -2.0, 1.0
; __device__ __forceinline__ u32x4 pack8(const float (&f)[8]) { u32x4 o; o.x = pk2(f[0], f[1]); o.y = pk2(f[2], f[3]); o.z = pk2(f[4], f[5]); o.w = pk2(f[6], f[7]); return o; }
; __device__ __forceinline__ float sigmoidf_(float x) { return __builtin_amdgcn_rcpf(1.0f + __expf(-x)); }
; __device__ __forceinline__ float tanhf_(float x) { return 1.0f - 2.0f * __builtin_amdgcn_rcpf(__expf(2.0f * x) + 1.0f); }
; template <int CH> __device__ __forceinline__ void p2_rwkv_chunk(const Params& p, int t0, int lane) {
;     ...
;         for (int q = 0; q < 8; ++q) zs[q] = C[q] + mu[q] * (0.5f * (P[q] + N[q]) - C[q]);
;         if (CH < 3) {
;             *(u32x4*)(RKV + (size_t)t * 1536 + c) = pack8(zs);
;             if (CH == 1) { float s2 = 0.f;
; #pragma unroll
;                 for (int q = 0; q < 8; ++q) { const float v = zs[q] * kq[q]; s2 += v * v; }
;                 s2 = red8s(s2);
;                 if ((lane & 7) == 0) RINV[t * 8 + (lane >> 3)] = rsqrtf(fmaxf(s2, 1e-24f)); }
;         } else {
;             const int cc = c - 1536; float o[8];
; #pragma unroll
;             for (int q = 0; q < 8; ++q) o[q] = cc < 128 ? tanhf_(zs[q]) : (cc < 192 ? zs[q] : sigmoidf_(zs[q]));
;             *(u32x4*)(AP + (size_t)t * KLORA + cc) = pack8(o);
	v_cndmask_b32_e64 v144, v144, v128, s[76:77]
	v_cndmask_b32_e64 v145, v145, v129, s[76:77]
	v_cndmask_b32_e64 v146, v146, v130, s[76:77]
	v_cndmask_b32_e64 v147, v147, v131, s[76:77]
	v_cndmask_b32_e64 v148, v148, v132, s[76:77]
	v_cndmask_b32_e64 v149, v149, v133, s[76:77]
	v_cndmask_b32_e64 v150, v150, v134, s[76:77]
	v_cndmask_b32_e64 v151, v151, v135, s[76:77]
	v_cndmask_b32_e64 v144, v144, v136, s[74:75]
	v_cndmask_b32_e64 v145, v145, v137, s[74:75]
	v_cndmask_b32_e64 v146, v146, v138, s[74:75]
	v_cndmask_b32_e64 v147, v147, v139, s[74:75]
	v_cndmask_b32_e64 v148, v148, v140, s[74:75]
	v_cndmask_b32_e64 v149, v149, v141, s[74:75]
	v_cndmask_b32_e64 v150, v150, v142, s[74:75]
	v_cndmask_b32_e64 v151, v151, v143, s[74:75]
	v_cndmask_b32_e64 v144, 0, v144, s[64:65]
	v_cndmask_b32_e64 v145, 0, v145, s[64:65]
	v_cndmask_b32_e64 v146, 0, v146, s[64:65]
	v_cndmask_b32_e64 v147, 0, v147, s[64:65]
	v_cndmask_b32_e64 v148, 0, v148, s[64:65]
	v_cndmask_b32_e64 v149, 0, v149, s[64:65]
	v_cndmask_b32_e64 v150, 0, v150, s[64:65]
	v_cndmask_b32_e64 v151, 0, v151, s[64:65]
	v_cvt_pk_bf16_f32 v246, v144, v145
	v_cvt_pk_bf16_f32 v247, v146, v147
	v_cvt_pk_bf16_f32 v248, v148, v149
	v_cvt_pk_bf16_f32 v249, v150, v151
	s_mov_b64 s[42:43], exec
	s_and_b64 exec, exec, s[36:37]
	global_store_dwordx4 v5, v[246:249], s[56:57] nt
	s_mov_b64 exec, s[42:43]
	v_add_u32_e32 v5, 0x300, v5
	v_lshlrev_b32_e32 v96, 16, v188
	v_and_b32_e32 v97, 0xffff0000, v188
	v_lshlrev_b32_e32 v98, 16, v189
	v_and_b32_e32 v99, 0xffff0000, v189
	v_lshlrev_b32_e32 v100, 16, v190
	v_and_b32_e32 v101, 0xffff0000, v190
	v_lshlrev_b32_e32 v102, 16, v191
	v_and_b32_e32 v103, 0xffff0000, v191
	v_add_f32_e32 v136, v80, v96
	v_add_f32_e32 v137, v81, v97
	v_add_f32_e32 v138, v82, v98
	v_add_f32_e32 v139, v83, v99
	v_add_f32_e32 v140, v84, v100
	v_add_f32_e32 v141, v85, v101
	v_add_f32_e32 v142, v86, v102
	v_add_f32_e32 v143, v87, v103
	v_fma_f32 v136, v136, 0.5, -v88
	v_fma_f32 v137, v137, 0.5, -v89
	v_fma_f32 v138, v138, 0.5, -v90
	v_fma_f32 v139, v139, 0.5, -v91
	v_fma_f32 v140, v140, 0.5, -v92
	v_fma_f32 v141, v141, 0.5, -v93
	v_fma_f32 v142, v142, 0.5, -v94
	v_fma_f32 v143, v143, 0.5, -v95
	v_fma_f32 v128, v104, v136, v88
	v_fma_f32 v129, v105, v137, v89
	v_fma_f32 v130, v106, v138, v90
	v_fma_f32 v131, v107, v139, v91
	v_fma_f32 v132, v108, v140, v92
	v_fma_f32 v133, v109, v141, v93
	v_fma_f32 v134, v110, v142, v94
	v_fma_f32 v135, v111, v143, v95
	v_mul_f32_e32 v136, 0x4038aa3b, v128
	v_mul_f32_e32 v137, 0x4038aa3b, v129
	v_mul_f32_e32 v138, 0x4038aa3b, v130
	v_mul_f32_e32 v139, 0x4038aa3b, v131
	v_mul_f32_e32 v140, 0x4038aa3b, v132
	v_mul_f32_e32 v141, 0x4038aa3b, v133
	v_mul_f32_e32 v142, 0x4038aa3b, v134
	v_mul_f32_e32 v143, 0x4038aa3b, v135
	v_mul_f32_e32 v144, 0xbfb8aa3b, v128
	v_mul_f32_e32 v145, 0xbfb8aa3b, v129
	v_mul_f32_e32 v146, 0xbfb8aa3b, v130
	v_mul_f32_e32 v147, 0xbfb8aa3b, v131
	v_mul_f32_e32 v148, 0xbfb8aa3b, v132
	v_mul_f32_e32 v149, 0xbfb8aa3b, v133
	v_mul_f32_e32 v150, 0xbfb8aa3b, v134
	v_mul_f32_e32 v151, 0xbfb8aa3b, v135
	v_exp_f32_e32 v136, v136
	v_exp_f32_e32 v137, v137
	v_exp_f32_e32 v138, v138
	v_exp_f32_e32 v139, v139
	v_exp_f32_e32 v140, v140
	v_exp_f32_e32 v141, v141
	v_exp_f32_e32 v142, v142
	v_exp_f32_e32 v143, v143
	v_exp_f32_e32 v144, v144
	v_exp_f32_e32 v145, v145
	v_exp_f32_e32 v146, v146
	v_exp_f32_e32 v147, v147
	v_exp_f32_e32 v148, v148
	v_exp_f32_e32 v149, v149
	v_exp_f32_e32 v150, v150
	v_exp_f32_e32 v151, v151
	v_add_f32_e32 v136, 1.0, v136
	v_add_f32_e32 v137, 1.0, v137
	v_add_f32_e32 v138, 1.0, v138
	v_add_f32_e32 v139, 1.0, v139
	v_add_f32_e32 v140, 1.0, v140
	v_add_f32_e32 v141, 1.0, v141
	v_add_f32_e32 v142, 1.0, v142
	v_add_f32_e32 v143, 1.0, v143
	v_add_f32_e32 v144, 1.0, v144
	v_add_f32_e32 v145, 1.0, v145
	v_add_f32_e32 v146, 1.0, v146
	v_add_f32_e32 v147, 1.0, v147
	v_add_f32_e32 v148, 1.0, v148
	v_add_f32_e32 v149, 1.0, v149
	v_add_f32_e32 v150, 1.0, v150
	v_add_f32_e32 v151, 1.0, v151
	v_rcp_f32_e32 v136, v136
	v_rcp_f32_e32 v137, v137
	v_rcp_f32_e32 v138, v138
	v_rcp_f32_e32 v139, v139
	v_rcp_f32_e32 v140, v140
	v_rcp_f32_e32 v141, v141
	v_rcp_f32_e32 v142, v142
	v_rcp_f32_e32 v143, v143
	v_rcp_f32_e32 v144, v144
	v_rcp_f32_e32 v145, v145
	v_rcp_f32_e32 v146, v146
	v_rcp_f32_e32 v147, v147
	v_rcp_f32_e32 v148, v148
	v_rcp_f32_e32 v149, v149
	v_rcp_f32_e32 v150, v150
	v_rcp_f32_e32 v151, v151
	v_fma_f32 v136, v136, -2.0, 1.0
	v_fma_f32 v137, v137, -2.0, 1.0
	v_fma_f32 v138, v138, -2.0, 1.0
	v_fma_f32 v139, v139, -2.0, 1.0
	v_fma_f32 v140, v140, -2.0, 1.0
	v_fma_f32 v141, v141, -2.0, 1.0
	v_fma_f32 v142, v142, -2.0, 1.0
	v_fma_f32 v143, v143, -2.0, 1.0
	v_cndmask_b32_e64 v144, v144, v128, s[76:77]
	v_cndmask_b32_e64 v145, v145, v129, s[76:77]
	v_cndmask_b32_e64 v146, v146, v130, s[76:77]
	v_cndmask_b32_e64 v147, v147, v131, s[76:77]
	v_cndmask_b32_e64 v148, v148, v132, s[76:77]
	v_cndmask_b32_e64 v149, v149, v133, s[76:77]
	v_cndmask_b32_e64 v150, v150, v134, s[76:77]
	v_cndmask_b32_e64 v151, v151, v135, s[76:77]
	v_cndmask_b32_e64 v144, v144, v136, s[74:75]
	v_cndmask_b32_e64 v145, v145, v137, s[74:75]
	v_cndmask_b32_e64 v146, v146, v138, s[74:75]
	v_cndmask_b32_e64 v147, v147, v139, s[74:75]
	v_cndmask_b32_e64 v148, v148, v140, s[74:75]
	v_cndmask_b32_e64 v149, v149, v141, s[74:75]
	v_cndmask_b32_e64 v150, v150, v142, s[74:75]
	v_cndmask_b32_e64 v151, v151, v143, s[74:75]
	v_cndmask_b32_e64 v144, 0, v144, s[64:65]
	v_cndmask_b32_e64 v145, 0, v145, s[64:65]
	v_cndmask_b32_e64 v146, 0, v146, s[64:65]
	v_cndmask_b32_e64 v147, 0, v147, s[64:65]
	v_cndmask_b32_e64 v148, 0, v148, s[64:65]
	v_cndmask_b32_e64 v149, 0, v149, s[64:65]
; __device__ __forceinline__ u32x4 pack8(const float (&f)[8]) { u32x4 o; o.x = pk2(f[0], f[1]); o.y = pk2(f[2], f[3]); o.z = pk2(f[4], f[5]); o.w = pk2(f[6], f[7]); return o; }
; __device__ __forceinline__ float sigmoidf_(float x) { return __builtin_amdgcn_rcpf(1.0f + __expf(-x)); }
; __device__ __forceinline__ float tanhf_(float x) { return 1.0f - 2.0f * __builtin_amdgcn_rcpf(__expf(2.0f * x) + 1.0f); }
; template <int CH> __device__ __forceinline__ void p2_rwkv_chunk(const Params& p, int t0, int lane) {
;     ...
;         for (int q = 0; q < 8; ++q) zs[q] = C[q] + mu[q] * (0.5f * (P[q] + N[q]) - C[q]);
;         if (CH < 3) {
;             *(u32x4*)(RKV + (size_t)t * 1536 + c) = pack8(zs);
;             if (CH == 1) { float s2 = 0.f;
; #pragma unroll
;                 for (int q = 0; q < 8; ++q) { const float v = zs[q] * kq[q]; s2 += v * v; }
;                 s2 = red8s(s2);
;                 if ((lane & 7) == 0) RINV[t * 8 + (lane >> 3)] = rsqrtf(fmaxf(s2, 1e-24f)); }
;         } else {
;             const int cc = c - 1536; float o[8];
; #pragma unroll
;             for (int q = 0; q < 8; ++q) o[q] = cc < 128 ? tanhf_(zs[q]) : (cc < 192 ? zs[q] : sigmoidf_(zs[q]));
;             *(u32x4*)(AP + (size_t)t * KLORA + cc) = pack8(o);
	v_cndmask_b32_e64 v150, 0, v150, s[64:65]
	v_cndmask_b32_e64 v151, 0, v151, s[64:65]
	v_cvt_pk_bf16_f32 v246, v144, v145
	v_cvt_pk_bf16_f32 v247, v146, v147
	v_cvt_pk_bf16_f32 v248, v148, v149
	v_cvt_pk_bf16_f32 v249, v150, v151
	s_mov_b64 s[42:43], exec
	s_and_b64 exec, exec, s[36:37]
	global_store_dwordx4 v5, v[246:249], s[56:57] nt
	s_mov_b64 exec, s[42:43]
	v_add_u32_e32 v5, 0x300, v5
	v_lshlrev_b32_e32 v80, 16, v192
	v_and_b32_e32 v81, 0xffff0000, v192
	v_lshlrev_b32_e32 v82, 16, v193
	v_and_b32_e32 v83, 0xffff0000, v193
	v_lshlrev_b32_e32 v84, 16, v194
	v_and_b32_e32 v85, 0xffff0000, v194
	v_lshlrev_b32_e32 v86, 16, v195
	v_and_b32_e32 v87, 0xffff0000, v195
	v_add_f32_e32 v136, v88, v80
	v_add_f32_e32 v137, v89, v81
	v_add_f32_e32 v138, v90, v82
	v_add_f32_e32 v139, v91, v83
	v_add_f32_e32 v140, v92, v84
	v_add_f32_e32 v141, v93, v85
	v_add_f32_e32 v142, v94, v86
	v_add_f32_e32 v143, v95, v87
	v_fma_f32 v136, v136, 0.5, -v96
	v_fma_f32 v137, v137, 0.5, -v97
	v_fma_f32 v138, v138, 0.5, -v98
	v_fma_f32 v139, v139, 0.5, -v99
	v_fma_f32 v140, v140, 0.5, -v100
	v_fma_f32 v141, v141, 0.5, -v101
	v_fma_f32 v142, v142, 0.5, -v102
	v_fma_f32 v143, v143, 0.5, -v103
	v_fma_f32 v128, v104, v136, v96
	v_fma_f32 v129, v105, v137, v97
	v_fma_f32 v130, v106, v138, v98
	v_fma_f32 v131, v107, v139, v99
	v_fma_f32 v132, v108, v140, v100
	v_fma_f32 v133, v109, v141, v101
	v_fma_f32 v134, v110, v142, v102
	v_fma_f32 v135, v111, v143, v103
	v_mul_f32_e32 v136, 0x4038aa3b, v128
	v_mul_f32_e32 v137, 0x4038aa3b, v129
	v_mul_f32_e32 v138, 0x4038aa3b, v130
	v_mul_f32_e32 v139, 0x4038aa3b, v131
	v_mul_f32_e32 v140, 0x4038aa3b, v132
	v_mul_f32_e32 v141, 0x4038aa3b, v133
	v_mul_f32_e32 v142, 0x4038aa3b, v134
	v_mul_f32_e32 v143, 0x4038aa3b, v135
	v_mul_f32_e32 v144, 0xbfb8aa3b, v128
	v_mul_f32_e32 v145, 0xbfb8aa3b, v129
	v_mul_f32_e32 v146, 0xbfb8aa3b, v130
	v_mul_f32_e32 v147, 0xbfb8aa3b, v131
	v_mul_f32_e32 v148, 0xbfb8aa3b, v132
	v_mul_f32_e32 v149, 0xbfb8aa3b, v133
	v_mul_f32_e32 v150, 0xbfb8aa3b, v134
	v_mul_f32_e32 v151, 0xbfb8aa3b, v135
	v_exp_f32_e32 v136, v136
	v_exp_f32_e32 v137, v137
	v_exp_f32_e32 v138, v138
	v_exp_f32_e32 v139, v139
	v_exp_f32_e32 v140, v140
	v_exp_f32_e32 v141, v141
	v_exp_f32_e32 v142, v142
	v_exp_f32_e32 v143, v143
	v_exp_f32_e32 v144, v144
	v_exp_f32_e32 v145, v145
	v_exp_f32_e32 v146, v146
	v_exp_f32_e32 v147, v147
	v_exp_f32_e32 v148, v148
	v_exp_f32_e32 v149, v149
	v_exp_f32_e32 v150, v150
	v_exp_f32_e32 v151, v151
	v_add_f32_e32 v136, 1.0, v136
	v_add_f32_e32 v137, 1.0, v137
	v_add_f32_e32 v138, 1.0, v138
	v_add_f32_e32 v139, 1.0, v139
	v_add_f32_e32 v140, 1.0, v140
	v_add_f32_e32 v141, 1.0, v141
	v_add_f32_e32 v142, 1.0, v142
	v_add_f32_e32 v143, 1.0, v143
	v_add_f32_e32 v144, 1.0, v144
	v_add_f32_e32 v145, 1.0, v145
	v_add_f32_e32 v146, 1.0, v146
	v_add_f32_e32 v147, 1.0, v147
	v_add_f32_e32 v148, 1.0, v148
	v_add_f32_e32 v149, 1.0, v149
	v_add_f32_e32 v150, 1.0, v150
	v_add_f32_e32 v151, 1.0, v151
	v_rcp_f32_e32 v136, v136
	v_rcp_f32_e32 v137, v137
	v_rcp_f32_e32 v138, v138
	v_rcp_f32_e32 v139, v139
	v_rcp_f32_e32 v140, v140
	v_rcp_f32_e32 v141, v141
	v_rcp_f32_e32 v142, v142
	v_rcp_f32_e32 v143, v143
	v_rcp_f32_e32 v144, v144
	v_rcp_f32_e32 v145, v145
	v_rcp_f32_e32 v146, v146
	v_rcp_f32_e32 v147, v147
	v_rcp_f32_e32 v148, v148
	v_rcp_f32_e32 v149, v149
	v_rcp_f32_e32 v150, v150
	v_rcp_f32_e32 v151, v151
	v_fma_f32 v136, v136, -2.0, 1.0
	v_fma_f32 v137, v137, -2.0, 1.0
	v_fma_f32 v138, v138, -2.0, 1.0
	v_fma_f32 v139, v139, -2.0, 1.0
	v_fma_f32 v140, v140, -2.0, 1.0
	v_fma_f32 v141, v141, -2.0, 1.0
	v_fma_f32 v142, v142, -2.0, 1.0
	v_fma_f32 v143, v143, -2.0, 1.0
	v_cndmask_b32_e64 v144, v144, v128, s[76:77]
	v_cndmask_b32_e64 v145, v145, v129, s[76:77]
	v_cndmask_b32_e64 v146, v146, v130, s[76:77]
	v_cndmask_b32_e64 v147, v147, v131, s[76:77]
	v_cndmask_b32_e64 v148, v148, v132, s[76:77]
	v_cndmask_b32_e64 v149, v149, v133, s[76:77]
	v_cndmask_b32_e64 v150, v150, v134, s[76:77]
	v_cndmask_b32_e64 v151, v151, v135, s[76:77]
	v_cndmask_b32_e64 v144, v144, v136, s[74:75]
	v_cndmask_b32_e64 v145, v145, v137, s[74:75]
	v_cndmask_b32_e64 v146, v146, v138, s[74:75]
	v_cndmask_b32_e64 v147, v147, v139, s[74:75]
	v_cndmask_b32_e64 v148, v148, v140, s[74:75]
	v_cndmask_b32_e64 v149, v149, v141, s[74:75]
	v_cndmask_b32_e64 v150, v150, v142, s[74:75]
	v_cndmask_b32_e64 v151, v151, v143, s[74:75]
	v_cndmask_b32_e64 v144, 0, v144, s[64:65]
	v_cndmask_b32_e64 v145, 0, v145, s[64:65]
	v_cndmask_b32_e64 v146, 0, v146, s[64:65]
	v_cndmask_b32_e64 v147, 0, v147, s[64:65]
	v_cndmask_b32_e64 v148, 0, v148, s[64:65]
	v_cndmask_b32_e64 v149, 0, v149, s[64:65]
	v_cndmask_b32_e64 v150, 0, v150, s[64:65]
	v_cndmask_b32_e64 v151, 0, v151, s[64:65]
	v_cvt_pk_bf16_f32 v246, v144, v145
	v_cvt_pk_bf16_f32 v247, v146, v147
	v_cvt_pk_bf16_f32 v248, v148, v149
	v_cvt_pk_bf16_f32 v249, v150, v151
	s_mov_b64 s[42:43], exec
	s_and_b64 exec, exec, s[36:37]
	global_store_dwordx4 v5, v[246:249], s[56:57] nt
	s_mov_b64 exec, s[42:43]
	v_add_u32_e32 v5, 0x300, v5
	v_lshlrev_b32_e32 v88, 16, v196
	v_and_b32_e32 v89, 0xffff0000, v196
	v_lshlrev_b32_e32 v90, 16, v197
	v_and_b32_e32 v91, 0xffff0000, v197
	v_lshlrev_b32_e32 v92, 16, v198
	v_and_b32_e32 v93, 0xffff0000, v198
	v_lshlrev_b32_e32 v94, 16, v199
	v_and_b32_e32 v95, 0xffff0000, v199
	v_add_f32_e32 v136, v96, v88
	v_add_f32_e32 v137, v97, v89
	v_add_f32_e32 v138, v98, v90
	v_add_f32_e32 v139, v99, v91
	v_add_f32_e32 v140, v100, v92
	v_add_f32_e32 v141, v101, v93
	v_add_f32_e32 v142, v102, v94
	v_add_f32_e32 v143, v103, v95
	v_fma_f32 v136, v136, 0.5, -v80
	v_fma_f32 v137, v137, 0.5, -v81
; __device__ __forceinline__ u32x4 pack8(const float (&f)[8]) { u32x4 o; o.x = pk2(f[0], f[1]); o.y = pk2(f[2], f[3]); o.z = pk2(f[4], f[5]); o.w = pk2(f[6], f[7]); return o; }
; __device__ __forceinline__ float sigmoidf_(float x) { return __builtin_amdgcn_rcpf(1.0f + __expf(-x)); }
; __device__ __forceinline__ float tanhf_(float x) { return 1.0f - 2.0f * __builtin_amdgcn_rcpf(__expf(2.0f * x) + 1.0f); }
; template <int CH> __device__ __forceinline__ void p2_rwkv_chunk(const Params& p, int t0, int lane) {
;     ...
;         for (int q = 0; q < 8; ++q) zs[q] = C[q] + mu[q] * (0.5f * (P[q] + N[q]) - C[q]);
;         if (CH < 3) {
;             *(u32x4*)(RKV + (size_t)t * 1536 + c) = pack8(zs);
;             if (CH == 1) { float s2 = 0.f;
; #pragma unroll
;                 for (int q = 0; q < 8; ++q) { const float v = zs[q] * kq[q]; s2 += v * v; }
;                 s2 = red8s(s2);
;                 if ((lane & 7) == 0) RINV[t * 8 + (lane >> 3)] = rsqrtf(fmaxf(s2, 1e-24f)); }
;         } else {
;             const int cc = c - 1536; float o[8];
; #pragma unroll
;             for (int q = 0; q < 8; ++q) o[q] = cc < 128 ? tanhf_(zs[q]) : (cc < 192 ? zs[q] : sigmoidf_(zs[q]));
;             *(u32x4*)(AP + (size_t)t * KLORA + cc) = pack8(o);
	v_fma_f32 v138, v138, 0.5, -v82
	v_fma_f32 v139, v139, 0.5, -v83
	v_fma_f32 v140, v140, 0.5, -v84
	v_fma_f32 v141, v141, 0.5, -v85
	v_fma_f32 v142, v142, 0.5, -v86
	v_fma_f32 v143, v143, 0.5, -v87
	v_fma_f32 v128, v104, v136, v80
	v_fma_f32 v129, v105, v137, v81
	v_fma_f32 v130, v106, v138, v82
	v_fma_f32 v131, v107, v139, v83
	v_fma_f32 v132, v108, v140, v84
	v_fma_f32 v133, v109, v141, v85
	v_fma_f32 v134, v110, v142, v86
	v_fma_f32 v135, v111, v143, v87
	v_mul_f32_e32 v136, 0x4038aa3b, v128
	v_mul_f32_e32 v137, 0x4038aa3b, v129
	v_mul_f32_e32 v138, 0x4038aa3b, v130
	v_mul_f32_e32 v139, 0x4038aa3b, v131
	v_mul_f32_e32 v140, 0x4038aa3b, v132
	v_mul_f32_e32 v141, 0x4038aa3b, v133
	v_mul_f32_e32 v142, 0x4038aa3b, v134
	v_mul_f32_e32 v143, 0x4038aa3b, v135
	v_mul_f32_e32 v144, 0xbfb8aa3b, v128
	v_mul_f32_e32 v145, 0xbfb8aa3b, v129
	v_mul_f32_e32 v146, 0xbfb8aa3b, v130
	v_mul_f32_e32 v147, 0xbfb8aa3b, v131
	v_mul_f32_e32 v148, 0xbfb8aa3b, v132
	v_mul_f32_e32 v149, 0xbfb8aa3b, v133
	v_mul_f32_e32 v150, 0xbfb8aa3b, v134
	v_mul_f32_e32 v151, 0xbfb8aa3b, v135
	v_exp_f32_e32 v136, v136
	v_exp_f32_e32 v137, v137
	v_exp_f32_e32 v138, v138
	v_exp_f32_e32 v139, v139
	v_exp_f32_e32 v140, v140
	v_exp_f32_e32 v141, v141
	v_exp_f32_e32 v142, v142
	v_exp_f32_e32 v143, v143
	v_exp_f32_e32 v144, v144
	v_exp_f32_e32 v145, v145
	v_exp_f32_e32 v146, v146
	v_exp_f32_e32 v147, v147
	v_exp_f32_e32 v148, v148
	v_exp_f32_e32 v149, v149
	v_exp_f32_e32 v150, v150
	v_exp_f32_e32 v151, v151
	v_add_f32_e32 v136, 1.0, v136
	v_add_f32_e32 v137, 1.0, v137
	v_add_f32_e32 v138, 1.0, v138
	v_add_f32_e32 v139, 1.0, v139
	v_add_f32_e32 v140, 1.0, v140
	v_add_f32_e32 v141, 1.0, v141
	v_add_f32_e32 v142, 1.0, v142
	v_add_f32_e32 v143, 1.0, v143
	v_add_f32_e32 v144, 1.0, v144
	v_add_f32_e32 v145, 1.0, v145
	v_add_f32_e32 v146, 1.0, v146
	v_add_f32_e32 v147, 1.0, v147
	v_add_f32_e32 v148, 1.0, v148
	v_add_f32_e32 v149, 1.0, v149
	v_add_f32_e32 v150, 1.0, v150
	v_add_f32_e32 v151, 1.0, v151
	v_rcp_f32_e32 v136, v136
	v_rcp_f32_e32 v137, v137
	v_rcp_f32_e32 v138, v138
	v_rcp_f32_e32 v139, v139
	v_rcp_f32_e32 v140, v140
	v_rcp_f32_e32 v141, v141
	v_rcp_f32_e32 v142, v142
	v_rcp_f32_e32 v143, v143
	v_rcp_f32_e32 v144, v144
	v_rcp_f32_e32 v145, v145
	v_rcp_f32_e32 v146, v146
	v_rcp_f32_e32 v147, v147
	v_rcp_f32_e32 v148, v148
	v_rcp_f32_e32 v149, v149
	v_rcp_f32_e32 v150, v150
	v_rcp_f32_e32 v151, v151
	v_fma_f32 v136, v136, -2.0, 1.0
	v_fma_f32 v137, v137, -2.0, 1.0
	v_fma_f32 v138, v138, -2.0, 1.0
	v_fma_f32 v139, v139, -2.0, 1.0
	v_fma_f32 v140, v140, -2.0, 1.0
	v_fma_f32 v141, v141, -2.0, 1.0
	v_fma_f32 v142, v142, -2.0, 1.0
	v_fma_f32 v143, v143, -2.0, 1.0
	v_cndmask_b32_e64 v144, v144, v128, s[76:77]
	v_cndmask_b32_e64 v145, v145, v129, s[76:77]
	v_cndmask_b32_e64 v146, v146, v130, s[76:77]
	v_cndmask_b32_e64 v147, v147, v131, s[76:77]
	v_cndmask_b32_e64 v148, v148, v132, s[76:77]
	v_cndmask_b32_e64 v149, v149, v133, s[76:77]
	v_cndmask_b32_e64 v150, v150, v134, s[76:77]
	v_cndmask_b32_e64 v151, v151, v135, s[76:77]
	v_cndmask_b32_e64 v144, v144, v136, s[74:75]
	v_cndmask_b32_e64 v145, v145, v137, s[74:75]
	v_cndmask_b32_e64 v146, v146, v138, s[74:75]
	v_cndmask_b32_e64 v147, v147, v139, s[74:75]
	v_cndmask_b32_e64 v148, v148, v140, s[74:75]
	v_cndmask_b32_e64 v149, v149, v141, s[74:75]
	v_cndmask_b32_e64 v150, v150, v142, s[74:75]
	v_cndmask_b32_e64 v151, v151, v143, s[74:75]
	v_cndmask_b32_e64 v144, 0, v144, s[64:65]
	v_cndmask_b32_e64 v145, 0, v145, s[64:65]
	v_cndmask_b32_e64 v146, 0, v146, s[64:65]
	v_cndmask_b32_e64 v147, 0, v147, s[64:65]
	v_cndmask_b32_e64 v148, 0, v148, s[64:65]
	v_cndmask_b32_e64 v149, 0, v149, s[64:65]
	v_cndmask_b32_e64 v150, 0, v150, s[64:65]
	v_cndmask_b32_e64 v151, 0, v151, s[64:65]
	v_cvt_pk_bf16_f32 v246, v144, v145
	v_cvt_pk_bf16_f32 v247, v146, v147
	v_cvt_pk_bf16_f32 v248, v148, v149
	v_cvt_pk_bf16_f32 v249, v150, v151
	s_mov_b64 s[42:43], exec
	s_and_b64 exec, exec, s[36:37]
	global_store_dwordx4 v5, v[246:249], s[56:57] nt
	s_mov_b64 exec, s[42:43]
	v_add_u32_e32 v5, 0x300, v5
	v_lshlrev_b32_e32 v96, 16, v200
	v_and_b32_e32 v97, 0xffff0000, v200
	v_lshlrev_b32_e32 v98, 16, v201
	v_and_b32_e32 v99, 0xffff0000, v201
	v_lshlrev_b32_e32 v100, 16, v202
	v_and_b32_e32 v101, 0xffff0000, v202
	v_lshlrev_b32_e32 v102, 16, v203
	v_and_b32_e32 v103, 0xffff0000, v203
	v_add_f32_e32 v136, v80, v96
	v_add_f32_e32 v137, v81, v97
	v_add_f32_e32 v138, v82, v98
	v_add_f32_e32 v139, v83, v99
	v_add_f32_e32 v140, v84, v100
	v_add_f32_e32 v141, v85, v101
	v_add_f32_e32 v142, v86, v102
	v_add_f32_e32 v143, v87, v103
	v_fma_f32 v136, v136, 0.5, -v88
	v_fma_f32 v137, v137, 0.5, -v89
	v_fma_f32 v138, v138, 0.5, -v90
	v_fma_f32 v139, v139, 0.5, -v91
	v_fma_f32 v140, v140, 0.5, -v92
	v_fma_f32 v141, v141, 0.5, -v93
	v_fma_f32 v142, v142, 0.5, -v94
	v_fma_f32 v143, v143, 0.5, -v95
	v_fma_f32 v128, v104, v136, v88
	v_fma_f32 v129, v105, v137, v89
	v_fma_f32 v130, v106, v138, v90
	v_fma_f32 v131, v107, v139, v91
	v_fma_f32 v132, v108, v140, v92
	v_fma_f32 v133, v109, v141, v93
	v_fma_f32 v134, v110, v142, v94
	v_fma_f32 v135, v111, v143, v95
	v_mul_f32_e32 v136, 0x4038aa3b, v128
	v_mul_f32_e32 v137, 0x4038aa3b, v129
	v_mul_f32_e32 v138, 0x4038aa3b, v130
	v_mul_f32_e32 v139, 0x4038aa3b, v131
	v_mul_f32_e32 v140, 0x4038aa3b, v132
	v_mul_f32_e32 v141, 0x4038aa3b, v133
	v_mul_f32_e32 v142, 0x4038aa3b, v134
	v_mul_f32_e32 v143, 0x4038aa3b, v135
	v_mul_f32_e32 v144, 0xbfb8aa3b, v128
	v_mul_f32_e32 v145, 0xbfb8aa3b, v129
	v_mul_f32_e32 v146, 0xbfb8aa3b, v130
	v_mul_f32_e32 v147, 0xbfb8aa3b, v131
	v_mul_f32_e32 v148, 0xbfb8aa3b, v132
	v_mul_f32_e32 v149, 0xbfb8aa3b, v133
; __device__ __forceinline__ u32x4 pack8(const float (&f)[8]) { u32x4 o; o.x = pk2(f[0], f[1]); o.y = pk2(f[2], f[3]); o.z = pk2(f[4], f[5]); o.w = pk2(f[6], f[7]); return o; }
; __device__ __forceinline__ float sigmoidf_(float x) { return __builtin_amdgcn_rcpf(1.0f + __expf(-x)); }
; __device__ __forceinline__ float tanhf_(float x) { return 1.0f - 2.0f * __builtin_amdgcn_rcpf(__expf(2.0f * x) + 1.0f); }
; template <int CH> __device__ __forceinline__ void p2_rwkv_chunk(const Params& p, int t0, int lane) {
;     ...
;         for (int q = 0; q < 8; ++q) zs[q] = C[q] + mu[q] * (0.5f * (P[q] + N[q]) - C[q]);
;         if (CH < 3) {
;             *(u32x4*)(RKV + (size_t)t * 1536 + c) = pack8(zs);
;             if (CH == 1) { float s2 = 0.f;
; #pragma unroll
;                 for (int q = 0; q < 8; ++q) { const float v = zs[q] * kq[q]; s2 += v * v; }
;                 s2 = red8s(s2);
;                 if ((lane & 7) == 0) RINV[t * 8 + (lane >> 3)] = rsqrtf(fmaxf(s2, 1e-24f)); }
;         } else {
;             const int cc = c - 1536; float o[8];
; #pragma unroll
;             for (int q = 0; q < 8; ++q) o[q] = cc < 128 ? tanhf_(zs[q]) : (cc < 192 ? zs[q] : sigmoidf_(zs[q]));
;             *(u32x4*)(AP + (size_t)t * KLORA + cc) = pack8(o);
	v_mul_f32_e32 v150, 0xbfb8aa3b, v134
	v_mul_f32_e32 v151, 0xbfb8aa3b, v135
	v_exp_f32_e32 v136, v136
	v_exp_f32_e32 v137, v137
	v_exp_f32_e32 v138, v138
	v_exp_f32_e32 v139, v139
	v_exp_f32_e32 v140, v140
	v_exp_f32_e32 v141, v141
	v_exp_f32_e32 v142, v142
	v_exp_f32_e32 v143, v143
	v_exp_f32_e32 v144, v144
	v_exp_f32_e32 v145, v145
	v_exp_f32_e32 v146, v146
	v_exp_f32_e32 v147, v147
	v_exp_f32_e32 v148, v148
	v_exp_f32_e32 v149, v149
	v_exp_f32_e32 v150, v150
	v_exp_f32_e32 v151, v151
	v_add_f32_e32 v136, 1.0, v136
	v_add_f32_e32 v137, 1.0, v137
	v_add_f32_e32 v138, 1.0, v138
	v_add_f32_e32 v139, 1.0, v139
	v_add_f32_e32 v140, 1.0, v140
	v_add_f32_e32 v141, 1.0, v141
	v_add_f32_e32 v142, 1.0, v142
	v_add_f32_e32 v143, 1.0, v143
	v_add_f32_e32 v144, 1.0, v144
	v_add_f32_e32 v145, 1.0, v145
	v_add_f32_e32 v146, 1.0, v146
	v_add_f32_e32 v147, 1.0, v147
	v_add_f32_e32 v148, 1.0, v148
	v_add_f32_e32 v149, 1.0, v149
	v_add_f32_e32 v150, 1.0, v150
	v_add_f32_e32 v151, 1.0, v151
	v_rcp_f32_e32 v136, v136
	v_rcp_f32_e32 v137, v137
	v_rcp_f32_e32 v138, v138
	v_rcp_f32_e32 v139, v139
	v_rcp_f32_e32 v140, v140
	v_rcp_f32_e32 v141, v141
	v_rcp_f32_e32 v142, v142
	v_rcp_f32_e32 v143, v143
	v_rcp_f32_e32 v144, v144
	v_rcp_f32_e32 v145, v145
	v_rcp_f32_e32 v146, v146
	v_rcp_f32_e32 v147, v147
	v_rcp_f32_e32 v148, v148
	v_rcp_f32_e32 v149, v149
	v_rcp_f32_e32 v150, v150
	v_rcp_f32_e32 v151, v151
	v_fma_f32 v136, v136, -2.0, 1.0
	v_fma_f32 v137, v137, -2.0, 1.0
	v_fma_f32 v138, v138, -2.0, 1.0
	v_fma_f32 v139, v139, -2.0, 1.0
	v_fma_f32 v140, v140, -2.0, 1.0
	v_fma_f32 v141, v141, -2.0, 1.0
	v_fma_f32 v142, v142, -2.0, 1.0
	v_fma_f32 v143, v143, -2.0, 1.0
	v_cndmask_b32_e64 v144, v144, v128, s[76:77]
	v_cndmask_b32_e64 v145, v145, v129, s[76:77]
	v_cndmask_b32_e64 v146, v146, v130, s[76:77]
	v_cndmask_b32_e64 v147, v147, v131, s[76:77]
	v_cndmask_b32_e64 v148, v148, v132, s[76:77]
	v_cndmask_b32_e64 v149, v149, v133, s[76:77]
	v_cndmask_b32_e64 v150, v150, v134, s[76:77]
	v_cndmask_b32_e64 v151, v151, v135, s[76:77]
	v_cndmask_b32_e64 v144, v144, v136, s[74:75]
	v_cndmask_b32_e64 v145, v145, v137, s[74:75]
	v_cndmask_b32_e64 v146, v146, v138, s[74:75]
	v_cndmask_b32_e64 v147, v147, v139, s[74:75]
	v_cndmask_b32_e64 v148, v148, v140, s[74:75]
	v_cndmask_b32_e64 v149, v149, v141, s[74:75]
	v_cndmask_b32_e64 v150, v150, v142, s[74:75]
	v_cndmask_b32_e64 v151, v151, v143, s[74:75]
	v_cndmask_b32_e64 v144, 0, v144, s[64:65]
	v_cndmask_b32_e64 v145, 0, v145, s[64:65]
	v_cndmask_b32_e64 v146, 0, v146, s[64:65]
	v_cndmask_b32_e64 v147, 0, v147, s[64:65]
	v_cndmask_b32_e64 v148, 0, v148, s[64:65]
	v_cndmask_b32_e64 v149, 0, v149, s[64:65]
	v_cndmask_b32_e64 v150, 0, v150, s[64:65]
	v_cndmask_b32_e64 v151, 0, v151, s[64:65]
	v_cvt_pk_bf16_f32 v246, v144, v145
	v_cvt_pk_bf16_f32 v247, v146, v147
	v_cvt_pk_bf16_f32 v248, v148, v149
	v_cvt_pk_bf16_f32 v249, v150, v151
	s_mov_b64 s[42:43], exec
	s_and_b64 exec, exec, s[36:37]
	global_store_dwordx4 v5, v[246:249], s[56:57] nt
	s_mov_b64 exec, s[42:43]
	v_add_u32_e32 v5, 0x300, v5
	v_lshlrev_b32_e32 v80, 16, v204
	v_and_b32_e32 v81, 0xffff0000, v204
	v_lshlrev_b32_e32 v82, 16, v205
	v_and_b32_e32 v83, 0xffff0000, v205
	v_lshlrev_b32_e32 v84, 16, v206
	v_and_b32_e32 v85, 0xffff0000, v206
	v_lshlrev_b32_e32 v86, 16, v207
	v_and_b32_e32 v87, 0xffff0000, v207
	v_add_f32_e32 v136, v88, v80
	v_add_f32_e32 v137, v89, v81
	v_add_f32_e32 v138, v90, v82
	v_add_f32_e32 v139, v91, v83
	v_add_f32_e32 v140, v92, v84
	v_add_f32_e32 v141, v93, v85
	v_add_f32_e32 v142, v94, v86
	v_add_f32_e32 v143, v95, v87
	v_fma_f32 v136, v136, 0.5, -v96
	v_fma_f32 v137, v137, 0.5, -v97
	v_fma_f32 v138, v138, 0.5, -v98
	v_fma_f32 v139, v139, 0.5, -v99
	v_fma_f32 v140, v140, 0.5, -v100
	v_fma_f32 v141, v141, 0.5, -v101
	v_fma_f32 v142, v142, 0.5, -v102
	v_fma_f32 v143, v143, 0.5, -v103
	v_fma_f32 v128, v104, v136, v96
	v_fma_f32 v129, v105, v137, v97
	v_fma_f32 v130, v106, v138, v98
	v_fma_f32 v131, v107, v139, v99
	v_fma_f32 v132, v108, v140, v100
	v_fma_f32 v133, v109, v141, v101
	v_fma_f32 v134, v110, v142, v102
	v_fma_f32 v135, v111, v143, v103
	v_mul_f32_e32 v136, 0x4038aa3b, v128
	v_mul_f32_e32 v137, 0x4038aa3b, v129
	v_mul_f32_e32 v138, 0x4038aa3b, v130
	v_mul_f32_e32 v139, 0x4038aa3b, v131
	v_mul_f32_e32 v140, 0x4038aa3b, v132
	v_mul_f32_e32 v141, 0x4038aa3b, v133
	v_mul_f32_e32 v142, 0x4038aa3b, v134
	v_mul_f32_e32 v143, 0x4038aa3b, v135
	v_mul_f32_e32 v144, 0xbfb8aa3b, v128
	v_mul_f32_e32 v145, 0xbfb8aa3b, v129
	v_mul_f32_e32 v146, 0xbfb8aa3b, v130
	v_mul_f32_e32 v147, 0xbfb8aa3b, v131
	v_mul_f32_e32 v148, 0xbfb8aa3b, v132
	v_mul_f32_e32 v149, 0xbfb8aa3b, v133
	v_mul_f32_e32 v150, 0xbfb8aa3b, v134
	v_mul_f32_e32 v151, 0xbfb8aa3b, v135
	v_exp_f32_e32 v136, v136
	v_exp_f32_e32 v137, v137
	v_exp_f32_e32 v138, v138
	v_exp_f32_e32 v139, v139
	v_exp_f32_e32 v140, v140
	v_exp_f32_e32 v141, v141
	v_exp_f32_e32 v142, v142
	v_exp_f32_e32 v143, v143
	v_exp_f32_e32 v144, v144
	v_exp_f32_e32 v145, v145
	v_exp_f32_e32 v146, v146
	v_exp_f32_e32 v147, v147
	v_exp_f32_e32 v148, v148
	v_exp_f32_e32 v149, v149
	v_exp_f32_e32 v150, v150
	v_exp_f32_e32 v151, v151
	v_add_f32_e32 v136, 1.0, v136
	v_add_f32_e32 v137, 1.0, v137
	v_add_f32_e32 v138, 1.0, v138
	v_add_f32_e32 v139, 1.0, v139
	v_add_f32_e32 v140, 1.0, v140
	v_add_f32_e32 v141, 1.0, v141
	v_add_f32_e32 v142, 1.0, v142
	v_add_f32_e32 v143, 1.0, v143
	v_add_f32_e32 v144, 1.0, v144
	v_add_f32_e32 v145, 1.0, v145
	v_add_f32_e32 v146, 1.0, v146
	v_add_f32_e32 v147, 1.0, v147
	v_add_f32_e32 v148, 1.0, v148
	v_add_f32_e32 v149, 1.0, v149
	v_add_f32_e32 v150, 1.0, v150
	v_add_f32_e32 v151, 1.0, v151
; __device__ __forceinline__ u32x4 pack8(const float (&f)[8]) { u32x4 o; o.x = pk2(f[0], f[1]); o.y = pk2(f[2], f[3]); o.z = pk2(f[4], f[5]); o.w = pk2(f[6], f[7]); return o; }
; __device__ __forceinline__ float sigmoidf_(float x) { return __builtin_amdgcn_rcpf(1.0f + __expf(-x)); }
; __device__ __forceinline__ float tanhf_(float x) { return 1.0f - 2.0f * __builtin_amdgcn_rcpf(__expf(2.0f * x) + 1.0f); }
; template <int CH> __device__ __forceinline__ void p2_rwkv_chunk(const Params& p, int t0, int lane) {
;     ...
;         for (int q = 0; q < 8; ++q) zs[q] = C[q] + mu[q] * (0.5f * (P[q] + N[q]) - C[q]);
;         if (CH < 3) {
;             *(u32x4*)(RKV + (size_t)t * 1536 + c) = pack8(zs);
;             if (CH == 1) { float s2 = 0.f;
; #pragma unroll
;                 for (int q = 0; q < 8; ++q) { const float v = zs[q] * kq[q]; s2 += v * v; }
;                 s2 = red8s(s2);
;                 if ((lane & 7) == 0) RINV[t * 8 + (lane >> 3)] = rsqrtf(fmaxf(s2, 1e-24f)); }
;         } else {
;             const int cc = c - 1536; float o[8];
; #pragma unroll
;             for (int q = 0; q < 8; ++q) o[q] = cc < 128 ? tanhf_(zs[q]) : (cc < 192 ? zs[q] : sigmoidf_(zs[q]));
;             *(u32x4*)(AP + (size_t)t * KLORA + cc) = pack8(o);
	v_rcp_f32_e32 v136, v136
	v_rcp_f32_e32 v137, v137
	v_rcp_f32_e32 v138, v138
	v_rcp_f32_e32 v139, v139
	v_rcp_f32_e32 v140, v140
	v_rcp_f32_e32 v141, v141
	v_rcp_f32_e32 v142, v142
	v_rcp_f32_e32 v143, v143
	v_rcp_f32_e32 v144, v144
	v_rcp_f32_e32 v145, v145
	v_rcp_f32_e32 v146, v146
	v_rcp_f32_e32 v147, v147
	v_rcp_f32_e32 v148, v148
	v_rcp_f32_e32 v149, v149
	v_rcp_f32_e32 v150, v150
	v_rcp_f32_e32 v151, v151
	v_fma_f32 v136, v136, -2.0, 1.0
	v_fma_f32 v137, v137, -2.0, 1.0
	v_fma_f32 v138, v138, -2.0, 1.0
	v_fma_f32 v139, v139, -2.0, 1.0
	v_fma_f32 v140, v140, -2.0, 1.0
	v_fma_f32 v141, v141, -2.0, 1.0
	v_fma_f32 v142, v142, -2.0, 1.0
	v_fma_f32 v143, v143, -2.0, 1.0
	v_cndmask_b32_e64 v144, v144, v128, s[76:77]
	v_cndmask_b32_e64 v145, v145, v129, s[76:77]
	v_cndmask_b32_e64 v146, v146, v130, s[76:77]
	v_cndmask_b32_e64 v147, v147, v131, s[76:77]
	v_cndmask_b32_e64 v148, v148, v132, s[76:77]
	v_cndmask_b32_e64 v149, v149, v133, s[76:77]
	v_cndmask_b32_e64 v150, v150, v134, s[76:77]
	v_cndmask_b32_e64 v151, v151, v135, s[76:77]
	v_cndmask_b32_e64 v144, v144, v136, s[74:75]
	v_cndmask_b32_e64 v145, v145, v137, s[74:75]
	v_cndmask_b32_e64 v146, v146, v138, s[74:75]
	v_cndmask_b32_e64 v147, v147, v139, s[74:75]
	v_cndmask_b32_e64 v148, v148, v140, s[74:75]
	v_cndmask_b32_e64 v149, v149, v141, s[74:75]
	v_cndmask_b32_e64 v150, v150, v142, s[74:75]
	v_cndmask_b32_e64 v151, v151, v143, s[74:75]
	v_cndmask_b32_e64 v144, 0, v144, s[64:65]
	v_cndmask_b32_e64 v145, 0, v145, s[64:65]
	v_cndmask_b32_e64 v146, 0, v146, s[64:65]
	v_cndmask_b32_e64 v147, 0, v147, s[64:65]
	v_cndmask_b32_e64 v148, 0, v148, s[64:65]
	v_cndmask_b32_e64 v149, 0, v149, s[64:65]
	v_cndmask_b32_e64 v150, 0, v150, s[64:65]
	v_cndmask_b32_e64 v151, 0, v151, s[64:65]
	v_cvt_pk_bf16_f32 v246, v144, v145
	v_cvt_pk_bf16_f32 v247, v146, v147
	v_cvt_pk_bf16_f32 v248, v148, v149
	v_cvt_pk_bf16_f32 v249, v150, v151
	s_mov_b64 s[42:43], exec
	s_and_b64 exec, exec, s[36:37]
	global_store_dwordx4 v5, v[246:249], s[56:57] nt
	s_mov_b64 exec, s[42:43]
	v_add_u32_e32 v5, 0x300, v5
	v_lshlrev_b32_e32 v88, 16, v208
	v_and_b32_e32 v89, 0xffff0000, v208
	v_lshlrev_b32_e32 v90, 16, v209
	v_and_b32_e32 v91, 0xffff0000, v209
	v_lshlrev_b32_e32 v92, 16, v210
	v_and_b32_e32 v93, 0xffff0000, v210
	v_lshlrev_b32_e32 v94, 16, v211
	v_and_b32_e32 v95, 0xffff0000, v211
	v_add_f32_e32 v136, v96, v88
	v_add_f32_e32 v137, v97, v89
	v_add_f32_e32 v138, v98, v90
	v_add_f32_e32 v139, v99, v91
	v_add_f32_e32 v140, v100, v92
	v_add_f32_e32 v141, v101, v93
	v_add_f32_e32 v142, v102, v94
	v_add_f32_e32 v143, v103, v95
	v_fma_f32 v136, v136, 0.5, -v80
	v_fma_f32 v137, v137, 0.5, -v81
	v_fma_f32 v138, v138, 0.5, -v82
	v_fma_f32 v139, v139, 0.5, -v83
	v_fma_f32 v140, v140, 0.5, -v84
	v_fma_f32 v141, v141, 0.5, -v85
	v_fma_f32 v142, v142, 0.5, -v86
	v_fma_f32 v143, v143, 0.5, -v87
	v_fma_f32 v128, v104, v136, v80
	v_fma_f32 v129, v105, v137, v81
	v_fma_f32 v130, v106, v138, v82
	v_fma_f32 v131, v107, v139, v83
	v_fma_f32 v132, v108, v140, v84
	v_fma_f32 v133, v109, v141, v85
	v_fma_f32 v134, v110, v142, v86
	v_fma_f32 v135, v111, v143, v87
	v_mul_f32_e32 v136, 0x4038aa3b, v128
	v_mul_f32_e32 v137, 0x4038aa3b, v129
	v_mul_f32_e32 v138, 0x4038aa3b, v130
	v_mul_f32_e32 v139, 0x4038aa3b, v131
	v_mul_f32_e32 v140, 0x4038aa3b, v132
	v_mul_f32_e32 v141, 0x4038aa3b, v133
	v_mul_f32_e32 v142, 0x4038aa3b, v134
	v_mul_f32_e32 v143, 0x4038aa3b, v135
	v_mul_f32_e32 v144, 0xbfb8aa3b, v128
	v_mul_f32_e32 v145, 0xbfb8aa3b, v129
	v_mul_f32_e32 v146, 0xbfb8aa3b, v130
	v_mul_f32_e32 v147, 0xbfb8aa3b, v131
	v_mul_f32_e32 v148, 0xbfb8aa3b, v132
	v_mul_f32_e32 v149, 0xbfb8aa3b, v133
	v_mul_f32_e32 v150, 0xbfb8aa3b, v134
	v_mul_f32_e32 v151, 0xbfb8aa3b, v135
	v_exp_f32_e32 v136, v136
	v_exp_f32_e32 v137, v137
	v_exp_f32_e32 v138, v138
	v_exp_f32_e32 v139, v139
	v_exp_f32_e32 v140, v140
	v_exp_f32_e32 v141, v141
	v_exp_f32_e32 v142, v142
	v_exp_f32_e32 v143, v143
	v_exp_f32_e32 v144, v144
	v_exp_f32_e32 v145, v145
	v_exp_f32_e32 v146, v146
	v_exp_f32_e32 v147, v147
	v_exp_f32_e32 v148, v148
	v_exp_f32_e32 v149, v149
	v_exp_f32_e32 v150, v150
	v_exp_f32_e32 v151, v151
	v_add_f32_e32 v136, 1.0, v136
	v_add_f32_e32 v137, 1.0, v137
	v_add_f32_e32 v138, 1.0, v138
	v_add_f32_e32 v139, 1.0, v139
	v_add_f32_e32 v140, 1.0, v140
	v_add_f32_e32 v141, 1.0, v141
	v_add_f32_e32 v142, 1.0, v142
	v_add_f32_e32 v143, 1.0, v143
	v_add_f32_e32 v144, 1.0, v144
	v_add_f32_e32 v145, 1.0, v145
	v_add_f32_e32 v146, 1.0, v146
	v_add_f32_e32 v147, 1.0, v147
	v_add_f32_e32 v148, 1.0, v148
	v_add_f32_e32 v149, 1.0, v149
	v_add_f32_e32 v150, 1.0, v150
	v_add_f32_e32 v151, 1.0, v151
	v_rcp_f32_e32 v136, v136
	v_rcp_f32_e32 v137, v137
	v_rcp_f32_e32 v138, v138
	v_rcp_f32_e32 v139, v139
	v_rcp_f32_e32 v140, v140
	v_rcp_f32_e32 v141, v141
	v_rcp_f32_e32 v142, v142
	v_rcp_f32_e32 v143, v143
	v_rcp_f32_e32 v144, v144
	v_rcp_f32_e32 v145, v145
	v_rcp_f32_e32 v146, v146
	v_rcp_f32_e32 v147, v147
	v_rcp_f32_e32 v148, v148
	v_rcp_f32_e32 v149, v149
	v_rcp_f32_e32 v150, v150
	v_rcp_f32_e32 v151, v151
	v_fma_f32 v136, v136, -2.0, 1.0
	v_fma_f32 v137, v137, -2.0, 1.0
	v_fma_f32 v138, v138, -2.0, 1.0
	v_fma_f32 v139, v139, -2.0, 1.0
	v_fma_f32 v140, v140, -2.0, 1.0
	v_fma_f32 v141, v141, -2.0, 1.0
	v_fma_f32 v142, v142, -2.0, 1.0
	v_fma_f32 v143, v143, -2.0, 1.0
	v_cndmask_b32_e64 v144, v144, v128, s[76:77]
	v_cndmask_b32_e64 v145, v145, v129, s[76:77]
	v_cndmask_b32_e64 v146, v146, v130, s[76:77]
	v_cndmask_b32_e64 v147, v147, v131, s[76:77]
	v_cndmask_b32_e64 v148, v148, v132, s[76:77]
	v_cndmask_b32_e64 v149, v149, v133, s[76:77]
	v_cndmask_b32_e64 v150, v150, v134, s[76:77]
; __device__ __forceinline__ u32x4 pack8(const float (&f)[8]) { u32x4 o; o.x = pk2(f[0], f[1]); o.y = pk2(f[2], f[3]); o.z = pk2(f[4], f[5]); o.w = pk2(f[6], f[7]); return o; }
; __device__ __forceinline__ float sigmoidf_(float x) { return __builtin_amdgcn_rcpf(1.0f + __expf(-x)); }
; __device__ __forceinline__ float tanhf_(float x) { return 1.0f - 2.0f * __builtin_amdgcn_rcpf(__expf(2.0f * x) + 1.0f); }
; template <int CH> __device__ __forceinline__ void p2_rwkv_chunk(const Params& p, int t0, int lane) {
;     ...
;         for (int q = 0; q < 8; ++q) zs[q] = C[q] + mu[q] * (0.5f * (P[q] + N[q]) - C[q]);
;         if (CH < 3) {
;             *(u32x4*)(RKV + (size_t)t * 1536 + c) = pack8(zs);
;             if (CH == 1) { float s2 = 0.f;
; #pragma unroll
;                 for (int q = 0; q < 8; ++q) { const float v = zs[q] * kq[q]; s2 += v * v; }
;                 s2 = red8s(s2);
;                 if ((lane & 7) == 0) RINV[t * 8 + (lane >> 3)] = rsqrtf(fmaxf(s2, 1e-24f)); }
;         } else {
;             const int cc = c - 1536; float o[8];
; #pragma unroll
;             for (int q = 0; q < 8; ++q) o[q] = cc < 128 ? tanhf_(zs[q]) : (cc < 192 ? zs[q] : sigmoidf_(zs[q]));
;             *(u32x4*)(AP + (size_t)t * KLORA + cc) = pack8(o);
	v_cndmask_b32_e64 v151, v151, v135, s[76:77]
	v_cndmask_b32_e64 v144, v144, v136, s[74:75]
	v_cndmask_b32_e64 v145, v145, v137, s[74:75]
	v_cndmask_b32_e64 v146, v146, v138, s[74:75]
	v_cndmask_b32_e64 v147, v147, v139, s[74:75]
	v_cndmask_b32_e64 v148, v148, v140, s[74:75]
	v_cndmask_b32_e64 v149, v149, v141, s[74:75]
	v_cndmask_b32_e64 v150, v150, v142, s[74:75]
	v_cndmask_b32_e64 v151, v151, v143, s[74:75]
	v_cndmask_b32_e64 v144, 0, v144, s[64:65]
	v_cndmask_b32_e64 v145, 0, v145, s[64:65]
	v_cndmask_b32_e64 v146, 0, v146, s[64:65]
	v_cndmask_b32_e64 v147, 0, v147, s[64:65]
	v_cndmask_b32_e64 v148, 0, v148, s[64:65]
	v_cndmask_b32_e64 v149, 0, v149, s[64:65]
	v_cndmask_b32_e64 v150, 0, v150, s[64:65]
	v_cndmask_b32_e64 v151, 0, v151, s[64:65]
	v_cvt_pk_bf16_f32 v246, v144, v145
	v_cvt_pk_bf16_f32 v247, v146, v147
	v_cvt_pk_bf16_f32 v248, v148, v149
	v_cvt_pk_bf16_f32 v249, v150, v151
	s_mov_b64 s[42:43], exec
	s_and_b64 exec, exec, s[36:37]
	global_store_dwordx4 v5, v[246:249], s[56:57] nt
	s_mov_b64 exec, s[42:43]
	v_add_u32_e32 v5, 0x300, v5
	v_lshlrev_b32_e32 v96, 16, v212
	v_and_b32_e32 v97, 0xffff0000, v212
	v_lshlrev_b32_e32 v98, 16, v213
	v_and_b32_e32 v99, 0xffff0000, v213
	v_lshlrev_b32_e32 v100, 16, v214
	v_and_b32_e32 v101, 0xffff0000, v214
	v_lshlrev_b32_e32 v102, 16, v215
	v_and_b32_e32 v103, 0xffff0000, v215
	v_add_f32_e32 v136, v80, v96
	v_add_f32_e32 v137, v81, v97
	v_add_f32_e32 v138, v82, v98
	v_add_f32_e32 v139, v83, v99
	v_add_f32_e32 v140, v84, v100
	v_add_f32_e32 v141, v85, v101
	v_add_f32_e32 v142, v86, v102
	v_add_f32_e32 v143, v87, v103
	v_fma_f32 v136, v136, 0.5, -v88
	v_fma_f32 v137, v137, 0.5, -v89
	v_fma_f32 v138, v138, 0.5, -v90
	v_fma_f32 v139, v139, 0.5, -v91
	v_fma_f32 v140, v140, 0.5, -v92
	v_fma_f32 v141, v141, 0.5, -v93
	v_fma_f32 v142, v142, 0.5, -v94
	v_fma_f32 v143, v143, 0.5, -v95
	v_fma_f32 v128, v104, v136, v88
	v_fma_f32 v129, v105, v137, v89
	v_fma_f32 v130, v106, v138, v90
	v_fma_f32 v131, v107, v139, v91
	v_fma_f32 v132, v108, v140, v92
	v_fma_f32 v133, v109, v141, v93
	v_fma_f32 v134, v110, v142, v94
	v_fma_f32 v135, v111, v143, v95
	v_mul_f32_e32 v136, 0x4038aa3b, v128
	v_mul_f32_e32 v137, 0x4038aa3b, v129
	v_mul_f32_e32 v138, 0x4038aa3b, v130
	v_mul_f32_e32 v139, 0x4038aa3b, v131
	v_mul_f32_e32 v140, 0x4038aa3b, v132
	v_mul_f32_e32 v141, 0x4038aa3b, v133
	v_mul_f32_e32 v142, 0x4038aa3b, v134
	v_mul_f32_e32 v143, 0x4038aa3b, v135
	v_mul_f32_e32 v144, 0xbfb8aa3b, v128
	v_mul_f32_e32 v145, 0xbfb8aa3b, v129
	v_mul_f32_e32 v146, 0xbfb8aa3b, v130
	v_mul_f32_e32 v147, 0xbfb8aa3b, v131
	v_mul_f32_e32 v148, 0xbfb8aa3b, v132
	v_mul_f32_e32 v149, 0xbfb8aa3b, v133
	v_mul_f32_e32 v150, 0xbfb8aa3b, v134
	v_mul_f32_e32 v151, 0xbfb8aa3b, v135
	v_exp_f32_e32 v136, v136
	v_exp_f32_e32 v137, v137
	v_exp_f32_e32 v138, v138
	v_exp_f32_e32 v139, v139
	v_exp_f32_e32 v140, v140
	v_exp_f32_e32 v141, v141
	v_exp_f32_e32 v142, v142
	v_exp_f32_e32 v143, v143
	v_exp_f32_e32 v144, v144
	v_exp_f32_e32 v145, v145
	v_exp_f32_e32 v146, v146
	v_exp_f32_e32 v147, v147
	v_exp_f32_e32 v148, v148
	v_exp_f32_e32 v149, v149
	v_exp_f32_e32 v150, v150
	v_exp_f32_e32 v151, v151
	v_add_f32_e32 v136, 1.0, v136
	v_add_f32_e32 v137, 1.0, v137
	v_add_f32_e32 v138, 1.0, v138
	v_add_f32_e32 v139, 1.0, v139
	v_add_f32_e32 v140, 1.0, v140
	v_add_f32_e32 v141, 1.0, v141
	v_add_f32_e32 v142, 1.0, v142
	v_add_f32_e32 v143, 1.0, v143
	v_add_f32_e32 v144, 1.0, v144
	v_add_f32_e32 v145, 1.0, v145
	v_add_f32_e32 v146, 1.0, v146
	v_add_f32_e32 v147, 1.0, v147
	v_add_f32_e32 v148, 1.0, v148
	v_add_f32_e32 v149, 1.0, v149
	v_add_f32_e32 v150, 1.0, v150
	v_add_f32_e32 v151, 1.0, v151
	v_rcp_f32_e32 v136, v136
	v_rcp_f32_e32 v137, v137
	v_rcp_f32_e32 v138, v138
	v_rcp_f32_e32 v139, v139
	v_rcp_f32_e32 v140, v140
	v_rcp_f32_e32 v141, v141
	v_rcp_f32_e32 v142, v142
	v_rcp_f32_e32 v143, v143
	v_rcp_f32_e32 v144, v144
	v_rcp_f32_e32 v145, v145
	v_rcp_f32_e32 v146, v146
	v_rcp_f32_e32 v147, v147
	v_rcp_f32_e32 v148, v148
	v_rcp_f32_e32 v149, v149
	v_rcp_f32_e32 v150, v150
	v_rcp_f32_e32 v151, v151
	v_fma_f32 v136, v136, -2.0, 1.0
	v_fma_f32 v137, v137, -2.0, 1.0
	v_fma_f32 v138, v138, -2.0, 1.0
	v_fma_f32 v139, v139, -2.0, 1.0
	v_fma_f32 v140, v140, -2.0, 1.0
	v_fma_f32 v141, v141, -2.0, 1.0
	v_fma_f32 v142, v142, -2.0, 1.0
	v_fma_f32 v143, v143, -2.0, 1.0
	v_cndmask_b32_e64 v144, v144, v128, s[76:77]
	v_cndmask_b32_e64 v145, v145, v129, s[76:77]
	v_cndmask_b32_e64 v146, v146, v130, s[76:77]
	v_cndmask_b32_e64 v147, v147, v131, s[76:77]
	v_cndmask_b32_e64 v148, v148, v132, s[76:77]
	v_cndmask_b32_e64 v149, v149, v133, s[76:77]
	v_cndmask_b32_e64 v150, v150, v134, s[76:77]
	v_cndmask_b32_e64 v151, v151, v135, s[76:77]
	v_cndmask_b32_e64 v144, v144, v136, s[74:75]
	v_cndmask_b32_e64 v145, v145, v137, s[74:75]
	v_cndmask_b32_e64 v146, v146, v138, s[74:75]
	v_cndmask_b32_e64 v147, v147, v139, s[74:75]
	v_cndmask_b32_e64 v148, v148, v140, s[74:75]
	v_cndmask_b32_e64 v149, v149, v141, s[74:75]
	v_cndmask_b32_e64 v150, v150, v142, s[74:75]
	v_cndmask_b32_e64 v151, v151, v143, s[74:75]
	v_cndmask_b32_e64 v144, 0, v144, s[64:65]
	v_cndmask_b32_e64 v145, 0, v145, s[64:65]
	v_cndmask_b32_e64 v146, 0, v146, s[64:65]
	v_cndmask_b32_e64 v147, 0, v147, s[64:65]
	v_cndmask_b32_e64 v148, 0, v148, s[64:65]
	v_cndmask_b32_e64 v149, 0, v149, s[64:65]
	v_cndmask_b32_e64 v150, 0, v150, s[64:65]
	v_cndmask_b32_e64 v151, 0, v151, s[64:65]
	v_cvt_pk_bf16_f32 v246, v144, v145
	v_cvt_pk_bf16_f32 v247, v146, v147
	v_cvt_pk_bf16_f32 v248, v148, v149
	v_cvt_pk_bf16_f32 v249, v150, v151
	s_mov_b64 s[42:43], exec
	s_and_b64 exec, exec, s[36:37]
	global_store_dwordx4 v5, v[246:249], s[56:57] nt
; __device__ __forceinline__ u32x4 pack8(const float (&f)[8]) { u32x4 o; o.x = pk2(f[0], f[1]); o.y = pk2(f[2], f[3]); o.z = pk2(f[4], f[5]); o.w = pk2(f[6], f[7]); return o; }
; __device__ __forceinline__ float sigmoidf_(float x) { return __builtin_amdgcn_rcpf(1.0f + __expf(-x)); }
; __device__ __forceinline__ float tanhf_(float x) { return 1.0f - 2.0f * __builtin_amdgcn_rcpf(__expf(2.0f * x) + 1.0f); }
; template <int CH> __device__ __forceinline__ void p2_rwkv_chunk(const Params& p, int t0, int lane) {
;     ...
;         for (int q = 0; q < 8; ++q) zs[q] = C[q] + mu[q] * (0.5f * (P[q] + N[q]) - C[q]);
;         if (CH < 3) {
;             *(u32x4*)(RKV + (size_t)t * 1536 + c) = pack8(zs);
;             if (CH == 1) { float s2 = 0.f;
; #pragma unroll
;                 for (int q = 0; q < 8; ++q) { const float v = zs[q] * kq[q]; s2 += v * v; }
;                 s2 = red8s(s2);
;                 if ((lane & 7) == 0) RINV[t * 8 + (lane >> 3)] = rsqrtf(fmaxf(s2, 1e-24f)); }
;         } else {
;             const int cc = c - 1536; float o[8];
; #pragma unroll
;             for (int q = 0; q < 8; ++q) o[q] = cc < 128 ? tanhf_(zs[q]) : (cc < 192 ? zs[q] : sigmoidf_(zs[q]));
;             *(u32x4*)(AP + (size_t)t * KLORA + cc) = pack8(o);
	s_mov_b64 exec, s[42:43]
	v_add_u32_e32 v5, 0x300, v5
	v_lshlrev_b32_e32 v80, 16, v216
	v_and_b32_e32 v81, 0xffff0000, v216
	v_lshlrev_b32_e32 v82, 16, v217
	v_and_b32_e32 v83, 0xffff0000, v217
	v_lshlrev_b32_e32 v84, 16, v218
	v_and_b32_e32 v85, 0xffff0000, v218
	v_lshlrev_b32_e32 v86, 16, v219
	v_and_b32_e32 v87, 0xffff0000, v219
	v_add_f32_e32 v136, v88, v80
	v_add_f32_e32 v137, v89, v81
	v_add_f32_e32 v138, v90, v82
	v_add_f32_e32 v139, v91, v83
	v_add_f32_e32 v140, v92, v84
	v_add_f32_e32 v141, v93, v85
	v_add_f32_e32 v142, v94, v86
	v_add_f32_e32 v143, v95, v87
	v_fma_f32 v136, v136, 0.5, -v96
	v_fma_f32 v137, v137, 0.5, -v97
	v_fma_f32 v138, v138, 0.5, -v98
	v_fma_f32 v139, v139, 0.5, -v99
	v_fma_f32 v140, v140, 0.5, -v100
	v_fma_f32 v141, v141, 0.5, -v101
	v_fma_f32 v142, v142, 0.5, -v102
	v_fma_f32 v143, v143, 0.5, -v103
	v_fma_f32 v128, v104, v136, v96
	v_fma_f32 v129, v105, v137, v97
	v_fma_f32 v130, v106, v138, v98
	v_fma_f32 v131, v107, v139, v99
	v_fma_f32 v132, v108, v140, v100
	v_fma_f32 v133, v109, v141, v101
	v_fma_f32 v134, v110, v142, v102
	v_fma_f32 v135, v111, v143, v103
	v_mul_f32_e32 v136, 0x4038aa3b, v128
	v_mul_f32_e32 v137, 0x4038aa3b, v129
	v_mul_f32_e32 v138, 0x4038aa3b, v130
	v_mul_f32_e32 v139, 0x4038aa3b, v131
	v_mul_f32_e32 v140, 0x4038aa3b, v132
	v_mul_f32_e32 v141, 0x4038aa3b, v133
	v_mul_f32_e32 v142, 0x4038aa3b, v134
	v_mul_f32_e32 v143, 0x4038aa3b, v135
	v_mul_f32_e32 v144, 0xbfb8aa3b, v128
	v_mul_f32_e32 v145, 0xbfb8aa3b, v129
	v_mul_f32_e32 v146, 0xbfb8aa3b, v130
	v_mul_f32_e32 v147, 0xbfb8aa3b, v131
	v_mul_f32_e32 v148, 0xbfb8aa3b, v132
	v_mul_f32_e32 v149, 0xbfb8aa3b, v133
	v_mul_f32_e32 v150, 0xbfb8aa3b, v134
	v_mul_f32_e32 v151, 0xbfb8aa3b, v135
	v_exp_f32_e32 v136, v136
	v_exp_f32_e32 v137, v137
	v_exp_f32_e32 v138, v138
	v_exp_f32_e32 v139, v139
	v_exp_f32_e32 v140, v140
	v_exp_f32_e32 v141, v141
	v_exp_f32_e32 v142, v142
	v_exp_f32_e32 v143, v143
	v_exp_f32_e32 v144, v144
	v_exp_f32_e32 v145, v145
	v_exp_f32_e32 v146, v146
	v_exp_f32_e32 v147, v147
	v_exp_f32_e32 v148, v148
	v_exp_f32_e32 v149, v149
	v_exp_f32_e32 v150, v150
	v_exp_f32_e32 v151, v151
	v_add_f32_e32 v136, 1.0, v136
	v_add_f32_e32 v137, 1.0, v137
	v_add_f32_e32 v138, 1.0, v138
	v_add_f32_e32 v139, 1.0, v139
	v_add_f32_e32 v140, 1.0, v140
	v_add_f32_e32 v141, 1.0, v141
	v_add_f32_e32 v142, 1.0, v142
	v_add_f32_e32 v143, 1.0, v143
	v_add_f32_e32 v144, 1.0, v144
	v_add_f32_e32 v145, 1.0, v145
	v_add_f32_e32 v146, 1.0, v146
	v_add_f32_e32 v147, 1.0, v147
	v_add_f32_e32 v148, 1.0, v148
	v_add_f32_e32 v149, 1.0, v149
	v_add_f32_e32 v150, 1.0, v150
	v_add_f32_e32 v151, 1.0, v151
	v_rcp_f32_e32 v136, v136
	v_rcp_f32_e32 v137, v137
	v_rcp_f32_e32 v138, v138
	v_rcp_f32_e32 v139, v139
	v_rcp_f32_e32 v140, v140
	v_rcp_f32_e32 v141, v141
	v_rcp_f32_e32 v142, v142
	v_rcp_f32_e32 v143, v143
	v_rcp_f32_e32 v144, v144
	v_rcp_f32_e32 v145, v145
	v_rcp_f32_e32 v146, v146
	v_rcp_f32_e32 v147, v147
	v_rcp_f32_e32 v148, v148
	v_rcp_f32_e32 v149, v149
	v_rcp_f32_e32 v150, v150
	v_rcp_f32_e32 v151, v151
	v_fma_f32 v136, v136, -2.0, 1.0
	v_fma_f32 v137, v137, -2.0, 1.0
	v_fma_f32 v138, v138, -2.0, 1.0
	v_fma_f32 v139, v139, -2.0, 1.0
	v_fma_f32 v140, v140, -2.0, 1.0
	v_fma_f32 v141, v141, -2.0, 1.0
	v_fma_f32 v142, v142, -2.0, 1.0
	v_fma_f32 v143, v143, -2.0, 1.0
	v_cndmask_b32_e64 v144, v144, v128, s[76:77]
	v_cndmask_b32_e64 v145, v145, v129, s[76:77]
	v_cndmask_b32_e64 v146, v146, v130, s[76:77]
	v_cndmask_b32_e64 v147, v147, v131, s[76:77]
	v_cndmask_b32_e64 v148, v148, v132, s[76:77]
	v_cndmask_b32_e64 v149, v149, v133, s[76:77]
	v_cndmask_b32_e64 v150, v150, v134, s[76:77]
	v_cndmask_b32_e64 v151, v151, v135, s[76:77]
	v_cndmask_b32_e64 v144, v144, v136, s[74:75]
	v_cndmask_b32_e64 v145, v145, v137, s[74:75]
	v_cndmask_b32_e64 v146, v146, v138, s[74:75]
	v_cndmask_b32_e64 v147, v147, v139, s[74:75]
	v_cndmask_b32_e64 v148, v148, v140, s[74:75]
	v_cndmask_b32_e64 v149, v149, v141, s[74:75]
	v_cndmask_b32_e64 v150, v150, v142, s[74:75]
	v_cndmask_b32_e64 v151, v151, v143, s[74:75]
	v_cndmask_b32_e64 v144, 0, v144, s[64:65]
	v_cndmask_b32_e64 v145, 0, v145, s[64:65]
	v_cndmask_b32_e64 v146, 0, v146, s[64:65]
	v_cndmask_b32_e64 v147, 0, v147, s[64:65]
	v_cndmask_b32_e64 v148, 0, v148, s[64:65]
	v_cndmask_b32_e64 v149, 0, v149, s[64:65]
	v_cndmask_b32_e64 v150, 0, v150, s[64:65]
	v_cndmask_b32_e64 v151, 0, v151, s[64:65]
	v_cvt_pk_bf16_f32 v246, v144, v145
	v_cvt_pk_bf16_f32 v247, v146, v147
	v_cvt_pk_bf16_f32 v248, v148, v149
	v_cvt_pk_bf16_f32 v249, v150, v151
	s_mov_b64 s[42:43], exec
	s_and_b64 exec, exec, s[36:37]
	global_store_dwordx4 v5, v[246:249], s[56:57] nt
	s_mov_b64 exec, s[42:43]
	v_add_u32_e32 v5, 0x300, v5
	v_lshlrev_b32_e32 v88, 16, v220
	v_and_b32_e32 v89, 0xffff0000, v220
	v_lshlrev_b32_e32 v90, 16, v221
	v_and_b32_e32 v91, 0xffff0000, v221
	v_lshlrev_b32_e32 v92, 16, v222
	v_and_b32_e32 v93, 0xffff0000, v222
	v_lshlrev_b32_e32 v94, 16, v223
	v_and_b32_e32 v95, 0xffff0000, v223
	v_add_f32_e32 v136, v96, v88
	v_add_f32_e32 v137, v97, v89
	v_add_f32_e32 v138, v98, v90
	v_add_f32_e32 v139, v99, v91
	v_add_f32_e32 v140, v100, v92
	v_add_f32_e32 v141, v101, v93
	v_add_f32_e32 v142, v102, v94
	v_add_f32_e32 v143, v103, v95
	v_fma_f32 v136, v136, 0.5, -v80
	v_fma_f32 v137, v137, 0.5, -v81
	v_fma_f32 v138, v138, 0.5, -v82
	v_fma_f32 v139, v139, 0.5, -v83
	v_fma_f32 v140, v140, 0.5, -v84
	v_fma_f32 v141, v141, 0.5, -v85
	v_fma_f32 v142, v142, 0.5, -v86
	v_fma_f32 v143, v143, 0.5, -v87
	v_fma_f32 v128, v104, v136, v80
	v_fma_f32 v129, v105, v137, v81
	v_fma_f32 v130, v106, v138, v82
	v_fma_f32 v131, v107, v139, v83
	v_fma_f32 v132, v108, v140, v84
; __device__ __forceinline__ u32x4 pack8(const float (&f)[8]) { u32x4 o; o.x = pk2(f[0], f[1]); o.y = pk2(f[2], f[3]); o.z = pk2(f[4], f[5]); o.w = pk2(f[6], f[7]); return o; }
; __device__ __forceinline__ float sigmoidf_(float x) { return __builtin_amdgcn_rcpf(1.0f + __expf(-x)); }
; __device__ __forceinline__ float tanhf_(float x) { return 1.0f - 2.0f * __builtin_amdgcn_rcpf(__expf(2.0f * x) + 1.0f); }
; template <int CH> __device__ __forceinline__ void p2_rwkv_chunk(const Params& p, int t0, int lane) {
;     ...
;         for (int q = 0; q < 8; ++q) zs[q] = C[q] + mu[q] * (0.5f * (P[q] + N[q]) - C[q]);
;         if (CH < 3) {
;             *(u32x4*)(RKV + (size_t)t * 1536 + c) = pack8(zs);
;             if (CH == 1) { float s2 = 0.f;
; #pragma unroll
;                 for (int q = 0; q < 8; ++q) { const float v = zs[q] * kq[q]; s2 += v * v; }
;                 s2 = red8s(s2);
;                 if ((lane & 7) == 0) RINV[t * 8 + (lane >> 3)] = rsqrtf(fmaxf(s2, 1e-24f)); }
;         } else {
;             const int cc = c - 1536; float o[8];
; #pragma unroll
;             for (int q = 0; q < 8; ++q) o[q] = cc < 128 ? tanhf_(zs[q]) : (cc < 192 ? zs[q] : sigmoidf_(zs[q]));
;             *(u32x4*)(AP + (size_t)t * KLORA + cc) = pack8(o);
	v_fma_f32 v133, v109, v141, v85
	v_fma_f32 v134, v110, v142, v86
	v_fma_f32 v135, v111, v143, v87
	v_mul_f32_e32 v136, 0x4038aa3b, v128
	v_mul_f32_e32 v137, 0x4038aa3b, v129
	v_mul_f32_e32 v138, 0x4038aa3b, v130
	v_mul_f32_e32 v139, 0x4038aa3b, v131
	v_mul_f32_e32 v140, 0x4038aa3b, v132
	v_mul_f32_e32 v141, 0x4038aa3b, v133
	v_mul_f32_e32 v142, 0x4038aa3b, v134
	v_mul_f32_e32 v143, 0x4038aa3b, v135
	v_mul_f32_e32 v144, 0xbfb8aa3b, v128
	v_mul_f32_e32 v145, 0xbfb8aa3b, v129
	v_mul_f32_e32 v146, 0xbfb8aa3b, v130
	v_mul_f32_e32 v147, 0xbfb8aa3b, v131
	v_mul_f32_e32 v148, 0xbfb8aa3b, v132
	v_mul_f32_e32 v149, 0xbfb8aa3b, v133
	v_mul_f32_e32 v150, 0xbfb8aa3b, v134
	v_mul_f32_e32 v151, 0xbfb8aa3b, v135
	v_exp_f32_e32 v136, v136
	v_exp_f32_e32 v137, v137
	v_exp_f32_e32 v138, v138
	v_exp_f32_e32 v139, v139
	v_exp_f32_e32 v140, v140
	v_exp_f32_e32 v141, v141
	v_exp_f32_e32 v142, v142
	v_exp_f32_e32 v143, v143
	v_exp_f32_e32 v144, v144
	v_exp_f32_e32 v145, v145
	v_exp_f32_e32 v146, v146
	v_exp_f32_e32 v147, v147
	v_exp_f32_e32 v148, v148
	v_exp_f32_e32 v149, v149
	v_exp_f32_e32 v150, v150
	v_exp_f32_e32 v151, v151
	v_add_f32_e32 v136, 1.0, v136
	v_add_f32_e32 v137, 1.0, v137
	v_add_f32_e32 v138, 1.0, v138
	v_add_f32_e32 v139, 1.0, v139
	v_add_f32_e32 v140, 1.0, v140
	v_add_f32_e32 v141, 1.0, v141
	v_add_f32_e32 v142, 1.0, v142
	v_add_f32_e32 v143, 1.0, v143
	v_add_f32_e32 v144, 1.0, v144
	v_add_f32_e32 v145, 1.0, v145
	v_add_f32_e32 v146, 1.0, v146
	v_add_f32_e32 v147, 1.0, v147
	v_add_f32_e32 v148, 1.0, v148
	v_add_f32_e32 v149, 1.0, v149
	v_add_f32_e32 v150, 1.0, v150
	v_add_f32_e32 v151, 1.0, v151
	v_rcp_f32_e32 v136, v136
	v_rcp_f32_e32 v137, v137
	v_rcp_f32_e32 v138, v138
	v_rcp_f32_e32 v139, v139
	v_rcp_f32_e32 v140, v140
	v_rcp_f32_e32 v141, v141
	v_rcp_f32_e32 v142, v142
	v_rcp_f32_e32 v143, v143
	v_rcp_f32_e32 v144, v144
	v_rcp_f32_e32 v145, v145
	v_rcp_f32_e32 v146, v146
	v_rcp_f32_e32 v147, v147
	v_rcp_f32_e32 v148, v148
	v_rcp_f32_e32 v149, v149
	v_rcp_f32_e32 v150, v150
	v_rcp_f32_e32 v151, v151
	v_fma_f32 v136, v136, -2.0, 1.0
	v_fma_f32 v137, v137, -2.0, 1.0
	v_fma_f32 v138, v138, -2.0, 1.0
	v_fma_f32 v139, v139, -2.0, 1.0
	v_fma_f32 v140, v140, -2.0, 1.0
	v_fma_f32 v141, v141, -2.0, 1.0
	v_fma_f32 v142, v142, -2.0, 1.0
	v_fma_f32 v143, v143, -2.0, 1.0
	v_cndmask_b32_e64 v144, v144, v128, s[76:77]
	v_cndmask_b32_e64 v145, v145, v129, s[76:77]
	v_cndmask_b32_e64 v146, v146, v130, s[76:77]
	v_cndmask_b32_e64 v147, v147, v131, s[76:77]
	v_cndmask_b32_e64 v148, v148, v132, s[76:77]
	v_cndmask_b32_e64 v149, v149, v133, s[76:77]
	v_cndmask_b32_e64 v150, v150, v134, s[76:77]
	v_cndmask_b32_e64 v151, v151, v135, s[76:77]
	v_cndmask_b32_e64 v144, v144, v136, s[74:75]
	v_cndmask_b32_e64 v145, v145, v137, s[74:75]
	v_cndmask_b32_e64 v146, v146, v138, s[74:75]
	v_cndmask_b32_e64 v147, v147, v139, s[74:75]
	v_cndmask_b32_e64 v148, v148, v140, s[74:75]
	v_cndmask_b32_e64 v149, v149, v141, s[74:75]
	v_cndmask_b32_e64 v150, v150, v142, s[74:75]
	v_cndmask_b32_e64 v151, v151, v143, s[74:75]
	v_cndmask_b32_e64 v144, 0, v144, s[64:65]
	v_cndmask_b32_e64 v145, 0, v145, s[64:65]
	v_cndmask_b32_e64 v146, 0, v146, s[64:65]
	v_cndmask_b32_e64 v147, 0, v147, s[64:65]
	v_cndmask_b32_e64 v148, 0, v148, s[64:65]
	v_cndmask_b32_e64 v149, 0, v149, s[64:65]
	v_cndmask_b32_e64 v150, 0, v150, s[64:65]
	v_cndmask_b32_e64 v151, 0, v151, s[64:65]
	v_cvt_pk_bf16_f32 v246, v144, v145
	v_cvt_pk_bf16_f32 v247, v146, v147
	v_cvt_pk_bf16_f32 v248, v148, v149
	v_cvt_pk_bf16_f32 v249, v150, v151
	s_mov_b64 s[42:43], exec
	s_and_b64 exec, exec, s[36:37]
	global_store_dwordx4 v5, v[246:249], s[56:57] nt
	s_mov_b64 exec, s[42:43]
	v_add_u32_e32 v5, 0x300, v5
	v_lshlrev_b32_e32 v96, 16, v224
	v_and_b32_e32 v97, 0xffff0000, v224
	v_lshlrev_b32_e32 v98, 16, v225
	v_and_b32_e32 v99, 0xffff0000, v225
	v_lshlrev_b32_e32 v100, 16, v226
	v_and_b32_e32 v101, 0xffff0000, v226
	v_lshlrev_b32_e32 v102, 16, v227
	v_and_b32_e32 v103, 0xffff0000, v227
	v_add_f32_e32 v136, v80, v96
	v_add_f32_e32 v137, v81, v97
	v_add_f32_e32 v138, v82, v98
	v_add_f32_e32 v139, v83, v99
	v_add_f32_e32 v140, v84, v100
	v_add_f32_e32 v141, v85, v101
	v_add_f32_e32 v142, v86, v102
	v_add_f32_e32 v143, v87, v103
	v_fma_f32 v136, v136, 0.5, -v88
	v_fma_f32 v137, v137, 0.5, -v89
	v_fma_f32 v138, v138, 0.5, -v90
	v_fma_f32 v139, v139, 0.5, -v91
	v_fma_f32 v140, v140, 0.5, -v92
	v_fma_f32 v141, v141, 0.5, -v93
	v_fma_f32 v142, v142, 0.5, -v94
	v_fma_f32 v143, v143, 0.5, -v95
	v_fma_f32 v128, v104, v136, v88
	v_fma_f32 v129, v105, v137, v89
	v_fma_f32 v130, v106, v138, v90
	v_fma_f32 v131, v107, v139, v91
	v_fma_f32 v132, v108, v140, v92
	v_fma_f32 v133, v109, v141, v93
	v_fma_f32 v134, v110, v142, v94
	v_fma_f32 v135, v111, v143, v95
	v_mul_f32_e32 v136, 0x4038aa3b, v128
	v_mul_f32_e32 v137, 0x4038aa3b, v129
	v_mul_f32_e32 v138, 0x4038aa3b, v130
	v_mul_f32_e32 v139, 0x4038aa3b, v131
	v_mul_f32_e32 v140, 0x4038aa3b, v132
	v_mul_f32_e32 v141, 0x4038aa3b, v133
	v_mul_f32_e32 v142, 0x4038aa3b, v134
	v_mul_f32_e32 v143, 0x4038aa3b, v135
	v_mul_f32_e32 v144, 0xbfb8aa3b, v128
	v_mul_f32_e32 v145, 0xbfb8aa3b, v129
	v_mul_f32_e32 v146, 0xbfb8aa3b, v130
	v_mul_f32_e32 v147, 0xbfb8aa3b, v131
	v_mul_f32_e32 v148, 0xbfb8aa3b, v132
	v_mul_f32_e32 v149, 0xbfb8aa3b, v133
	v_mul_f32_e32 v150, 0xbfb8aa3b, v134
	v_mul_f32_e32 v151, 0xbfb8aa3b, v135
	v_exp_f32_e32 v136, v136
	v_exp_f32_e32 v137, v137
	v_exp_f32_e32 v138, v138
	v_exp_f32_e32 v139, v139
	v_exp_f32_e32 v140, v140
	v_exp_f32_e32 v141, v141
	v_exp_f32_e32 v142, v142
	v_exp_f32_e32 v143, v143
	v_exp_f32_e32 v144, v144
	v_exp_f32_e32 v145, v145
	v_exp_f32_e32 v146, v146
; __device__ __forceinline__ u32x4 pack8(const float (&f)[8]) { u32x4 o; o.x = pk2(f[0], f[1]); o.y = pk2(f[2], f[3]); o.z = pk2(f[4], f[5]); o.w = pk2(f[6], f[7]); return o; }
; __device__ __forceinline__ float sigmoidf_(float x) { return __builtin_amdgcn_rcpf(1.0f + __expf(-x)); }
; __device__ __forceinline__ float tanhf_(float x) { return 1.0f - 2.0f * __builtin_amdgcn_rcpf(__expf(2.0f * x) + 1.0f); }
; template <int CH> __device__ __forceinline__ void p2_rwkv_chunk(const Params& p, int t0, int lane) {
;     ...
;         for (int q = 0; q < 8; ++q) zs[q] = C[q] + mu[q] * (0.5f * (P[q] + N[q]) - C[q]);
;         if (CH < 3) {
;             *(u32x4*)(RKV + (size_t)t * 1536 + c) = pack8(zs);
;             if (CH == 1) { float s2 = 0.f;
; #pragma unroll
;                 for (int q = 0; q < 8; ++q) { const float v = zs[q] * kq[q]; s2 += v * v; }
;                 s2 = red8s(s2);
;                 if ((lane & 7) == 0) RINV[t * 8 + (lane >> 3)] = rsqrtf(fmaxf(s2, 1e-24f)); }
;         } else {
;             const int cc = c - 1536; float o[8];
; #pragma unroll
;             for (int q = 0; q < 8; ++q) o[q] = cc < 128 ? tanhf_(zs[q]) : (cc < 192 ? zs[q] : sigmoidf_(zs[q]));
;             *(u32x4*)(AP + (size_t)t * KLORA + cc) = pack8(o);
	v_exp_f32_e32 v147, v147
	v_exp_f32_e32 v148, v148
	v_exp_f32_e32 v149, v149
	v_exp_f32_e32 v150, v150
	v_exp_f32_e32 v151, v151
	v_add_f32_e32 v136, 1.0, v136
	v_add_f32_e32 v137, 1.0, v137
	v_add_f32_e32 v138, 1.0, v138
	v_add_f32_e32 v139, 1.0, v139
	v_add_f32_e32 v140, 1.0, v140
	v_add_f32_e32 v141, 1.0, v141
	v_add_f32_e32 v142, 1.0, v142
	v_add_f32_e32 v143, 1.0, v143
	v_add_f32_e32 v144, 1.0, v144
	v_add_f32_e32 v145, 1.0, v145
	v_add_f32_e32 v146, 1.0, v146
	v_add_f32_e32 v147, 1.0, v147
	v_add_f32_e32 v148, 1.0, v148
	v_add_f32_e32 v149, 1.0, v149
	v_add_f32_e32 v150, 1.0, v150
	v_add_f32_e32 v151, 1.0, v151
	v_rcp_f32_e32 v136, v136
	v_rcp_f32_e32 v137, v137
	v_rcp_f32_e32 v138, v138
	v_rcp_f32_e32 v139, v139
	v_rcp_f32_e32 v140, v140
	v_rcp_f32_e32 v141, v141
	v_rcp_f32_e32 v142, v142
	v_rcp_f32_e32 v143, v143
	v_rcp_f32_e32 v144, v144
	v_rcp_f32_e32 v145, v145
	v_rcp_f32_e32 v146, v146
	v_rcp_f32_e32 v147, v147
	v_rcp_f32_e32 v148, v148
	v_rcp_f32_e32 v149, v149
	v_rcp_f32_e32 v150, v150
	v_rcp_f32_e32 v151, v151
	v_fma_f32 v136, v136, -2.0, 1.0
	v_fma_f32 v137, v137, -2.0, 1.0
	v_fma_f32 v138, v138, -2.0, 1.0
	v_fma_f32 v139, v139, -2.0, 1.0
	v_fma_f32 v140, v140, -2.0, 1.0
	v_fma_f32 v141, v141, -2.0, 1.0
	v_fma_f32 v142, v142, -2.0, 1.0
	v_fma_f32 v143, v143, -2.0, 1.0
	v_cndmask_b32_e64 v144, v144, v128, s[76:77]
	v_cndmask_b32_e64 v145, v145, v129, s[76:77]
	v_cndmask_b32_e64 v146, v146, v130, s[76:77]
	v_cndmask_b32_e64 v147, v147, v131, s[76:77]
	v_cndmask_b32_e64 v148, v148, v132, s[76:77]
	v_cndmask_b32_e64 v149, v149, v133, s[76:77]
	v_cndmask_b32_e64 v150, v150, v134, s[76:77]
	v_cndmask_b32_e64 v151, v151, v135, s[76:77]
	v_cndmask_b32_e64 v144, v144, v136, s[74:75]
	v_cndmask_b32_e64 v145, v145, v137, s[74:75]
	v_cndmask_b32_e64 v146, v146, v138, s[74:75]
	v_cndmask_b32_e64 v147, v147, v139, s[74:75]
	v_cndmask_b32_e64 v148, v148, v140, s[74:75]
	v_cndmask_b32_e64 v149, v149, v141, s[74:75]
	v_cndmask_b32_e64 v150, v150, v142, s[74:75]
	v_cndmask_b32_e64 v151, v151, v143, s[74:75]
	v_cndmask_b32_e64 v144, 0, v144, s[64:65]
	v_cndmask_b32_e64 v145, 0, v145, s[64:65]
	v_cndmask_b32_e64 v146, 0, v146, s[64:65]
	v_cndmask_b32_e64 v147, 0, v147, s[64:65]
	v_cndmask_b32_e64 v148, 0, v148, s[64:65]
	v_cndmask_b32_e64 v149, 0, v149, s[64:65]
	v_cndmask_b32_e64 v150, 0, v150, s[64:65]
	v_cndmask_b32_e64 v151, 0, v151, s[64:65]
	v_cvt_pk_bf16_f32 v246, v144, v145
	v_cvt_pk_bf16_f32 v247, v146, v147
	v_cvt_pk_bf16_f32 v248, v148, v149
	v_cvt_pk_bf16_f32 v249, v150, v151
	s_mov_b64 s[42:43], exec
	s_and_b64 exec, exec, s[36:37]
	global_store_dwordx4 v5, v[246:249], s[56:57] nt
	s_mov_b64 exec, s[42:43]
	v_add_u32_e32 v5, 0x300, v5
	v_lshlrev_b32_e32 v80, 16, v228
	v_and_b32_e32 v81, 0xffff0000, v228
	v_lshlrev_b32_e32 v82, 16, v229
	v_and_b32_e32 v83, 0xffff0000, v229
	v_lshlrev_b32_e32 v84, 16, v230
	v_and_b32_e32 v85, 0xffff0000, v230
	v_lshlrev_b32_e32 v86, 16, v231
	v_and_b32_e32 v87, 0xffff0000, v231
	v_add_f32_e32 v136, v88, v80
	v_add_f32_e32 v137, v89, v81
	v_add_f32_e32 v138, v90, v82
	v_add_f32_e32 v139, v91, v83
	v_add_f32_e32 v140, v92, v84
	v_add_f32_e32 v141, v93, v85
	v_add_f32_e32 v142, v94, v86
	v_add_f32_e32 v143, v95, v87
	v_fma_f32 v136, v136, 0.5, -v96
	v_fma_f32 v137, v137, 0.5, -v97
	v_fma_f32 v138, v138, 0.5, -v98
	v_fma_f32 v139, v139, 0.5, -v99
	v_fma_f32 v140, v140, 0.5, -v100
	v_fma_f32 v141, v141, 0.5, -v101
	v_fma_f32 v142, v142, 0.5, -v102
	v_fma_f32 v143, v143, 0.5, -v103
	v_fma_f32 v128, v104, v136, v96
	v_fma_f32 v129, v105, v137, v97
	v_fma_f32 v130, v106, v138, v98
	v_fma_f32 v131, v107, v139, v99
	v_fma_f32 v132, v108, v140, v100
	v_fma_f32 v133, v109, v141, v101
	v_fma_f32 v134, v110, v142, v102
	v_fma_f32 v135, v111, v143, v103
	v_mul_f32_e32 v136, 0x4038aa3b, v128
	v_mul_f32_e32 v137, 0x4038aa3b, v129
	v_mul_f32_e32 v138, 0x4038aa3b, v130
	v_mul_f32_e32 v139, 0x4038aa3b, v131
	v_mul_f32_e32 v140, 0x4038aa3b, v132
	v_mul_f32_e32 v141, 0x4038aa3b, v133
	v_mul_f32_e32 v142, 0x4038aa3b, v134
	v_mul_f32_e32 v143, 0x4038aa3b, v135
	v_mul_f32_e32 v144, 0xbfb8aa3b, v128
	v_mul_f32_e32 v145, 0xbfb8aa3b, v129
	v_mul_f32_e32 v146, 0xbfb8aa3b, v130
	v_mul_f32_e32 v147, 0xbfb8aa3b, v131
	v_mul_f32_e32 v148, 0xbfb8aa3b, v132
	v_mul_f32_e32 v149, 0xbfb8aa3b, v133
	v_mul_f32_e32 v150, 0xbfb8aa3b, v134
	v_mul_f32_e32 v151, 0xbfb8aa3b, v135
	v_exp_f32_e32 v136, v136
	v_exp_f32_e32 v137, v137
	v_exp_f32_e32 v138, v138
	v_exp_f32_e32 v139, v139
	v_exp_f32_e32 v140, v140
	v_exp_f32_e32 v141, v141
	v_exp_f32_e32 v142, v142
	v_exp_f32_e32 v143, v143
	v_exp_f32_e32 v144, v144
	v_exp_f32_e32 v145, v145
	v_exp_f32_e32 v146, v146
	v_exp_f32_e32 v147, v147
	v_exp_f32_e32 v148, v148
	v_exp_f32_e32 v149, v149
	v_exp_f32_e32 v150, v150
	v_exp_f32_e32 v151, v151
	v_add_f32_e32 v136, 1.0, v136
	v_add_f32_e32 v137, 1.0, v137
	v_add_f32_e32 v138, 1.0, v138
	v_add_f32_e32 v139, 1.0, v139
	v_add_f32_e32 v140, 1.0, v140
	v_add_f32_e32 v141, 1.0, v141
	v_add_f32_e32 v142, 1.0, v142
	v_add_f32_e32 v143, 1.0, v143
	v_add_f32_e32 v144, 1.0, v144
	v_add_f32_e32 v145, 1.0, v145
	v_add_f32_e32 v146, 1.0, v146
	v_add_f32_e32 v147, 1.0, v147
	v_add_f32_e32 v148, 1.0, v148
	v_add_f32_e32 v149, 1.0, v149
	v_add_f32_e32 v150, 1.0, v150
	v_add_f32_e32 v151, 1.0, v151
	v_rcp_f32_e32 v136, v136
	v_rcp_f32_e32 v137, v137
	v_rcp_f32_e32 v138, v138
	v_rcp_f32_e32 v139, v139
	v_rcp_f32_e32 v140, v140
	v_rcp_f32_e32 v141, v141
	v_rcp_f32_e32 v142, v142
	v_rcp_f32_e32 v143, v143
	v_rcp_f32_e32 v144, v144
	v_rcp_f32_e32 v145, v145
	v_rcp_f32_e32 v146, v146
	v_rcp_f32_e32 v147, v147
	v_rcp_f32_e32 v148, v148
	v_rcp_f32_e32 v149, v149
; __device__ __forceinline__ void unpack8(const u32x4 w, float (&f)[8]) { f[0] = bflo(w.x); f[1] = bfhi(w.x); f[2] = bflo(w.y); f[3] = bfhi(w.y); f[4] = bflo(w.z); f[5] = bfhi(w.z); f[6] = bflo(w.w); f[7] = bfhi(w.w); }
; __device__ __forceinline__ u32x4 pack8(const float (&f)[8]) { u32x4 o; o.x = pk2(f[0], f[1]); o.y = pk2(f[2], f[3]); o.z = pk2(f[4], f[5]); o.w = pk2(f[6], f[7]); return o; }
; __device__ __forceinline__ float sigmoidf_(float x) { return __builtin_amdgcn_rcpf(1.0f + __expf(-x)); }
; __device__ __forceinline__ float tanhf_(float x) { return 1.0f - 2.0f * __builtin_amdgcn_rcpf(__expf(2.0f * x) + 1.0f); }
; template <int CH> __device__ __forceinline__ void p2_rwkv_chunk(const Params& p, int t0, int lane) {
;     ...
;         const int t = t0 + i; const bool hasn = (t & (T_SEQ - 1)) != T_SEQ - 1;
;         if (hasn) unpack8(raw, N); else {
; #pragma unroll
;             for (int q = 0; q < 8; ++q) N[q] = 0.f; }
;     ...
;         for (int q = 0; q < 8; ++q) zs[q] = C[q] + mu[q] * (0.5f * (P[q] + N[q]) - C[q]);
;         if (CH < 3) {
;             *(u32x4*)(RKV + (size_t)t * 1536 + c) = pack8(zs);
;             if (CH == 1) { float s2 = 0.f;
; #pragma unroll
;                 for (int q = 0; q < 8; ++q) { const float v = zs[q] * kq[q]; s2 += v * v; }
;                 s2 = red8s(s2);
;                 if ((lane & 7) == 0) RINV[t * 8 + (lane >> 3)] = rsqrtf(fmaxf(s2, 1e-24f)); }
;         } else {
;             const int cc = c - 1536; float o[8];
; #pragma unroll
;             for (int q = 0; q < 8; ++q) o[q] = cc < 128 ? tanhf_(zs[q]) : (cc < 192 ? zs[q] : sigmoidf_(zs[q]));
;             *(u32x4*)(AP + (size_t)t * KLORA + cc) = pack8(o);
	v_rcp_f32_e32 v150, v150
	v_rcp_f32_e32 v151, v151
	v_fma_f32 v136, v136, -2.0, 1.0
	v_fma_f32 v137, v137, -2.0, 1.0
	v_fma_f32 v138, v138, -2.0, 1.0
	v_fma_f32 v139, v139, -2.0, 1.0
	v_fma_f32 v140, v140, -2.0, 1.0
	v_fma_f32 v141, v141, -2.0, 1.0
	v_fma_f32 v142, v142, -2.0, 1.0
	v_fma_f32 v143, v143, -2.0, 1.0
	v_cndmask_b32_e64 v144, v144, v128, s[76:77]
	v_cndmask_b32_e64 v145, v145, v129, s[76:77]
	v_cndmask_b32_e64 v146, v146, v130, s[76:77]
	v_cndmask_b32_e64 v147, v147, v131, s[76:77]
	v_cndmask_b32_e64 v148, v148, v132, s[76:77]
	v_cndmask_b32_e64 v149, v149, v133, s[76:77]
	v_cndmask_b32_e64 v150, v150, v134, s[76:77]
	v_cndmask_b32_e64 v151, v151, v135, s[76:77]
	v_cndmask_b32_e64 v144, v144, v136, s[74:75]
	v_cndmask_b32_e64 v145, v145, v137, s[74:75]
	v_cndmask_b32_e64 v146, v146, v138, s[74:75]
	v_cndmask_b32_e64 v147, v147, v139, s[74:75]
	v_cndmask_b32_e64 v148, v148, v140, s[74:75]
	v_cndmask_b32_e64 v149, v149, v141, s[74:75]
	v_cndmask_b32_e64 v150, v150, v142, s[74:75]
	v_cndmask_b32_e64 v151, v151, v143, s[74:75]
	v_cndmask_b32_e64 v144, 0, v144, s[64:65]
	v_cndmask_b32_e64 v145, 0, v145, s[64:65]
	v_cndmask_b32_e64 v146, 0, v146, s[64:65]
	v_cndmask_b32_e64 v147, 0, v147, s[64:65]
	v_cndmask_b32_e64 v148, 0, v148, s[64:65]
	v_cndmask_b32_e64 v149, 0, v149, s[64:65]
	v_cndmask_b32_e64 v150, 0, v150, s[64:65]
	v_cndmask_b32_e64 v151, 0, v151, s[64:65]
	v_cvt_pk_bf16_f32 v246, v144, v145
	v_cvt_pk_bf16_f32 v247, v146, v147
	v_cvt_pk_bf16_f32 v248, v148, v149
	v_cvt_pk_bf16_f32 v249, v150, v151
	s_mov_b64 s[42:43], exec
	s_and_b64 exec, exec, s[36:37]
	global_store_dwordx4 v5, v[246:249], s[56:57] nt
	s_mov_b64 exec, s[42:43]
	v_add_u32_e32 v5, 0x300, v5
	v_lshlrev_b32_e32 v88, 16, v232
	v_and_b32_e32 v89, 0xffff0000, v232
	v_lshlrev_b32_e32 v90, 16, v233
	v_and_b32_e32 v91, 0xffff0000, v233
	v_lshlrev_b32_e32 v92, 16, v234
	v_and_b32_e32 v93, 0xffff0000, v234
	v_lshlrev_b32_e32 v94, 16, v235
	v_and_b32_e32 v95, 0xffff0000, v235
	v_add_f32_e32 v136, v96, v88
	v_add_f32_e32 v137, v97, v89
	v_add_f32_e32 v138, v98, v90
	v_add_f32_e32 v139, v99, v91
	v_add_f32_e32 v140, v100, v92
	v_add_f32_e32 v141, v101, v93
	v_add_f32_e32 v142, v102, v94
	v_add_f32_e32 v143, v103, v95
	v_fma_f32 v136, v136, 0.5, -v80
	v_fma_f32 v137, v137, 0.5, -v81
	v_fma_f32 v138, v138, 0.5, -v82
	v_fma_f32 v139, v139, 0.5, -v83
	v_fma_f32 v140, v140, 0.5, -v84
	v_fma_f32 v141, v141, 0.5, -v85
	v_fma_f32 v142, v142, 0.5, -v86
	v_fma_f32 v143, v143, 0.5, -v87
	v_fma_f32 v128, v104, v136, v80
	v_fma_f32 v129, v105, v137, v81
	v_fma_f32 v130, v106, v138, v82
	v_fma_f32 v131, v107, v139, v83
	v_fma_f32 v132, v108, v140, v84
	v_fma_f32 v133, v109, v141, v85
	v_fma_f32 v134, v110, v142, v86
	v_fma_f32 v135, v111, v143, v87
	v_mul_f32_e32 v136, 0x4038aa3b, v128
	v_mul_f32_e32 v137, 0x4038aa3b, v129
	v_mul_f32_e32 v138, 0x4038aa3b, v130
	v_mul_f32_e32 v139, 0x4038aa3b, v131
	v_mul_f32_e32 v140, 0x4038aa3b, v132
	v_mul_f32_e32 v141, 0x4038aa3b, v133
	v_mul_f32_e32 v142, 0x4038aa3b, v134
	v_mul_f32_e32 v143, 0x4038aa3b, v135
	v_mul_f32_e32 v144, 0xbfb8aa3b, v128
	v_mul_f32_e32 v145, 0xbfb8aa3b, v129
	v_mul_f32_e32 v146, 0xbfb8aa3b, v130
	v_mul_f32_e32 v147, 0xbfb8aa3b, v131
	v_mul_f32_e32 v148, 0xbfb8aa3b, v132
	v_mul_f32_e32 v149, 0xbfb8aa3b, v133
	v_mul_f32_e32 v150, 0xbfb8aa3b, v134
	v_mul_f32_e32 v151, 0xbfb8aa3b, v135
	v_exp_f32_e32 v136, v136
	v_exp_f32_e32 v137, v137
	v_exp_f32_e32 v138, v138
	v_exp_f32_e32 v139, v139
	v_exp_f32_e32 v140, v140
	v_exp_f32_e32 v141, v141
	v_exp_f32_e32 v142, v142
	v_exp_f32_e32 v143, v143
	v_exp_f32_e32 v144, v144
	v_exp_f32_e32 v145, v145
	v_exp_f32_e32 v146, v146
	v_exp_f32_e32 v147, v147
	v_exp_f32_e32 v148, v148
	v_exp_f32_e32 v149, v149
	v_exp_f32_e32 v150, v150
	v_exp_f32_e32 v151, v151
	v_add_f32_e32 v136, 1.0, v136
	v_add_f32_e32 v137, 1.0, v137
	v_add_f32_e32 v138, 1.0, v138
	v_add_f32_e32 v139, 1.0, v139
	v_add_f32_e32 v140, 1.0, v140
	v_add_f32_e32 v141, 1.0, v141
	v_add_f32_e32 v142, 1.0, v142
	v_add_f32_e32 v143, 1.0, v143
	v_add_f32_e32 v144, 1.0, v144
	v_add_f32_e32 v145, 1.0, v145
	v_add_f32_e32 v146, 1.0, v146
	v_add_f32_e32 v147, 1.0, v147
	v_add_f32_e32 v148, 1.0, v148
	v_add_f32_e32 v149, 1.0, v149
	v_add_f32_e32 v150, 1.0, v150
	v_add_f32_e32 v151, 1.0, v151
	v_rcp_f32_e32 v136, v136
	v_rcp_f32_e32 v137, v137
	v_rcp_f32_e32 v138, v138
	v_rcp_f32_e32 v139, v139
	v_rcp_f32_e32 v140, v140
	v_rcp_f32_e32 v141, v141
	v_rcp_f32_e32 v142, v142
	v_rcp_f32_e32 v143, v143
	v_rcp_f32_e32 v144, v144
	v_rcp_f32_e32 v145, v145
	v_rcp_f32_e32 v146, v146
	v_rcp_f32_e32 v147, v147
	v_rcp_f32_e32 v148, v148
	v_rcp_f32_e32 v149, v149
	v_rcp_f32_e32 v150, v150
	v_rcp_f32_e32 v151, v151
	v_fma_f32 v136, v136, -2.0, 1.0
	v_fma_f32 v137, v137, -2.0, 1.0
	v_fma_f32 v138, v138, -2.0, 1.0
	v_fma_f32 v139, v139, -2.0, 1.0
	v_fma_f32 v140, v140, -2.0, 1.0
	v_fma_f32 v141, v141, -2.0, 1.0
	v_fma_f32 v142, v142, -2.0, 1.0
	v_fma_f32 v143, v143, -2.0, 1.0
	v_cndmask_b32_e64 v144, v144, v128, s[76:77]
	v_cndmask_b32_e64 v145, v145, v129, s[76:77]
	v_cndmask_b32_e64 v146, v146, v130, s[76:77]
	v_cndmask_b32_e64 v147, v147, v131, s[76:77]
	v_cndmask_b32_e64 v148, v148, v132, s[76:77]
	v_cndmask_b32_e64 v149, v149, v133, s[76:77]
	v_cndmask_b32_e64 v150, v150, v134, s[76:77]
	v_cndmask_b32_e64 v151, v151, v135, s[76:77]
	v_cndmask_b32_e64 v144, v144, v136, s[74:75]
	v_cndmask_b32_e64 v145, v145, v137, s[74:75]
	v_cndmask_b32_e64 v146, v146, v138, s[74:75]
	v_cndmask_b32_e64 v147, v147, v139, s[74:75]
	v_cndmask_b32_e64 v148, v148, v140, s[74:75]
	v_cndmask_b32_e64 v149, v149, v141, s[74:75]
	v_cndmask_b32_e64 v150, v150, v142, s[74:75]
	v_cndmask_b32_e64 v151, v151, v143, s[74:75]
	v_cndmask_b32_e64 v144, 0, v144, s[64:65]
	v_cndmask_b32_e64 v145, 0, v145, s[64:65]
	v_cndmask_b32_e64 v146, 0, v146, s[64:65]
	v_cndmask_b32_e64 v147, 0, v147, s[64:65]
	v_cndmask_b32_e64 v148, 0, v148, s[64:65]
	v_cndmask_b32_e64 v149, 0, v149, s[64:65]
	v_cndmask_b32_e64 v150, 0, v150, s[64:65]
	v_cndmask_b32_e64 v151, 0, v151, s[64:65]
	v_cvt_pk_bf16_f32 v246, v144, v145
	v_cvt_pk_bf16_f32 v247, v146, v147
	v_cvt_pk_bf16_f32 v248, v148, v149
	v_cvt_pk_bf16_f32 v249, v150, v151
	s_mov_b64 s[42:43], exec
	s_and_b64 exec, exec, s[36:37]
	global_store_dwordx4 v5, v[246:249], s[56:57] nt
	s_mov_b64 exec, s[42:43]
	v_add_u32_e32 v5, 0x300, v5
	s_cmp_eq_u32 s67, 0
	s_cbranch_scc1 .Lp2_nz_10
	v_mov_b32_e32 v236, 0
	v_mov_b32_e32 v237, 0
	v_mov_b32_e32 v238, 0
	v_mov_b32_e32 v239, 0
; __device__ __forceinline__ void unpack8(const u32x4 w, float (&f)[8]) { f[0] = bflo(w.x); f[1] = bfhi(w.x); f[2] = bflo(w.y); f[3] = bfhi(w.y); f[4] = bflo(w.z); f[5] = bfhi(w.z); f[6] = bflo(w.w); f[7] = bfhi(w.w); }
; __device__ __forceinline__ u32x4 pack8(const float (&f)[8]) { u32x4 o; o.x = pk2(f[0], f[1]); o.y = pk2(f[2], f[3]); o.z = pk2(f[4], f[5]); o.w = pk2(f[6], f[7]); return o; }
; __device__ __forceinline__ float sigmoidf_(float x) { return __builtin_amdgcn_rcpf(1.0f + __expf(-x)); }
; template <int CH> __device__ __forceinline__ void p2_rwkv_chunk(const Params& p, int t0, int lane) {
;     ...
;         for (int q = 0; q < 8; ++q) zs[q] = C[q] + mu[q] * (0.5f * (P[q] + N[q]) - C[q]);
;         if (CH < 3) {
;             *(u32x4*)(RKV + (size_t)t * 1536 + c) = pack8(zs);
;             if (CH == 1) { float s2 = 0.f;
; #pragma unroll
;                 for (int q = 0; q < 8; ++q) { const float v = zs[q] * kq[q]; s2 += v * v; }
;                 s2 = red8s(s2);
;                 if ((lane & 7) == 0) RINV[t * 8 + (lane >> 3)] = rsqrtf(fmaxf(s2, 1e-24f)); }
;         } else {
;             const int cc = c - 1536; float o[8];
; #pragma unroll
;             for (int q = 0; q < 8; ++q) o[q] = cc < 128 ? tanhf_(zs[q]) : (cc < 192 ? zs[q] : sigmoidf_(zs[q]));
;             *(u32x4*)(AP + (size_t)t * KLORA + cc) = pack8(o);
; template <int CH> __device__ __forceinline__ void p2_gla_chunk(const Params& p, int t0, int lane) {
;     ...
;     const int c = (lane + 64 * CH) * 8; const float sc = c < 256 ? 0.125f : 1.0f;
;     bf16_t* GQKV = (bf16_t*)(ws + WS_GQKV);
;     const bf16_t* zc = (const bf16_t*)(ws + WS_Z) + (size_t)t0 * ZLD + NRW + c;
;     float w0[8], w1[8], w2[8];
; #pragma unroll
;     for (int h = 0; h < 2; ++h) { const f32x4 a = *(const f32x4*)(p.in[19] + c + 4 * h), b = *(const f32x4*)(p.in[19] + 1024 + c + 4 * h), d = *(const f32x4*)(p.in[19] + 2048 + c + 4 * h);
; #pragma unroll
;         for (int i = 0; i < 4; ++i) { w0[4 * h + i] = a[i]; w1[4 * h + i] = b[i]; w2[4 * h + i] = d[i]; } }
;     float P[8], C[8], N[8];
;     if ((t0 & (T_SEQ - 1)) != 0) unpack8(__builtin_nontemporal_load((const u32x4*)(zc - ZLD)), P); else {
; #pragma unroll
;         for (int i = 0; i < 8; ++i) P[i] = 0.f; }
;     unpack8(__builtin_nontemporal_load((const u32x4*)(zc)), C);
;     u32x4 raw = __builtin_nontemporal_load((const u32x4*)(zc + ZLD));
.Lp2_nz_10:
	v_lshlrev_b32_e32 v96, 16, v236
	v_and_b32_e32 v97, 0xffff0000, v236
	v_lshlrev_b32_e32 v98, 16, v237
	v_and_b32_e32 v99, 0xffff0000, v237
	v_lshlrev_b32_e32 v100, 16, v238
	v_and_b32_e32 v101, 0xffff0000, v238
	v_lshlrev_b32_e32 v102, 16, v239
	v_and_b32_e32 v103, 0xffff0000, v239
	v_add_f32_e32 v136, v80, v96
	v_add_f32_e32 v137, v81, v97
	v_add_f32_e32 v138, v82, v98
	v_add_f32_e32 v139, v83, v99
	v_add_f32_e32 v140, v84, v100
	v_add_f32_e32 v141, v85, v101
	v_add_f32_e32 v142, v86, v102
	v_add_f32_e32 v143, v87, v103
	v_fma_f32 v136, v136, 0.5, -v88
	v_fma_f32 v137, v137, 0.5, -v89
	v_fma_f32 v138, v138, 0.5, -v90
	v_fma_f32 v139, v139, 0.5, -v91
	v_fma_f32 v140, v140, 0.5, -v92
	v_fma_f32 v141, v141, 0.5, -v93
	v_fma_f32 v142, v142, 0.5, -v94
	v_fma_f32 v143, v143, 0.5, -v95
	v_fma_f32 v128, v104, v136, v88
	v_fma_f32 v129, v105, v137, v89
	v_fma_f32 v130, v106, v138, v90
	v_fma_f32 v131, v107, v139, v91
	v_fma_f32 v132, v108, v140, v92
	v_fma_f32 v133, v109, v141, v93
	v_fma_f32 v134, v110, v142, v94
	v_fma_f32 v135, v111, v143, v95
	v_mul_f32_e32 v136, 0x4038aa3b, v128
	v_mul_f32_e32 v137, 0x4038aa3b, v129
	v_mul_f32_e32 v138, 0x4038aa3b, v130
	v_mul_f32_e32 v139, 0x4038aa3b, v131
	v_mul_f32_e32 v140, 0x4038aa3b, v132
	v_mul_f32_e32 v141, 0x4038aa3b, v133
	v_mul_f32_e32 v142, 0x4038aa3b, v134
	v_mul_f32_e32 v143, 0x4038aa3b, v135
	v_mul_f32_e32 v144, 0xbfb8aa3b, v128
	v_mul_f32_e32 v145, 0xbfb8aa3b, v129
	v_mul_f32_e32 v146, 0xbfb8aa3b, v130
	v_mul_f32_e32 v147, 0xbfb8aa3b, v131
	v_mul_f32_e32 v148, 0xbfb8aa3b, v132
	v_mul_f32_e32 v149, 0xbfb8aa3b, v133
	v_mul_f32_e32 v150, 0xbfb8aa3b, v134
	v_mul_f32_e32 v151, 0xbfb8aa3b, v135
	v_exp_f32_e32 v136, v136
	v_exp_f32_e32 v137, v137
	v_exp_f32_e32 v138, v138
	v_exp_f32_e32 v139, v139
	v_exp_f32_e32 v140, v140
	v_exp_f32_e32 v141, v141
	v_exp_f32_e32 v142, v142
	v_exp_f32_e32 v143, v143
	v_exp_f32_e32 v144, v144
	v_exp_f32_e32 v145, v145
	v_exp_f32_e32 v146, v146
	v_exp_f32_e32 v147, v147
	v_exp_f32_e32 v148, v148
	v_exp_f32_e32 v149, v149
	v_exp_f32_e32 v150, v150
	v_exp_f32_e32 v151, v151
	v_add_f32_e32 v136, 1.0, v136
	v_add_f32_e32 v137, 1.0, v137
	v_add_f32_e32 v138, 1.0, v138
	v_add_f32_e32 v139, 1.0, v139
	v_add_f32_e32 v140, 1.0, v140
	v_add_f32_e32 v141, 1.0, v141
	v_add_f32_e32 v142, 1.0, v142
	v_add_f32_e32 v143, 1.0, v143
	v_add_f32_e32 v144, 1.0, v144
	v_add_f32_e32 v145, 1.0, v145
	v_add_f32_e32 v146, 1.0, v146
	v_add_f32_e32 v147, 1.0, v147
	v_add_f32_e32 v148, 1.0, v148
	v_add_f32_e32 v149, 1.0, v149
	v_add_f32_e32 v150, 1.0, v150
	v_add_f32_e32 v151, 1.0, v151
	v_rcp_f32_e32 v136, v136
	v_rcp_f32_e32 v137, v137
	v_rcp_f32_e32 v138, v138
	v_rcp_f32_e32 v139, v139
	v_rcp_f32_e32 v140, v140
	v_rcp_f32_e32 v141, v141
	v_rcp_f32_e32 v142, v142
	v_rcp_f32_e32 v143, v143
	v_rcp_f32_e32 v144, v144
	v_rcp_f32_e32 v145, v145
	v_rcp_f32_e32 v146, v146
	v_rcp_f32_e32 v147, v147
	v_rcp_f32_e32 v148, v148
	v_rcp_f32_e32 v149, v149
	v_rcp_f32_e32 v150, v150
	v_rcp_f32_e32 v151, v151
	v_fma_f32 v136, v136, -2.0, 1.0
	v_fma_f32 v137, v137, -2.0, 1.0
	v_fma_f32 v138, v138, -2.0, 1.0
	v_fma_f32 v139, v139, -2.0, 1.0
	v_fma_f32 v140, v140, -2.0, 1.0
	v_fma_f32 v141, v141, -2.0, 1.0
	v_fma_f32 v142, v142, -2.0, 1.0
	v_fma_f32 v143, v143, -2.0, 1.0
	v_cndmask_b32_e64 v144, v144, v128, s[76:77]
	v_cndmask_b32_e64 v145, v145, v129, s[76:77]
	v_cndmask_b32_e64 v146, v146, v130, s[76:77]
	v_cndmask_b32_e64 v147, v147, v131, s[76:77]
	v_cndmask_b32_e64 v148, v148, v132, s[76:77]
	v_cndmask_b32_e64 v149, v149, v133, s[76:77]
	v_cndmask_b32_e64 v150, v150, v134, s[76:77]
	v_cndmask_b32_e64 v151, v151, v135, s[76:77]
	v_cndmask_b32_e64 v144, v144, v136, s[74:75]
	v_cndmask_b32_e64 v145, v145, v137, s[74:75]
	v_cndmask_b32_e64 v146, v146, v138, s[74:75]
	v_cndmask_b32_e64 v147, v147, v139, s[74:75]
	v_cndmask_b32_e64 v148, v148, v140, s[74:75]
	v_cndmask_b32_e64 v149, v149, v141, s[74:75]
	v_cndmask_b32_e64 v150, v150, v142, s[74:75]
	v_cndmask_b32_e64 v151, v151, v143, s[74:75]
	v_cndmask_b32_e64 v144, 0, v144, s[64:65]
	v_cndmask_b32_e64 v145, 0, v145, s[64:65]
	v_cndmask_b32_e64 v146, 0, v146, s[64:65]
	v_cndmask_b32_e64 v147, 0, v147, s[64:65]
	v_cndmask_b32_e64 v148, 0, v148, s[64:65]
	v_cndmask_b32_e64 v149, 0, v149, s[64:65]
	v_cndmask_b32_e64 v150, 0, v150, s[64:65]
	v_cndmask_b32_e64 v151, 0, v151, s[64:65]
	v_cvt_pk_bf16_f32 v246, v144, v145
	v_cvt_pk_bf16_f32 v247, v146, v147
	v_cvt_pk_bf16_f32 v248, v148, v149
	v_cvt_pk_bf16_f32 v249, v150, v151
	s_mov_b64 s[42:43], exec
	s_and_b64 exec, exec, s[36:37]
	global_store_dwordx4 v5, v[246:249], s[56:57] nt
	s_mov_b64 exec, s[42:43]
	v_add_u32_e32 v5, 0x300, v5
	v_readlane_b32 s26, v254, 27
	v_readlane_b32 s27, v254, 28
	v_lshlrev_b32_e32 v1, 5, v0
	s_nop 3
	global_load_dwordx4 v[104:107], v1, s[26:27]
	global_load_dwordx4 v[108:111], v1, s[26:27] offset:16
	v_add_u32_e32 v1, 0x1000, v1
	global_load_dwordx4 v[112:115], v1, s[26:27]
	global_load_dwordx4 v[116:119], v1, s[26:27] offset:16
	v_add_u32_e32 v1, 0x1000, v1
	global_load_dwordx4 v[120:123], v1, s[26:27]
	global_load_dwordx4 v[124:127], v1, s[26:27] offset:16
	s_mul_i32 s63, s62, 0x1c00
	s_add_u32 s63, s63, 0x7001280
	v_lshl_add_u32 v4, v0, 4, s63
	v_add_u32_e32 v1, 0xffffe400, v4
	s_cmp_lg_u32 s66, 0
	s_cselect_b64 vcc, -1, 0
	s_nop 1
	v_cndmask_b32_e32 v1, v1, v4, vcc
	global_load_dwordx4 v[168:171], v1, s[58:59] nt
	global_load_dwordx4 v[172:175], v4, s[58:59] nt
	v_mov_b32_e32 v1, v4
	v_add_u32_e32 v1, 0x1c00, v1
	global_load_dwordx4 v[176:179], v1, s[58:59] nt
	v_add_u32_e32 v1, 0x1c00, v1
	global_load_dwordx4 v[180:183], v1, s[58:59] nt
	v_add_u32_e32 v1, 0x1c00, v1
	global_load_dwordx4 v[184:187], v1, s[58:59] nt
	v_add_u32_e32 v1, 0x1c00, v1
	global_load_dwordx4 v[188:191], v1, s[58:59] nt
	v_add_u32_e32 v1, 0x1c00, v1
	global_load_dwordx4 v[192:195], v1, s[58:59] nt
	v_add_u32_e32 v1, 0x1c00, v1
	global_load_dwordx4 v[196:199], v1, s[58:59] nt
	v_add_u32_e32 v1, 0x1c00, v1
	global_load_dwordx4 v[200:203], v1, s[58:59] nt
	v_add_u32_e32 v1, 0x1c00, v1
	global_load_dwordx4 v[204:207], v1, s[58:59] nt
	v_add_u32_e32 v1, 0x1c00, v1
	global_load_dwordx4 v[208:211], v1, s[58:59] nt
	v_add_u32_e32 v1, 0x1c00, v1
	global_load_dwordx4 v[212:215], v1, s[58:59] nt
	v_add_u32_e32 v1, 0x1c00, v1
	global_load_dwordx4 v[216:219], v1, s[58:59] nt
	v_add_u32_e32 v1, 0x1c00, v1
	global_load_dwordx4 v[220:223], v1, s[58:59] nt
	v_add_u32_e32 v1, 0x1c00, v1
	global_load_dwordx4 v[224:227], v1, s[58:59] nt
	v_add_u32_e32 v1, 0x1c00, v1
	global_load_dwordx4 v[228:231], v1, s[58:59] nt
	v_add_u32_e32 v1, 0x1c00, v1
	global_load_dwordx4 v[232:235], v1, s[58:59] nt
	v_add_u32_e32 v1, 0x1c00, v1
	s_cmp_lg_u32 s67, 0
	s_cselect_b64 vcc, -1, 0
	s_nop 1
	v_cndmask_b32_e32 v1, v1, v4, vcc
	global_load_dwordx4 v[236:239], v1, s[58:59] nt
	v_cmp_gt_u32_e32 vcc, 32, v0
	v_mov_b32_e32 v252, 1.0
	v_mov_b32_e32 v253, 0.125
	v_cndmask_b32_e32 v252, v252, v253, vcc
	s_mul_i32 s63, s62, 0x800
	s_add_u32 s63, s63, 0x1b000000
	v_lshl_add_u32 v5, v0, 4, s63
	s_waitcnt vmcnt(18)
; __device__ __forceinline__ void unpack8(const u32x4 w, float (&f)[8]) { f[0] = bflo(w.x); f[1] = bfhi(w.x); f[2] = bflo(w.y); f[3] = bfhi(w.y); f[4] = bflo(w.z); f[5] = bfhi(w.z); f[6] = bflo(w.w); f[7] = bfhi(w.w); }
; __device__ __forceinline__ u32x4 pack8(const float (&f)[8]) { u32x4 o; o.x = pk2(f[0], f[1]); o.y = pk2(f[2], f[3]); o.z = pk2(f[4], f[5]); o.w = pk2(f[6], f[7]); return o; }
; __device__ __forceinline__ float siluf_(float x) { return x * __builtin_amdgcn_rcpf(1.0f + __expf(-x)); }
; template <int CH> __device__ __forceinline__ void p2_gla_chunk(const Params& p, int t0, int lane) {
;     ...
;     if ((t0 & (T_SEQ - 1)) != 0) unpack8(__builtin_nontemporal_load((const u32x4*)(zc - ZLD)), P); else {
; #pragma unroll
;         for (int i = 0; i < 8; ++i) P[i] = 0.f; }
;     unpack8(__builtin_nontemporal_load((const u32x4*)(zc)), C);
;     u32x4 raw = __builtin_nontemporal_load((const u32x4*)(zc + ZLD));
; #pragma unroll 2
;     for (int i = 0; i < 16; ++i) {
;         const int t = t0 + i; const bool hasn = (t & (T_SEQ - 1)) != T_SEQ - 1;
;         if (hasn) unpack8(raw, N); else {
; #pragma unroll
;             for (int q = 0; q < 8; ++q) N[q] = 0.f; }
;         if (i < 15 && ((t + 1) & (T_SEQ - 1)) != T_SEQ - 1) raw = __builtin_nontemporal_load((const u32x4*)(zc + (size_t)(i + 2) * ZLD));
;         float o[8];
; #pragma unroll
;         for (int q = 0; q < 8; ++q) { const float y = w0[q] * P[q] + w1[q] * C[q] + w2[q] * N[q]; o[q] = siluf_(y) * sc; }
;         *(u32x4*)(GQKV + (size_t)t * 1024 + c) = pack8(o);
	s_cmp_eq_u32 s66, 0
	s_cbranch_scc1 .Lp2_nz_11
	v_mov_b32_e32 v8, 0
	v_mov_b32_e32 v9, 0
	v_mov_b32_e32 v10, 0
	v_mov_b32_e32 v11, 0
.Lp2_nz_11:
	v_lshlrev_b32_e32 v80, 16, v8
	v_and_b32_e32 v81, 0xffff0000, v8
	v_lshlrev_b32_e32 v82, 16, v9
	v_and_b32_e32 v83, 0xffff0000, v9
	v_lshlrev_b32_e32 v84, 16, v10
	v_and_b32_e32 v85, 0xffff0000, v10
	v_lshlrev_b32_e32 v86, 16, v11
	v_and_b32_e32 v87, 0xffff0000, v11
	v_lshlrev_b32_e32 v88, 16, v12
	v_and_b32_e32 v89, 0xffff0000, v12
	v_lshlrev_b32_e32 v90, 16, v13
	v_and_b32_e32 v91, 0xffff0000, v13
	v_lshlrev_b32_e32 v92, 16, v14
	v_and_b32_e32 v93, 0xffff0000, v14
	v_lshlrev_b32_e32 v94, 16, v15
	v_and_b32_e32 v95, 0xffff0000, v15
	v_lshlrev_b32_e32 v96, 16, v16
	v_and_b32_e32 v97, 0xffff0000, v16
	v_lshlrev_b32_e32 v98, 16, v17
	v_and_b32_e32 v99, 0xffff0000, v17
	v_lshlrev_b32_e32 v100, 16, v18
	v_and_b32_e32 v101, 0xffff0000, v18
	v_lshlrev_b32_e32 v102, 16, v19
	v_and_b32_e32 v103, 0xffff0000, v19
	v_mul_f32_e32 v128, v104, v80
	v_mul_f32_e32 v129, v105, v81
	v_mul_f32_e32 v130, v106, v82
	v_mul_f32_e32 v131, v107, v83
	v_mul_f32_e32 v132, v108, v84
	v_mul_f32_e32 v133, v109, v85
	v_mul_f32_e32 v134, v110, v86
	v_mul_f32_e32 v135, v111, v87
	v_fmac_f32_e32 v128, v112, v88
	v_fmac_f32_e32 v129, v113, v89
	v_fmac_f32_e32 v130, v114, v90
	v_fmac_f32_e32 v131, v115, v91
	v_fmac_f32_e32 v132, v116, v92
	v_fmac_f32_e32 v133, v117, v93
	v_fmac_f32_e32 v134, v118, v94
	v_fmac_f32_e32 v135, v119, v95
	v_fmac_f32_e32 v128, v120, v96
	v_fmac_f32_e32 v129, v121, v97
	v_fmac_f32_e32 v130, v122, v98
	v_fmac_f32_e32 v131, v123, v99
	v_fmac_f32_e32 v132, v124, v100
	v_fmac_f32_e32 v133, v125, v101
	v_fmac_f32_e32 v134, v126, v102
	v_fmac_f32_e32 v135, v127, v103
	v_mul_f32_e32 v136, 0xbfb8aa3b, v128
	v_mul_f32_e32 v137, 0xbfb8aa3b, v129
	v_mul_f32_e32 v138, 0xbfb8aa3b, v130
	v_mul_f32_e32 v139, 0xbfb8aa3b, v131
	v_mul_f32_e32 v140, 0xbfb8aa3b, v132
	v_mul_f32_e32 v141, 0xbfb8aa3b, v133
	v_mul_f32_e32 v142, 0xbfb8aa3b, v134
	v_mul_f32_e32 v143, 0xbfb8aa3b, v135
	v_exp_f32_e32 v136, v136
	v_exp_f32_e32 v137, v137
	v_exp_f32_e32 v138, v138
	v_exp_f32_e32 v139, v139
	v_exp_f32_e32 v140, v140
	v_exp_f32_e32 v141, v141
	v_exp_f32_e32 v142, v142
	v_exp_f32_e32 v143, v143
	v_add_f32_e32 v136, 1.0, v136
	v_add_f32_e32 v137, 1.0, v137
	v_add_f32_e32 v138, 1.0, v138
	v_add_f32_e32 v139, 1.0, v139
	v_add_f32_e32 v140, 1.0, v140
	v_add_f32_e32 v141, 1.0, v141
	v_add_f32_e32 v142, 1.0, v142
	v_add_f32_e32 v143, 1.0, v143
	v_rcp_f32_e32 v136, v136
	v_rcp_f32_e32 v137, v137
	v_rcp_f32_e32 v138, v138
	v_rcp_f32_e32 v139, v139
	v_rcp_f32_e32 v140, v140
	v_rcp_f32_e32 v141, v141
	v_rcp_f32_e32 v142, v142
	v_rcp_f32_e32 v143, v143
	v_mul_f32_e32 v128, v128, v136
	v_mul_f32_e32 v129, v129, v137
	v_mul_f32_e32 v130, v130, v138
	v_mul_f32_e32 v131, v131, v139
	v_mul_f32_e32 v132, v132, v140
	v_mul_f32_e32 v133, v133, v141
	v_mul_f32_e32 v134, v134, v142
	v_mul_f32_e32 v135, v135, v143
	v_mul_f32_e32 v128, v128, v252
	v_mul_f32_e32 v129, v129, v252
	v_mul_f32_e32 v130, v130, v252
	v_mul_f32_e32 v131, v131, v252
	v_mul_f32_e32 v132, v132, v252
	v_mul_f32_e32 v133, v133, v252
	v_mul_f32_e32 v134, v134, v252
	v_mul_f32_e32 v135, v135, v252
	v_cvt_pk_bf16_f32 v246, v128, v129
	v_cvt_pk_bf16_f32 v247, v130, v131
	v_cvt_pk_bf16_f32 v248, v132, v133
	v_cvt_pk_bf16_f32 v249, v134, v135
	global_store_dwordx4 v5, v[246:249], s[58:59] nt
	v_add_u32_e32 v5, 0x800, v5
	v_lshlrev_b32_e32 v80, 16, v20
	v_and_b32_e32 v81, 0xffff0000, v20
	v_lshlrev_b32_e32 v82, 16, v21
	v_and_b32_e32 v83, 0xffff0000, v21
	v_lshlrev_b32_e32 v84, 16, v22
	v_and_b32_e32 v85, 0xffff0000, v22
	v_lshlrev_b32_e32 v86, 16, v23
	v_and_b32_e32 v87, 0xffff0000, v23
	v_mul_f32_e32 v128, v104, v88
	v_mul_f32_e32 v129, v105, v89
	v_mul_f32_e32 v130, v106, v90
	v_mul_f32_e32 v131, v107, v91
	v_mul_f32_e32 v132, v108, v92
	v_mul_f32_e32 v133, v109, v93
	v_mul_f32_e32 v134, v110, v94
	v_mul_f32_e32 v135, v111, v95
	v_fmac_f32_e32 v128, v112, v96
	v_fmac_f32_e32 v129, v113, v97
	v_fmac_f32_e32 v130, v114, v98
	v_fmac_f32_e32 v131, v115, v99
	v_fmac_f32_e32 v132, v116, v100
	v_fmac_f32_e32 v133, v117, v101
	v_fmac_f32_e32 v134, v118, v102
	v_fmac_f32_e32 v135, v119, v103
	v_fmac_f32_e32 v128, v120, v80
	v_fmac_f32_e32 v129, v121, v81
	v_fmac_f32_e32 v130, v122, v82
	v_fmac_f32_e32 v131, v123, v83
	v_fmac_f32_e32 v132, v124, v84
	v_fmac_f32_e32 v133, v125, v85
	v_fmac_f32_e32 v134, v126, v86
	v_fmac_f32_e32 v135, v127, v87
	v_mul_f32_e32 v136, 0xbfb8aa3b, v128
	v_mul_f32_e32 v137, 0xbfb8aa3b, v129
	v_mul_f32_e32 v138, 0xbfb8aa3b, v130
	v_mul_f32_e32 v139, 0xbfb8aa3b, v131
	v_mul_f32_e32 v140, 0xbfb8aa3b, v132
	v_mul_f32_e32 v141, 0xbfb8aa3b, v133
	v_mul_f32_e32 v142, 0xbfb8aa3b, v134
	v_mul_f32_e32 v143, 0xbfb8aa3b, v135
	v_exp_f32_e32 v136, v136
	v_exp_f32_e32 v137, v137
	v_exp_f32_e32 v138, v138
	v_exp_f32_e32 v139, v139
	v_exp_f32_e32 v140, v140
	v_exp_f32_e32 v141, v141
	v_exp_f32_e32 v142, v142
	v_exp_f32_e32 v143, v143
	v_add_f32_e32 v136, 1.0, v136
	v_add_f32_e32 v137, 1.0, v137
	v_add_f32_e32 v138, 1.0, v138
	v_add_f32_e32 v139, 1.0, v139
	v_add_f32_e32 v140, 1.0, v140
	v_add_f32_e32 v141, 1.0, v141
	v_add_f32_e32 v142, 1.0, v142
	v_add_f32_e32 v143, 1.0, v143
	v_rcp_f32_e32 v136, v136
	v_rcp_f32_e32 v137, v137
	v_rcp_f32_e32 v138, v138
	v_rcp_f32_e32 v139, v139
	v_rcp_f32_e32 v140, v140
	v_rcp_f32_e32 v141, v141
	v_rcp_f32_e32 v142, v142
	v_rcp_f32_e32 v143, v143
	v_mul_f32_e32 v128, v128, v136
	v_mul_f32_e32 v129, v129, v137
	v_mul_f32_e32 v130, v130, v138
	v_mul_f32_e32 v131, v131, v139
	v_mul_f32_e32 v132, v132, v140
	v_mul_f32_e32 v133, v133, v141
; __device__ __forceinline__ u32x4 pack8(const float (&f)[8]) { u32x4 o; o.x = pk2(f[0], f[1]); o.y = pk2(f[2], f[3]); o.z = pk2(f[4], f[5]); o.w = pk2(f[6], f[7]); return o; }
; __device__ __forceinline__ float siluf_(float x) { return x * __builtin_amdgcn_rcpf(1.0f + __expf(-x)); }
; template <int CH> __device__ __forceinline__ void p2_gla_chunk(const Params& p, int t0, int lane) {
;     ...
;         float o[8];
; #pragma unroll
;         for (int q = 0; q < 8; ++q) { const float y = w0[q] * P[q] + w1[q] * C[q] + w2[q] * N[q]; o[q] = siluf_(y) * sc; }
;         *(u32x4*)(GQKV + (size_t)t * 1024 + c) = pack8(o);
	v_mul_f32_e32 v134, v134, v142
	v_mul_f32_e32 v135, v135, v143
	v_mul_f32_e32 v128, v128, v252
	v_mul_f32_e32 v129, v129, v252
	v_mul_f32_e32 v130, v130, v252
	v_mul_f32_e32 v131, v131, v252
	v_mul_f32_e32 v132, v132, v252
	v_mul_f32_e32 v133, v133, v252
	v_mul_f32_e32 v134, v134, v252
	v_mul_f32_e32 v135, v135, v252
	v_cvt_pk_bf16_f32 v246, v128, v129
	v_cvt_pk_bf16_f32 v247, v130, v131
	v_cvt_pk_bf16_f32 v248, v132, v133
	v_cvt_pk_bf16_f32 v249, v134, v135
	global_store_dwordx4 v5, v[246:249], s[58:59] nt
	v_add_u32_e32 v5, 0x800, v5
	v_lshlrev_b32_e32 v88, 16, v24
	v_and_b32_e32 v89, 0xffff0000, v24
	v_lshlrev_b32_e32 v90, 16, v25
	v_and_b32_e32 v91, 0xffff0000, v25
	v_lshlrev_b32_e32 v92, 16, v26
	v_and_b32_e32 v93, 0xffff0000, v26
	v_lshlrev_b32_e32 v94, 16, v27
	v_and_b32_e32 v95, 0xffff0000, v27
	v_mul_f32_e32 v128, v104, v96
	v_mul_f32_e32 v129, v105, v97
	v_mul_f32_e32 v130, v106, v98
	v_mul_f32_e32 v131, v107, v99
	v_mul_f32_e32 v132, v108, v100
	v_mul_f32_e32 v133, v109, v101
	v_mul_f32_e32 v134, v110, v102
	v_mul_f32_e32 v135, v111, v103
	v_fmac_f32_e32 v128, v112, v80
	v_fmac_f32_e32 v129, v113, v81
	v_fmac_f32_e32 v130, v114, v82
	v_fmac_f32_e32 v131, v115, v83
	v_fmac_f32_e32 v132, v116, v84
	v_fmac_f32_e32 v133, v117, v85
	v_fmac_f32_e32 v134, v118, v86
	v_fmac_f32_e32 v135, v119, v87
	v_fmac_f32_e32 v128, v120, v88
	v_fmac_f32_e32 v129, v121, v89
	v_fmac_f32_e32 v130, v122, v90
	v_fmac_f32_e32 v131, v123, v91
	v_fmac_f32_e32 v132, v124, v92
	v_fmac_f32_e32 v133, v125, v93
	v_fmac_f32_e32 v134, v126, v94
	v_fmac_f32_e32 v135, v127, v95
	v_mul_f32_e32 v136, 0xbfb8aa3b, v128
	v_mul_f32_e32 v137, 0xbfb8aa3b, v129
	v_mul_f32_e32 v138, 0xbfb8aa3b, v130
	v_mul_f32_e32 v139, 0xbfb8aa3b, v131
	v_mul_f32_e32 v140, 0xbfb8aa3b, v132
	v_mul_f32_e32 v141, 0xbfb8aa3b, v133
	v_mul_f32_e32 v142, 0xbfb8aa3b, v134
	v_mul_f32_e32 v143, 0xbfb8aa3b, v135
	v_exp_f32_e32 v136, v136
	v_exp_f32_e32 v137, v137
	v_exp_f32_e32 v138, v138
	v_exp_f32_e32 v139, v139
	v_exp_f32_e32 v140, v140
	v_exp_f32_e32 v141, v141
	v_exp_f32_e32 v142, v142
	v_exp_f32_e32 v143, v143
	v_add_f32_e32 v136, 1.0, v136
	v_add_f32_e32 v137, 1.0, v137
	v_add_f32_e32 v138, 1.0, v138
	v_add_f32_e32 v139, 1.0, v139
	v_add_f32_e32 v140, 1.0, v140
	v_add_f32_e32 v141, 1.0, v141
	v_add_f32_e32 v142, 1.0, v142
	v_add_f32_e32 v143, 1.0, v143
	v_rcp_f32_e32 v136, v136
	v_rcp_f32_e32 v137, v137
	v_rcp_f32_e32 v138, v138
	v_rcp_f32_e32 v139, v139
	v_rcp_f32_e32 v140, v140
	v_rcp_f32_e32 v141, v141
	v_rcp_f32_e32 v142, v142
	v_rcp_f32_e32 v143, v143
	v_mul_f32_e32 v128, v128, v136
	v_mul_f32_e32 v129, v129, v137
	v_mul_f32_e32 v130, v130, v138
	v_mul_f32_e32 v131, v131, v139
	v_mul_f32_e32 v132, v132, v140
	v_mul_f32_e32 v133, v133, v141
	v_mul_f32_e32 v134, v134, v142
	v_mul_f32_e32 v135, v135, v143
	v_mul_f32_e32 v128, v128, v252
	v_mul_f32_e32 v129, v129, v252
	v_mul_f32_e32 v130, v130, v252
	v_mul_f32_e32 v131, v131, v252
	v_mul_f32_e32 v132, v132, v252
	v_mul_f32_e32 v133, v133, v252
	v_mul_f32_e32 v134, v134, v252
	v_mul_f32_e32 v135, v135, v252
	v_cvt_pk_bf16_f32 v246, v128, v129
	v_cvt_pk_bf16_f32 v247, v130, v131
	v_cvt_pk_bf16_f32 v248, v132, v133
	v_cvt_pk_bf16_f32 v249, v134, v135
	global_store_dwordx4 v5, v[246:249], s[58:59] nt
	v_add_u32_e32 v5, 0x800, v5
	v_lshlrev_b32_e32 v96, 16, v28
	v_and_b32_e32 v97, 0xffff0000, v28
	v_lshlrev_b32_e32 v98, 16, v29
	v_and_b32_e32 v99, 0xffff0000, v29
	v_lshlrev_b32_e32 v100, 16, v30
	v_and_b32_e32 v101, 0xffff0000, v30
	v_lshlrev_b32_e32 v102, 16, v31
	v_and_b32_e32 v103, 0xffff0000, v31
	v_mul_f32_e32 v128, v104, v80
	v_mul_f32_e32 v129, v105, v81
	v_mul_f32_e32 v130, v106, v82
	v_mul_f32_e32 v131, v107, v83
	v_mul_f32_e32 v132, v108, v84
	v_mul_f32_e32 v133, v109, v85
	v_mul_f32_e32 v134, v110, v86
	v_mul_f32_e32 v135, v111, v87
	v_fmac_f32_e32 v128, v112, v88
	v_fmac_f32_e32 v129, v113, v89
	v_fmac_f32_e32 v130, v114, v90
	v_fmac_f32_e32 v131, v115, v91
	v_fmac_f32_e32 v132, v116, v92
	v_fmac_f32_e32 v133, v117, v93
	v_fmac_f32_e32 v134, v118, v94
	v_fmac_f32_e32 v135, v119, v95
	v_fmac_f32_e32 v128, v120, v96
	v_fmac_f32_e32 v129, v121, v97
	v_fmac_f32_e32 v130, v122, v98
	v_fmac_f32_e32 v131, v123, v99
	v_fmac_f32_e32 v132, v124, v100
	v_fmac_f32_e32 v133, v125, v101
	v_fmac_f32_e32 v134, v126, v102
	v_fmac_f32_e32 v135, v127, v103
	v_mul_f32_e32 v136, 0xbfb8aa3b, v128
	v_mul_f32_e32 v137, 0xbfb8aa3b, v129
	v_mul_f32_e32 v138, 0xbfb8aa3b, v130
	v_mul_f32_e32 v139, 0xbfb8aa3b, v131
	v_mul_f32_e32 v140, 0xbfb8aa3b, v132
	v_mul_f32_e32 v141, 0xbfb8aa3b, v133
	v_mul_f32_e32 v142, 0xbfb8aa3b, v134
	v_mul_f32_e32 v143, 0xbfb8aa3b, v135
	v_exp_f32_e32 v136, v136
	v_exp_f32_e32 v137, v137
	v_exp_f32_e32 v138, v138
	v_exp_f32_e32 v139, v139
	v_exp_f32_e32 v140, v140
	v_exp_f32_e32 v141, v141
	v_exp_f32_e32 v142, v142
	v_exp_f32_e32 v143, v143
	v_add_f32_e32 v136, 1.0, v136
	v_add_f32_e32 v137, 1.0, v137
	v_add_f32_e32 v138, 1.0, v138
	v_add_f32_e32 v139, 1.0, v139
	v_add_f32_e32 v140, 1.0, v140
	v_add_f32_e32 v141, 1.0, v141
	v_add_f32_e32 v142, 1.0, v142
	v_add_f32_e32 v143, 1.0, v143
	v_rcp_f32_e32 v136, v136
	v_rcp_f32_e32 v137, v137
	v_rcp_f32_e32 v138, v138
	v_rcp_f32_e32 v139, v139
	v_rcp_f32_e32 v140, v140
	v_rcp_f32_e32 v141, v141
	v_rcp_f32_e32 v142, v142
	v_rcp_f32_e32 v143, v143
	v_mul_f32_e32 v128, v128, v136
	v_mul_f32_e32 v129, v129, v137
	v_mul_f32_e32 v130, v130, v138
	v_mul_f32_e32 v131, v131, v139
	v_mul_f32_e32 v132, v132, v140
	v_mul_f32_e32 v133, v133, v141
	v_mul_f32_e32 v134, v134, v142
	v_mul_f32_e32 v135, v135, v143
	v_mul_f32_e32 v128, v128, v252
	v_mul_f32_e32 v129, v129, v252
	v_mul_f32_e32 v130, v130, v252
; __device__ __forceinline__ u32x4 pack8(const float (&f)[8]) { u32x4 o; o.x = pk2(f[0], f[1]); o.y = pk2(f[2], f[3]); o.z = pk2(f[4], f[5]); o.w = pk2(f[6], f[7]); return o; }
; __device__ __forceinline__ float siluf_(float x) { return x * __builtin_amdgcn_rcpf(1.0f + __expf(-x)); }
; template <int CH> __device__ __forceinline__ void p2_gla_chunk(const Params& p, int t0, int lane) {
;     ...
;         float o[8];
; #pragma unroll
;         for (int q = 0; q < 8; ++q) { const float y = w0[q] * P[q] + w1[q] * C[q] + w2[q] * N[q]; o[q] = siluf_(y) * sc; }
;         *(u32x4*)(GQKV + (size_t)t * 1024 + c) = pack8(o);
	v_mul_f32_e32 v131, v131, v252
	v_mul_f32_e32 v132, v132, v252
	v_mul_f32_e32 v133, v133, v252
	v_mul_f32_e32 v134, v134, v252
	v_mul_f32_e32 v135, v135, v252
	v_cvt_pk_bf16_f32 v246, v128, v129
	v_cvt_pk_bf16_f32 v247, v130, v131
	v_cvt_pk_bf16_f32 v248, v132, v133
	v_cvt_pk_bf16_f32 v249, v134, v135
	global_store_dwordx4 v5, v[246:249], s[58:59] nt
	v_add_u32_e32 v5, 0x800, v5
	v_lshlrev_b32_e32 v80, 16, v32
	v_and_b32_e32 v81, 0xffff0000, v32
	v_lshlrev_b32_e32 v82, 16, v33
	v_and_b32_e32 v83, 0xffff0000, v33
	v_lshlrev_b32_e32 v84, 16, v34
	v_and_b32_e32 v85, 0xffff0000, v34
	v_lshlrev_b32_e32 v86, 16, v35
	v_and_b32_e32 v87, 0xffff0000, v35
	v_mul_f32_e32 v128, v104, v88
	v_mul_f32_e32 v129, v105, v89
	v_mul_f32_e32 v130, v106, v90
	v_mul_f32_e32 v131, v107, v91
	v_mul_f32_e32 v132, v108, v92
	v_mul_f32_e32 v133, v109, v93
	v_mul_f32_e32 v134, v110, v94
	v_mul_f32_e32 v135, v111, v95
	v_fmac_f32_e32 v128, v112, v96
	v_fmac_f32_e32 v129, v113, v97
	v_fmac_f32_e32 v130, v114, v98
	v_fmac_f32_e32 v131, v115, v99
	v_fmac_f32_e32 v132, v116, v100
	v_fmac_f32_e32 v133, v117, v101
	v_fmac_f32_e32 v134, v118, v102
	v_fmac_f32_e32 v135, v119, v103
	v_fmac_f32_e32 v128, v120, v80
	v_fmac_f32_e32 v129, v121, v81
	v_fmac_f32_e32 v130, v122, v82
	v_fmac_f32_e32 v131, v123, v83
	v_fmac_f32_e32 v132, v124, v84
	v_fmac_f32_e32 v133, v125, v85
	v_fmac_f32_e32 v134, v126, v86
	v_fmac_f32_e32 v135, v127, v87
	v_mul_f32_e32 v136, 0xbfb8aa3b, v128
	v_mul_f32_e32 v137, 0xbfb8aa3b, v129
	v_mul_f32_e32 v138, 0xbfb8aa3b, v130
	v_mul_f32_e32 v139, 0xbfb8aa3b, v131
	v_mul_f32_e32 v140, 0xbfb8aa3b, v132
	v_mul_f32_e32 v141, 0xbfb8aa3b, v133
	v_mul_f32_e32 v142, 0xbfb8aa3b, v134
	v_mul_f32_e32 v143, 0xbfb8aa3b, v135
	v_exp_f32_e32 v136, v136
	v_exp_f32_e32 v137, v137
	v_exp_f32_e32 v138, v138
	v_exp_f32_e32 v139, v139
	v_exp_f32_e32 v140, v140
	v_exp_f32_e32 v141, v141
	v_exp_f32_e32 v142, v142
	v_exp_f32_e32 v143, v143
	v_add_f32_e32 v136, 1.0, v136
	v_add_f32_e32 v137, 1.0, v137
	v_add_f32_e32 v138, 1.0, v138
	v_add_f32_e32 v139, 1.0, v139
	v_add_f32_e32 v140, 1.0, v140
	v_add_f32_e32 v141, 1.0, v141
	v_add_f32_e32 v142, 1.0, v142
	v_add_f32_e32 v143, 1.0, v143
	v_rcp_f32_e32 v136, v136
	v_rcp_f32_e32 v137, v137
	v_rcp_f32_e32 v138, v138
	v_rcp_f32_e32 v139, v139
	v_rcp_f32_e32 v140, v140
	v_rcp_f32_e32 v141, v141
	v_rcp_f32_e32 v142, v142
	v_rcp_f32_e32 v143, v143
	v_mul_f32_e32 v128, v128, v136
	v_mul_f32_e32 v129, v129, v137
	v_mul_f32_e32 v130, v130, v138
	v_mul_f32_e32 v131, v131, v139
	v_mul_f32_e32 v132, v132, v140
	v_mul_f32_e32 v133, v133, v141
	v_mul_f32_e32 v134, v134, v142
	v_mul_f32_e32 v135, v135, v143
	v_mul_f32_e32 v128, v128, v252
	v_mul_f32_e32 v129, v129, v252
	v_mul_f32_e32 v130, v130, v252
	v_mul_f32_e32 v131, v131, v252
	v_mul_f32_e32 v132, v132, v252
	v_mul_f32_e32 v133, v133, v252
	v_mul_f32_e32 v134, v134, v252
	v_mul_f32_e32 v135, v135, v252
	v_cvt_pk_bf16_f32 v246, v128, v129
	v_cvt_pk_bf16_f32 v247, v130, v131
	v_cvt_pk_bf16_f32 v248, v132, v133
	v_cvt_pk_bf16_f32 v249, v134, v135
	global_store_dwordx4 v5, v[246:249], s[58:59] nt
	v_add_u32_e32 v5, 0x800, v5
	v_lshlrev_b32_e32 v88, 16, v36
	v_and_b32_e32 v89, 0xffff0000, v36
	v_lshlrev_b32_e32 v90, 16, v37
	v_and_b32_e32 v91, 0xffff0000, v37
	v_lshlrev_b32_e32 v92, 16, v38
	v_and_b32_e32 v93, 0xffff0000, v38
	v_lshlrev_b32_e32 v94, 16, v39
	v_and_b32_e32 v95, 0xffff0000, v39
	v_mul_f32_e32 v128, v104, v96
	v_mul_f32_e32 v129, v105, v97
	v_mul_f32_e32 v130, v106, v98
	v_mul_f32_e32 v131, v107, v99
	v_mul_f32_e32 v132, v108, v100
	v_mul_f32_e32 v133, v109, v101
	v_mul_f32_e32 v134, v110, v102
	v_mul_f32_e32 v135, v111, v103
	v_fmac_f32_e32 v128, v112, v80
	v_fmac_f32_e32 v129, v113, v81
	v_fmac_f32_e32 v130, v114, v82
	v_fmac_f32_e32 v131, v115, v83
	v_fmac_f32_e32 v132, v116, v84
	v_fmac_f32_e32 v133, v117, v85
	v_fmac_f32_e32 v134, v118, v86
	v_fmac_f32_e32 v135, v119, v87
	v_fmac_f32_e32 v128, v120, v88
	v_fmac_f32_e32 v129, v121, v89
	v_fmac_f32_e32 v130, v122, v90
	v_fmac_f32_e32 v131, v123, v91
	v_fmac_f32_e32 v132, v124, v92
	v_fmac_f32_e32 v133, v125, v93
	v_fmac_f32_e32 v134, v126, v94
	v_fmac_f32_e32 v135, v127, v95
	v_mul_f32_e32 v136, 0xbfb8aa3b, v128
	v_mul_f32_e32 v137, 0xbfb8aa3b, v129
	v_mul_f32_e32 v138, 0xbfb8aa3b, v130
	v_mul_f32_e32 v139, 0xbfb8aa3b, v131
	v_mul_f32_e32 v140, 0xbfb8aa3b, v132
	v_mul_f32_e32 v141, 0xbfb8aa3b, v133
	v_mul_f32_e32 v142, 0xbfb8aa3b, v134
	v_mul_f32_e32 v143, 0xbfb8aa3b, v135
	v_exp_f32_e32 v136, v136
	v_exp_f32_e32 v137, v137
	v_exp_f32_e32 v138, v138
	v_exp_f32_e32 v139, v139
	v_exp_f32_e32 v140, v140
	v_exp_f32_e32 v141, v141
	v_exp_f32_e32 v142, v142
	v_exp_f32_e32 v143, v143
	v_add_f32_e32 v136, 1.0, v136
	v_add_f32_e32 v137, 1.0, v137
	v_add_f32_e32 v138, 1.0, v138
	v_add_f32_e32 v139, 1.0, v139
	v_add_f32_e32 v140, 1.0, v140
	v_add_f32_e32 v141, 1.0, v141
	v_add_f32_e32 v142, 1.0, v142
	v_add_f32_e32 v143, 1.0, v143
	v_rcp_f32_e32 v136, v136
	v_rcp_f32_e32 v137, v137
	v_rcp_f32_e32 v138, v138
	v_rcp_f32_e32 v139, v139
	v_rcp_f32_e32 v140, v140
	v_rcp_f32_e32 v141, v141
	v_rcp_f32_e32 v142, v142
	v_rcp_f32_e32 v143, v143
	v_mul_f32_e32 v128, v128, v136
	v_mul_f32_e32 v129, v129, v137
	v_mul_f32_e32 v130, v130, v138
	v_mul_f32_e32 v131, v131, v139
	v_mul_f32_e32 v132, v132, v140
	v_mul_f32_e32 v133, v133, v141
	v_mul_f32_e32 v134, v134, v142
	v_mul_f32_e32 v135, v135, v143
	v_mul_f32_e32 v128, v128, v252
	v_mul_f32_e32 v129, v129, v252
	v_mul_f32_e32 v130, v130, v252
	v_mul_f32_e32 v131, v131, v252
	v_mul_f32_e32 v132, v132, v252
	v_mul_f32_e32 v133, v133, v252
	v_mul_f32_e32 v134, v134, v252
	v_mul_f32_e32 v135, v135, v252
; __device__ __forceinline__ u32x4 pack8(const float (&f)[8]) { u32x4 o; o.x = pk2(f[0], f[1]); o.y = pk2(f[2], f[3]); o.z = pk2(f[4], f[5]); o.w = pk2(f[6], f[7]); return o; }
; __device__ __forceinline__ float siluf_(float x) { return x * __builtin_amdgcn_rcpf(1.0f + __expf(-x)); }
; template <int CH> __device__ __forceinline__ void p2_gla_chunk(const Params& p, int t0, int lane) {
;     ...
;         float o[8];
; #pragma unroll
;         for (int q = 0; q < 8; ++q) { const float y = w0[q] * P[q] + w1[q] * C[q] + w2[q] * N[q]; o[q] = siluf_(y) * sc; }
;         *(u32x4*)(GQKV + (size_t)t * 1024 + c) = pack8(o);
	v_cvt_pk_bf16_f32 v246, v128, v129
	v_cvt_pk_bf16_f32 v247, v130, v131
	v_cvt_pk_bf16_f32 v248, v132, v133
	v_cvt_pk_bf16_f32 v249, v134, v135
	global_store_dwordx4 v5, v[246:249], s[58:59] nt
	v_add_u32_e32 v5, 0x800, v5
	v_lshlrev_b32_e32 v96, 16, v40
	v_and_b32_e32 v97, 0xffff0000, v40
	v_lshlrev_b32_e32 v98, 16, v41
	v_and_b32_e32 v99, 0xffff0000, v41
	v_lshlrev_b32_e32 v100, 16, v42
	v_and_b32_e32 v101, 0xffff0000, v42
	v_lshlrev_b32_e32 v102, 16, v43
	v_and_b32_e32 v103, 0xffff0000, v43
	v_mul_f32_e32 v128, v104, v80
	v_mul_f32_e32 v129, v105, v81
	v_mul_f32_e32 v130, v106, v82
	v_mul_f32_e32 v131, v107, v83
	v_mul_f32_e32 v132, v108, v84
	v_mul_f32_e32 v133, v109, v85
	v_mul_f32_e32 v134, v110, v86
	v_mul_f32_e32 v135, v111, v87
	v_fmac_f32_e32 v128, v112, v88
	v_fmac_f32_e32 v129, v113, v89
	v_fmac_f32_e32 v130, v114, v90
	v_fmac_f32_e32 v131, v115, v91
	v_fmac_f32_e32 v132, v116, v92
	v_fmac_f32_e32 v133, v117, v93
	v_fmac_f32_e32 v134, v118, v94
	v_fmac_f32_e32 v135, v119, v95
	v_fmac_f32_e32 v128, v120, v96
	v_fmac_f32_e32 v129, v121, v97
	v_fmac_f32_e32 v130, v122, v98
	v_fmac_f32_e32 v131, v123, v99
	v_fmac_f32_e32 v132, v124, v100
	v_fmac_f32_e32 v133, v125, v101
	v_fmac_f32_e32 v134, v126, v102
	v_fmac_f32_e32 v135, v127, v103
	v_mul_f32_e32 v136, 0xbfb8aa3b, v128
	v_mul_f32_e32 v137, 0xbfb8aa3b, v129
	v_mul_f32_e32 v138, 0xbfb8aa3b, v130
	v_mul_f32_e32 v139, 0xbfb8aa3b, v131
	v_mul_f32_e32 v140, 0xbfb8aa3b, v132
	v_mul_f32_e32 v141, 0xbfb8aa3b, v133
	v_mul_f32_e32 v142, 0xbfb8aa3b, v134
	v_mul_f32_e32 v143, 0xbfb8aa3b, v135
	v_exp_f32_e32 v136, v136
	v_exp_f32_e32 v137, v137
	v_exp_f32_e32 v138, v138
	v_exp_f32_e32 v139, v139
	v_exp_f32_e32 v140, v140
	v_exp_f32_e32 v141, v141
	v_exp_f32_e32 v142, v142
	v_exp_f32_e32 v143, v143
	v_add_f32_e32 v136, 1.0, v136
	v_add_f32_e32 v137, 1.0, v137
	v_add_f32_e32 v138, 1.0, v138
	v_add_f32_e32 v139, 1.0, v139
	v_add_f32_e32 v140, 1.0, v140
	v_add_f32_e32 v141, 1.0, v141
	v_add_f32_e32 v142, 1.0, v142
	v_add_f32_e32 v143, 1.0, v143
	v_rcp_f32_e32 v136, v136
	v_rcp_f32_e32 v137, v137
	v_rcp_f32_e32 v138, v138
	v_rcp_f32_e32 v139, v139
	v_rcp_f32_e32 v140, v140
	v_rcp_f32_e32 v141, v141
	v_rcp_f32_e32 v142, v142
	v_rcp_f32_e32 v143, v143
	v_mul_f32_e32 v128, v128, v136
	v_mul_f32_e32 v129, v129, v137
	v_mul_f32_e32 v130, v130, v138
	v_mul_f32_e32 v131, v131, v139
	v_mul_f32_e32 v132, v132, v140
	v_mul_f32_e32 v133, v133, v141
	v_mul_f32_e32 v134, v134, v142
	v_mul_f32_e32 v135, v135, v143
	v_mul_f32_e32 v128, v128, v252
	v_mul_f32_e32 v129, v129, v252
	v_mul_f32_e32 v130, v130, v252
	v_mul_f32_e32 v131, v131, v252
	v_mul_f32_e32 v132, v132, v252
	v_mul_f32_e32 v133, v133, v252
	v_mul_f32_e32 v134, v134, v252
	v_mul_f32_e32 v135, v135, v252
	v_cvt_pk_bf16_f32 v246, v128, v129
	v_cvt_pk_bf16_f32 v247, v130, v131
	v_cvt_pk_bf16_f32 v248, v132, v133
	v_cvt_pk_bf16_f32 v249, v134, v135
	global_store_dwordx4 v5, v[246:249], s[58:59] nt
	v_add_u32_e32 v5, 0x800, v5
	v_lshlrev_b32_e32 v80, 16, v44
	v_and_b32_e32 v81, 0xffff0000, v44
	v_lshlrev_b32_e32 v82, 16, v45
	v_and_b32_e32 v83, 0xffff0000, v45
	v_lshlrev_b32_e32 v84, 16, v46
	v_and_b32_e32 v85, 0xffff0000, v46
	v_lshlrev_b32_e32 v86, 16, v47
	v_and_b32_e32 v87, 0xffff0000, v47
	v_mul_f32_e32 v128, v104, v88
	v_mul_f32_e32 v129, v105, v89
	v_mul_f32_e32 v130, v106, v90
	v_mul_f32_e32 v131, v107, v91
	v_mul_f32_e32 v132, v108, v92
	v_mul_f32_e32 v133, v109, v93
	v_mul_f32_e32 v134, v110, v94
	v_mul_f32_e32 v135, v111, v95
	v_fmac_f32_e32 v128, v112, v96
	v_fmac_f32_e32 v129, v113, v97
	v_fmac_f32_e32 v130, v114, v98
	v_fmac_f32_e32 v131, v115, v99
	v_fmac_f32_e32 v132, v116, v100
	v_fmac_f32_e32 v133, v117, v101
	v_fmac_f32_e32 v134, v118, v102
	v_fmac_f32_e32 v135, v119, v103
	v_fmac_f32_e32 v128, v120, v80
	v_fmac_f32_e32 v129, v121, v81
	v_fmac_f32_e32 v130, v122, v82
	v_fmac_f32_e32 v131, v123, v83
	v_fmac_f32_e32 v132, v124, v84
	v_fmac_f32_e32 v133, v125, v85
	v_fmac_f32_e32 v134, v126, v86
	v_fmac_f32_e32 v135, v127, v87
	v_mul_f32_e32 v136, 0xbfb8aa3b, v128
	v_mul_f32_e32 v137, 0xbfb8aa3b, v129
	v_mul_f32_e32 v138, 0xbfb8aa3b, v130
	v_mul_f32_e32 v139, 0xbfb8aa3b, v131
	v_mul_f32_e32 v140, 0xbfb8aa3b, v132
	v_mul_f32_e32 v141, 0xbfb8aa3b, v133
	v_mul_f32_e32 v142, 0xbfb8aa3b, v134
	v_mul_f32_e32 v143, 0xbfb8aa3b, v135
	v_exp_f32_e32 v136, v136
	v_exp_f32_e32 v137, v137
	v_exp_f32_e32 v138, v138
	v_exp_f32_e32 v139, v139
	v_exp_f32_e32 v140, v140
	v_exp_f32_e32 v141, v141
	v_exp_f32_e32 v142, v142
	v_exp_f32_e32 v143, v143
	v_add_f32_e32 v136, 1.0, v136
	v_add_f32_e32 v137, 1.0, v137
	v_add_f32_e32 v138, 1.0, v138
	v_add_f32_e32 v139, 1.0, v139
	v_add_f32_e32 v140, 1.0, v140
	v_add_f32_e32 v141, 1.0, v141
	v_add_f32_e32 v142, 1.0, v142
	v_add_f32_e32 v143, 1.0, v143
	v_rcp_f32_e32 v136, v136
	v_rcp_f32_e32 v137, v137
	v_rcp_f32_e32 v138, v138
	v_rcp_f32_e32 v139, v139
	v_rcp_f32_e32 v140, v140
	v_rcp_f32_e32 v141, v141
	v_rcp_f32_e32 v142, v142
	v_rcp_f32_e32 v143, v143
	v_mul_f32_e32 v128, v128, v136
	v_mul_f32_e32 v129, v129, v137
	v_mul_f32_e32 v130, v130, v138
	v_mul_f32_e32 v131, v131, v139
	v_mul_f32_e32 v132, v132, v140
	v_mul_f32_e32 v133, v133, v141
	v_mul_f32_e32 v134, v134, v142
	v_mul_f32_e32 v135, v135, v143
	v_mul_f32_e32 v128, v128, v252
	v_mul_f32_e32 v129, v129, v252
	v_mul_f32_e32 v130, v130, v252
	v_mul_f32_e32 v131, v131, v252
	v_mul_f32_e32 v132, v132, v252
	v_mul_f32_e32 v133, v133, v252
	v_mul_f32_e32 v134, v134, v252
	v_mul_f32_e32 v135, v135, v252
	v_cvt_pk_bf16_f32 v246, v128, v129
	v_cvt_pk_bf16_f32 v247, v130, v131
	v_cvt_pk_bf16_f32 v248, v132, v133
	v_cvt_pk_bf16_f32 v249, v134, v135
; __device__ __forceinline__ u32x4 pack8(const float (&f)[8]) { u32x4 o; o.x = pk2(f[0], f[1]); o.y = pk2(f[2], f[3]); o.z = pk2(f[4], f[5]); o.w = pk2(f[6], f[7]); return o; }
; __device__ __forceinline__ float siluf_(float x) { return x * __builtin_amdgcn_rcpf(1.0f + __expf(-x)); }
; template <int CH> __device__ __forceinline__ void p2_gla_chunk(const Params& p, int t0, int lane) {
;     ...
;         float o[8];
; #pragma unroll
;         for (int q = 0; q < 8; ++q) { const float y = w0[q] * P[q] + w1[q] * C[q] + w2[q] * N[q]; o[q] = siluf_(y) * sc; }
;         *(u32x4*)(GQKV + (size_t)t * 1024 + c) = pack8(o);
	global_store_dwordx4 v5, v[246:249], s[58:59] nt
	v_add_u32_e32 v5, 0x800, v5
	v_lshlrev_b32_e32 v88, 16, v48
	v_and_b32_e32 v89, 0xffff0000, v48
	v_lshlrev_b32_e32 v90, 16, v49
	v_and_b32_e32 v91, 0xffff0000, v49
	v_lshlrev_b32_e32 v92, 16, v50
	v_and_b32_e32 v93, 0xffff0000, v50
	v_lshlrev_b32_e32 v94, 16, v51
	v_and_b32_e32 v95, 0xffff0000, v51
	v_mul_f32_e32 v128, v104, v96
	v_mul_f32_e32 v129, v105, v97
	v_mul_f32_e32 v130, v106, v98
	v_mul_f32_e32 v131, v107, v99
	v_mul_f32_e32 v132, v108, v100
	v_mul_f32_e32 v133, v109, v101
	v_mul_f32_e32 v134, v110, v102
	v_mul_f32_e32 v135, v111, v103
	v_fmac_f32_e32 v128, v112, v80
	v_fmac_f32_e32 v129, v113, v81
	v_fmac_f32_e32 v130, v114, v82
	v_fmac_f32_e32 v131, v115, v83
	v_fmac_f32_e32 v132, v116, v84
	v_fmac_f32_e32 v133, v117, v85
	v_fmac_f32_e32 v134, v118, v86
	v_fmac_f32_e32 v135, v119, v87
	v_fmac_f32_e32 v128, v120, v88
	v_fmac_f32_e32 v129, v121, v89
	v_fmac_f32_e32 v130, v122, v90
	v_fmac_f32_e32 v131, v123, v91
	v_fmac_f32_e32 v132, v124, v92
	v_fmac_f32_e32 v133, v125, v93
	v_fmac_f32_e32 v134, v126, v94
	v_fmac_f32_e32 v135, v127, v95
	v_mul_f32_e32 v136, 0xbfb8aa3b, v128
	v_mul_f32_e32 v137, 0xbfb8aa3b, v129
	v_mul_f32_e32 v138, 0xbfb8aa3b, v130
	v_mul_f32_e32 v139, 0xbfb8aa3b, v131
	v_mul_f32_e32 v140, 0xbfb8aa3b, v132
	v_mul_f32_e32 v141, 0xbfb8aa3b, v133
	v_mul_f32_e32 v142, 0xbfb8aa3b, v134
	v_mul_f32_e32 v143, 0xbfb8aa3b, v135
	v_exp_f32_e32 v136, v136
	v_exp_f32_e32 v137, v137
	v_exp_f32_e32 v138, v138
	v_exp_f32_e32 v139, v139
	v_exp_f32_e32 v140, v140
	v_exp_f32_e32 v141, v141
	v_exp_f32_e32 v142, v142
	v_exp_f32_e32 v143, v143
	v_add_f32_e32 v136, 1.0, v136
	v_add_f32_e32 v137, 1.0, v137
	v_add_f32_e32 v138, 1.0, v138
	v_add_f32_e32 v139, 1.0, v139
	v_add_f32_e32 v140, 1.0, v140
	v_add_f32_e32 v141, 1.0, v141
	v_add_f32_e32 v142, 1.0, v142
	v_add_f32_e32 v143, 1.0, v143
	v_rcp_f32_e32 v136, v136
	v_rcp_f32_e32 v137, v137
	v_rcp_f32_e32 v138, v138
	v_rcp_f32_e32 v139, v139
	v_rcp_f32_e32 v140, v140
	v_rcp_f32_e32 v141, v141
	v_rcp_f32_e32 v142, v142
	v_rcp_f32_e32 v143, v143
	v_mul_f32_e32 v128, v128, v136
	v_mul_f32_e32 v129, v129, v137
	v_mul_f32_e32 v130, v130, v138
	v_mul_f32_e32 v131, v131, v139
	v_mul_f32_e32 v132, v132, v140
	v_mul_f32_e32 v133, v133, v141
	v_mul_f32_e32 v134, v134, v142
	v_mul_f32_e32 v135, v135, v143
	v_mul_f32_e32 v128, v128, v252
	v_mul_f32_e32 v129, v129, v252
	v_mul_f32_e32 v130, v130, v252
	v_mul_f32_e32 v131, v131, v252
	v_mul_f32_e32 v132, v132, v252
	v_mul_f32_e32 v133, v133, v252
	v_mul_f32_e32 v134, v134, v252
	v_mul_f32_e32 v135, v135, v252
	v_cvt_pk_bf16_f32 v246, v128, v129
	v_cvt_pk_bf16_f32 v247, v130, v131
	v_cvt_pk_bf16_f32 v248, v132, v133
	v_cvt_pk_bf16_f32 v249, v134, v135
	global_store_dwordx4 v5, v[246:249], s[58:59] nt
	v_add_u32_e32 v5, 0x800, v5
	v_lshlrev_b32_e32 v96, 16, v52
	v_and_b32_e32 v97, 0xffff0000, v52
	v_lshlrev_b32_e32 v98, 16, v53
	v_and_b32_e32 v99, 0xffff0000, v53
	v_lshlrev_b32_e32 v100, 16, v54
	v_and_b32_e32 v101, 0xffff0000, v54
	v_lshlrev_b32_e32 v102, 16, v55
	v_and_b32_e32 v103, 0xffff0000, v55
	v_mul_f32_e32 v128, v104, v80
	v_mul_f32_e32 v129, v105, v81
	v_mul_f32_e32 v130, v106, v82
	v_mul_f32_e32 v131, v107, v83
	v_mul_f32_e32 v132, v108, v84
	v_mul_f32_e32 v133, v109, v85
	v_mul_f32_e32 v134, v110, v86
	v_mul_f32_e32 v135, v111, v87
	v_fmac_f32_e32 v128, v112, v88
	v_fmac_f32_e32 v129, v113, v89
	v_fmac_f32_e32 v130, v114, v90
	v_fmac_f32_e32 v131, v115, v91
	v_fmac_f32_e32 v132, v116, v92
	v_fmac_f32_e32 v133, v117, v93
	v_fmac_f32_e32 v134, v118, v94
	v_fmac_f32_e32 v135, v119, v95
	v_fmac_f32_e32 v128, v120, v96
	v_fmac_f32_e32 v129, v121, v97
	v_fmac_f32_e32 v130, v122, v98
	v_fmac_f32_e32 v131, v123, v99
	v_fmac_f32_e32 v132, v124, v100
	v_fmac_f32_e32 v133, v125, v101
	v_fmac_f32_e32 v134, v126, v102
	v_fmac_f32_e32 v135, v127, v103
	v_mul_f32_e32 v136, 0xbfb8aa3b, v128
	v_mul_f32_e32 v137, 0xbfb8aa3b, v129
	v_mul_f32_e32 v138, 0xbfb8aa3b, v130
	v_mul_f32_e32 v139, 0xbfb8aa3b, v131
	v_mul_f32_e32 v140, 0xbfb8aa3b, v132
	v_mul_f32_e32 v141, 0xbfb8aa3b, v133
	v_mul_f32_e32 v142, 0xbfb8aa3b, v134
	v_mul_f32_e32 v143, 0xbfb8aa3b, v135
	v_exp_f32_e32 v136, v136
	v_exp_f32_e32 v137, v137
	v_exp_f32_e32 v138, v138
	v_exp_f32_e32 v139, v139
	v_exp_f32_e32 v140, v140
	v_exp_f32_e32 v141, v141
	v_exp_f32_e32 v142, v142
	v_exp_f32_e32 v143, v143
	v_add_f32_e32 v136, 1.0, v136
	v_add_f32_e32 v137, 1.0, v137
	v_add_f32_e32 v138, 1.0, v138
	v_add_f32_e32 v139, 1.0, v139
	v_add_f32_e32 v140, 1.0, v140
	v_add_f32_e32 v141, 1.0, v141
	v_add_f32_e32 v142, 1.0, v142
	v_add_f32_e32 v143, 1.0, v143
	v_rcp_f32_e32 v136, v136
	v_rcp_f32_e32 v137, v137
	v_rcp_f32_e32 v138, v138
	v_rcp_f32_e32 v139, v139
	v_rcp_f32_e32 v140, v140
	v_rcp_f32_e32 v141, v141
	v_rcp_f32_e32 v142, v142
	v_rcp_f32_e32 v143, v143
	v_mul_f32_e32 v128, v128, v136
	v_mul_f32_e32 v129, v129, v137
	v_mul_f32_e32 v130, v130, v138
	v_mul_f32_e32 v131, v131, v139
	v_mul_f32_e32 v132, v132, v140
	v_mul_f32_e32 v133, v133, v141
	v_mul_f32_e32 v134, v134, v142
	v_mul_f32_e32 v135, v135, v143
	v_mul_f32_e32 v128, v128, v252
	v_mul_f32_e32 v129, v129, v252
	v_mul_f32_e32 v130, v130, v252
	v_mul_f32_e32 v131, v131, v252
	v_mul_f32_e32 v132, v132, v252
	v_mul_f32_e32 v133, v133, v252
	v_mul_f32_e32 v134, v134, v252
	v_mul_f32_e32 v135, v135, v252
	v_cvt_pk_bf16_f32 v246, v128, v129
	v_cvt_pk_bf16_f32 v247, v130, v131
	v_cvt_pk_bf16_f32 v248, v132, v133
	v_cvt_pk_bf16_f32 v249, v134, v135
	global_store_dwordx4 v5, v[246:249], s[58:59] nt
	v_add_u32_e32 v5, 0x800, v5
	v_lshlrev_b32_e32 v80, 16, v56
	v_and_b32_e32 v81, 0xffff0000, v56
; __device__ __forceinline__ u32x4 pack8(const float (&f)[8]) { u32x4 o; o.x = pk2(f[0], f[1]); o.y = pk2(f[2], f[3]); o.z = pk2(f[4], f[5]); o.w = pk2(f[6], f[7]); return o; }
; __device__ __forceinline__ float siluf_(float x) { return x * __builtin_amdgcn_rcpf(1.0f + __expf(-x)); }
; template <int CH> __device__ __forceinline__ void p2_gla_chunk(const Params& p, int t0, int lane) {
;     ...
;         float o[8];
; #pragma unroll
;         for (int q = 0; q < 8; ++q) { const float y = w0[q] * P[q] + w1[q] * C[q] + w2[q] * N[q]; o[q] = siluf_(y) * sc; }
;         *(u32x4*)(GQKV + (size_t)t * 1024 + c) = pack8(o);
	v_lshlrev_b32_e32 v82, 16, v57
	v_and_b32_e32 v83, 0xffff0000, v57
	v_lshlrev_b32_e32 v84, 16, v58
	v_and_b32_e32 v85, 0xffff0000, v58
	v_lshlrev_b32_e32 v86, 16, v59
	v_and_b32_e32 v87, 0xffff0000, v59
	v_mul_f32_e32 v128, v104, v88
	v_mul_f32_e32 v129, v105, v89
	v_mul_f32_e32 v130, v106, v90
	v_mul_f32_e32 v131, v107, v91
	v_mul_f32_e32 v132, v108, v92
	v_mul_f32_e32 v133, v109, v93
	v_mul_f32_e32 v134, v110, v94
	v_mul_f32_e32 v135, v111, v95
	v_fmac_f32_e32 v128, v112, v96
	v_fmac_f32_e32 v129, v113, v97
	v_fmac_f32_e32 v130, v114, v98
	v_fmac_f32_e32 v131, v115, v99
	v_fmac_f32_e32 v132, v116, v100
	v_fmac_f32_e32 v133, v117, v101
	v_fmac_f32_e32 v134, v118, v102
	v_fmac_f32_e32 v135, v119, v103
	v_fmac_f32_e32 v128, v120, v80
	v_fmac_f32_e32 v129, v121, v81
	v_fmac_f32_e32 v130, v122, v82
	v_fmac_f32_e32 v131, v123, v83
	v_fmac_f32_e32 v132, v124, v84
	v_fmac_f32_e32 v133, v125, v85
	v_fmac_f32_e32 v134, v126, v86
	v_fmac_f32_e32 v135, v127, v87
	v_mul_f32_e32 v136, 0xbfb8aa3b, v128
	v_mul_f32_e32 v137, 0xbfb8aa3b, v129
	v_mul_f32_e32 v138, 0xbfb8aa3b, v130
	v_mul_f32_e32 v139, 0xbfb8aa3b, v131
	v_mul_f32_e32 v140, 0xbfb8aa3b, v132
	v_mul_f32_e32 v141, 0xbfb8aa3b, v133
	v_mul_f32_e32 v142, 0xbfb8aa3b, v134
	v_mul_f32_e32 v143, 0xbfb8aa3b, v135
	v_exp_f32_e32 v136, v136
	v_exp_f32_e32 v137, v137
	v_exp_f32_e32 v138, v138
	v_exp_f32_e32 v139, v139
	v_exp_f32_e32 v140, v140
	v_exp_f32_e32 v141, v141
	v_exp_f32_e32 v142, v142
	v_exp_f32_e32 v143, v143
	v_add_f32_e32 v136, 1.0, v136
	v_add_f32_e32 v137, 1.0, v137
	v_add_f32_e32 v138, 1.0, v138
	v_add_f32_e32 v139, 1.0, v139
	v_add_f32_e32 v140, 1.0, v140
	v_add_f32_e32 v141, 1.0, v141
	v_add_f32_e32 v142, 1.0, v142
	v_add_f32_e32 v143, 1.0, v143
	v_rcp_f32_e32 v136, v136
	v_rcp_f32_e32 v137, v137
	v_rcp_f32_e32 v138, v138
	v_rcp_f32_e32 v139, v139
	v_rcp_f32_e32 v140, v140
	v_rcp_f32_e32 v141, v141
	v_rcp_f32_e32 v142, v142
	v_rcp_f32_e32 v143, v143
	v_mul_f32_e32 v128, v128, v136
	v_mul_f32_e32 v129, v129, v137
	v_mul_f32_e32 v130, v130, v138
	v_mul_f32_e32 v131, v131, v139
	v_mul_f32_e32 v132, v132, v140
	v_mul_f32_e32 v133, v133, v141
	v_mul_f32_e32 v134, v134, v142
	v_mul_f32_e32 v135, v135, v143
	v_mul_f32_e32 v128, v128, v252
	v_mul_f32_e32 v129, v129, v252
	v_mul_f32_e32 v130, v130, v252
	v_mul_f32_e32 v131, v131, v252
	v_mul_f32_e32 v132, v132, v252
	v_mul_f32_e32 v133, v133, v252
	v_mul_f32_e32 v134, v134, v252
	v_mul_f32_e32 v135, v135, v252
	v_cvt_pk_bf16_f32 v246, v128, v129
	v_cvt_pk_bf16_f32 v247, v130, v131
	v_cvt_pk_bf16_f32 v248, v132, v133
	v_cvt_pk_bf16_f32 v249, v134, v135
	global_store_dwordx4 v5, v[246:249], s[58:59] nt
	v_add_u32_e32 v5, 0x800, v5
	v_lshlrev_b32_e32 v88, 16, v60
	v_and_b32_e32 v89, 0xffff0000, v60
	v_lshlrev_b32_e32 v90, 16, v61
	v_and_b32_e32 v91, 0xffff0000, v61
	v_lshlrev_b32_e32 v92, 16, v62
	v_and_b32_e32 v93, 0xffff0000, v62
	v_lshlrev_b32_e32 v94, 16, v63
	v_and_b32_e32 v95, 0xffff0000, v63
	v_mul_f32_e32 v128, v104, v96
	v_mul_f32_e32 v129, v105, v97
	v_mul_f32_e32 v130, v106, v98
	v_mul_f32_e32 v131, v107, v99
	v_mul_f32_e32 v132, v108, v100
	v_mul_f32_e32 v133, v109, v101
	v_mul_f32_e32 v134, v110, v102
	v_mul_f32_e32 v135, v111, v103
	v_fmac_f32_e32 v128, v112, v80
	v_fmac_f32_e32 v129, v113, v81
	v_fmac_f32_e32 v130, v114, v82
	v_fmac_f32_e32 v131, v115, v83
	v_fmac_f32_e32 v132, v116, v84
	v_fmac_f32_e32 v133, v117, v85
	v_fmac_f32_e32 v134, v118, v86
	v_fmac_f32_e32 v135, v119, v87
	v_fmac_f32_e32 v128, v120, v88
	v_fmac_f32_e32 v129, v121, v89
	v_fmac_f32_e32 v130, v122, v90
	v_fmac_f32_e32 v131, v123, v91
	v_fmac_f32_e32 v132, v124, v92
	v_fmac_f32_e32 v133, v125, v93
	v_fmac_f32_e32 v134, v126, v94
	v_fmac_f32_e32 v135, v127, v95
	v_mul_f32_e32 v136, 0xbfb8aa3b, v128
	v_mul_f32_e32 v137, 0xbfb8aa3b, v129
	v_mul_f32_e32 v138, 0xbfb8aa3b, v130
	v_mul_f32_e32 v139, 0xbfb8aa3b, v131
	v_mul_f32_e32 v140, 0xbfb8aa3b, v132
	v_mul_f32_e32 v141, 0xbfb8aa3b, v133
	v_mul_f32_e32 v142, 0xbfb8aa3b, v134
	v_mul_f32_e32 v143, 0xbfb8aa3b, v135
	v_exp_f32_e32 v136, v136
	v_exp_f32_e32 v137, v137
	v_exp_f32_e32 v138, v138
	v_exp_f32_e32 v139, v139
	v_exp_f32_e32 v140, v140
	v_exp_f32_e32 v141, v141
	v_exp_f32_e32 v142, v142
	v_exp_f32_e32 v143, v143
	v_add_f32_e32 v136, 1.0, v136
	v_add_f32_e32 v137, 1.0, v137
	v_add_f32_e32 v138, 1.0, v138
	v_add_f32_e32 v139, 1.0, v139
	v_add_f32_e32 v140, 1.0, v140
	v_add_f32_e32 v141, 1.0, v141
	v_add_f32_e32 v142, 1.0, v142
	v_add_f32_e32 v143, 1.0, v143
	v_rcp_f32_e32 v136, v136
	v_rcp_f32_e32 v137, v137
	v_rcp_f32_e32 v138, v138
	v_rcp_f32_e32 v139, v139
	v_rcp_f32_e32 v140, v140
	v_rcp_f32_e32 v141, v141
	v_rcp_f32_e32 v142, v142
	v_rcp_f32_e32 v143, v143
	v_mul_f32_e32 v128, v128, v136
	v_mul_f32_e32 v129, v129, v137
	v_mul_f32_e32 v130, v130, v138
	v_mul_f32_e32 v131, v131, v139
	v_mul_f32_e32 v132, v132, v140
	v_mul_f32_e32 v133, v133, v141
	v_mul_f32_e32 v134, v134, v142
	v_mul_f32_e32 v135, v135, v143
	v_mul_f32_e32 v128, v128, v252
	v_mul_f32_e32 v129, v129, v252
	v_mul_f32_e32 v130, v130, v252
	v_mul_f32_e32 v131, v131, v252
	v_mul_f32_e32 v132, v132, v252
	v_mul_f32_e32 v133, v133, v252
	v_mul_f32_e32 v134, v134, v252
	v_mul_f32_e32 v135, v135, v252
	v_cvt_pk_bf16_f32 v246, v128, v129
	v_cvt_pk_bf16_f32 v247, v130, v131
	v_cvt_pk_bf16_f32 v248, v132, v133
	v_cvt_pk_bf16_f32 v249, v134, v135
	global_store_dwordx4 v5, v[246:249], s[58:59] nt
	v_add_u32_e32 v5, 0x800, v5
	v_lshlrev_b32_e32 v96, 16, v64
	v_and_b32_e32 v97, 0xffff0000, v64
	v_lshlrev_b32_e32 v98, 16, v65
	v_and_b32_e32 v99, 0xffff0000, v65
	v_lshlrev_b32_e32 v100, 16, v66
	v_and_b32_e32 v101, 0xffff0000, v66
	v_lshlrev_b32_e32 v102, 16, v67
; __device__ __forceinline__ u32x4 pack8(const float (&f)[8]) { u32x4 o; o.x = pk2(f[0], f[1]); o.y = pk2(f[2], f[3]); o.z = pk2(f[4], f[5]); o.w = pk2(f[6], f[7]); return o; }
; __device__ __forceinline__ float siluf_(float x) { return x * __builtin_amdgcn_rcpf(1.0f + __expf(-x)); }
; template <int CH> __device__ __forceinline__ void p2_gla_chunk(const Params& p, int t0, int lane) {
;     ...
;         float o[8];
; #pragma unroll
;         for (int q = 0; q < 8; ++q) { const float y = w0[q] * P[q] + w1[q] * C[q] + w2[q] * N[q]; o[q] = siluf_(y) * sc; }
;         *(u32x4*)(GQKV + (size_t)t * 1024 + c) = pack8(o);
	v_and_b32_e32 v103, 0xffff0000, v67
	v_mul_f32_e32 v128, v104, v80
	v_mul_f32_e32 v129, v105, v81
	v_mul_f32_e32 v130, v106, v82
	v_mul_f32_e32 v131, v107, v83
	v_mul_f32_e32 v132, v108, v84
	v_mul_f32_e32 v133, v109, v85
	v_mul_f32_e32 v134, v110, v86
	v_mul_f32_e32 v135, v111, v87
	v_fmac_f32_e32 v128, v112, v88
	v_fmac_f32_e32 v129, v113, v89
	v_fmac_f32_e32 v130, v114, v90
	v_fmac_f32_e32 v131, v115, v91
	v_fmac_f32_e32 v132, v116, v92
	v_fmac_f32_e32 v133, v117, v93
	v_fmac_f32_e32 v134, v118, v94
	v_fmac_f32_e32 v135, v119, v95
	v_fmac_f32_e32 v128, v120, v96
	v_fmac_f32_e32 v129, v121, v97
	v_fmac_f32_e32 v130, v122, v98
	v_fmac_f32_e32 v131, v123, v99
	v_fmac_f32_e32 v132, v124, v100
	v_fmac_f32_e32 v133, v125, v101
	v_fmac_f32_e32 v134, v126, v102
	v_fmac_f32_e32 v135, v127, v103
	v_mul_f32_e32 v136, 0xbfb8aa3b, v128
	v_mul_f32_e32 v137, 0xbfb8aa3b, v129
	v_mul_f32_e32 v138, 0xbfb8aa3b, v130
	v_mul_f32_e32 v139, 0xbfb8aa3b, v131
	v_mul_f32_e32 v140, 0xbfb8aa3b, v132
	v_mul_f32_e32 v141, 0xbfb8aa3b, v133
	v_mul_f32_e32 v142, 0xbfb8aa3b, v134
	v_mul_f32_e32 v143, 0xbfb8aa3b, v135
	v_exp_f32_e32 v136, v136
	v_exp_f32_e32 v137, v137
	v_exp_f32_e32 v138, v138
	v_exp_f32_e32 v139, v139
	v_exp_f32_e32 v140, v140
	v_exp_f32_e32 v141, v141
	v_exp_f32_e32 v142, v142
	v_exp_f32_e32 v143, v143
	v_add_f32_e32 v136, 1.0, v136
	v_add_f32_e32 v137, 1.0, v137
	v_add_f32_e32 v138, 1.0, v138
	v_add_f32_e32 v139, 1.0, v139
	v_add_f32_e32 v140, 1.0, v140
	v_add_f32_e32 v141, 1.0, v141
	v_add_f32_e32 v142, 1.0, v142
	v_add_f32_e32 v143, 1.0, v143
	v_rcp_f32_e32 v136, v136
	v_rcp_f32_e32 v137, v137
	v_rcp_f32_e32 v138, v138
	v_rcp_f32_e32 v139, v139
	v_rcp_f32_e32 v140, v140
	v_rcp_f32_e32 v141, v141
	v_rcp_f32_e32 v142, v142
	v_rcp_f32_e32 v143, v143
	v_mul_f32_e32 v128, v128, v136
	v_mul_f32_e32 v129, v129, v137
	v_mul_f32_e32 v130, v130, v138
	v_mul_f32_e32 v131, v131, v139
	v_mul_f32_e32 v132, v132, v140
	v_mul_f32_e32 v133, v133, v141
	v_mul_f32_e32 v134, v134, v142
	v_mul_f32_e32 v135, v135, v143
	v_mul_f32_e32 v128, v128, v252
	v_mul_f32_e32 v129, v129, v252
	v_mul_f32_e32 v130, v130, v252
	v_mul_f32_e32 v131, v131, v252
	v_mul_f32_e32 v132, v132, v252
	v_mul_f32_e32 v133, v133, v252
	v_mul_f32_e32 v134, v134, v252
	v_mul_f32_e32 v135, v135, v252
	v_cvt_pk_bf16_f32 v246, v128, v129
	v_cvt_pk_bf16_f32 v247, v130, v131
	v_cvt_pk_bf16_f32 v248, v132, v133
	v_cvt_pk_bf16_f32 v249, v134, v135
	global_store_dwordx4 v5, v[246:249], s[58:59] nt
	v_add_u32_e32 v5, 0x800, v5
	v_lshlrev_b32_e32 v80, 16, v68
	v_and_b32_e32 v81, 0xffff0000, v68
	v_lshlrev_b32_e32 v82, 16, v69
	v_and_b32_e32 v83, 0xffff0000, v69
	v_lshlrev_b32_e32 v84, 16, v70
	v_and_b32_e32 v85, 0xffff0000, v70
	v_lshlrev_b32_e32 v86, 16, v71
	v_and_b32_e32 v87, 0xffff0000, v71
	v_mul_f32_e32 v128, v104, v88
	v_mul_f32_e32 v129, v105, v89
	v_mul_f32_e32 v130, v106, v90
	v_mul_f32_e32 v131, v107, v91
	v_mul_f32_e32 v132, v108, v92
	v_mul_f32_e32 v133, v109, v93
	v_mul_f32_e32 v134, v110, v94
	v_mul_f32_e32 v135, v111, v95
	v_fmac_f32_e32 v128, v112, v96
	v_fmac_f32_e32 v129, v113, v97
	v_fmac_f32_e32 v130, v114, v98
	v_fmac_f32_e32 v131, v115, v99
	v_fmac_f32_e32 v132, v116, v100
	v_fmac_f32_e32 v133, v117, v101
	v_fmac_f32_e32 v134, v118, v102
	v_fmac_f32_e32 v135, v119, v103
	v_fmac_f32_e32 v128, v120, v80
	v_fmac_f32_e32 v129, v121, v81
	v_fmac_f32_e32 v130, v122, v82
	v_fmac_f32_e32 v131, v123, v83
	v_fmac_f32_e32 v132, v124, v84
	v_fmac_f32_e32 v133, v125, v85
	v_fmac_f32_e32 v134, v126, v86
	v_fmac_f32_e32 v135, v127, v87
	v_mul_f32_e32 v136, 0xbfb8aa3b, v128
	v_mul_f32_e32 v137, 0xbfb8aa3b, v129
	v_mul_f32_e32 v138, 0xbfb8aa3b, v130
	v_mul_f32_e32 v139, 0xbfb8aa3b, v131
	v_mul_f32_e32 v140, 0xbfb8aa3b, v132
	v_mul_f32_e32 v141, 0xbfb8aa3b, v133
	v_mul_f32_e32 v142, 0xbfb8aa3b, v134
	v_mul_f32_e32 v143, 0xbfb8aa3b, v135
	v_exp_f32_e32 v136, v136
	v_exp_f32_e32 v137, v137
	v_exp_f32_e32 v138, v138
	v_exp_f32_e32 v139, v139
	v_exp_f32_e32 v140, v140
	v_exp_f32_e32 v141, v141
	v_exp_f32_e32 v142, v142
	v_exp_f32_e32 v143, v143
	v_add_f32_e32 v136, 1.0, v136
	v_add_f32_e32 v137, 1.0, v137
	v_add_f32_e32 v138, 1.0, v138
	v_add_f32_e32 v139, 1.0, v139
	v_add_f32_e32 v140, 1.0, v140
	v_add_f32_e32 v141, 1.0, v141
	v_add_f32_e32 v142, 1.0, v142
	v_add_f32_e32 v143, 1.0, v143
	v_rcp_f32_e32 v136, v136
	v_rcp_f32_e32 v137, v137
	v_rcp_f32_e32 v138, v138
	v_rcp_f32_e32 v139, v139
	v_rcp_f32_e32 v140, v140
	v_rcp_f32_e32 v141, v141
	v_rcp_f32_e32 v142, v142
	v_rcp_f32_e32 v143, v143
	v_mul_f32_e32 v128, v128, v136
	v_mul_f32_e32 v129, v129, v137
	v_mul_f32_e32 v130, v130, v138
	v_mul_f32_e32 v131, v131, v139
	v_mul_f32_e32 v132, v132, v140
	v_mul_f32_e32 v133, v133, v141
	v_mul_f32_e32 v134, v134, v142
	v_mul_f32_e32 v135, v135, v143
	v_mul_f32_e32 v128, v128, v252
	v_mul_f32_e32 v129, v129, v252
	v_mul_f32_e32 v130, v130, v252
	v_mul_f32_e32 v131, v131, v252
	v_mul_f32_e32 v132, v132, v252
	v_mul_f32_e32 v133, v133, v252
	v_mul_f32_e32 v134, v134, v252
	v_mul_f32_e32 v135, v135, v252
	v_cvt_pk_bf16_f32 v246, v128, v129
	v_cvt_pk_bf16_f32 v247, v130, v131
	v_cvt_pk_bf16_f32 v248, v132, v133
	v_cvt_pk_bf16_f32 v249, v134, v135
	global_store_dwordx4 v5, v[246:249], s[58:59] nt
	v_add_u32_e32 v5, 0x800, v5
	v_lshlrev_b32_e32 v88, 16, v72
	v_and_b32_e32 v89, 0xffff0000, v72
	v_lshlrev_b32_e32 v90, 16, v73
	v_and_b32_e32 v91, 0xffff0000, v73
	v_lshlrev_b32_e32 v92, 16, v74
	v_and_b32_e32 v93, 0xffff0000, v74
	v_lshlrev_b32_e32 v94, 16, v75
	v_and_b32_e32 v95, 0xffff0000, v75
	v_mul_f32_e32 v128, v104, v96
	v_mul_f32_e32 v129, v105, v97
	v_mul_f32_e32 v130, v106, v98
	v_mul_f32_e32 v131, v107, v99
; __device__ __forceinline__ void unpack8(const u32x4 w, float (&f)[8]) { f[0] = bflo(w.x); f[1] = bfhi(w.x); f[2] = bflo(w.y); f[3] = bfhi(w.y); f[4] = bflo(w.z); f[5] = bfhi(w.z); f[6] = bflo(w.w); f[7] = bfhi(w.w); }
; __device__ __forceinline__ u32x4 pack8(const float (&f)[8]) { u32x4 o; o.x = pk2(f[0], f[1]); o.y = pk2(f[2], f[3]); o.z = pk2(f[4], f[5]); o.w = pk2(f[6], f[7]); return o; }
; __device__ __forceinline__ float siluf_(float x) { return x * __builtin_amdgcn_rcpf(1.0f + __expf(-x)); }
; template <int CH> __device__ __forceinline__ void p2_gla_chunk(const Params& p, int t0, int lane) {
;     ...
;     const int c = (lane + 64 * CH) * 8; const float sc = c < 256 ? 0.125f : 1.0f;
;     bf16_t* GQKV = (bf16_t*)(ws + WS_GQKV);
;     const bf16_t* zc = (const bf16_t*)(ws + WS_Z) + (size_t)t0 * ZLD + NRW + c;
;     float w0[8], w1[8], w2[8];
; #pragma unroll
;     for (int h = 0; h < 2; ++h) { const f32x4 a = *(const f32x4*)(p.in[19] + c + 4 * h), b = *(const f32x4*)(p.in[19] + 1024 + c + 4 * h), d = *(const f32x4*)(p.in[19] + 2048 + c + 4 * h);
; #pragma unroll
;         for (int i = 0; i < 4; ++i) { w0[4 * h + i] = a[i]; w1[4 * h + i] = b[i]; w2[4 * h + i] = d[i]; } }
;     float P[8], C[8], N[8];
;     if ((t0 & (T_SEQ - 1)) != 0) unpack8(__builtin_nontemporal_load((const u32x4*)(zc - ZLD)), P); else {
; #pragma unroll
;         for (int i = 0; i < 8; ++i) P[i] = 0.f; }
;     unpack8(__builtin_nontemporal_load((const u32x4*)(zc)), C);
;     u32x4 raw = __builtin_nontemporal_load((const u32x4*)(zc + ZLD));
;     ...
;         float o[8];
; #pragma unroll
;         for (int q = 0; q < 8; ++q) { const float y = w0[q] * P[q] + w1[q] * C[q] + w2[q] * N[q]; o[q] = siluf_(y) * sc; }
;         *(u32x4*)(GQKV + (size_t)t * 1024 + c) = pack8(o);
	v_mul_f32_e32 v132, v108, v100
	v_mul_f32_e32 v133, v109, v101
	v_mul_f32_e32 v134, v110, v102
	v_mul_f32_e32 v135, v111, v103
	v_fmac_f32_e32 v128, v112, v80
	v_fmac_f32_e32 v129, v113, v81
	v_fmac_f32_e32 v130, v114, v82
	v_fmac_f32_e32 v131, v115, v83
	v_fmac_f32_e32 v132, v116, v84
	v_fmac_f32_e32 v133, v117, v85
	v_fmac_f32_e32 v134, v118, v86
	v_fmac_f32_e32 v135, v119, v87
	v_fmac_f32_e32 v128, v120, v88
	v_fmac_f32_e32 v129, v121, v89
	v_fmac_f32_e32 v130, v122, v90
	v_fmac_f32_e32 v131, v123, v91
	v_fmac_f32_e32 v132, v124, v92
	v_fmac_f32_e32 v133, v125, v93
	v_fmac_f32_e32 v134, v126, v94
	v_fmac_f32_e32 v135, v127, v95
	v_mul_f32_e32 v136, 0xbfb8aa3b, v128
	v_mul_f32_e32 v137, 0xbfb8aa3b, v129
	v_mul_f32_e32 v138, 0xbfb8aa3b, v130
	v_mul_f32_e32 v139, 0xbfb8aa3b, v131
	v_mul_f32_e32 v140, 0xbfb8aa3b, v132
	v_mul_f32_e32 v141, 0xbfb8aa3b, v133
	v_mul_f32_e32 v142, 0xbfb8aa3b, v134
	v_mul_f32_e32 v143, 0xbfb8aa3b, v135
	v_exp_f32_e32 v136, v136
	v_exp_f32_e32 v137, v137
	v_exp_f32_e32 v138, v138
	v_exp_f32_e32 v139, v139
	v_exp_f32_e32 v140, v140
	v_exp_f32_e32 v141, v141
	v_exp_f32_e32 v142, v142
	v_exp_f32_e32 v143, v143
	v_add_f32_e32 v136, 1.0, v136
	v_add_f32_e32 v137, 1.0, v137
	v_add_f32_e32 v138, 1.0, v138
	v_add_f32_e32 v139, 1.0, v139
	v_add_f32_e32 v140, 1.0, v140
	v_add_f32_e32 v141, 1.0, v141
	v_add_f32_e32 v142, 1.0, v142
	v_add_f32_e32 v143, 1.0, v143
	v_rcp_f32_e32 v136, v136
	v_rcp_f32_e32 v137, v137
	v_rcp_f32_e32 v138, v138
	v_rcp_f32_e32 v139, v139
	v_rcp_f32_e32 v140, v140
	v_rcp_f32_e32 v141, v141
	v_rcp_f32_e32 v142, v142
	v_rcp_f32_e32 v143, v143
	v_mul_f32_e32 v128, v128, v136
	v_mul_f32_e32 v129, v129, v137
	v_mul_f32_e32 v130, v130, v138
	v_mul_f32_e32 v131, v131, v139
	v_mul_f32_e32 v132, v132, v140
	v_mul_f32_e32 v133, v133, v141
	v_mul_f32_e32 v134, v134, v142
	v_mul_f32_e32 v135, v135, v143
	v_mul_f32_e32 v128, v128, v252
	v_mul_f32_e32 v129, v129, v252
	v_mul_f32_e32 v130, v130, v252
	v_mul_f32_e32 v131, v131, v252
	v_mul_f32_e32 v132, v132, v252
	v_mul_f32_e32 v133, v133, v252
	v_mul_f32_e32 v134, v134, v252
	v_mul_f32_e32 v135, v135, v252
	v_cvt_pk_bf16_f32 v246, v128, v129
	v_cvt_pk_bf16_f32 v247, v130, v131
	v_cvt_pk_bf16_f32 v248, v132, v133
	v_cvt_pk_bf16_f32 v249, v134, v135
	global_store_dwordx4 v5, v[246:249], s[58:59] nt
	v_add_u32_e32 v5, 0x800, v5
	s_cmp_eq_u32 s67, 0
	s_cbranch_scc1 .Lp2_nz_12
	v_mov_b32_e32 v76, 0
	v_mov_b32_e32 v77, 0
	v_mov_b32_e32 v78, 0
	v_mov_b32_e32 v79, 0
.Lp2_nz_12:
	v_lshlrev_b32_e32 v96, 16, v76
	v_and_b32_e32 v97, 0xffff0000, v76
	v_lshlrev_b32_e32 v98, 16, v77
	v_and_b32_e32 v99, 0xffff0000, v77
	v_lshlrev_b32_e32 v100, 16, v78
	v_and_b32_e32 v101, 0xffff0000, v78
	v_lshlrev_b32_e32 v102, 16, v79
	v_and_b32_e32 v103, 0xffff0000, v79
	v_mul_f32_e32 v128, v104, v80
	v_mul_f32_e32 v129, v105, v81
	v_mul_f32_e32 v130, v106, v82
	v_mul_f32_e32 v131, v107, v83
	v_mul_f32_e32 v132, v108, v84
	v_mul_f32_e32 v133, v109, v85
	v_mul_f32_e32 v134, v110, v86
	v_mul_f32_e32 v135, v111, v87
	v_fmac_f32_e32 v128, v112, v88
	v_fmac_f32_e32 v129, v113, v89
	v_fmac_f32_e32 v130, v114, v90
	v_fmac_f32_e32 v131, v115, v91
	v_fmac_f32_e32 v132, v116, v92
	v_fmac_f32_e32 v133, v117, v93
	v_fmac_f32_e32 v134, v118, v94
	v_fmac_f32_e32 v135, v119, v95
	v_fmac_f32_e32 v128, v120, v96
	v_fmac_f32_e32 v129, v121, v97
	v_fmac_f32_e32 v130, v122, v98
	v_fmac_f32_e32 v131, v123, v99
	v_fmac_f32_e32 v132, v124, v100
	v_fmac_f32_e32 v133, v125, v101
	v_fmac_f32_e32 v134, v126, v102
	v_fmac_f32_e32 v135, v127, v103
	v_mul_f32_e32 v136, 0xbfb8aa3b, v128
	v_mul_f32_e32 v137, 0xbfb8aa3b, v129
	v_mul_f32_e32 v138, 0xbfb8aa3b, v130
	v_mul_f32_e32 v139, 0xbfb8aa3b, v131
	v_mul_f32_e32 v140, 0xbfb8aa3b, v132
	v_mul_f32_e32 v141, 0xbfb8aa3b, v133
	v_mul_f32_e32 v142, 0xbfb8aa3b, v134
	v_mul_f32_e32 v143, 0xbfb8aa3b, v135
	v_exp_f32_e32 v136, v136
	v_exp_f32_e32 v137, v137
	v_exp_f32_e32 v138, v138
	v_exp_f32_e32 v139, v139
	v_exp_f32_e32 v140, v140
	v_exp_f32_e32 v141, v141
	v_exp_f32_e32 v142, v142
	v_exp_f32_e32 v143, v143
	v_add_f32_e32 v136, 1.0, v136
	v_add_f32_e32 v137, 1.0, v137
	v_add_f32_e32 v138, 1.0, v138
	v_add_f32_e32 v139, 1.0, v139
	v_add_f32_e32 v140, 1.0, v140
	v_add_f32_e32 v141, 1.0, v141
	v_add_f32_e32 v142, 1.0, v142
	v_add_f32_e32 v143, 1.0, v143
	v_rcp_f32_e32 v136, v136
	v_rcp_f32_e32 v137, v137
	v_rcp_f32_e32 v138, v138
	v_rcp_f32_e32 v139, v139
	v_rcp_f32_e32 v140, v140
	v_rcp_f32_e32 v141, v141
	v_rcp_f32_e32 v142, v142
	v_rcp_f32_e32 v143, v143
	v_mul_f32_e32 v128, v128, v136
	v_mul_f32_e32 v129, v129, v137
	v_mul_f32_e32 v130, v130, v138
	v_mul_f32_e32 v131, v131, v139
	v_mul_f32_e32 v132, v132, v140
	v_mul_f32_e32 v133, v133, v141
	v_mul_f32_e32 v134, v134, v142
	v_mul_f32_e32 v135, v135, v143
	v_mul_f32_e32 v128, v128, v252
	v_mul_f32_e32 v129, v129, v252
	v_mul_f32_e32 v130, v130, v252
	v_mul_f32_e32 v131, v131, v252
	v_mul_f32_e32 v132, v132, v252
	v_mul_f32_e32 v133, v133, v252
	v_mul_f32_e32 v134, v134, v252
	v_mul_f32_e32 v135, v135, v252
	v_cvt_pk_bf16_f32 v246, v128, v129
	v_cvt_pk_bf16_f32 v247, v130, v131
	v_cvt_pk_bf16_f32 v248, v132, v133
	v_cvt_pk_bf16_f32 v249, v134, v135
	global_store_dwordx4 v5, v[246:249], s[58:59] nt
	v_add_u32_e32 v5, 0x800, v5
	v_readlane_b32 s26, v254, 27
	v_readlane_b32 s27, v254, 28
	v_lshlrev_b32_e32 v1, 5, v0
	v_add_u32_e32 v1, 0x800, v1
	s_nop 3
	global_load_dwordx4 v[104:107], v1, s[26:27]
	global_load_dwordx4 v[108:111], v1, s[26:27] offset:16
	v_add_u32_e32 v1, 0x1000, v1
	global_load_dwordx4 v[112:115], v1, s[26:27]
	global_load_dwordx4 v[116:119], v1, s[26:27] offset:16
	v_add_u32_e32 v1, 0x1000, v1
	global_load_dwordx4 v[120:123], v1, s[26:27]
	global_load_dwordx4 v[124:127], v1, s[26:27] offset:16
	s_mul_i32 s63, s62, 0x800
	s_add_u32 s63, s63, 0x1b000400
	v_lshl_add_u32 v5, v0, 4, s63
	s_waitcnt vmcnt(0)
	s_cmp_eq_u32 s66, 0
	s_cbranch_scc1 .Lp2_nz_13
	v_mov_b32_e32 v168, 0
	v_mov_b32_e32 v169, 0
	v_mov_b32_e32 v170, 0
	v_mov_b32_e32 v171, 0
; __device__ __forceinline__ void unpack8(const u32x4 w, float (&f)[8]) { f[0] = bflo(w.x); f[1] = bfhi(w.x); f[2] = bflo(w.y); f[3] = bfhi(w.y); f[4] = bflo(w.z); f[5] = bfhi(w.z); f[6] = bflo(w.w); f[7] = bfhi(w.w); }
; __device__ __forceinline__ u32x4 pack8(const float (&f)[8]) { u32x4 o; o.x = pk2(f[0], f[1]); o.y = pk2(f[2], f[3]); o.z = pk2(f[4], f[5]); o.w = pk2(f[6], f[7]); return o; }
; __device__ __forceinline__ float siluf_(float x) { return x * __builtin_amdgcn_rcpf(1.0f + __expf(-x)); }
; template <int CH> __device__ __forceinline__ void p2_gla_chunk(const Params& p, int t0, int lane) {
;     ...
;     for (int i = 0; i < 16; ++i) {
;         const int t = t0 + i; const bool hasn = (t & (T_SEQ - 1)) != T_SEQ - 1;
;         if (hasn) unpack8(raw, N); else {
; #pragma unroll
;             for (int q = 0; q < 8; ++q) N[q] = 0.f; }
;         if (i < 15 && ((t + 1) & (T_SEQ - 1)) != T_SEQ - 1) raw = __builtin_nontemporal_load((const u32x4*)(zc + (size_t)(i + 2) * ZLD));
;         float o[8];
; #pragma unroll
;         for (int q = 0; q < 8; ++q) { const float y = w0[q] * P[q] + w1[q] * C[q] + w2[q] * N[q]; o[q] = siluf_(y) * sc; }
;         *(u32x4*)(GQKV + (size_t)t * 1024 + c) = pack8(o);
; #pragma unroll
;         for (int q = 0; q < 8; ++q) { P[q] = C[q]; C[q] = N[q]; }
;     }
.Lp2_nz_13:
	v_lshlrev_b32_e32 v80, 16, v168
	v_and_b32_e32 v81, 0xffff0000, v168
	v_lshlrev_b32_e32 v82, 16, v169
	v_and_b32_e32 v83, 0xffff0000, v169
	v_lshlrev_b32_e32 v84, 16, v170
	v_and_b32_e32 v85, 0xffff0000, v170
	v_lshlrev_b32_e32 v86, 16, v171
	v_and_b32_e32 v87, 0xffff0000, v171
	v_lshlrev_b32_e32 v88, 16, v172
	v_and_b32_e32 v89, 0xffff0000, v172
	v_lshlrev_b32_e32 v90, 16, v173
	v_and_b32_e32 v91, 0xffff0000, v173
	v_lshlrev_b32_e32 v92, 16, v174
	v_and_b32_e32 v93, 0xffff0000, v174
	v_lshlrev_b32_e32 v94, 16, v175
	v_and_b32_e32 v95, 0xffff0000, v175
	v_lshlrev_b32_e32 v96, 16, v176
	v_and_b32_e32 v97, 0xffff0000, v176
	v_lshlrev_b32_e32 v98, 16, v177
	v_and_b32_e32 v99, 0xffff0000, v177
	v_lshlrev_b32_e32 v100, 16, v178
	v_and_b32_e32 v101, 0xffff0000, v178
	v_lshlrev_b32_e32 v102, 16, v179
	v_and_b32_e32 v103, 0xffff0000, v179
	v_mul_f32_e32 v128, v104, v80
	v_mul_f32_e32 v129, v105, v81
	v_mul_f32_e32 v130, v106, v82
	v_mul_f32_e32 v131, v107, v83
	v_mul_f32_e32 v132, v108, v84
	v_mul_f32_e32 v133, v109, v85
	v_mul_f32_e32 v134, v110, v86
	v_mul_f32_e32 v135, v111, v87
	v_fmac_f32_e32 v128, v112, v88
	v_fmac_f32_e32 v129, v113, v89
	v_fmac_f32_e32 v130, v114, v90
	v_fmac_f32_e32 v131, v115, v91
	v_fmac_f32_e32 v132, v116, v92
	v_fmac_f32_e32 v133, v117, v93
	v_fmac_f32_e32 v134, v118, v94
	v_fmac_f32_e32 v135, v119, v95
	v_fmac_f32_e32 v128, v120, v96
	v_fmac_f32_e32 v129, v121, v97
	v_fmac_f32_e32 v130, v122, v98
	v_fmac_f32_e32 v131, v123, v99
	v_fmac_f32_e32 v132, v124, v100
	v_fmac_f32_e32 v133, v125, v101
	v_fmac_f32_e32 v134, v126, v102
	v_fmac_f32_e32 v135, v127, v103
	v_mul_f32_e32 v136, 0xbfb8aa3b, v128
	v_mul_f32_e32 v137, 0xbfb8aa3b, v129
	v_mul_f32_e32 v138, 0xbfb8aa3b, v130
	v_mul_f32_e32 v139, 0xbfb8aa3b, v131
	v_mul_f32_e32 v140, 0xbfb8aa3b, v132
	v_mul_f32_e32 v141, 0xbfb8aa3b, v133
	v_mul_f32_e32 v142, 0xbfb8aa3b, v134
	v_mul_f32_e32 v143, 0xbfb8aa3b, v135
	v_exp_f32_e32 v136, v136
	v_exp_f32_e32 v137, v137
	v_exp_f32_e32 v138, v138
	v_exp_f32_e32 v139, v139
	v_exp_f32_e32 v140, v140
	v_exp_f32_e32 v141, v141
	v_exp_f32_e32 v142, v142
	v_exp_f32_e32 v143, v143
	v_add_f32_e32 v136, 1.0, v136
	v_add_f32_e32 v137, 1.0, v137
	v_add_f32_e32 v138, 1.0, v138
	v_add_f32_e32 v139, 1.0, v139
	v_add_f32_e32 v140, 1.0, v140
	v_add_f32_e32 v141, 1.0, v141
	v_add_f32_e32 v142, 1.0, v142
	v_add_f32_e32 v143, 1.0, v143
	v_rcp_f32_e32 v136, v136
	v_rcp_f32_e32 v137, v137
	v_rcp_f32_e32 v138, v138
	v_rcp_f32_e32 v139, v139
	v_rcp_f32_e32 v140, v140
	v_rcp_f32_e32 v141, v141
	v_rcp_f32_e32 v142, v142
	v_rcp_f32_e32 v143, v143
	v_mul_f32_e32 v128, v128, v136
	v_mul_f32_e32 v129, v129, v137
	v_mul_f32_e32 v130, v130, v138
	v_mul_f32_e32 v131, v131, v139
	v_mul_f32_e32 v132, v132, v140
	v_mul_f32_e32 v133, v133, v141
	v_mul_f32_e32 v134, v134, v142
	v_mul_f32_e32 v135, v135, v143
	v_cvt_pk_bf16_f32 v246, v128, v129
	v_cvt_pk_bf16_f32 v247, v130, v131
	v_cvt_pk_bf16_f32 v248, v132, v133
	v_cvt_pk_bf16_f32 v249, v134, v135
	global_store_dwordx4 v5, v[246:249], s[58:59] nt
	v_add_u32_e32 v5, 0x800, v5
	v_lshlrev_b32_e32 v80, 16, v180
	v_and_b32_e32 v81, 0xffff0000, v180
	v_lshlrev_b32_e32 v82, 16, v181
	v_and_b32_e32 v83, 0xffff0000, v181
	v_lshlrev_b32_e32 v84, 16, v182
	v_and_b32_e32 v85, 0xffff0000, v182
	v_lshlrev_b32_e32 v86, 16, v183
	v_and_b32_e32 v87, 0xffff0000, v183
	v_mul_f32_e32 v128, v104, v88
	v_mul_f32_e32 v129, v105, v89
	v_mul_f32_e32 v130, v106, v90
	v_mul_f32_e32 v131, v107, v91
	v_mul_f32_e32 v132, v108, v92
	v_mul_f32_e32 v133, v109, v93
	v_mul_f32_e32 v134, v110, v94
	v_mul_f32_e32 v135, v111, v95
	v_fmac_f32_e32 v128, v112, v96
	v_fmac_f32_e32 v129, v113, v97
	v_fmac_f32_e32 v130, v114, v98
	v_fmac_f32_e32 v131, v115, v99
	v_fmac_f32_e32 v132, v116, v100
	v_fmac_f32_e32 v133, v117, v101
	v_fmac_f32_e32 v134, v118, v102
	v_fmac_f32_e32 v135, v119, v103
	v_fmac_f32_e32 v128, v120, v80
	v_fmac_f32_e32 v129, v121, v81
	v_fmac_f32_e32 v130, v122, v82
	v_fmac_f32_e32 v131, v123, v83
	v_fmac_f32_e32 v132, v124, v84
	v_fmac_f32_e32 v133, v125, v85
	v_fmac_f32_e32 v134, v126, v86
	v_fmac_f32_e32 v135, v127, v87
	v_mul_f32_e32 v136, 0xbfb8aa3b, v128
	v_mul_f32_e32 v137, 0xbfb8aa3b, v129
	v_mul_f32_e32 v138, 0xbfb8aa3b, v130
	v_mul_f32_e32 v139, 0xbfb8aa3b, v131
	v_mul_f32_e32 v140, 0xbfb8aa3b, v132
	v_mul_f32_e32 v141, 0xbfb8aa3b, v133
	v_mul_f32_e32 v142, 0xbfb8aa3b, v134
	v_mul_f32_e32 v143, 0xbfb8aa3b, v135
	v_exp_f32_e32 v136, v136
	v_exp_f32_e32 v137, v137
	v_exp_f32_e32 v138, v138
	v_exp_f32_e32 v139, v139
	v_exp_f32_e32 v140, v140
	v_exp_f32_e32 v141, v141
	v_exp_f32_e32 v142, v142
	v_exp_f32_e32 v143, v143
	v_add_f32_e32 v136, 1.0, v136
	v_add_f32_e32 v137, 1.0, v137
	v_add_f32_e32 v138, 1.0, v138
	v_add_f32_e32 v139, 1.0, v139
	v_add_f32_e32 v140, 1.0, v140
	v_add_f32_e32 v141, 1.0, v141
	v_add_f32_e32 v142, 1.0, v142
	v_add_f32_e32 v143, 1.0, v143
	v_rcp_f32_e32 v136, v136
	v_rcp_f32_e32 v137, v137
	v_rcp_f32_e32 v138, v138
	v_rcp_f32_e32 v139, v139
	v_rcp_f32_e32 v140, v140
	v_rcp_f32_e32 v141, v141
	v_rcp_f32_e32 v142, v142
	v_rcp_f32_e32 v143, v143
	v_mul_f32_e32 v128, v128, v136
	v_mul_f32_e32 v129, v129, v137
	v_mul_f32_e32 v130, v130, v138
	v_mul_f32_e32 v131, v131, v139
	v_mul_f32_e32 v132, v132, v140
	v_mul_f32_e32 v133, v133, v141
	v_mul_f32_e32 v134, v134, v142
	v_mul_f32_e32 v135, v135, v143
	v_cvt_pk_bf16_f32 v246, v128, v129
	v_cvt_pk_bf16_f32 v247, v130, v131
	v_cvt_pk_bf16_f32 v248, v132, v133
	v_cvt_pk_bf16_f32 v249, v134, v135
	global_store_dwordx4 v5, v[246:249], s[58:59] nt
	v_add_u32_e32 v5, 0x800, v5
	v_lshlrev_b32_e32 v88, 16, v184
	v_and_b32_e32 v89, 0xffff0000, v184
; __device__ __forceinline__ void unpack8(const u32x4 w, float (&f)[8]) { f[0] = bflo(w.x); f[1] = bfhi(w.x); f[2] = bflo(w.y); f[3] = bfhi(w.y); f[4] = bflo(w.z); f[5] = bfhi(w.z); f[6] = bflo(w.w); f[7] = bfhi(w.w); }
; __device__ __forceinline__ u32x4 pack8(const float (&f)[8]) { u32x4 o; o.x = pk2(f[0], f[1]); o.y = pk2(f[2], f[3]); o.z = pk2(f[4], f[5]); o.w = pk2(f[6], f[7]); return o; }
; __device__ __forceinline__ float siluf_(float x) { return x * __builtin_amdgcn_rcpf(1.0f + __expf(-x)); }
; template <int CH> __device__ __forceinline__ void p2_gla_chunk(const Params& p, int t0, int lane) {
;     ...
;     for (int i = 0; i < 16; ++i) {
;         const int t = t0 + i; const bool hasn = (t & (T_SEQ - 1)) != T_SEQ - 1;
;         if (hasn) unpack8(raw, N); else {
; #pragma unroll
;             for (int q = 0; q < 8; ++q) N[q] = 0.f; }
;         if (i < 15 && ((t + 1) & (T_SEQ - 1)) != T_SEQ - 1) raw = __builtin_nontemporal_load((const u32x4*)(zc + (size_t)(i + 2) * ZLD));
;         float o[8];
; #pragma unroll
;         for (int q = 0; q < 8; ++q) { const float y = w0[q] * P[q] + w1[q] * C[q] + w2[q] * N[q]; o[q] = siluf_(y) * sc; }
;         *(u32x4*)(GQKV + (size_t)t * 1024 + c) = pack8(o);
; #pragma unroll
;         for (int q = 0; q < 8; ++q) { P[q] = C[q]; C[q] = N[q]; }
;     }
	v_lshlrev_b32_e32 v90, 16, v185
	v_and_b32_e32 v91, 0xffff0000, v185
	v_lshlrev_b32_e32 v92, 16, v186
	v_and_b32_e32 v93, 0xffff0000, v186
	v_lshlrev_b32_e32 v94, 16, v187
	v_and_b32_e32 v95, 0xffff0000, v187
	v_mul_f32_e32 v128, v104, v96
	v_mul_f32_e32 v129, v105, v97
	v_mul_f32_e32 v130, v106, v98
	v_mul_f32_e32 v131, v107, v99
	v_mul_f32_e32 v132, v108, v100
	v_mul_f32_e32 v133, v109, v101
	v_mul_f32_e32 v134, v110, v102
	v_mul_f32_e32 v135, v111, v103
	v_fmac_f32_e32 v128, v112, v80
	v_fmac_f32_e32 v129, v113, v81
	v_fmac_f32_e32 v130, v114, v82
	v_fmac_f32_e32 v131, v115, v83
	v_fmac_f32_e32 v132, v116, v84
	v_fmac_f32_e32 v133, v117, v85
	v_fmac_f32_e32 v134, v118, v86
	v_fmac_f32_e32 v135, v119, v87
	v_fmac_f32_e32 v128, v120, v88
	v_fmac_f32_e32 v129, v121, v89
	v_fmac_f32_e32 v130, v122, v90
	v_fmac_f32_e32 v131, v123, v91
	v_fmac_f32_e32 v132, v124, v92
	v_fmac_f32_e32 v133, v125, v93
	v_fmac_f32_e32 v134, v126, v94
	v_fmac_f32_e32 v135, v127, v95
	v_mul_f32_e32 v136, 0xbfb8aa3b, v128
	v_mul_f32_e32 v137, 0xbfb8aa3b, v129
	v_mul_f32_e32 v138, 0xbfb8aa3b, v130
	v_mul_f32_e32 v139, 0xbfb8aa3b, v131
	v_mul_f32_e32 v140, 0xbfb8aa3b, v132
	v_mul_f32_e32 v141, 0xbfb8aa3b, v133
	v_mul_f32_e32 v142, 0xbfb8aa3b, v134
	v_mul_f32_e32 v143, 0xbfb8aa3b, v135
	v_exp_f32_e32 v136, v136
	v_exp_f32_e32 v137, v137
	v_exp_f32_e32 v138, v138
	v_exp_f32_e32 v139, v139
	v_exp_f32_e32 v140, v140
	v_exp_f32_e32 v141, v141
	v_exp_f32_e32 v142, v142
	v_exp_f32_e32 v143, v143
	v_add_f32_e32 v136, 1.0, v136
	v_add_f32_e32 v137, 1.0, v137
	v_add_f32_e32 v138, 1.0, v138
	v_add_f32_e32 v139, 1.0, v139
	v_add_f32_e32 v140, 1.0, v140
	v_add_f32_e32 v141, 1.0, v141
	v_add_f32_e32 v142, 1.0, v142
	v_add_f32_e32 v143, 1.0, v143
	v_rcp_f32_e32 v136, v136
	v_rcp_f32_e32 v137, v137
	v_rcp_f32_e32 v138, v138
	v_rcp_f32_e32 v139, v139
	v_rcp_f32_e32 v140, v140
	v_rcp_f32_e32 v141, v141
	v_rcp_f32_e32 v142, v142
	v_rcp_f32_e32 v143, v143
	v_mul_f32_e32 v128, v128, v136
	v_mul_f32_e32 v129, v129, v137
	v_mul_f32_e32 v130, v130, v138
	v_mul_f32_e32 v131, v131, v139
	v_mul_f32_e32 v132, v132, v140
	v_mul_f32_e32 v133, v133, v141
	v_mul_f32_e32 v134, v134, v142
	v_mul_f32_e32 v135, v135, v143
	v_cvt_pk_bf16_f32 v246, v128, v129
	v_cvt_pk_bf16_f32 v247, v130, v131
	v_cvt_pk_bf16_f32 v248, v132, v133
	v_cvt_pk_bf16_f32 v249, v134, v135
	global_store_dwordx4 v5, v[246:249], s[58:59] nt
	v_add_u32_e32 v5, 0x800, v5
	v_lshlrev_b32_e32 v96, 16, v188
	v_and_b32_e32 v97, 0xffff0000, v188
	v_lshlrev_b32_e32 v98, 16, v189
	v_and_b32_e32 v99, 0xffff0000, v189
	v_lshlrev_b32_e32 v100, 16, v190
	v_and_b32_e32 v101, 0xffff0000, v190
	v_lshlrev_b32_e32 v102, 16, v191
	v_and_b32_e32 v103, 0xffff0000, v191
	v_mul_f32_e32 v128, v104, v80
	v_mul_f32_e32 v129, v105, v81
	v_mul_f32_e32 v130, v106, v82
	v_mul_f32_e32 v131, v107, v83
	v_mul_f32_e32 v132, v108, v84
	v_mul_f32_e32 v133, v109, v85
	v_mul_f32_e32 v134, v110, v86
	v_mul_f32_e32 v135, v111, v87
	v_fmac_f32_e32 v128, v112, v88
	v_fmac_f32_e32 v129, v113, v89
	v_fmac_f32_e32 v130, v114, v90
	v_fmac_f32_e32 v131, v115, v91
	v_fmac_f32_e32 v132, v116, v92
	v_fmac_f32_e32 v133, v117, v93
	v_fmac_f32_e32 v134, v118, v94
	v_fmac_f32_e32 v135, v119, v95
	v_fmac_f32_e32 v128, v120, v96
	v_fmac_f32_e32 v129, v121, v97
	v_fmac_f32_e32 v130, v122, v98
	v_fmac_f32_e32 v131, v123, v99
	v_fmac_f32_e32 v132, v124, v100
	v_fmac_f32_e32 v133, v125, v101
	v_fmac_f32_e32 v134, v126, v102
	v_fmac_f32_e32 v135, v127, v103
	v_mul_f32_e32 v136, 0xbfb8aa3b, v128
	v_mul_f32_e32 v137, 0xbfb8aa3b, v129
	v_mul_f32_e32 v138, 0xbfb8aa3b, v130
	v_mul_f32_e32 v139, 0xbfb8aa3b, v131
	v_mul_f32_e32 v140, 0xbfb8aa3b, v132
	v_mul_f32_e32 v141, 0xbfb8aa3b, v133
	v_mul_f32_e32 v142, 0xbfb8aa3b, v134
	v_mul_f32_e32 v143, 0xbfb8aa3b, v135
	v_exp_f32_e32 v136, v136
	v_exp_f32_e32 v137, v137
	v_exp_f32_e32 v138, v138
	v_exp_f32_e32 v139, v139
	v_exp_f32_e32 v140, v140
	v_exp_f32_e32 v141, v141
	v_exp_f32_e32 v142, v142
	v_exp_f32_e32 v143, v143
	v_add_f32_e32 v136, 1.0, v136
	v_add_f32_e32 v137, 1.0, v137
	v_add_f32_e32 v138, 1.0, v138
	v_add_f32_e32 v139, 1.0, v139
	v_add_f32_e32 v140, 1.0, v140
	v_add_f32_e32 v141, 1.0, v141
	v_add_f32_e32 v142, 1.0, v142
	v_add_f32_e32 v143, 1.0, v143
	v_rcp_f32_e32 v136, v136
	v_rcp_f32_e32 v137, v137
	v_rcp_f32_e32 v138, v138
	v_rcp_f32_e32 v139, v139
	v_rcp_f32_e32 v140, v140
	v_rcp_f32_e32 v141, v141
	v_rcp_f32_e32 v142, v142
	v_rcp_f32_e32 v143, v143
	v_mul_f32_e32 v128, v128, v136
	v_mul_f32_e32 v129, v129, v137
	v_mul_f32_e32 v130, v130, v138
	v_mul_f32_e32 v131, v131, v139
	v_mul_f32_e32 v132, v132, v140
	v_mul_f32_e32 v133, v133, v141
	v_mul_f32_e32 v134, v134, v142
	v_mul_f32_e32 v135, v135, v143
	v_cvt_pk_bf16_f32 v246, v128, v129
	v_cvt_pk_bf16_f32 v247, v130, v131
	v_cvt_pk_bf16_f32 v248, v132, v133
	v_cvt_pk_bf16_f32 v249, v134, v135
	global_store_dwordx4 v5, v[246:249], s[58:59] nt
	v_add_u32_e32 v5, 0x800, v5
	v_lshlrev_b32_e32 v80, 16, v192
	v_and_b32_e32 v81, 0xffff0000, v192
	v_lshlrev_b32_e32 v82, 16, v193
	v_and_b32_e32 v83, 0xffff0000, v193
	v_lshlrev_b32_e32 v84, 16, v194
	v_and_b32_e32 v85, 0xffff0000, v194
	v_lshlrev_b32_e32 v86, 16, v195
	v_and_b32_e32 v87, 0xffff0000, v195
	v_mul_f32_e32 v128, v104, v88
	v_mul_f32_e32 v129, v105, v89
	v_mul_f32_e32 v130, v106, v90
	v_mul_f32_e32 v131, v107, v91
	v_mul_f32_e32 v132, v108, v92
	v_mul_f32_e32 v133, v109, v93
	v_mul_f32_e32 v134, v110, v94
	v_mul_f32_e32 v135, v111, v95
	v_fmac_f32_e32 v128, v112, v96
	v_fmac_f32_e32 v129, v113, v97
	v_fmac_f32_e32 v130, v114, v98
	v_fmac_f32_e32 v131, v115, v99
	v_fmac_f32_e32 v132, v116, v100
	v_fmac_f32_e32 v133, v117, v101
; __device__ __forceinline__ void unpack8(const u32x4 w, float (&f)[8]) { f[0] = bflo(w.x); f[1] = bfhi(w.x); f[2] = bflo(w.y); f[3] = bfhi(w.y); f[4] = bflo(w.z); f[5] = bfhi(w.z); f[6] = bflo(w.w); f[7] = bfhi(w.w); }
; __device__ __forceinline__ u32x4 pack8(const float (&f)[8]) { u32x4 o; o.x = pk2(f[0], f[1]); o.y = pk2(f[2], f[3]); o.z = pk2(f[4], f[5]); o.w = pk2(f[6], f[7]); return o; }
; __device__ __forceinline__ float siluf_(float x) { return x * __builtin_amdgcn_rcpf(1.0f + __expf(-x)); }
; template <int CH> __device__ __forceinline__ void p2_gla_chunk(const Params& p, int t0, int lane) {
;     ...
;     for (int i = 0; i < 16; ++i) {
;         const int t = t0 + i; const bool hasn = (t & (T_SEQ - 1)) != T_SEQ - 1;
;         if (hasn) unpack8(raw, N); else {
; #pragma unroll
;             for (int q = 0; q < 8; ++q) N[q] = 0.f; }
;         if (i < 15 && ((t + 1) & (T_SEQ - 1)) != T_SEQ - 1) raw = __builtin_nontemporal_load((const u32x4*)(zc + (size_t)(i + 2) * ZLD));
;         float o[8];
; #pragma unroll
;         for (int q = 0; q < 8; ++q) { const float y = w0[q] * P[q] + w1[q] * C[q] + w2[q] * N[q]; o[q] = siluf_(y) * sc; }
;         *(u32x4*)(GQKV + (size_t)t * 1024 + c) = pack8(o);
; #pragma unroll
;         for (int q = 0; q < 8; ++q) { P[q] = C[q]; C[q] = N[q]; }
;     }
	v_fmac_f32_e32 v134, v118, v102
	v_fmac_f32_e32 v135, v119, v103
	v_fmac_f32_e32 v128, v120, v80
	v_fmac_f32_e32 v129, v121, v81
	v_fmac_f32_e32 v130, v122, v82
	v_fmac_f32_e32 v131, v123, v83
	v_fmac_f32_e32 v132, v124, v84
	v_fmac_f32_e32 v133, v125, v85
	v_fmac_f32_e32 v134, v126, v86
	v_fmac_f32_e32 v135, v127, v87
	v_mul_f32_e32 v136, 0xbfb8aa3b, v128
	v_mul_f32_e32 v137, 0xbfb8aa3b, v129
	v_mul_f32_e32 v138, 0xbfb8aa3b, v130
	v_mul_f32_e32 v139, 0xbfb8aa3b, v131
	v_mul_f32_e32 v140, 0xbfb8aa3b, v132
	v_mul_f32_e32 v141, 0xbfb8aa3b, v133
	v_mul_f32_e32 v142, 0xbfb8aa3b, v134
	v_mul_f32_e32 v143, 0xbfb8aa3b, v135
	v_exp_f32_e32 v136, v136
	v_exp_f32_e32 v137, v137
	v_exp_f32_e32 v138, v138
	v_exp_f32_e32 v139, v139
	v_exp_f32_e32 v140, v140
	v_exp_f32_e32 v141, v141
	v_exp_f32_e32 v142, v142
	v_exp_f32_e32 v143, v143
	v_add_f32_e32 v136, 1.0, v136
	v_add_f32_e32 v137, 1.0, v137
	v_add_f32_e32 v138, 1.0, v138
	v_add_f32_e32 v139, 1.0, v139
	v_add_f32_e32 v140, 1.0, v140
	v_add_f32_e32 v141, 1.0, v141
	v_add_f32_e32 v142, 1.0, v142
	v_add_f32_e32 v143, 1.0, v143
	v_rcp_f32_e32 v136, v136
	v_rcp_f32_e32 v137, v137
	v_rcp_f32_e32 v138, v138
	v_rcp_f32_e32 v139, v139
	v_rcp_f32_e32 v140, v140
	v_rcp_f32_e32 v141, v141
	v_rcp_f32_e32 v142, v142
	v_rcp_f32_e32 v143, v143
	v_mul_f32_e32 v128, v128, v136
	v_mul_f32_e32 v129, v129, v137
	v_mul_f32_e32 v130, v130, v138
	v_mul_f32_e32 v131, v131, v139
	v_mul_f32_e32 v132, v132, v140
	v_mul_f32_e32 v133, v133, v141
	v_mul_f32_e32 v134, v134, v142
	v_mul_f32_e32 v135, v135, v143
	v_cvt_pk_bf16_f32 v246, v128, v129
	v_cvt_pk_bf16_f32 v247, v130, v131
	v_cvt_pk_bf16_f32 v248, v132, v133
	v_cvt_pk_bf16_f32 v249, v134, v135
	global_store_dwordx4 v5, v[246:249], s[58:59] nt
	v_add_u32_e32 v5, 0x800, v5
	v_lshlrev_b32_e32 v88, 16, v196
	v_and_b32_e32 v89, 0xffff0000, v196
	v_lshlrev_b32_e32 v90, 16, v197
	v_and_b32_e32 v91, 0xffff0000, v197
	v_lshlrev_b32_e32 v92, 16, v198
	v_and_b32_e32 v93, 0xffff0000, v198
	v_lshlrev_b32_e32 v94, 16, v199
	v_and_b32_e32 v95, 0xffff0000, v199
	v_mul_f32_e32 v128, v104, v96
	v_mul_f32_e32 v129, v105, v97
	v_mul_f32_e32 v130, v106, v98
	v_mul_f32_e32 v131, v107, v99
	v_mul_f32_e32 v132, v108, v100
	v_mul_f32_e32 v133, v109, v101
	v_mul_f32_e32 v134, v110, v102
	v_mul_f32_e32 v135, v111, v103
	v_fmac_f32_e32 v128, v112, v80
	v_fmac_f32_e32 v129, v113, v81
	v_fmac_f32_e32 v130, v114, v82
	v_fmac_f32_e32 v131, v115, v83
	v_fmac_f32_e32 v132, v116, v84
	v_fmac_f32_e32 v133, v117, v85
	v_fmac_f32_e32 v134, v118, v86
	v_fmac_f32_e32 v135, v119, v87
	v_fmac_f32_e32 v128, v120, v88
	v_fmac_f32_e32 v129, v121, v89
	v_fmac_f32_e32 v130, v122, v90
	v_fmac_f32_e32 v131, v123, v91
	v_fmac_f32_e32 v132, v124, v92
	v_fmac_f32_e32 v133, v125, v93
	v_fmac_f32_e32 v134, v126, v94
	v_fmac_f32_e32 v135, v127, v95
	v_mul_f32_e32 v136, 0xbfb8aa3b, v128
	v_mul_f32_e32 v137, 0xbfb8aa3b, v129
	v_mul_f32_e32 v138, 0xbfb8aa3b, v130
	v_mul_f32_e32 v139, 0xbfb8aa3b, v131
	v_mul_f32_e32 v140, 0xbfb8aa3b, v132
	v_mul_f32_e32 v141, 0xbfb8aa3b, v133
	v_mul_f32_e32 v142, 0xbfb8aa3b, v134
	v_mul_f32_e32 v143, 0xbfb8aa3b, v135
	v_exp_f32_e32 v136, v136
	v_exp_f32_e32 v137, v137
	v_exp_f32_e32 v138, v138
	v_exp_f32_e32 v139, v139
	v_exp_f32_e32 v140, v140
	v_exp_f32_e32 v141, v141
	v_exp_f32_e32 v142, v142
	v_exp_f32_e32 v143, v143
	v_add_f32_e32 v136, 1.0, v136
	v_add_f32_e32 v137, 1.0, v137
	v_add_f32_e32 v138, 1.0, v138
	v_add_f32_e32 v139, 1.0, v139
	v_add_f32_e32 v140, 1.0, v140
	v_add_f32_e32 v141, 1.0, v141
	v_add_f32_e32 v142, 1.0, v142
	v_add_f32_e32 v143, 1.0, v143
	v_rcp_f32_e32 v136, v136
	v_rcp_f32_e32 v137, v137
	v_rcp_f32_e32 v138, v138
	v_rcp_f32_e32 v139, v139
	v_rcp_f32_e32 v140, v140
	v_rcp_f32_e32 v141, v141
	v_rcp_f32_e32 v142, v142
	v_rcp_f32_e32 v143, v143
	v_mul_f32_e32 v128, v128, v136
	v_mul_f32_e32 v129, v129, v137
	v_mul_f32_e32 v130, v130, v138
	v_mul_f32_e32 v131, v131, v139
	v_mul_f32_e32 v132, v132, v140
	v_mul_f32_e32 v133, v133, v141
	v_mul_f32_e32 v134, v134, v142
	v_mul_f32_e32 v135, v135, v143
	v_cvt_pk_bf16_f32 v246, v128, v129
	v_cvt_pk_bf16_f32 v247, v130, v131
	v_cvt_pk_bf16_f32 v248, v132, v133
	v_cvt_pk_bf16_f32 v249, v134, v135
	global_store_dwordx4 v5, v[246:249], s[58:59] nt
	v_add_u32_e32 v5, 0x800, v5
	v_lshlrev_b32_e32 v96, 16, v200
	v_and_b32_e32 v97, 0xffff0000, v200
	v_lshlrev_b32_e32 v98, 16, v201
	v_and_b32_e32 v99, 0xffff0000, v201
	v_lshlrev_b32_e32 v100, 16, v202
	v_and_b32_e32 v101, 0xffff0000, v202
	v_lshlrev_b32_e32 v102, 16, v203
	v_and_b32_e32 v103, 0xffff0000, v203
	v_mul_f32_e32 v128, v104, v80
	v_mul_f32_e32 v129, v105, v81
	v_mul_f32_e32 v130, v106, v82
	v_mul_f32_e32 v131, v107, v83
	v_mul_f32_e32 v132, v108, v84
	v_mul_f32_e32 v133, v109, v85
	v_mul_f32_e32 v134, v110, v86
	v_mul_f32_e32 v135, v111, v87
	v_fmac_f32_e32 v128, v112, v88
	v_fmac_f32_e32 v129, v113, v89
	v_fmac_f32_e32 v130, v114, v90
	v_fmac_f32_e32 v131, v115, v91
	v_fmac_f32_e32 v132, v116, v92
	v_fmac_f32_e32 v133, v117, v93
	v_fmac_f32_e32 v134, v118, v94
	v_fmac_f32_e32 v135, v119, v95
	v_fmac_f32_e32 v128, v120, v96
	v_fmac_f32_e32 v129, v121, v97
	v_fmac_f32_e32 v130, v122, v98
	v_fmac_f32_e32 v131, v123, v99
	v_fmac_f32_e32 v132, v124, v100
	v_fmac_f32_e32 v133, v125, v101
	v_fmac_f32_e32 v134, v126, v102
	v_fmac_f32_e32 v135, v127, v103
	v_mul_f32_e32 v136, 0xbfb8aa3b, v128
	v_mul_f32_e32 v137, 0xbfb8aa3b, v129
	v_mul_f32_e32 v138, 0xbfb8aa3b, v130
	v_mul_f32_e32 v139, 0xbfb8aa3b, v131
	v_mul_f32_e32 v140, 0xbfb8aa3b, v132
	v_mul_f32_e32 v141, 0xbfb8aa3b, v133
	v_mul_f32_e32 v142, 0xbfb8aa3b, v134
	v_mul_f32_e32 v143, 0xbfb8aa3b, v135
	v_exp_f32_e32 v136, v136
; __device__ __forceinline__ void unpack8(const u32x4 w, float (&f)[8]) { f[0] = bflo(w.x); f[1] = bfhi(w.x); f[2] = bflo(w.y); f[3] = bfhi(w.y); f[4] = bflo(w.z); f[5] = bfhi(w.z); f[6] = bflo(w.w); f[7] = bfhi(w.w); }
; __device__ __forceinline__ u32x4 pack8(const float (&f)[8]) { u32x4 o; o.x = pk2(f[0], f[1]); o.y = pk2(f[2], f[3]); o.z = pk2(f[4], f[5]); o.w = pk2(f[6], f[7]); return o; }
; __device__ __forceinline__ float siluf_(float x) { return x * __builtin_amdgcn_rcpf(1.0f + __expf(-x)); }
; template <int CH> __device__ __forceinline__ void p2_gla_chunk(const Params& p, int t0, int lane) {
;     ...
;     for (int i = 0; i < 16; ++i) {
;         const int t = t0 + i; const bool hasn = (t & (T_SEQ - 1)) != T_SEQ - 1;
;         if (hasn) unpack8(raw, N); else {
; #pragma unroll
;             for (int q = 0; q < 8; ++q) N[q] = 0.f; }
;         if (i < 15 && ((t + 1) & (T_SEQ - 1)) != T_SEQ - 1) raw = __builtin_nontemporal_load((const u32x4*)(zc + (size_t)(i + 2) * ZLD));
;         float o[8];
; #pragma unroll
;         for (int q = 0; q < 8; ++q) { const float y = w0[q] * P[q] + w1[q] * C[q] + w2[q] * N[q]; o[q] = siluf_(y) * sc; }
;         *(u32x4*)(GQKV + (size_t)t * 1024 + c) = pack8(o);
; #pragma unroll
;         for (int q = 0; q < 8; ++q) { P[q] = C[q]; C[q] = N[q]; }
;     }
	v_exp_f32_e32 v137, v137
	v_exp_f32_e32 v138, v138
	v_exp_f32_e32 v139, v139
	v_exp_f32_e32 v140, v140
	v_exp_f32_e32 v141, v141
	v_exp_f32_e32 v142, v142
	v_exp_f32_e32 v143, v143
	v_add_f32_e32 v136, 1.0, v136
	v_add_f32_e32 v137, 1.0, v137
	v_add_f32_e32 v138, 1.0, v138
	v_add_f32_e32 v139, 1.0, v139
	v_add_f32_e32 v140, 1.0, v140
	v_add_f32_e32 v141, 1.0, v141
	v_add_f32_e32 v142, 1.0, v142
	v_add_f32_e32 v143, 1.0, v143
	v_rcp_f32_e32 v136, v136
	v_rcp_f32_e32 v137, v137
	v_rcp_f32_e32 v138, v138
	v_rcp_f32_e32 v139, v139
	v_rcp_f32_e32 v140, v140
	v_rcp_f32_e32 v141, v141
	v_rcp_f32_e32 v142, v142
	v_rcp_f32_e32 v143, v143
	v_mul_f32_e32 v128, v128, v136
	v_mul_f32_e32 v129, v129, v137
	v_mul_f32_e32 v130, v130, v138
	v_mul_f32_e32 v131, v131, v139
	v_mul_f32_e32 v132, v132, v140
	v_mul_f32_e32 v133, v133, v141
	v_mul_f32_e32 v134, v134, v142
	v_mul_f32_e32 v135, v135, v143
	v_cvt_pk_bf16_f32 v246, v128, v129
	v_cvt_pk_bf16_f32 v247, v130, v131
	v_cvt_pk_bf16_f32 v248, v132, v133
	v_cvt_pk_bf16_f32 v249, v134, v135
	global_store_dwordx4 v5, v[246:249], s[58:59] nt
	v_add_u32_e32 v5, 0x800, v5
	v_lshlrev_b32_e32 v80, 16, v204
	v_and_b32_e32 v81, 0xffff0000, v204
	v_lshlrev_b32_e32 v82, 16, v205
	v_and_b32_e32 v83, 0xffff0000, v205
	v_lshlrev_b32_e32 v84, 16, v206
	v_and_b32_e32 v85, 0xffff0000, v206
	v_lshlrev_b32_e32 v86, 16, v207
	v_and_b32_e32 v87, 0xffff0000, v207
	v_mul_f32_e32 v128, v104, v88
	v_mul_f32_e32 v129, v105, v89
	v_mul_f32_e32 v130, v106, v90
	v_mul_f32_e32 v131, v107, v91
	v_mul_f32_e32 v132, v108, v92
	v_mul_f32_e32 v133, v109, v93
	v_mul_f32_e32 v134, v110, v94
	v_mul_f32_e32 v135, v111, v95
	v_fmac_f32_e32 v128, v112, v96
	v_fmac_f32_e32 v129, v113, v97
	v_fmac_f32_e32 v130, v114, v98
	v_fmac_f32_e32 v131, v115, v99
	v_fmac_f32_e32 v132, v116, v100
	v_fmac_f32_e32 v133, v117, v101
	v_fmac_f32_e32 v134, v118, v102
	v_fmac_f32_e32 v135, v119, v103
	v_fmac_f32_e32 v128, v120, v80
	v_fmac_f32_e32 v129, v121, v81
	v_fmac_f32_e32 v130, v122, v82
	v_fmac_f32_e32 v131, v123, v83
	v_fmac_f32_e32 v132, v124, v84
	v_fmac_f32_e32 v133, v125, v85
	v_fmac_f32_e32 v134, v126, v86
	v_fmac_f32_e32 v135, v127, v87
	v_mul_f32_e32 v136, 0xbfb8aa3b, v128
	v_mul_f32_e32 v137, 0xbfb8aa3b, v129
	v_mul_f32_e32 v138, 0xbfb8aa3b, v130
	v_mul_f32_e32 v139, 0xbfb8aa3b, v131
	v_mul_f32_e32 v140, 0xbfb8aa3b, v132
	v_mul_f32_e32 v141, 0xbfb8aa3b, v133
	v_mul_f32_e32 v142, 0xbfb8aa3b, v134
	v_mul_f32_e32 v143, 0xbfb8aa3b, v135
	v_exp_f32_e32 v136, v136
	v_exp_f32_e32 v137, v137
	v_exp_f32_e32 v138, v138
	v_exp_f32_e32 v139, v139
	v_exp_f32_e32 v140, v140
	v_exp_f32_e32 v141, v141
	v_exp_f32_e32 v142, v142
	v_exp_f32_e32 v143, v143
	v_add_f32_e32 v136, 1.0, v136
	v_add_f32_e32 v137, 1.0, v137
	v_add_f32_e32 v138, 1.0, v138
	v_add_f32_e32 v139, 1.0, v139
	v_add_f32_e32 v140, 1.0, v140
	v_add_f32_e32 v141, 1.0, v141
	v_add_f32_e32 v142, 1.0, v142
	v_add_f32_e32 v143, 1.0, v143
	v_rcp_f32_e32 v136, v136
	v_rcp_f32_e32 v137, v137
	v_rcp_f32_e32 v138, v138
	v_rcp_f32_e32 v139, v139
	v_rcp_f32_e32 v140, v140
	v_rcp_f32_e32 v141, v141
	v_rcp_f32_e32 v142, v142
	v_rcp_f32_e32 v143, v143
	v_mul_f32_e32 v128, v128, v136
	v_mul_f32_e32 v129, v129, v137
	v_mul_f32_e32 v130, v130, v138
	v_mul_f32_e32 v131, v131, v139
	v_mul_f32_e32 v132, v132, v140
	v_mul_f32_e32 v133, v133, v141
	v_mul_f32_e32 v134, v134, v142
	v_mul_f32_e32 v135, v135, v143
	v_cvt_pk_bf16_f32 v246, v128, v129
	v_cvt_pk_bf16_f32 v247, v130, v131
	v_cvt_pk_bf16_f32 v248, v132, v133
	v_cvt_pk_bf16_f32 v249, v134, v135
	global_store_dwordx4 v5, v[246:249], s[58:59] nt
	v_add_u32_e32 v5, 0x800, v5
	v_lshlrev_b32_e32 v88, 16, v208
	v_and_b32_e32 v89, 0xffff0000, v208
	v_lshlrev_b32_e32 v90, 16, v209
	v_and_b32_e32 v91, 0xffff0000, v209
	v_lshlrev_b32_e32 v92, 16, v210
	v_and_b32_e32 v93, 0xffff0000, v210
	v_lshlrev_b32_e32 v94, 16, v211
	v_and_b32_e32 v95, 0xffff0000, v211
	v_mul_f32_e32 v128, v104, v96
	v_mul_f32_e32 v129, v105, v97
	v_mul_f32_e32 v130, v106, v98
	v_mul_f32_e32 v131, v107, v99
	v_mul_f32_e32 v132, v108, v100
	v_mul_f32_e32 v133, v109, v101
	v_mul_f32_e32 v134, v110, v102
	v_mul_f32_e32 v135, v111, v103
	v_fmac_f32_e32 v128, v112, v80
	v_fmac_f32_e32 v129, v113, v81
	v_fmac_f32_e32 v130, v114, v82
	v_fmac_f32_e32 v131, v115, v83
	v_fmac_f32_e32 v132, v116, v84
	v_fmac_f32_e32 v133, v117, v85
	v_fmac_f32_e32 v134, v118, v86
	v_fmac_f32_e32 v135, v119, v87
	v_fmac_f32_e32 v128, v120, v88
	v_fmac_f32_e32 v129, v121, v89
	v_fmac_f32_e32 v130, v122, v90
	v_fmac_f32_e32 v131, v123, v91
	v_fmac_f32_e32 v132, v124, v92
	v_fmac_f32_e32 v133, v125, v93
	v_fmac_f32_e32 v134, v126, v94
	v_fmac_f32_e32 v135, v127, v95
	v_mul_f32_e32 v136, 0xbfb8aa3b, v128
	v_mul_f32_e32 v137, 0xbfb8aa3b, v129
	v_mul_f32_e32 v138, 0xbfb8aa3b, v130
	v_mul_f32_e32 v139, 0xbfb8aa3b, v131
	v_mul_f32_e32 v140, 0xbfb8aa3b, v132
	v_mul_f32_e32 v141, 0xbfb8aa3b, v133
	v_mul_f32_e32 v142, 0xbfb8aa3b, v134
	v_mul_f32_e32 v143, 0xbfb8aa3b, v135
	v_exp_f32_e32 v136, v136
	v_exp_f32_e32 v137, v137
	v_exp_f32_e32 v138, v138
	v_exp_f32_e32 v139, v139
	v_exp_f32_e32 v140, v140
	v_exp_f32_e32 v141, v141
	v_exp_f32_e32 v142, v142
	v_exp_f32_e32 v143, v143
	v_add_f32_e32 v136, 1.0, v136
	v_add_f32_e32 v137, 1.0, v137
	v_add_f32_e32 v138, 1.0, v138
	v_add_f32_e32 v139, 1.0, v139
	v_add_f32_e32 v140, 1.0, v140
	v_add_f32_e32 v141, 1.0, v141
	v_add_f32_e32 v142, 1.0, v142
	v_add_f32_e32 v143, 1.0, v143
	v_rcp_f32_e32 v136, v136
	v_rcp_f32_e32 v137, v137
	v_rcp_f32_e32 v138, v138
	v_rcp_f32_e32 v139, v139
	v_rcp_f32_e32 v140, v140
	v_rcp_f32_e32 v141, v141
	v_rcp_f32_e32 v142, v142
	v_rcp_f32_e32 v143, v143
	v_mul_f32_e32 v128, v128, v136
; __device__ __forceinline__ void unpack8(const u32x4 w, float (&f)[8]) { f[0] = bflo(w.x); f[1] = bfhi(w.x); f[2] = bflo(w.y); f[3] = bfhi(w.y); f[4] = bflo(w.z); f[5] = bfhi(w.z); f[6] = bflo(w.w); f[7] = bfhi(w.w); }
; __device__ __forceinline__ u32x4 pack8(const float (&f)[8]) { u32x4 o; o.x = pk2(f[0], f[1]); o.y = pk2(f[2], f[3]); o.z = pk2(f[4], f[5]); o.w = pk2(f[6], f[7]); return o; }
; __device__ __forceinline__ float siluf_(float x) { return x * __builtin_amdgcn_rcpf(1.0f + __expf(-x)); }
; template <int CH> __device__ __forceinline__ void p2_gla_chunk(const Params& p, int t0, int lane) {
;     ...
;     for (int i = 0; i < 16; ++i) {
;         const int t = t0 + i; const bool hasn = (t & (T_SEQ - 1)) != T_SEQ - 1;
;         if (hasn) unpack8(raw, N); else {
; #pragma unroll
;             for (int q = 0; q < 8; ++q) N[q] = 0.f; }
;         if (i < 15 && ((t + 1) & (T_SEQ - 1)) != T_SEQ - 1) raw = __builtin_nontemporal_load((const u32x4*)(zc + (size_t)(i + 2) * ZLD));
;         float o[8];
; #pragma unroll
;         for (int q = 0; q < 8; ++q) { const float y = w0[q] * P[q] + w1[q] * C[q] + w2[q] * N[q]; o[q] = siluf_(y) * sc; }
;         *(u32x4*)(GQKV + (size_t)t * 1024 + c) = pack8(o);
; #pragma unroll
;         for (int q = 0; q < 8; ++q) { P[q] = C[q]; C[q] = N[q]; }
;     }
	v_mul_f32_e32 v129, v129, v137
	v_mul_f32_e32 v130, v130, v138
	v_mul_f32_e32 v131, v131, v139
	v_mul_f32_e32 v132, v132, v140
	v_mul_f32_e32 v133, v133, v141
	v_mul_f32_e32 v134, v134, v142
	v_mul_f32_e32 v135, v135, v143
	v_cvt_pk_bf16_f32 v246, v128, v129
	v_cvt_pk_bf16_f32 v247, v130, v131
	v_cvt_pk_bf16_f32 v248, v132, v133
	v_cvt_pk_bf16_f32 v249, v134, v135
	global_store_dwordx4 v5, v[246:249], s[58:59] nt
	v_add_u32_e32 v5, 0x800, v5
	v_lshlrev_b32_e32 v96, 16, v212
	v_and_b32_e32 v97, 0xffff0000, v212
	v_lshlrev_b32_e32 v98, 16, v213
	v_and_b32_e32 v99, 0xffff0000, v213
	v_lshlrev_b32_e32 v100, 16, v214
	v_and_b32_e32 v101, 0xffff0000, v214
	v_lshlrev_b32_e32 v102, 16, v215
	v_and_b32_e32 v103, 0xffff0000, v215
	v_mul_f32_e32 v128, v104, v80
	v_mul_f32_e32 v129, v105, v81
	v_mul_f32_e32 v130, v106, v82
	v_mul_f32_e32 v131, v107, v83
	v_mul_f32_e32 v132, v108, v84
	v_mul_f32_e32 v133, v109, v85
	v_mul_f32_e32 v134, v110, v86
	v_mul_f32_e32 v135, v111, v87
	v_fmac_f32_e32 v128, v112, v88
	v_fmac_f32_e32 v129, v113, v89
	v_fmac_f32_e32 v130, v114, v90
	v_fmac_f32_e32 v131, v115, v91
	v_fmac_f32_e32 v132, v116, v92
	v_fmac_f32_e32 v133, v117, v93
	v_fmac_f32_e32 v134, v118, v94
	v_fmac_f32_e32 v135, v119, v95
	v_fmac_f32_e32 v128, v120, v96
	v_fmac_f32_e32 v129, v121, v97
	v_fmac_f32_e32 v130, v122, v98
	v_fmac_f32_e32 v131, v123, v99
	v_fmac_f32_e32 v132, v124, v100
	v_fmac_f32_e32 v133, v125, v101
	v_fmac_f32_e32 v134, v126, v102
	v_fmac_f32_e32 v135, v127, v103
	v_mul_f32_e32 v136, 0xbfb8aa3b, v128
	v_mul_f32_e32 v137, 0xbfb8aa3b, v129
	v_mul_f32_e32 v138, 0xbfb8aa3b, v130
	v_mul_f32_e32 v139, 0xbfb8aa3b, v131
	v_mul_f32_e32 v140, 0xbfb8aa3b, v132
	v_mul_f32_e32 v141, 0xbfb8aa3b, v133
	v_mul_f32_e32 v142, 0xbfb8aa3b, v134
	v_mul_f32_e32 v143, 0xbfb8aa3b, v135
	v_exp_f32_e32 v136, v136
	v_exp_f32_e32 v137, v137
	v_exp_f32_e32 v138, v138
	v_exp_f32_e32 v139, v139
	v_exp_f32_e32 v140, v140
	v_exp_f32_e32 v141, v141
	v_exp_f32_e32 v142, v142
	v_exp_f32_e32 v143, v143
	v_add_f32_e32 v136, 1.0, v136
	v_add_f32_e32 v137, 1.0, v137
	v_add_f32_e32 v138, 1.0, v138
	v_add_f32_e32 v139, 1.0, v139
	v_add_f32_e32 v140, 1.0, v140
	v_add_f32_e32 v141, 1.0, v141
	v_add_f32_e32 v142, 1.0, v142
	v_add_f32_e32 v143, 1.0, v143
	v_rcp_f32_e32 v136, v136
	v_rcp_f32_e32 v137, v137
	v_rcp_f32_e32 v138, v138
	v_rcp_f32_e32 v139, v139
	v_rcp_f32_e32 v140, v140
	v_rcp_f32_e32 v141, v141
	v_rcp_f32_e32 v142, v142
	v_rcp_f32_e32 v143, v143
	v_mul_f32_e32 v128, v128, v136
	v_mul_f32_e32 v129, v129, v137
	v_mul_f32_e32 v130, v130, v138
	v_mul_f32_e32 v131, v131, v139
	v_mul_f32_e32 v132, v132, v140
	v_mul_f32_e32 v133, v133, v141
	v_mul_f32_e32 v134, v134, v142
	v_mul_f32_e32 v135, v135, v143
	v_cvt_pk_bf16_f32 v246, v128, v129
	v_cvt_pk_bf16_f32 v247, v130, v131
	v_cvt_pk_bf16_f32 v248, v132, v133
	v_cvt_pk_bf16_f32 v249, v134, v135
	global_store_dwordx4 v5, v[246:249], s[58:59] nt
	v_add_u32_e32 v5, 0x800, v5
	v_lshlrev_b32_e32 v80, 16, v216
	v_and_b32_e32 v81, 0xffff0000, v216
	v_lshlrev_b32_e32 v82, 16, v217
	v_and_b32_e32 v83, 0xffff0000, v217
	v_lshlrev_b32_e32 v84, 16, v218
	v_and_b32_e32 v85, 0xffff0000, v218
	v_lshlrev_b32_e32 v86, 16, v219
	v_and_b32_e32 v87, 0xffff0000, v219
	v_mul_f32_e32 v128, v104, v88
	v_mul_f32_e32 v129, v105, v89
	v_mul_f32_e32 v130, v106, v90
	v_mul_f32_e32 v131, v107, v91
	v_mul_f32_e32 v132, v108, v92
	v_mul_f32_e32 v133, v109, v93
	v_mul_f32_e32 v134, v110, v94
	v_mul_f32_e32 v135, v111, v95
	v_fmac_f32_e32 v128, v112, v96
	v_fmac_f32_e32 v129, v113, v97
	v_fmac_f32_e32 v130, v114, v98
	v_fmac_f32_e32 v131, v115, v99
	v_fmac_f32_e32 v132, v116, v100
	v_fmac_f32_e32 v133, v117, v101
	v_fmac_f32_e32 v134, v118, v102
	v_fmac_f32_e32 v135, v119, v103
	v_fmac_f32_e32 v128, v120, v80
	v_fmac_f32_e32 v129, v121, v81
	v_fmac_f32_e32 v130, v122, v82
	v_fmac_f32_e32 v131, v123, v83
	v_fmac_f32_e32 v132, v124, v84
	v_fmac_f32_e32 v133, v125, v85
	v_fmac_f32_e32 v134, v126, v86
	v_fmac_f32_e32 v135, v127, v87
	v_mul_f32_e32 v136, 0xbfb8aa3b, v128
	v_mul_f32_e32 v137, 0xbfb8aa3b, v129
	v_mul_f32_e32 v138, 0xbfb8aa3b, v130
	v_mul_f32_e32 v139, 0xbfb8aa3b, v131
	v_mul_f32_e32 v140, 0xbfb8aa3b, v132
	v_mul_f32_e32 v141, 0xbfb8aa3b, v133
	v_mul_f32_e32 v142, 0xbfb8aa3b, v134
	v_mul_f32_e32 v143, 0xbfb8aa3b, v135
	v_exp_f32_e32 v136, v136
	v_exp_f32_e32 v137, v137
	v_exp_f32_e32 v138, v138
	v_exp_f32_e32 v139, v139
	v_exp_f32_e32 v140, v140
	v_exp_f32_e32 v141, v141
	v_exp_f32_e32 v142, v142
	v_exp_f32_e32 v143, v143
	v_add_f32_e32 v136, 1.0, v136
	v_add_f32_e32 v137, 1.0, v137
	v_add_f32_e32 v138, 1.0, v138
	v_add_f32_e32 v139, 1.0, v139
	v_add_f32_e32 v140, 1.0, v140
	v_add_f32_e32 v141, 1.0, v141
	v_add_f32_e32 v142, 1.0, v142
	v_add_f32_e32 v143, 1.0, v143
	v_rcp_f32_e32 v136, v136
	v_rcp_f32_e32 v137, v137
	v_rcp_f32_e32 v138, v138
	v_rcp_f32_e32 v139, v139
	v_rcp_f32_e32 v140, v140
	v_rcp_f32_e32 v141, v141
	v_rcp_f32_e32 v142, v142
	v_rcp_f32_e32 v143, v143
	v_mul_f32_e32 v128, v128, v136
	v_mul_f32_e32 v129, v129, v137
	v_mul_f32_e32 v130, v130, v138
	v_mul_f32_e32 v131, v131, v139
	v_mul_f32_e32 v132, v132, v140
	v_mul_f32_e32 v133, v133, v141
	v_mul_f32_e32 v134, v134, v142
	v_mul_f32_e32 v135, v135, v143
	v_cvt_pk_bf16_f32 v246, v128, v129
	v_cvt_pk_bf16_f32 v247, v130, v131
	v_cvt_pk_bf16_f32 v248, v132, v133
	v_cvt_pk_bf16_f32 v249, v134, v135
	global_store_dwordx4 v5, v[246:249], s[58:59] nt
	v_add_u32_e32 v5, 0x800, v5
	v_lshlrev_b32_e32 v88, 16, v220
	v_and_b32_e32 v89, 0xffff0000, v220
	v_lshlrev_b32_e32 v90, 16, v221
	v_and_b32_e32 v91, 0xffff0000, v221
	v_lshlrev_b32_e32 v92, 16, v222
	v_and_b32_e32 v93, 0xffff0000, v222
; __device__ __forceinline__ void unpack8(const u32x4 w, float (&f)[8]) { f[0] = bflo(w.x); f[1] = bfhi(w.x); f[2] = bflo(w.y); f[3] = bfhi(w.y); f[4] = bflo(w.z); f[5] = bfhi(w.z); f[6] = bflo(w.w); f[7] = bfhi(w.w); }
; __device__ __forceinline__ u32x4 pack8(const float (&f)[8]) { u32x4 o; o.x = pk2(f[0], f[1]); o.y = pk2(f[2], f[3]); o.z = pk2(f[4], f[5]); o.w = pk2(f[6], f[7]); return o; }
; __device__ __forceinline__ float siluf_(float x) { return x * __builtin_amdgcn_rcpf(1.0f + __expf(-x)); }
; template <int CH> __device__ __forceinline__ void p2_gla_chunk(const Params& p, int t0, int lane) {
;     ...
;     for (int i = 0; i < 16; ++i) {
;         const int t = t0 + i; const bool hasn = (t & (T_SEQ - 1)) != T_SEQ - 1;
;         if (hasn) unpack8(raw, N); else {
; #pragma unroll
;             for (int q = 0; q < 8; ++q) N[q] = 0.f; }
;         if (i < 15 && ((t + 1) & (T_SEQ - 1)) != T_SEQ - 1) raw = __builtin_nontemporal_load((const u32x4*)(zc + (size_t)(i + 2) * ZLD));
;         float o[8];
; #pragma unroll
;         for (int q = 0; q < 8; ++q) { const float y = w0[q] * P[q] + w1[q] * C[q] + w2[q] * N[q]; o[q] = siluf_(y) * sc; }
;         *(u32x4*)(GQKV + (size_t)t * 1024 + c) = pack8(o);
; #pragma unroll
;         for (int q = 0; q < 8; ++q) { P[q] = C[q]; C[q] = N[q]; }
;     }
	v_lshlrev_b32_e32 v94, 16, v223
	v_and_b32_e32 v95, 0xffff0000, v223
	v_mul_f32_e32 v128, v104, v96
	v_mul_f32_e32 v129, v105, v97
	v_mul_f32_e32 v130, v106, v98
	v_mul_f32_e32 v131, v107, v99
	v_mul_f32_e32 v132, v108, v100
	v_mul_f32_e32 v133, v109, v101
	v_mul_f32_e32 v134, v110, v102
	v_mul_f32_e32 v135, v111, v103
	v_fmac_f32_e32 v128, v112, v80
	v_fmac_f32_e32 v129, v113, v81
	v_fmac_f32_e32 v130, v114, v82
	v_fmac_f32_e32 v131, v115, v83
	v_fmac_f32_e32 v132, v116, v84
	v_fmac_f32_e32 v133, v117, v85
	v_fmac_f32_e32 v134, v118, v86
	v_fmac_f32_e32 v135, v119, v87
	v_fmac_f32_e32 v128, v120, v88
	v_fmac_f32_e32 v129, v121, v89
	v_fmac_f32_e32 v130, v122, v90
	v_fmac_f32_e32 v131, v123, v91
	v_fmac_f32_e32 v132, v124, v92
	v_fmac_f32_e32 v133, v125, v93
	v_fmac_f32_e32 v134, v126, v94
	v_fmac_f32_e32 v135, v127, v95
	v_mul_f32_e32 v136, 0xbfb8aa3b, v128
	v_mul_f32_e32 v137, 0xbfb8aa3b, v129
	v_mul_f32_e32 v138, 0xbfb8aa3b, v130
	v_mul_f32_e32 v139, 0xbfb8aa3b, v131
	v_mul_f32_e32 v140, 0xbfb8aa3b, v132
	v_mul_f32_e32 v141, 0xbfb8aa3b, v133
	v_mul_f32_e32 v142, 0xbfb8aa3b, v134
	v_mul_f32_e32 v143, 0xbfb8aa3b, v135
	v_exp_f32_e32 v136, v136
	v_exp_f32_e32 v137, v137
	v_exp_f32_e32 v138, v138
	v_exp_f32_e32 v139, v139
	v_exp_f32_e32 v140, v140
	v_exp_f32_e32 v141, v141
	v_exp_f32_e32 v142, v142
	v_exp_f32_e32 v143, v143
	v_add_f32_e32 v136, 1.0, v136
	v_add_f32_e32 v137, 1.0, v137
	v_add_f32_e32 v138, 1.0, v138
	v_add_f32_e32 v139, 1.0, v139
	v_add_f32_e32 v140, 1.0, v140
	v_add_f32_e32 v141, 1.0, v141
	v_add_f32_e32 v142, 1.0, v142
	v_add_f32_e32 v143, 1.0, v143
	v_rcp_f32_e32 v136, v136
	v_rcp_f32_e32 v137, v137
	v_rcp_f32_e32 v138, v138
	v_rcp_f32_e32 v139, v139
	v_rcp_f32_e32 v140, v140
	v_rcp_f32_e32 v141, v141
	v_rcp_f32_e32 v142, v142
	v_rcp_f32_e32 v143, v143
	v_mul_f32_e32 v128, v128, v136
	v_mul_f32_e32 v129, v129, v137
	v_mul_f32_e32 v130, v130, v138
	v_mul_f32_e32 v131, v131, v139
	v_mul_f32_e32 v132, v132, v140
	v_mul_f32_e32 v133, v133, v141
	v_mul_f32_e32 v134, v134, v142
	v_mul_f32_e32 v135, v135, v143
	v_cvt_pk_bf16_f32 v246, v128, v129
	v_cvt_pk_bf16_f32 v247, v130, v131
	v_cvt_pk_bf16_f32 v248, v132, v133
	v_cvt_pk_bf16_f32 v249, v134, v135
	global_store_dwordx4 v5, v[246:249], s[58:59] nt
	v_add_u32_e32 v5, 0x800, v5
	v_lshlrev_b32_e32 v96, 16, v224
	v_and_b32_e32 v97, 0xffff0000, v224
	v_lshlrev_b32_e32 v98, 16, v225
	v_and_b32_e32 v99, 0xffff0000, v225
	v_lshlrev_b32_e32 v100, 16, v226
	v_and_b32_e32 v101, 0xffff0000, v226
	v_lshlrev_b32_e32 v102, 16, v227
	v_and_b32_e32 v103, 0xffff0000, v227
	v_mul_f32_e32 v128, v104, v80
	v_mul_f32_e32 v129, v105, v81
	v_mul_f32_e32 v130, v106, v82
	v_mul_f32_e32 v131, v107, v83
	v_mul_f32_e32 v132, v108, v84
	v_mul_f32_e32 v133, v109, v85
	v_mul_f32_e32 v134, v110, v86
	v_mul_f32_e32 v135, v111, v87
	v_fmac_f32_e32 v128, v112, v88
	v_fmac_f32_e32 v129, v113, v89
	v_fmac_f32_e32 v130, v114, v90
	v_fmac_f32_e32 v131, v115, v91
	v_fmac_f32_e32 v132, v116, v92
	v_fmac_f32_e32 v133, v117, v93
	v_fmac_f32_e32 v134, v118, v94
	v_fmac_f32_e32 v135, v119, v95
	v_fmac_f32_e32 v128, v120, v96
	v_fmac_f32_e32 v129, v121, v97
	v_fmac_f32_e32 v130, v122, v98
	v_fmac_f32_e32 v131, v123, v99
	v_fmac_f32_e32 v132, v124, v100
	v_fmac_f32_e32 v133, v125, v101
	v_fmac_f32_e32 v134, v126, v102
	v_fmac_f32_e32 v135, v127, v103
	v_mul_f32_e32 v136, 0xbfb8aa3b, v128
	v_mul_f32_e32 v137, 0xbfb8aa3b, v129
	v_mul_f32_e32 v138, 0xbfb8aa3b, v130
	v_mul_f32_e32 v139, 0xbfb8aa3b, v131
	v_mul_f32_e32 v140, 0xbfb8aa3b, v132
	v_mul_f32_e32 v141, 0xbfb8aa3b, v133
	v_mul_f32_e32 v142, 0xbfb8aa3b, v134
	v_mul_f32_e32 v143, 0xbfb8aa3b, v135
	v_exp_f32_e32 v136, v136
	v_exp_f32_e32 v137, v137
	v_exp_f32_e32 v138, v138
	v_exp_f32_e32 v139, v139
	v_exp_f32_e32 v140, v140
	v_exp_f32_e32 v141, v141
	v_exp_f32_e32 v142, v142
	v_exp_f32_e32 v143, v143
	v_add_f32_e32 v136, 1.0, v136
	v_add_f32_e32 v137, 1.0, v137
	v_add_f32_e32 v138, 1.0, v138
	v_add_f32_e32 v139, 1.0, v139
	v_add_f32_e32 v140, 1.0, v140
	v_add_f32_e32 v141, 1.0, v141
	v_add_f32_e32 v142, 1.0, v142
	v_add_f32_e32 v143, 1.0, v143
	v_rcp_f32_e32 v136, v136
	v_rcp_f32_e32 v137, v137
	v_rcp_f32_e32 v138, v138
	v_rcp_f32_e32 v139, v139
	v_rcp_f32_e32 v140, v140
	v_rcp_f32_e32 v141, v141
	v_rcp_f32_e32 v142, v142
	v_rcp_f32_e32 v143, v143
	v_mul_f32_e32 v128, v128, v136
	v_mul_f32_e32 v129, v129, v137
	v_mul_f32_e32 v130, v130, v138
	v_mul_f32_e32 v131, v131, v139
	v_mul_f32_e32 v132, v132, v140
	v_mul_f32_e32 v133, v133, v141
	v_mul_f32_e32 v134, v134, v142
	v_mul_f32_e32 v135, v135, v143
	v_cvt_pk_bf16_f32 v246, v128, v129
	v_cvt_pk_bf16_f32 v247, v130, v131
	v_cvt_pk_bf16_f32 v248, v132, v133
	v_cvt_pk_bf16_f32 v249, v134, v135
	global_store_dwordx4 v5, v[246:249], s[58:59] nt
	v_add_u32_e32 v5, 0x800, v5
	v_lshlrev_b32_e32 v80, 16, v228
	v_and_b32_e32 v81, 0xffff0000, v228
	v_lshlrev_b32_e32 v82, 16, v229
	v_and_b32_e32 v83, 0xffff0000, v229
	v_lshlrev_b32_e32 v84, 16, v230
	v_and_b32_e32 v85, 0xffff0000, v230
	v_lshlrev_b32_e32 v86, 16, v231
	v_and_b32_e32 v87, 0xffff0000, v231
	v_mul_f32_e32 v128, v104, v88
	v_mul_f32_e32 v129, v105, v89
	v_mul_f32_e32 v130, v106, v90
	v_mul_f32_e32 v131, v107, v91
	v_mul_f32_e32 v132, v108, v92
	v_mul_f32_e32 v133, v109, v93
	v_mul_f32_e32 v134, v110, v94
	v_mul_f32_e32 v135, v111, v95
	v_fmac_f32_e32 v128, v112, v96
	v_fmac_f32_e32 v129, v113, v97
	v_fmac_f32_e32 v130, v114, v98
	v_fmac_f32_e32 v131, v115, v99
	v_fmac_f32_e32 v132, v116, v100
	v_fmac_f32_e32 v133, v117, v101
	v_fmac_f32_e32 v134, v118, v102
	v_fmac_f32_e32 v135, v119, v103
	v_fmac_f32_e32 v128, v120, v80
	v_fmac_f32_e32 v129, v121, v81
; __device__ __forceinline__ void unpack8(const u32x4 w, float (&f)[8]) { f[0] = bflo(w.x); f[1] = bfhi(w.x); f[2] = bflo(w.y); f[3] = bfhi(w.y); f[4] = bflo(w.z); f[5] = bfhi(w.z); f[6] = bflo(w.w); f[7] = bfhi(w.w); }
; __device__ __forceinline__ u32x4 pack8(const float (&f)[8]) { u32x4 o; o.x = pk2(f[0], f[1]); o.y = pk2(f[2], f[3]); o.z = pk2(f[4], f[5]); o.w = pk2(f[6], f[7]); return o; }
; __device__ __forceinline__ float siluf_(float x) { return x * __builtin_amdgcn_rcpf(1.0f + __expf(-x)); }
; template <int CH> __device__ __forceinline__ void p2_gla_chunk(const Params& p, int t0, int lane) {
;     ...
;     for (int i = 0; i < 16; ++i) {
;         const int t = t0 + i; const bool hasn = (t & (T_SEQ - 1)) != T_SEQ - 1;
;         if (hasn) unpack8(raw, N); else {
; #pragma unroll
;             for (int q = 0; q < 8; ++q) N[q] = 0.f; }
;         if (i < 15 && ((t + 1) & (T_SEQ - 1)) != T_SEQ - 1) raw = __builtin_nontemporal_load((const u32x4*)(zc + (size_t)(i + 2) * ZLD));
;         float o[8];
; #pragma unroll
;         for (int q = 0; q < 8; ++q) { const float y = w0[q] * P[q] + w1[q] * C[q] + w2[q] * N[q]; o[q] = siluf_(y) * sc; }
;         *(u32x4*)(GQKV + (size_t)t * 1024 + c) = pack8(o);
; #pragma unroll
;         for (int q = 0; q < 8; ++q) { P[q] = C[q]; C[q] = N[q]; }
;     }
	v_fmac_f32_e32 v130, v122, v82
	v_fmac_f32_e32 v131, v123, v83
	v_fmac_f32_e32 v132, v124, v84
	v_fmac_f32_e32 v133, v125, v85
	v_fmac_f32_e32 v134, v126, v86
	v_fmac_f32_e32 v135, v127, v87
	v_mul_f32_e32 v136, 0xbfb8aa3b, v128
	v_mul_f32_e32 v137, 0xbfb8aa3b, v129
	v_mul_f32_e32 v138, 0xbfb8aa3b, v130
	v_mul_f32_e32 v139, 0xbfb8aa3b, v131
	v_mul_f32_e32 v140, 0xbfb8aa3b, v132
	v_mul_f32_e32 v141, 0xbfb8aa3b, v133
	v_mul_f32_e32 v142, 0xbfb8aa3b, v134
	v_mul_f32_e32 v143, 0xbfb8aa3b, v135
	v_exp_f32_e32 v136, v136
	v_exp_f32_e32 v137, v137
	v_exp_f32_e32 v138, v138
	v_exp_f32_e32 v139, v139
	v_exp_f32_e32 v140, v140
	v_exp_f32_e32 v141, v141
	v_exp_f32_e32 v142, v142
	v_exp_f32_e32 v143, v143
	v_add_f32_e32 v136, 1.0, v136
	v_add_f32_e32 v137, 1.0, v137
	v_add_f32_e32 v138, 1.0, v138
	v_add_f32_e32 v139, 1.0, v139
	v_add_f32_e32 v140, 1.0, v140
	v_add_f32_e32 v141, 1.0, v141
	v_add_f32_e32 v142, 1.0, v142
	v_add_f32_e32 v143, 1.0, v143
	v_rcp_f32_e32 v136, v136
	v_rcp_f32_e32 v137, v137
	v_rcp_f32_e32 v138, v138
	v_rcp_f32_e32 v139, v139
	v_rcp_f32_e32 v140, v140
	v_rcp_f32_e32 v141, v141
	v_rcp_f32_e32 v142, v142
	v_rcp_f32_e32 v143, v143
	v_mul_f32_e32 v128, v128, v136
	v_mul_f32_e32 v129, v129, v137
	v_mul_f32_e32 v130, v130, v138
	v_mul_f32_e32 v131, v131, v139
	v_mul_f32_e32 v132, v132, v140
	v_mul_f32_e32 v133, v133, v141
	v_mul_f32_e32 v134, v134, v142
	v_mul_f32_e32 v135, v135, v143
	v_cvt_pk_bf16_f32 v246, v128, v129
	v_cvt_pk_bf16_f32 v247, v130, v131
	v_cvt_pk_bf16_f32 v248, v132, v133
	v_cvt_pk_bf16_f32 v249, v134, v135
	global_store_dwordx4 v5, v[246:249], s[58:59] nt
	v_add_u32_e32 v5, 0x800, v5
	v_lshlrev_b32_e32 v88, 16, v232
	v_and_b32_e32 v89, 0xffff0000, v232
	v_lshlrev_b32_e32 v90, 16, v233
	v_and_b32_e32 v91, 0xffff0000, v233
	v_lshlrev_b32_e32 v92, 16, v234
	v_and_b32_e32 v93, 0xffff0000, v234
	v_lshlrev_b32_e32 v94, 16, v235
	v_and_b32_e32 v95, 0xffff0000, v235
	v_mul_f32_e32 v128, v104, v96
	v_mul_f32_e32 v129, v105, v97
	v_mul_f32_e32 v130, v106, v98
	v_mul_f32_e32 v131, v107, v99
	v_mul_f32_e32 v132, v108, v100
	v_mul_f32_e32 v133, v109, v101
	v_mul_f32_e32 v134, v110, v102
	v_mul_f32_e32 v135, v111, v103
	v_fmac_f32_e32 v128, v112, v80
	v_fmac_f32_e32 v129, v113, v81
	v_fmac_f32_e32 v130, v114, v82
	v_fmac_f32_e32 v131, v115, v83
	v_fmac_f32_e32 v132, v116, v84
	v_fmac_f32_e32 v133, v117, v85
	v_fmac_f32_e32 v134, v118, v86
	v_fmac_f32_e32 v135, v119, v87
	v_fmac_f32_e32 v128, v120, v88
	v_fmac_f32_e32 v129, v121, v89
	v_fmac_f32_e32 v130, v122, v90
	v_fmac_f32_e32 v131, v123, v91
	v_fmac_f32_e32 v132, v124, v92
	v_fmac_f32_e32 v133, v125, v93
	v_fmac_f32_e32 v134, v126, v94
	v_fmac_f32_e32 v135, v127, v95
	v_mul_f32_e32 v136, 0xbfb8aa3b, v128
	v_mul_f32_e32 v137, 0xbfb8aa3b, v129
	v_mul_f32_e32 v138, 0xbfb8aa3b, v130
	v_mul_f32_e32 v139, 0xbfb8aa3b, v131
	v_mul_f32_e32 v140, 0xbfb8aa3b, v132
	v_mul_f32_e32 v141, 0xbfb8aa3b, v133
	v_mul_f32_e32 v142, 0xbfb8aa3b, v134
	v_mul_f32_e32 v143, 0xbfb8aa3b, v135
	v_exp_f32_e32 v136, v136
	v_exp_f32_e32 v137, v137
	v_exp_f32_e32 v138, v138
	v_exp_f32_e32 v139, v139
	v_exp_f32_e32 v140, v140
	v_exp_f32_e32 v141, v141
	v_exp_f32_e32 v142, v142
	v_exp_f32_e32 v143, v143
	v_add_f32_e32 v136, 1.0, v136
	v_add_f32_e32 v137, 1.0, v137
	v_add_f32_e32 v138, 1.0, v138
	v_add_f32_e32 v139, 1.0, v139
	v_add_f32_e32 v140, 1.0, v140
	v_add_f32_e32 v141, 1.0, v141
	v_add_f32_e32 v142, 1.0, v142
	v_add_f32_e32 v143, 1.0, v143
	v_rcp_f32_e32 v136, v136
	v_rcp_f32_e32 v137, v137
	v_rcp_f32_e32 v138, v138
	v_rcp_f32_e32 v139, v139
	v_rcp_f32_e32 v140, v140
	v_rcp_f32_e32 v141, v141
	v_rcp_f32_e32 v142, v142
	v_rcp_f32_e32 v143, v143
	v_mul_f32_e32 v128, v128, v136
	v_mul_f32_e32 v129, v129, v137
	v_mul_f32_e32 v130, v130, v138
	v_mul_f32_e32 v131, v131, v139
	v_mul_f32_e32 v132, v132, v140
	v_mul_f32_e32 v133, v133, v141
	v_mul_f32_e32 v134, v134, v142
	v_mul_f32_e32 v135, v135, v143
	v_cvt_pk_bf16_f32 v246, v128, v129
	v_cvt_pk_bf16_f32 v247, v130, v131
	v_cvt_pk_bf16_f32 v248, v132, v133
	v_cvt_pk_bf16_f32 v249, v134, v135
	global_store_dwordx4 v5, v[246:249], s[58:59] nt
	v_add_u32_e32 v5, 0x800, v5
	s_cmp_eq_u32 s67, 0
	s_cbranch_scc1 .Lp2_nz_14
	v_mov_b32_e32 v236, 0
	v_mov_b32_e32 v237, 0
	v_mov_b32_e32 v238, 0
	v_mov_b32_e32 v239, 0
; __device__ __forceinline__ u32x4 pack8(const float (&f)[8]) { u32x4 o; o.x = pk2(f[0], f[1]); o.y = pk2(f[2], f[3]); o.z = pk2(f[4], f[5]); o.w = pk2(f[6], f[7]); return o; }
; __device__ __forceinline__ float siluf_(float x) { return x * __builtin_amdgcn_rcpf(1.0f + __expf(-x)); }
; template <int CH> __device__ __forceinline__ void p2_gla_chunk(const Params& p, int t0, int lane) {
;     ...
;         for (int q = 0; q < 8; ++q) { const float y = w0[q] * P[q] + w1[q] * C[q] + w2[q] * N[q]; o[q] = siluf_(y) * sc; }
;         *(u32x4*)(GQKV + (size_t)t * 1024 + c) = pack8(o);
; __device__ __forceinline__ void p2_gate(const Params& p, const LAS float* aup, int t0, int lane) {
;     unsigned char* ws = p.ws; bf16_t* GNL = (bf16_t*)(ws + WS_GNL); bf16_t* GG = (bf16_t*)(ws + WS_GG); const float* ab = p.in[21];
;     const f32x4 ab0 = *(const f32x4*)(ab + 4 * lane), ab1 = *(const f32x4*)(ab + 256 + 4 * lane);
; #pragma unroll 2
;     for (int i = 0; i < 16; ++i) {
;         const int t = t0 + i; const bf16_t* zg = (const bf16_t*)(ws + WS_Z) + (size_t)t * ZLD + NRW;
;         *(u32x4*)(GG + (size_t)t * 512 + lane * 8) = __builtin_nontemporal_load((const u32x4*)(zg + 1024 + lane * 8));
;         const unsigned short araw = zg[1536 + (lane & 31)]; const int alo = (int)((unsigned)araw << 16);
;         f32x4 acc0 = ab0, acc1 = ab1;
; #pragma unroll
;         for (int r = 0; r < 16; ++r) { const float a0 = __int_as_float(__builtin_amdgcn_readlane(alo, r)), a1 = __int_as_float(__builtin_amdgcn_readlane(alo, 16 + r));
;             acc0 += a0 * *(const LAS f32x4*)(aup + r * 256 + 4 * lane); acc1 += a1 * *(const LAS f32x4*)(aup + (16 + r) * 256 + 4 * lane); }
.Lp2_nz_14:
	v_lshlrev_b32_e32 v96, 16, v236
	v_and_b32_e32 v97, 0xffff0000, v236
	v_lshlrev_b32_e32 v98, 16, v237
	v_and_b32_e32 v99, 0xffff0000, v237
	v_lshlrev_b32_e32 v100, 16, v238
	v_and_b32_e32 v101, 0xffff0000, v238
	v_lshlrev_b32_e32 v102, 16, v239
	v_and_b32_e32 v103, 0xffff0000, v239
	v_mul_f32_e32 v128, v104, v80
	v_mul_f32_e32 v129, v105, v81
	v_mul_f32_e32 v130, v106, v82
	v_mul_f32_e32 v131, v107, v83
	v_mul_f32_e32 v132, v108, v84
	v_mul_f32_e32 v133, v109, v85
	v_mul_f32_e32 v134, v110, v86
	v_mul_f32_e32 v135, v111, v87
	v_fmac_f32_e32 v128, v112, v88
	v_fmac_f32_e32 v129, v113, v89
	v_fmac_f32_e32 v130, v114, v90
	v_fmac_f32_e32 v131, v115, v91
	v_fmac_f32_e32 v132, v116, v92
	v_fmac_f32_e32 v133, v117, v93
	v_fmac_f32_e32 v134, v118, v94
	v_fmac_f32_e32 v135, v119, v95
	v_fmac_f32_e32 v128, v120, v96
	v_fmac_f32_e32 v129, v121, v97
	v_fmac_f32_e32 v130, v122, v98
	v_fmac_f32_e32 v131, v123, v99
	v_fmac_f32_e32 v132, v124, v100
	v_fmac_f32_e32 v133, v125, v101
	v_fmac_f32_e32 v134, v126, v102
	v_fmac_f32_e32 v135, v127, v103
	v_mul_f32_e32 v136, 0xbfb8aa3b, v128
	v_mul_f32_e32 v137, 0xbfb8aa3b, v129
	v_mul_f32_e32 v138, 0xbfb8aa3b, v130
	v_mul_f32_e32 v139, 0xbfb8aa3b, v131
	v_mul_f32_e32 v140, 0xbfb8aa3b, v132
	v_mul_f32_e32 v141, 0xbfb8aa3b, v133
	v_mul_f32_e32 v142, 0xbfb8aa3b, v134
	v_mul_f32_e32 v143, 0xbfb8aa3b, v135
	v_exp_f32_e32 v136, v136
	v_exp_f32_e32 v137, v137
	v_exp_f32_e32 v138, v138
	v_exp_f32_e32 v139, v139
	v_exp_f32_e32 v140, v140
	v_exp_f32_e32 v141, v141
	v_exp_f32_e32 v142, v142
	v_exp_f32_e32 v143, v143
	v_add_f32_e32 v136, 1.0, v136
	v_add_f32_e32 v137, 1.0, v137
	v_add_f32_e32 v138, 1.0, v138
	v_add_f32_e32 v139, 1.0, v139
	v_add_f32_e32 v140, 1.0, v140
	v_add_f32_e32 v141, 1.0, v141
	v_add_f32_e32 v142, 1.0, v142
	v_add_f32_e32 v143, 1.0, v143
	v_rcp_f32_e32 v136, v136
	v_rcp_f32_e32 v137, v137
	v_rcp_f32_e32 v138, v138
	v_rcp_f32_e32 v139, v139
	v_rcp_f32_e32 v140, v140
	v_rcp_f32_e32 v141, v141
	v_rcp_f32_e32 v142, v142
	v_rcp_f32_e32 v143, v143
	v_mul_f32_e32 v128, v128, v136
	v_mul_f32_e32 v129, v129, v137
	v_mul_f32_e32 v130, v130, v138
	v_mul_f32_e32 v131, v131, v139
	v_mul_f32_e32 v132, v132, v140
	v_mul_f32_e32 v133, v133, v141
	v_mul_f32_e32 v134, v134, v142
	v_mul_f32_e32 v135, v135, v143
	v_cvt_pk_bf16_f32 v246, v128, v129
	v_cvt_pk_bf16_f32 v247, v130, v131
	v_cvt_pk_bf16_f32 v248, v132, v133
	v_cvt_pk_bf16_f32 v249, v134, v135
	global_store_dwordx4 v5, v[246:249], s[58:59] nt
	v_add_u32_e32 v5, 0x800, v5
	s_mov_b32 s101, 0xbfb8aa3b
	v_lshlrev_b32_e32 v1, 4, v0
	ds_read_b128 v[8:11], v1 offset:0
	ds_read_b128 v[12:15], v1 offset:1024
	ds_read_b128 v[16:19], v1 offset:2048
	ds_read_b128 v[20:23], v1 offset:3072
	ds_read_b128 v[24:27], v1 offset:4096
	ds_read_b128 v[28:31], v1 offset:5120
	ds_read_b128 v[32:35], v1 offset:6144
	ds_read_b128 v[36:39], v1 offset:7168
	ds_read_b128 v[40:43], v1 offset:8192
	ds_read_b128 v[44:47], v1 offset:9216
	ds_read_b128 v[48:51], v1 offset:10240
	ds_read_b128 v[52:55], v1 offset:11264
	ds_read_b128 v[56:59], v1 offset:12288
	ds_read_b128 v[60:63], v1 offset:13312
	ds_read_b128 v[64:67], v1 offset:14336
	ds_read_b128 v[68:71], v1 offset:15360
	ds_read_b128 v[72:75], v1 offset:16384
	ds_read_b128 v[76:79], v1 offset:17408
	ds_read_b128 v[80:83], v1 offset:18432
	ds_read_b128 v[84:87], v1 offset:19456
	ds_read_b128 v[88:91], v1 offset:20480
	ds_read_b128 v[92:95], v1 offset:21504
	ds_read_b128 v[96:99], v1 offset:22528
	ds_read_b128 v[100:103], v1 offset:23552
	ds_read_b128 v[104:107], v1 offset:24576
	ds_read_b128 v[108:111], v1 offset:25600
	ds_read_b128 v[112:115], v1 offset:26624
	ds_read_b128 v[116:119], v1 offset:27648
	ds_read_b128 v[120:123], v1 offset:28672
	ds_read_b128 v[124:127], v1 offset:29696
	ds_read_b128 v[128:131], v1 offset:30720
	ds_read_b128 v[132:135], v1 offset:31744
	v_readlane_b32 s98, v254, 31
	v_readlane_b32 s99, v254, 32
	s_mul_i32 s3, s62, 0x1c00
	s_add_u32 s3, s3, 0x7001680
	v_lshl_add_u32 v4, v0, 4, s3
	v_and_b32_e32 v6, 31, v0
	s_add_u32 s3, s3, 1024
	v_lshl_add_u32 v6, v6, 1, s3
	global_load_dwordx4 v[228:231], v1, s[98:99]
	global_load_dwordx4 v[232:235], v1, s[98:99] offset:1024
	global_load_dwordx4 v[136:139], v4, s[58:59] nt
	global_load_ushort v200, v6, s[58:59]
	v_add_u32_e32 v4, 0x1c00, v4
	v_add_u32_e32 v6, 0x1c00, v6
	global_load_dwordx4 v[140:143], v4, s[58:59] nt
	global_load_ushort v201, v6, s[58:59]
	v_add_u32_e32 v4, 0x1c00, v4
	v_add_u32_e32 v6, 0x1c00, v6
	global_load_dwordx4 v[144:147], v4, s[58:59] nt
	global_load_ushort v202, v6, s[58:59]
	v_add_u32_e32 v4, 0x1c00, v4
	v_add_u32_e32 v6, 0x1c00, v6
	global_load_dwordx4 v[148:151], v4, s[58:59] nt
	global_load_ushort v203, v6, s[58:59]
	v_add_u32_e32 v4, 0x1c00, v4
	v_add_u32_e32 v6, 0x1c00, v6
	global_load_dwordx4 v[152:155], v4, s[58:59] nt
	global_load_ushort v204, v6, s[58:59]
	v_add_u32_e32 v4, 0x1c00, v4
	v_add_u32_e32 v6, 0x1c00, v6
	global_load_dwordx4 v[156:159], v4, s[58:59] nt
	global_load_ushort v205, v6, s[58:59]
	v_add_u32_e32 v4, 0x1c00, v4
	v_add_u32_e32 v6, 0x1c00, v6
	global_load_dwordx4 v[160:163], v4, s[58:59] nt
	global_load_ushort v206, v6, s[58:59]
	v_add_u32_e32 v4, 0x1c00, v4
	v_add_u32_e32 v6, 0x1c00, v6
	global_load_dwordx4 v[164:167], v4, s[58:59] nt
	global_load_ushort v207, v6, s[58:59]
	v_add_u32_e32 v4, 0x1c00, v4
	v_add_u32_e32 v6, 0x1c00, v6
	global_load_dwordx4 v[168:171], v4, s[58:59] nt
	global_load_ushort v208, v6, s[58:59]
	v_add_u32_e32 v4, 0x1c00, v4
	v_add_u32_e32 v6, 0x1c00, v6
	global_load_dwordx4 v[172:175], v4, s[58:59] nt
	global_load_ushort v209, v6, s[58:59]
	v_add_u32_e32 v4, 0x1c00, v4
	v_add_u32_e32 v6, 0x1c00, v6
	global_load_dwordx4 v[176:179], v4, s[58:59] nt
	global_load_ushort v210, v6, s[58:59]
	v_add_u32_e32 v4, 0x1c00, v4
	v_add_u32_e32 v6, 0x1c00, v6
	global_load_dwordx4 v[180:183], v4, s[58:59] nt
	global_load_ushort v211, v6, s[58:59]
	v_add_u32_e32 v4, 0x1c00, v4
	v_add_u32_e32 v6, 0x1c00, v6
	global_load_dwordx4 v[184:187], v4, s[58:59] nt
	global_load_ushort v212, v6, s[58:59]
	v_add_u32_e32 v4, 0x1c00, v4
	v_add_u32_e32 v6, 0x1c00, v6
	global_load_dwordx4 v[188:191], v4, s[58:59] nt
	global_load_ushort v213, v6, s[58:59]
	v_add_u32_e32 v4, 0x1c00, v4
	v_add_u32_e32 v6, 0x1c00, v6
	global_load_dwordx4 v[192:195], v4, s[58:59] nt
	global_load_ushort v214, v6, s[58:59]
	v_add_u32_e32 v4, 0x1c00, v4
	v_add_u32_e32 v6, 0x1c00, v6
	global_load_dwordx4 v[196:199], v4, s[58:59] nt
	global_load_ushort v215, v6, s[58:59]
	s_lshl_b32 s3, s62, 10
	s_add_u32 s0, s3, 0x5000000
	v_lshl_add_u32 v5, v0, 4, s0
	s_add_u32 s0, s3, 0x3000000
	v_lshl_add_u32 v4, v0, 3, s0
	s_waitcnt lgkmcnt(0)
; __device__ __forceinline__ void p2_gate(const Params& p, const LAS float* aup, int t0, int lane) {
;     ...
;         *(u32x4*)(GG + (size_t)t * 512 + lane * 8) = __builtin_nontemporal_load((const u32x4*)(zg + 1024 + lane * 8));
;         const unsigned short araw = zg[1536 + (lane & 31)]; const int alo = (int)((unsigned)araw << 16);
;         f32x4 acc0 = ab0, acc1 = ab1;
; #pragma unroll
;         for (int r = 0; r < 16; ++r) { const float a0 = __int_as_float(__builtin_amdgcn_readlane(alo, r)), a1 = __int_as_float(__builtin_amdgcn_readlane(alo, 16 + r));
;             acc0 += a0 * *(const LAS f32x4*)(aup + r * 256 + 4 * lane); acc1 += a1 * *(const LAS f32x4*)(aup + (16 + r) * 256 + 4 * lane); }
;         float n0[4], n1[4];
; #pragma unroll
;         for (int j = 0; j < 4; ++j) { const float y0 = -acc0[j], y1 = -acc1[j];
;             n0[j] = (fmaxf(y0, 0.f) + __logf(1.0f + __expf(-fabsf(y0)))) * 0.0625f; n1[j] = (fmaxf(y1, 0.f) + __logf(1.0f + __expf(-fabsf(y1)))) * 0.0625f; }
	s_waitcnt vmcnt(30)
	global_store_dwordx4 v5, v[136:139], s[58:59] nt
	v_lshlrev_b32_e32 v200, 16, v200
	v_mov_b32_e32 v216, v228
	v_mov_b32_e32 v217, v229
	v_mov_b32_e32 v218, v230
	v_mov_b32_e32 v219, v231
	v_mov_b32_e32 v220, v232
	v_mov_b32_e32 v221, v233
	v_mov_b32_e32 v222, v234
	v_mov_b32_e32 v223, v235
	s_nop 0
	v_readlane_b32 s14, v200, 0
	v_readlane_b32 s15, v200, 1
	v_readlane_b32 s25, v200, 2
	v_readlane_b32 s26, v200, 3
	v_readlane_b32 s27, v200, 4
	v_readlane_b32 s36, v200, 5
	v_readlane_b32 s37, v200, 6
	v_readlane_b32 s42, v200, 7
	v_readlane_b32 s43, v200, 16
	v_readlane_b32 s63, v200, 17
	v_readlane_b32 s64, v200, 18
	v_readlane_b32 s65, v200, 19
	v_readlane_b32 s74, v200, 20
	v_readlane_b32 s75, v200, 21
	v_readlane_b32 s76, v200, 22
	v_readlane_b32 s77, v200, 23
	s_nop 1
	v_fmac_f32_e32 v216, s14, v8
	v_fmac_f32_e32 v217, s14, v9
	v_fmac_f32_e32 v218, s14, v10
	v_fmac_f32_e32 v219, s14, v11
	v_fmac_f32_e32 v220, s43, v72
	v_fmac_f32_e32 v221, s43, v73
	v_fmac_f32_e32 v222, s43, v74
	v_fmac_f32_e32 v223, s43, v75
	v_fmac_f32_e32 v216, s15, v12
	v_fmac_f32_e32 v217, s15, v13
	v_fmac_f32_e32 v218, s15, v14
	v_fmac_f32_e32 v219, s15, v15
	v_fmac_f32_e32 v220, s63, v76
	v_fmac_f32_e32 v221, s63, v77
	v_fmac_f32_e32 v222, s63, v78
	v_fmac_f32_e32 v223, s63, v79
	v_fmac_f32_e32 v216, s25, v16
	v_fmac_f32_e32 v217, s25, v17
	v_fmac_f32_e32 v218, s25, v18
	v_fmac_f32_e32 v219, s25, v19
	v_fmac_f32_e32 v220, s64, v80
	v_fmac_f32_e32 v221, s64, v81
	v_fmac_f32_e32 v222, s64, v82
	v_fmac_f32_e32 v223, s64, v83
	v_fmac_f32_e32 v216, s26, v20
	v_fmac_f32_e32 v217, s26, v21
	v_fmac_f32_e32 v218, s26, v22
	v_fmac_f32_e32 v219, s26, v23
	v_fmac_f32_e32 v220, s65, v84
	v_fmac_f32_e32 v221, s65, v85
	v_fmac_f32_e32 v222, s65, v86
	v_fmac_f32_e32 v223, s65, v87
	v_fmac_f32_e32 v216, s27, v24
	v_fmac_f32_e32 v217, s27, v25
	v_fmac_f32_e32 v218, s27, v26
	v_fmac_f32_e32 v219, s27, v27
	v_fmac_f32_e32 v220, s74, v88
	v_fmac_f32_e32 v221, s74, v89
	v_fmac_f32_e32 v222, s74, v90
	v_fmac_f32_e32 v223, s74, v91
	v_fmac_f32_e32 v216, s36, v28
	v_fmac_f32_e32 v217, s36, v29
	v_fmac_f32_e32 v218, s36, v30
	v_fmac_f32_e32 v219, s36, v31
	v_fmac_f32_e32 v220, s75, v92
	v_fmac_f32_e32 v221, s75, v93
	v_fmac_f32_e32 v222, s75, v94
	v_fmac_f32_e32 v223, s75, v95
	v_fmac_f32_e32 v216, s37, v32
	v_fmac_f32_e32 v217, s37, v33
	v_fmac_f32_e32 v218, s37, v34
	v_fmac_f32_e32 v219, s37, v35
	v_fmac_f32_e32 v220, s76, v96
	v_fmac_f32_e32 v221, s76, v97
	v_fmac_f32_e32 v222, s76, v98
	v_fmac_f32_e32 v223, s76, v99
	v_fmac_f32_e32 v216, s42, v36
	v_fmac_f32_e32 v217, s42, v37
	v_fmac_f32_e32 v218, s42, v38
	v_fmac_f32_e32 v219, s42, v39
	v_fmac_f32_e32 v220, s77, v100
	v_fmac_f32_e32 v221, s77, v101
	v_fmac_f32_e32 v222, s77, v102
	v_fmac_f32_e32 v223, s77, v103
	s_nop 0
	v_readlane_b32 s14, v200, 8
	v_readlane_b32 s15, v200, 9
	v_readlane_b32 s25, v200, 10
	v_readlane_b32 s26, v200, 11
	v_readlane_b32 s27, v200, 12
	v_readlane_b32 s36, v200, 13
	v_readlane_b32 s37, v200, 14
	v_readlane_b32 s42, v200, 15
	v_readlane_b32 s43, v200, 24
	v_readlane_b32 s63, v200, 25
	v_readlane_b32 s64, v200, 26
	v_readlane_b32 s65, v200, 27
	v_readlane_b32 s74, v200, 28
	v_readlane_b32 s75, v200, 29
	v_readlane_b32 s76, v200, 30
	v_readlane_b32 s77, v200, 31
	s_nop 1
	v_fmac_f32_e32 v216, s14, v40
	v_fmac_f32_e32 v217, s14, v41
	v_fmac_f32_e32 v218, s14, v42
	v_fmac_f32_e32 v219, s14, v43
	v_fmac_f32_e32 v220, s43, v104
	v_fmac_f32_e32 v221, s43, v105
	v_fmac_f32_e32 v222, s43, v106
	v_fmac_f32_e32 v223, s43, v107
	v_fmac_f32_e32 v216, s15, v44
	v_fmac_f32_e32 v217, s15, v45
	v_fmac_f32_e32 v218, s15, v46
	v_fmac_f32_e32 v219, s15, v47
	v_fmac_f32_e32 v220, s63, v108
	v_fmac_f32_e32 v221, s63, v109
	v_fmac_f32_e32 v222, s63, v110
	v_fmac_f32_e32 v223, s63, v111
	v_fmac_f32_e32 v216, s25, v48
	v_fmac_f32_e32 v217, s25, v49
	v_fmac_f32_e32 v218, s25, v50
	v_fmac_f32_e32 v219, s25, v51
	v_fmac_f32_e32 v220, s64, v112
	v_fmac_f32_e32 v221, s64, v113
	v_fmac_f32_e32 v222, s64, v114
	v_fmac_f32_e32 v223, s64, v115
	v_fmac_f32_e32 v216, s26, v52
	v_fmac_f32_e32 v217, s26, v53
	v_fmac_f32_e32 v218, s26, v54
	v_fmac_f32_e32 v219, s26, v55
	v_fmac_f32_e32 v220, s65, v116
	v_fmac_f32_e32 v221, s65, v117
	v_fmac_f32_e32 v222, s65, v118
	v_fmac_f32_e32 v223, s65, v119
	v_fmac_f32_e32 v216, s27, v56
	v_fmac_f32_e32 v217, s27, v57
	v_fmac_f32_e32 v218, s27, v58
	v_fmac_f32_e32 v219, s27, v59
	v_fmac_f32_e32 v220, s74, v120
	v_fmac_f32_e32 v221, s74, v121
	v_fmac_f32_e32 v222, s74, v122
	v_fmac_f32_e32 v223, s74, v123
	v_fmac_f32_e32 v216, s36, v60
	v_fmac_f32_e32 v217, s36, v61
	v_fmac_f32_e32 v218, s36, v62
	v_fmac_f32_e32 v219, s36, v63
	v_fmac_f32_e32 v220, s75, v124
	v_fmac_f32_e32 v221, s75, v125
	v_fmac_f32_e32 v222, s75, v126
	v_fmac_f32_e32 v223, s75, v127
	v_fmac_f32_e32 v216, s37, v64
	v_fmac_f32_e32 v217, s37, v65
	v_fmac_f32_e32 v218, s37, v66
	v_fmac_f32_e32 v219, s37, v67
	v_fmac_f32_e32 v220, s76, v128
	v_fmac_f32_e32 v221, s76, v129
	v_fmac_f32_e32 v222, s76, v130
	v_fmac_f32_e32 v223, s76, v131
	v_fmac_f32_e32 v216, s42, v68
	v_fmac_f32_e32 v217, s42, v69
	v_fmac_f32_e32 v218, s42, v70
	v_fmac_f32_e32 v219, s42, v71
	v_fmac_f32_e32 v220, s77, v132
	v_fmac_f32_e32 v221, s77, v133
	v_fmac_f32_e32 v222, s77, v134
	v_fmac_f32_e32 v223, s77, v135
	v_mul_f32_e64 v224, |v216|, s101
	v_mul_f32_e64 v225, |v217|, s101
	v_mul_f32_e64 v226, |v218|, s101
	v_mul_f32_e64 v227, |v219|, s101
	v_exp_f32_e32 v224, v224
	v_exp_f32_e32 v225, v225
	v_exp_f32_e32 v226, v226
	v_exp_f32_e32 v227, v227
	v_max_f32_e64 v216, -v216, 0
	v_max_f32_e64 v217, -v217, 0
	v_max_f32_e64 v218, -v218, 0
; __device__ __forceinline__ unsigned pk2(float lo, float hi) { unsigned r; asm("v_cvt_pk_bf16_f32 %0, %1, %2" : "=v"(r) : "v"(lo), "v"(hi)); return r; }
; __device__ __forceinline__ void p2_gate(const Params& p, const LAS float* aup, int t0, int lane) {
;     ...
;         *(u32x4*)(GG + (size_t)t * 512 + lane * 8) = __builtin_nontemporal_load((const u32x4*)(zg + 1024 + lane * 8));
;         const unsigned short araw = zg[1536 + (lane & 31)]; const int alo = (int)((unsigned)araw << 16);
;         f32x4 acc0 = ab0, acc1 = ab1;
; #pragma unroll
;         for (int r = 0; r < 16; ++r) { const float a0 = __int_as_float(__builtin_amdgcn_readlane(alo, r)), a1 = __int_as_float(__builtin_amdgcn_readlane(alo, 16 + r));
;             acc0 += a0 * *(const LAS f32x4*)(aup + r * 256 + 4 * lane); acc1 += a1 * *(const LAS f32x4*)(aup + (16 + r) * 256 + 4 * lane); }
;         float n0[4], n1[4];
; #pragma unroll
;         for (int j = 0; j < 4; ++j) { const float y0 = -acc0[j], y1 = -acc1[j];
;             n0[j] = (fmaxf(y0, 0.f) + __logf(1.0f + __expf(-fabsf(y0)))) * 0.0625f; n1[j] = (fmaxf(y1, 0.f) + __logf(1.0f + __expf(-fabsf(y1)))) * 0.0625f; }
;         u32x2 w; w.x = pk2(n0[0], n0[1]); w.y = pk2(n0[2], n0[3]); *(u32x2*)(GNL + (size_t)t * 512 + 4 * lane) = w;
;         w.x = pk2(n1[0], n1[1]); w.y = pk2(n1[2], n1[3]); *(u32x2*)(GNL + (size_t)t * 512 + 256 + 4 * lane) = w;
	v_max_f32_e64 v219, -v219, 0
	v_add_f32_e32 v224, 1.0, v224
	v_add_f32_e32 v225, 1.0, v225
	v_add_f32_e32 v226, 1.0, v226
	v_add_f32_e32 v227, 1.0, v227
	v_log_f32_e32 v224, v224
	v_log_f32_e32 v225, v225
	v_log_f32_e32 v226, v226
	v_log_f32_e32 v227, v227
	s_nop 0
	v_fmac_f32_e32 v216, 0x3f317218, v224
	v_fmac_f32_e32 v217, 0x3f317218, v225
	v_fmac_f32_e32 v218, 0x3f317218, v226
	v_fmac_f32_e32 v219, 0x3f317218, v227
	v_mul_f32_e32 v216, 0x3d800000, v216
	v_mul_f32_e32 v217, 0x3d800000, v217
	v_mul_f32_e32 v218, 0x3d800000, v218
	v_mul_f32_e32 v219, 0x3d800000, v219
	v_mul_f32_e64 v224, |v220|, s101
	v_mul_f32_e64 v225, |v221|, s101
	v_mul_f32_e64 v226, |v222|, s101
	v_mul_f32_e64 v227, |v223|, s101
	v_exp_f32_e32 v224, v224
	v_exp_f32_e32 v225, v225
	v_exp_f32_e32 v226, v226
	v_exp_f32_e32 v227, v227
	v_max_f32_e64 v220, -v220, 0
	v_max_f32_e64 v221, -v221, 0
	v_max_f32_e64 v222, -v222, 0
	v_max_f32_e64 v223, -v223, 0
	v_add_f32_e32 v224, 1.0, v224
	v_add_f32_e32 v225, 1.0, v225
	v_add_f32_e32 v226, 1.0, v226
	v_add_f32_e32 v227, 1.0, v227
	v_log_f32_e32 v224, v224
	v_log_f32_e32 v225, v225
	v_log_f32_e32 v226, v226
	v_log_f32_e32 v227, v227
	s_nop 0
	v_fmac_f32_e32 v220, 0x3f317218, v224
	v_fmac_f32_e32 v221, 0x3f317218, v225
	v_fmac_f32_e32 v222, 0x3f317218, v226
	v_fmac_f32_e32 v223, 0x3f317218, v227
	v_mul_f32_e32 v220, 0x3d800000, v220
	v_mul_f32_e32 v221, 0x3d800000, v221
	v_mul_f32_e32 v222, 0x3d800000, v222
	v_mul_f32_e32 v223, 0x3d800000, v223
	v_cvt_pk_bf16_f32 v224, v216, v217
	v_cvt_pk_bf16_f32 v225, v218, v219
	v_cvt_pk_bf16_f32 v226, v220, v221
	v_cvt_pk_bf16_f32 v227, v222, v223
	global_store_dwordx2 v4, v[224:225], s[58:59] nt
	global_store_dwordx2 v4, v[226:227], s[58:59] offset:512 nt
	v_add_u32_e32 v5, 0x400, v5
	v_add_u32_e32 v4, 0x400, v4
	s_waitcnt vmcnt(31)
	global_store_dwordx4 v5, v[140:143], s[58:59] nt
	v_lshlrev_b32_e32 v201, 16, v201
	v_mov_b32_e32 v216, v228
	v_mov_b32_e32 v217, v229
	v_mov_b32_e32 v218, v230
	v_mov_b32_e32 v219, v231
	v_mov_b32_e32 v220, v232
	v_mov_b32_e32 v221, v233
	v_mov_b32_e32 v222, v234
	v_mov_b32_e32 v223, v235
	s_nop 0
	v_readlane_b32 s14, v201, 0
	v_readlane_b32 s15, v201, 1
	v_readlane_b32 s25, v201, 2
	v_readlane_b32 s26, v201, 3
	v_readlane_b32 s27, v201, 4
	v_readlane_b32 s36, v201, 5
	v_readlane_b32 s37, v201, 6
	v_readlane_b32 s42, v201, 7
	v_readlane_b32 s43, v201, 16
	v_readlane_b32 s63, v201, 17
	v_readlane_b32 s64, v201, 18
	v_readlane_b32 s65, v201, 19
	v_readlane_b32 s74, v201, 20
	v_readlane_b32 s75, v201, 21
	v_readlane_b32 s76, v201, 22
	v_readlane_b32 s77, v201, 23
	s_nop 1
	v_fmac_f32_e32 v216, s14, v8
	v_fmac_f32_e32 v217, s14, v9
	v_fmac_f32_e32 v218, s14, v10
	v_fmac_f32_e32 v219, s14, v11
	v_fmac_f32_e32 v220, s43, v72
	v_fmac_f32_e32 v221, s43, v73
	v_fmac_f32_e32 v222, s43, v74
	v_fmac_f32_e32 v223, s43, v75
	v_fmac_f32_e32 v216, s15, v12
	v_fmac_f32_e32 v217, s15, v13
	v_fmac_f32_e32 v218, s15, v14
	v_fmac_f32_e32 v219, s15, v15
	v_fmac_f32_e32 v220, s63, v76
	v_fmac_f32_e32 v221, s63, v77
	v_fmac_f32_e32 v222, s63, v78
	v_fmac_f32_e32 v223, s63, v79
	v_fmac_f32_e32 v216, s25, v16
	v_fmac_f32_e32 v217, s25, v17
	v_fmac_f32_e32 v218, s25, v18
	v_fmac_f32_e32 v219, s25, v19
	v_fmac_f32_e32 v220, s64, v80
	v_fmac_f32_e32 v221, s64, v81
	v_fmac_f32_e32 v222, s64, v82
	v_fmac_f32_e32 v223, s64, v83
	v_fmac_f32_e32 v216, s26, v20
	v_fmac_f32_e32 v217, s26, v21
	v_fmac_f32_e32 v218, s26, v22
	v_fmac_f32_e32 v219, s26, v23
	v_fmac_f32_e32 v220, s65, v84
	v_fmac_f32_e32 v221, s65, v85
	v_fmac_f32_e32 v222, s65, v86
	v_fmac_f32_e32 v223, s65, v87
	v_fmac_f32_e32 v216, s27, v24
	v_fmac_f32_e32 v217, s27, v25
	v_fmac_f32_e32 v218, s27, v26
	v_fmac_f32_e32 v219, s27, v27
	v_fmac_f32_e32 v220, s74, v88
	v_fmac_f32_e32 v221, s74, v89
	v_fmac_f32_e32 v222, s74, v90
	v_fmac_f32_e32 v223, s74, v91
	v_fmac_f32_e32 v216, s36, v28
	v_fmac_f32_e32 v217, s36, v29
	v_fmac_f32_e32 v218, s36, v30
	v_fmac_f32_e32 v219, s36, v31
	v_fmac_f32_e32 v220, s75, v92
	v_fmac_f32_e32 v221, s75, v93
	v_fmac_f32_e32 v222, s75, v94
	v_fmac_f32_e32 v223, s75, v95
	v_fmac_f32_e32 v216, s37, v32
	v_fmac_f32_e32 v217, s37, v33
	v_fmac_f32_e32 v218, s37, v34
	v_fmac_f32_e32 v219, s37, v35
	v_fmac_f32_e32 v220, s76, v96
	v_fmac_f32_e32 v221, s76, v97
	v_fmac_f32_e32 v222, s76, v98
	v_fmac_f32_e32 v223, s76, v99
	v_fmac_f32_e32 v216, s42, v36
	v_fmac_f32_e32 v217, s42, v37
	v_fmac_f32_e32 v218, s42, v38
	v_fmac_f32_e32 v219, s42, v39
	v_fmac_f32_e32 v220, s77, v100
	v_fmac_f32_e32 v221, s77, v101
	v_fmac_f32_e32 v222, s77, v102
	v_fmac_f32_e32 v223, s77, v103
	s_nop 0
	v_readlane_b32 s14, v201, 8
	v_readlane_b32 s15, v201, 9
	v_readlane_b32 s25, v201, 10
	v_readlane_b32 s26, v201, 11
	v_readlane_b32 s27, v201, 12
	v_readlane_b32 s36, v201, 13
	v_readlane_b32 s37, v201, 14
	v_readlane_b32 s42, v201, 15
	v_readlane_b32 s43, v201, 24
	v_readlane_b32 s63, v201, 25
	v_readlane_b32 s64, v201, 26
	v_readlane_b32 s65, v201, 27
	v_readlane_b32 s74, v201, 28
	v_readlane_b32 s75, v201, 29
	v_readlane_b32 s76, v201, 30
	v_readlane_b32 s77, v201, 31
	s_nop 1
	v_fmac_f32_e32 v216, s14, v40
	v_fmac_f32_e32 v217, s14, v41
	v_fmac_f32_e32 v218, s14, v42
	v_fmac_f32_e32 v219, s14, v43
	v_fmac_f32_e32 v220, s43, v104
	v_fmac_f32_e32 v221, s43, v105
	v_fmac_f32_e32 v222, s43, v106
	v_fmac_f32_e32 v223, s43, v107
	v_fmac_f32_e32 v216, s15, v44
	v_fmac_f32_e32 v217, s15, v45
	v_fmac_f32_e32 v218, s15, v46
	v_fmac_f32_e32 v219, s15, v47
	v_fmac_f32_e32 v220, s63, v108
	v_fmac_f32_e32 v221, s63, v109
	v_fmac_f32_e32 v222, s63, v110
	v_fmac_f32_e32 v223, s63, v111
	v_fmac_f32_e32 v216, s25, v48
	v_fmac_f32_e32 v217, s25, v49
; __device__ __forceinline__ unsigned pk2(float lo, float hi) { unsigned r; asm("v_cvt_pk_bf16_f32 %0, %1, %2" : "=v"(r) : "v"(lo), "v"(hi)); return r; }
; __device__ __forceinline__ void p2_gate(const Params& p, const LAS float* aup, int t0, int lane) {
;     ...
;         *(u32x4*)(GG + (size_t)t * 512 + lane * 8) = __builtin_nontemporal_load((const u32x4*)(zg + 1024 + lane * 8));
;         const unsigned short araw = zg[1536 + (lane & 31)]; const int alo = (int)((unsigned)araw << 16);
;         f32x4 acc0 = ab0, acc1 = ab1;
; #pragma unroll
;         for (int r = 0; r < 16; ++r) { const float a0 = __int_as_float(__builtin_amdgcn_readlane(alo, r)), a1 = __int_as_float(__builtin_amdgcn_readlane(alo, 16 + r));
;             acc0 += a0 * *(const LAS f32x4*)(aup + r * 256 + 4 * lane); acc1 += a1 * *(const LAS f32x4*)(aup + (16 + r) * 256 + 4 * lane); }
;         float n0[4], n1[4];
; #pragma unroll
;         for (int j = 0; j < 4; ++j) { const float y0 = -acc0[j], y1 = -acc1[j];
;             n0[j] = (fmaxf(y0, 0.f) + __logf(1.0f + __expf(-fabsf(y0)))) * 0.0625f; n1[j] = (fmaxf(y1, 0.f) + __logf(1.0f + __expf(-fabsf(y1)))) * 0.0625f; }
;         u32x2 w; w.x = pk2(n0[0], n0[1]); w.y = pk2(n0[2], n0[3]); *(u32x2*)(GNL + (size_t)t * 512 + 4 * lane) = w;
;         w.x = pk2(n1[0], n1[1]); w.y = pk2(n1[2], n1[3]); *(u32x2*)(GNL + (size_t)t * 512 + 256 + 4 * lane) = w;
	v_fmac_f32_e32 v218, s25, v50
	v_fmac_f32_e32 v219, s25, v51
	v_fmac_f32_e32 v220, s64, v112
	v_fmac_f32_e32 v221, s64, v113
	v_fmac_f32_e32 v222, s64, v114
	v_fmac_f32_e32 v223, s64, v115
	v_fmac_f32_e32 v216, s26, v52
	v_fmac_f32_e32 v217, s26, v53
	v_fmac_f32_e32 v218, s26, v54
	v_fmac_f32_e32 v219, s26, v55
	v_fmac_f32_e32 v220, s65, v116
	v_fmac_f32_e32 v221, s65, v117
	v_fmac_f32_e32 v222, s65, v118
	v_fmac_f32_e32 v223, s65, v119
	v_fmac_f32_e32 v216, s27, v56
	v_fmac_f32_e32 v217, s27, v57
	v_fmac_f32_e32 v218, s27, v58
	v_fmac_f32_e32 v219, s27, v59
	v_fmac_f32_e32 v220, s74, v120
	v_fmac_f32_e32 v221, s74, v121
	v_fmac_f32_e32 v222, s74, v122
	v_fmac_f32_e32 v223, s74, v123
	v_fmac_f32_e32 v216, s36, v60
	v_fmac_f32_e32 v217, s36, v61
	v_fmac_f32_e32 v218, s36, v62
	v_fmac_f32_e32 v219, s36, v63
	v_fmac_f32_e32 v220, s75, v124
	v_fmac_f32_e32 v221, s75, v125
	v_fmac_f32_e32 v222, s75, v126
	v_fmac_f32_e32 v223, s75, v127
	v_fmac_f32_e32 v216, s37, v64
	v_fmac_f32_e32 v217, s37, v65
	v_fmac_f32_e32 v218, s37, v66
	v_fmac_f32_e32 v219, s37, v67
	v_fmac_f32_e32 v220, s76, v128
	v_fmac_f32_e32 v221, s76, v129
	v_fmac_f32_e32 v222, s76, v130
	v_fmac_f32_e32 v223, s76, v131
	v_fmac_f32_e32 v216, s42, v68
	v_fmac_f32_e32 v217, s42, v69
	v_fmac_f32_e32 v218, s42, v70
	v_fmac_f32_e32 v219, s42, v71
	v_fmac_f32_e32 v220, s77, v132
	v_fmac_f32_e32 v221, s77, v133
	v_fmac_f32_e32 v222, s77, v134
	v_fmac_f32_e32 v223, s77, v135
	v_mul_f32_e64 v224, |v216|, s101
	v_mul_f32_e64 v225, |v217|, s101
	v_mul_f32_e64 v226, |v218|, s101
	v_mul_f32_e64 v227, |v219|, s101
	v_exp_f32_e32 v224, v224
	v_exp_f32_e32 v225, v225
	v_exp_f32_e32 v226, v226
	v_exp_f32_e32 v227, v227
	v_max_f32_e64 v216, -v216, 0
	v_max_f32_e64 v217, -v217, 0
	v_max_f32_e64 v218, -v218, 0
	v_max_f32_e64 v219, -v219, 0
	v_add_f32_e32 v224, 1.0, v224
	v_add_f32_e32 v225, 1.0, v225
	v_add_f32_e32 v226, 1.0, v226
	v_add_f32_e32 v227, 1.0, v227
	v_log_f32_e32 v224, v224
	v_log_f32_e32 v225, v225
	v_log_f32_e32 v226, v226
	v_log_f32_e32 v227, v227
	s_nop 0
	v_fmac_f32_e32 v216, 0x3f317218, v224
	v_fmac_f32_e32 v217, 0x3f317218, v225
	v_fmac_f32_e32 v218, 0x3f317218, v226
	v_fmac_f32_e32 v219, 0x3f317218, v227
	v_mul_f32_e32 v216, 0x3d800000, v216
	v_mul_f32_e32 v217, 0x3d800000, v217
	v_mul_f32_e32 v218, 0x3d800000, v218
	v_mul_f32_e32 v219, 0x3d800000, v219
	v_mul_f32_e64 v224, |v220|, s101
	v_mul_f32_e64 v225, |v221|, s101
	v_mul_f32_e64 v226, |v222|, s101
	v_mul_f32_e64 v227, |v223|, s101
	v_exp_f32_e32 v224, v224
	v_exp_f32_e32 v225, v225
	v_exp_f32_e32 v226, v226
	v_exp_f32_e32 v227, v227
	v_max_f32_e64 v220, -v220, 0
	v_max_f32_e64 v221, -v221, 0
	v_max_f32_e64 v222, -v222, 0
	v_max_f32_e64 v223, -v223, 0
	v_add_f32_e32 v224, 1.0, v224
	v_add_f32_e32 v225, 1.0, v225
	v_add_f32_e32 v226, 1.0, v226
	v_add_f32_e32 v227, 1.0, v227
	v_log_f32_e32 v224, v224
	v_log_f32_e32 v225, v225
	v_log_f32_e32 v226, v226
	v_log_f32_e32 v227, v227
	s_nop 0
	v_fmac_f32_e32 v220, 0x3f317218, v224
	v_fmac_f32_e32 v221, 0x3f317218, v225
	v_fmac_f32_e32 v222, 0x3f317218, v226
	v_fmac_f32_e32 v223, 0x3f317218, v227
	v_mul_f32_e32 v220, 0x3d800000, v220
	v_mul_f32_e32 v221, 0x3d800000, v221
	v_mul_f32_e32 v222, 0x3d800000, v222
	v_mul_f32_e32 v223, 0x3d800000, v223
	v_cvt_pk_bf16_f32 v224, v216, v217
	v_cvt_pk_bf16_f32 v225, v218, v219
	v_cvt_pk_bf16_f32 v226, v220, v221
	v_cvt_pk_bf16_f32 v227, v222, v223
	global_store_dwordx2 v4, v[224:225], s[58:59] nt
	global_store_dwordx2 v4, v[226:227], s[58:59] offset:512 nt
	v_add_u32_e32 v5, 0x400, v5
	v_add_u32_e32 v4, 0x400, v4
	s_waitcnt vmcnt(32)
	global_store_dwordx4 v5, v[144:147], s[58:59] nt
	v_lshlrev_b32_e32 v202, 16, v202
	v_mov_b32_e32 v216, v228
	v_mov_b32_e32 v217, v229
	v_mov_b32_e32 v218, v230
	v_mov_b32_e32 v219, v231
	v_mov_b32_e32 v220, v232
	v_mov_b32_e32 v221, v233
	v_mov_b32_e32 v222, v234
	v_mov_b32_e32 v223, v235
	s_nop 0
	v_readlane_b32 s14, v202, 0
	v_readlane_b32 s15, v202, 1
	v_readlane_b32 s25, v202, 2
	v_readlane_b32 s26, v202, 3
	v_readlane_b32 s27, v202, 4
	v_readlane_b32 s36, v202, 5
	v_readlane_b32 s37, v202, 6
	v_readlane_b32 s42, v202, 7
	v_readlane_b32 s43, v202, 16
	v_readlane_b32 s63, v202, 17
	v_readlane_b32 s64, v202, 18
	v_readlane_b32 s65, v202, 19
	v_readlane_b32 s74, v202, 20
	v_readlane_b32 s75, v202, 21
	v_readlane_b32 s76, v202, 22
	v_readlane_b32 s77, v202, 23
	s_nop 1
	v_fmac_f32_e32 v216, s14, v8
	v_fmac_f32_e32 v217, s14, v9
	v_fmac_f32_e32 v218, s14, v10
	v_fmac_f32_e32 v219, s14, v11
	v_fmac_f32_e32 v220, s43, v72
	v_fmac_f32_e32 v221, s43, v73
	v_fmac_f32_e32 v222, s43, v74
	v_fmac_f32_e32 v223, s43, v75
	v_fmac_f32_e32 v216, s15, v12
	v_fmac_f32_e32 v217, s15, v13
	v_fmac_f32_e32 v218, s15, v14
	v_fmac_f32_e32 v219, s15, v15
	v_fmac_f32_e32 v220, s63, v76
	v_fmac_f32_e32 v221, s63, v77
	v_fmac_f32_e32 v222, s63, v78
	v_fmac_f32_e32 v223, s63, v79
	v_fmac_f32_e32 v216, s25, v16
	v_fmac_f32_e32 v217, s25, v17
	v_fmac_f32_e32 v218, s25, v18
	v_fmac_f32_e32 v219, s25, v19
	v_fmac_f32_e32 v220, s64, v80
	v_fmac_f32_e32 v221, s64, v81
	v_fmac_f32_e32 v222, s64, v82
	v_fmac_f32_e32 v223, s64, v83
	v_fmac_f32_e32 v216, s26, v20
	v_fmac_f32_e32 v217, s26, v21
	v_fmac_f32_e32 v218, s26, v22
	v_fmac_f32_e32 v219, s26, v23
	v_fmac_f32_e32 v220, s65, v84
	v_fmac_f32_e32 v221, s65, v85
	v_fmac_f32_e32 v222, s65, v86
	v_fmac_f32_e32 v223, s65, v87
	v_fmac_f32_e32 v216, s27, v24
	v_fmac_f32_e32 v217, s27, v25
	v_fmac_f32_e32 v218, s27, v26
	v_fmac_f32_e32 v219, s27, v27
	v_fmac_f32_e32 v220, s74, v88
	v_fmac_f32_e32 v221, s74, v89
	v_fmac_f32_e32 v222, s74, v90
	v_fmac_f32_e32 v223, s74, v91
	v_fmac_f32_e32 v216, s36, v28
; __device__ __forceinline__ unsigned pk2(float lo, float hi) { unsigned r; asm("v_cvt_pk_bf16_f32 %0, %1, %2" : "=v"(r) : "v"(lo), "v"(hi)); return r; }
; __device__ __forceinline__ void p2_gate(const Params& p, const LAS float* aup, int t0, int lane) {
;     ...
;         for (int r = 0; r < 16; ++r) { const float a0 = __int_as_float(__builtin_amdgcn_readlane(alo, r)), a1 = __int_as_float(__builtin_amdgcn_readlane(alo, 16 + r));
;             acc0 += a0 * *(const LAS f32x4*)(aup + r * 256 + 4 * lane); acc1 += a1 * *(const LAS f32x4*)(aup + (16 + r) * 256 + 4 * lane); }
;         float n0[4], n1[4];
; #pragma unroll
;         for (int j = 0; j < 4; ++j) { const float y0 = -acc0[j], y1 = -acc1[j];
;             n0[j] = (fmaxf(y0, 0.f) + __logf(1.0f + __expf(-fabsf(y0)))) * 0.0625f; n1[j] = (fmaxf(y1, 0.f) + __logf(1.0f + __expf(-fabsf(y1)))) * 0.0625f; }
;         u32x2 w; w.x = pk2(n0[0], n0[1]); w.y = pk2(n0[2], n0[3]); *(u32x2*)(GNL + (size_t)t * 512 + 4 * lane) = w;
;         w.x = pk2(n1[0], n1[1]); w.y = pk2(n1[2], n1[3]); *(u32x2*)(GNL + (size_t)t * 512 + 256 + 4 * lane) = w;
	v_fmac_f32_e32 v217, s36, v29
	v_fmac_f32_e32 v218, s36, v30
	v_fmac_f32_e32 v219, s36, v31
	v_fmac_f32_e32 v220, s75, v92
	v_fmac_f32_e32 v221, s75, v93
	v_fmac_f32_e32 v222, s75, v94
	v_fmac_f32_e32 v223, s75, v95
	v_fmac_f32_e32 v216, s37, v32
	v_fmac_f32_e32 v217, s37, v33
	v_fmac_f32_e32 v218, s37, v34
	v_fmac_f32_e32 v219, s37, v35
	v_fmac_f32_e32 v220, s76, v96
	v_fmac_f32_e32 v221, s76, v97
	v_fmac_f32_e32 v222, s76, v98
	v_fmac_f32_e32 v223, s76, v99
	v_fmac_f32_e32 v216, s42, v36
	v_fmac_f32_e32 v217, s42, v37
	v_fmac_f32_e32 v218, s42, v38
	v_fmac_f32_e32 v219, s42, v39
	v_fmac_f32_e32 v220, s77, v100
	v_fmac_f32_e32 v221, s77, v101
	v_fmac_f32_e32 v222, s77, v102
	v_fmac_f32_e32 v223, s77, v103
	s_nop 0
	v_readlane_b32 s14, v202, 8
	v_readlane_b32 s15, v202, 9
	v_readlane_b32 s25, v202, 10
	v_readlane_b32 s26, v202, 11
	v_readlane_b32 s27, v202, 12
	v_readlane_b32 s36, v202, 13
	v_readlane_b32 s37, v202, 14
	v_readlane_b32 s42, v202, 15
	v_readlane_b32 s43, v202, 24
	v_readlane_b32 s63, v202, 25
	v_readlane_b32 s64, v202, 26
	v_readlane_b32 s65, v202, 27
	v_readlane_b32 s74, v202, 28
	v_readlane_b32 s75, v202, 29
	v_readlane_b32 s76, v202, 30
	v_readlane_b32 s77, v202, 31
	s_nop 1
	v_fmac_f32_e32 v216, s14, v40
	v_fmac_f32_e32 v217, s14, v41
	v_fmac_f32_e32 v218, s14, v42
	v_fmac_f32_e32 v219, s14, v43
	v_fmac_f32_e32 v220, s43, v104
	v_fmac_f32_e32 v221, s43, v105
	v_fmac_f32_e32 v222, s43, v106
	v_fmac_f32_e32 v223, s43, v107
	v_fmac_f32_e32 v216, s15, v44
	v_fmac_f32_e32 v217, s15, v45
	v_fmac_f32_e32 v218, s15, v46
	v_fmac_f32_e32 v219, s15, v47
	v_fmac_f32_e32 v220, s63, v108
	v_fmac_f32_e32 v221, s63, v109
	v_fmac_f32_e32 v222, s63, v110
	v_fmac_f32_e32 v223, s63, v111
	v_fmac_f32_e32 v216, s25, v48
	v_fmac_f32_e32 v217, s25, v49
	v_fmac_f32_e32 v218, s25, v50
	v_fmac_f32_e32 v219, s25, v51
	v_fmac_f32_e32 v220, s64, v112
	v_fmac_f32_e32 v221, s64, v113
	v_fmac_f32_e32 v222, s64, v114
	v_fmac_f32_e32 v223, s64, v115
	v_fmac_f32_e32 v216, s26, v52
	v_fmac_f32_e32 v217, s26, v53
	v_fmac_f32_e32 v218, s26, v54
	v_fmac_f32_e32 v219, s26, v55
	v_fmac_f32_e32 v220, s65, v116
	v_fmac_f32_e32 v221, s65, v117
	v_fmac_f32_e32 v222, s65, v118
	v_fmac_f32_e32 v223, s65, v119
	v_fmac_f32_e32 v216, s27, v56
	v_fmac_f32_e32 v217, s27, v57
	v_fmac_f32_e32 v218, s27, v58
	v_fmac_f32_e32 v219, s27, v59
	v_fmac_f32_e32 v220, s74, v120
	v_fmac_f32_e32 v221, s74, v121
	v_fmac_f32_e32 v222, s74, v122
	v_fmac_f32_e32 v223, s74, v123
	v_fmac_f32_e32 v216, s36, v60
	v_fmac_f32_e32 v217, s36, v61
	v_fmac_f32_e32 v218, s36, v62
	v_fmac_f32_e32 v219, s36, v63
	v_fmac_f32_e32 v220, s75, v124
	v_fmac_f32_e32 v221, s75, v125
	v_fmac_f32_e32 v222, s75, v126
	v_fmac_f32_e32 v223, s75, v127
	v_fmac_f32_e32 v216, s37, v64
	v_fmac_f32_e32 v217, s37, v65
	v_fmac_f32_e32 v218, s37, v66
	v_fmac_f32_e32 v219, s37, v67
	v_fmac_f32_e32 v220, s76, v128
	v_fmac_f32_e32 v221, s76, v129
	v_fmac_f32_e32 v222, s76, v130
	v_fmac_f32_e32 v223, s76, v131
	v_fmac_f32_e32 v216, s42, v68
	v_fmac_f32_e32 v217, s42, v69
	v_fmac_f32_e32 v218, s42, v70
	v_fmac_f32_e32 v219, s42, v71
	v_fmac_f32_e32 v220, s77, v132
	v_fmac_f32_e32 v221, s77, v133
	v_fmac_f32_e32 v222, s77, v134
	v_fmac_f32_e32 v223, s77, v135
	v_mul_f32_e64 v224, |v216|, s101
	v_mul_f32_e64 v225, |v217|, s101
	v_mul_f32_e64 v226, |v218|, s101
	v_mul_f32_e64 v227, |v219|, s101
	v_exp_f32_e32 v224, v224
	v_exp_f32_e32 v225, v225
	v_exp_f32_e32 v226, v226
	v_exp_f32_e32 v227, v227
	v_max_f32_e64 v216, -v216, 0
	v_max_f32_e64 v217, -v217, 0
	v_max_f32_e64 v218, -v218, 0
	v_max_f32_e64 v219, -v219, 0
	v_add_f32_e32 v224, 1.0, v224
	v_add_f32_e32 v225, 1.0, v225
	v_add_f32_e32 v226, 1.0, v226
	v_add_f32_e32 v227, 1.0, v227
	v_log_f32_e32 v224, v224
	v_log_f32_e32 v225, v225
	v_log_f32_e32 v226, v226
	v_log_f32_e32 v227, v227
	s_nop 0
	v_fmac_f32_e32 v216, 0x3f317218, v224
	v_fmac_f32_e32 v217, 0x3f317218, v225
	v_fmac_f32_e32 v218, 0x3f317218, v226
	v_fmac_f32_e32 v219, 0x3f317218, v227
	v_mul_f32_e32 v216, 0x3d800000, v216
	v_mul_f32_e32 v217, 0x3d800000, v217
	v_mul_f32_e32 v218, 0x3d800000, v218
	v_mul_f32_e32 v219, 0x3d800000, v219
	v_mul_f32_e64 v224, |v220|, s101
	v_mul_f32_e64 v225, |v221|, s101
	v_mul_f32_e64 v226, |v222|, s101
	v_mul_f32_e64 v227, |v223|, s101
	v_exp_f32_e32 v224, v224
	v_exp_f32_e32 v225, v225
	v_exp_f32_e32 v226, v226
	v_exp_f32_e32 v227, v227
	v_max_f32_e64 v220, -v220, 0
	v_max_f32_e64 v221, -v221, 0
	v_max_f32_e64 v222, -v222, 0
	v_max_f32_e64 v223, -v223, 0
	v_add_f32_e32 v224, 1.0, v224
	v_add_f32_e32 v225, 1.0, v225
	v_add_f32_e32 v226, 1.0, v226
	v_add_f32_e32 v227, 1.0, v227
	v_log_f32_e32 v224, v224
	v_log_f32_e32 v225, v225
	v_log_f32_e32 v226, v226
	v_log_f32_e32 v227, v227
	s_nop 0
	v_fmac_f32_e32 v220, 0x3f317218, v224
	v_fmac_f32_e32 v221, 0x3f317218, v225
	v_fmac_f32_e32 v222, 0x3f317218, v226
	v_fmac_f32_e32 v223, 0x3f317218, v227
	v_mul_f32_e32 v220, 0x3d800000, v220
	v_mul_f32_e32 v221, 0x3d800000, v221
	v_mul_f32_e32 v222, 0x3d800000, v222
	v_mul_f32_e32 v223, 0x3d800000, v223
	v_cvt_pk_bf16_f32 v224, v216, v217
	v_cvt_pk_bf16_f32 v225, v218, v219
	v_cvt_pk_bf16_f32 v226, v220, v221
	v_cvt_pk_bf16_f32 v227, v222, v223
	global_store_dwordx2 v4, v[224:225], s[58:59] nt
	global_store_dwordx2 v4, v[226:227], s[58:59] offset:512 nt
	v_add_u32_e32 v5, 0x400, v5
	v_add_u32_e32 v4, 0x400, v4
	s_waitcnt vmcnt(33)
; __device__ __forceinline__ void p2_gate(const Params& p, const LAS float* aup, int t0, int lane) {
;     ...
;         *(u32x4*)(GG + (size_t)t * 512 + lane * 8) = __builtin_nontemporal_load((const u32x4*)(zg + 1024 + lane * 8));
;         const unsigned short araw = zg[1536 + (lane & 31)]; const int alo = (int)((unsigned)araw << 16);
;         f32x4 acc0 = ab0, acc1 = ab1;
; #pragma unroll
;         for (int r = 0; r < 16; ++r) { const float a0 = __int_as_float(__builtin_amdgcn_readlane(alo, r)), a1 = __int_as_float(__builtin_amdgcn_readlane(alo, 16 + r));
;             acc0 += a0 * *(const LAS f32x4*)(aup + r * 256 + 4 * lane); acc1 += a1 * *(const LAS f32x4*)(aup + (16 + r) * 256 + 4 * lane); }
;         float n0[4], n1[4];
; #pragma unroll
;         for (int j = 0; j < 4; ++j) { const float y0 = -acc0[j], y1 = -acc1[j];
;             n0[j] = (fmaxf(y0, 0.f) + __logf(1.0f + __expf(-fabsf(y0)))) * 0.0625f; n1[j] = (fmaxf(y1, 0.f) + __logf(1.0f + __expf(-fabsf(y1)))) * 0.0625f; }
	global_store_dwordx4 v5, v[148:151], s[58:59] nt
	v_lshlrev_b32_e32 v203, 16, v203
	v_mov_b32_e32 v216, v228
	v_mov_b32_e32 v217, v229
	v_mov_b32_e32 v218, v230
	v_mov_b32_e32 v219, v231
	v_mov_b32_e32 v220, v232
	v_mov_b32_e32 v221, v233
	v_mov_b32_e32 v222, v234
	v_mov_b32_e32 v223, v235
	s_nop 0
	v_readlane_b32 s14, v203, 0
	v_readlane_b32 s15, v203, 1
	v_readlane_b32 s25, v203, 2
	v_readlane_b32 s26, v203, 3
	v_readlane_b32 s27, v203, 4
	v_readlane_b32 s36, v203, 5
	v_readlane_b32 s37, v203, 6
	v_readlane_b32 s42, v203, 7
	v_readlane_b32 s43, v203, 16
	v_readlane_b32 s63, v203, 17
	v_readlane_b32 s64, v203, 18
	v_readlane_b32 s65, v203, 19
	v_readlane_b32 s74, v203, 20
	v_readlane_b32 s75, v203, 21
	v_readlane_b32 s76, v203, 22
	v_readlane_b32 s77, v203, 23
	s_nop 1
	v_fmac_f32_e32 v216, s14, v8
	v_fmac_f32_e32 v217, s14, v9
	v_fmac_f32_e32 v218, s14, v10
	v_fmac_f32_e32 v219, s14, v11
	v_fmac_f32_e32 v220, s43, v72
	v_fmac_f32_e32 v221, s43, v73
	v_fmac_f32_e32 v222, s43, v74
	v_fmac_f32_e32 v223, s43, v75
	v_fmac_f32_e32 v216, s15, v12
	v_fmac_f32_e32 v217, s15, v13
	v_fmac_f32_e32 v218, s15, v14
	v_fmac_f32_e32 v219, s15, v15
	v_fmac_f32_e32 v220, s63, v76
	v_fmac_f32_e32 v221, s63, v77
	v_fmac_f32_e32 v222, s63, v78
	v_fmac_f32_e32 v223, s63, v79
	v_fmac_f32_e32 v216, s25, v16
	v_fmac_f32_e32 v217, s25, v17
	v_fmac_f32_e32 v218, s25, v18
	v_fmac_f32_e32 v219, s25, v19
	v_fmac_f32_e32 v220, s64, v80
	v_fmac_f32_e32 v221, s64, v81
	v_fmac_f32_e32 v222, s64, v82
	v_fmac_f32_e32 v223, s64, v83
	v_fmac_f32_e32 v216, s26, v20
	v_fmac_f32_e32 v217, s26, v21
	v_fmac_f32_e32 v218, s26, v22
	v_fmac_f32_e32 v219, s26, v23
	v_fmac_f32_e32 v220, s65, v84
	v_fmac_f32_e32 v221, s65, v85
	v_fmac_f32_e32 v222, s65, v86
	v_fmac_f32_e32 v223, s65, v87
	v_fmac_f32_e32 v216, s27, v24
	v_fmac_f32_e32 v217, s27, v25
	v_fmac_f32_e32 v218, s27, v26
	v_fmac_f32_e32 v219, s27, v27
	v_fmac_f32_e32 v220, s74, v88
	v_fmac_f32_e32 v221, s74, v89
	v_fmac_f32_e32 v222, s74, v90
	v_fmac_f32_e32 v223, s74, v91
	v_fmac_f32_e32 v216, s36, v28
	v_fmac_f32_e32 v217, s36, v29
	v_fmac_f32_e32 v218, s36, v30
	v_fmac_f32_e32 v219, s36, v31
	v_fmac_f32_e32 v220, s75, v92
	v_fmac_f32_e32 v221, s75, v93
	v_fmac_f32_e32 v222, s75, v94
	v_fmac_f32_e32 v223, s75, v95
	v_fmac_f32_e32 v216, s37, v32
	v_fmac_f32_e32 v217, s37, v33
	v_fmac_f32_e32 v218, s37, v34
	v_fmac_f32_e32 v219, s37, v35
	v_fmac_f32_e32 v220, s76, v96
	v_fmac_f32_e32 v221, s76, v97
	v_fmac_f32_e32 v222, s76, v98
	v_fmac_f32_e32 v223, s76, v99
	v_fmac_f32_e32 v216, s42, v36
	v_fmac_f32_e32 v217, s42, v37
	v_fmac_f32_e32 v218, s42, v38
	v_fmac_f32_e32 v219, s42, v39
	v_fmac_f32_e32 v220, s77, v100
	v_fmac_f32_e32 v221, s77, v101
	v_fmac_f32_e32 v222, s77, v102
	v_fmac_f32_e32 v223, s77, v103
	s_nop 0
	v_readlane_b32 s14, v203, 8
	v_readlane_b32 s15, v203, 9
	v_readlane_b32 s25, v203, 10
	v_readlane_b32 s26, v203, 11
	v_readlane_b32 s27, v203, 12
	v_readlane_b32 s36, v203, 13
	v_readlane_b32 s37, v203, 14
	v_readlane_b32 s42, v203, 15
	v_readlane_b32 s43, v203, 24
	v_readlane_b32 s63, v203, 25
	v_readlane_b32 s64, v203, 26
	v_readlane_b32 s65, v203, 27
	v_readlane_b32 s74, v203, 28
	v_readlane_b32 s75, v203, 29
	v_readlane_b32 s76, v203, 30
	v_readlane_b32 s77, v203, 31
	s_nop 1
	v_fmac_f32_e32 v216, s14, v40
	v_fmac_f32_e32 v217, s14, v41
	v_fmac_f32_e32 v218, s14, v42
	v_fmac_f32_e32 v219, s14, v43
	v_fmac_f32_e32 v220, s43, v104
	v_fmac_f32_e32 v221, s43, v105
	v_fmac_f32_e32 v222, s43, v106
	v_fmac_f32_e32 v223, s43, v107
	v_fmac_f32_e32 v216, s15, v44
	v_fmac_f32_e32 v217, s15, v45
	v_fmac_f32_e32 v218, s15, v46
	v_fmac_f32_e32 v219, s15, v47
	v_fmac_f32_e32 v220, s63, v108
	v_fmac_f32_e32 v221, s63, v109
	v_fmac_f32_e32 v222, s63, v110
	v_fmac_f32_e32 v223, s63, v111
	v_fmac_f32_e32 v216, s25, v48
	v_fmac_f32_e32 v217, s25, v49
	v_fmac_f32_e32 v218, s25, v50
	v_fmac_f32_e32 v219, s25, v51
	v_fmac_f32_e32 v220, s64, v112
	v_fmac_f32_e32 v221, s64, v113
	v_fmac_f32_e32 v222, s64, v114
	v_fmac_f32_e32 v223, s64, v115
	v_fmac_f32_e32 v216, s26, v52
	v_fmac_f32_e32 v217, s26, v53
	v_fmac_f32_e32 v218, s26, v54
	v_fmac_f32_e32 v219, s26, v55
	v_fmac_f32_e32 v220, s65, v116
	v_fmac_f32_e32 v221, s65, v117
	v_fmac_f32_e32 v222, s65, v118
	v_fmac_f32_e32 v223, s65, v119
	v_fmac_f32_e32 v216, s27, v56
	v_fmac_f32_e32 v217, s27, v57
	v_fmac_f32_e32 v218, s27, v58
	v_fmac_f32_e32 v219, s27, v59
	v_fmac_f32_e32 v220, s74, v120
	v_fmac_f32_e32 v221, s74, v121
	v_fmac_f32_e32 v222, s74, v122
	v_fmac_f32_e32 v223, s74, v123
	v_fmac_f32_e32 v216, s36, v60
	v_fmac_f32_e32 v217, s36, v61
	v_fmac_f32_e32 v218, s36, v62
	v_fmac_f32_e32 v219, s36, v63
	v_fmac_f32_e32 v220, s75, v124
	v_fmac_f32_e32 v221, s75, v125
	v_fmac_f32_e32 v222, s75, v126
	v_fmac_f32_e32 v223, s75, v127
	v_fmac_f32_e32 v216, s37, v64
	v_fmac_f32_e32 v217, s37, v65
	v_fmac_f32_e32 v218, s37, v66
	v_fmac_f32_e32 v219, s37, v67
	v_fmac_f32_e32 v220, s76, v128
	v_fmac_f32_e32 v221, s76, v129
	v_fmac_f32_e32 v222, s76, v130
	v_fmac_f32_e32 v223, s76, v131
	v_fmac_f32_e32 v216, s42, v68
	v_fmac_f32_e32 v217, s42, v69
	v_fmac_f32_e32 v218, s42, v70
	v_fmac_f32_e32 v219, s42, v71
	v_fmac_f32_e32 v220, s77, v132
	v_fmac_f32_e32 v221, s77, v133
	v_fmac_f32_e32 v222, s77, v134
	v_fmac_f32_e32 v223, s77, v135
	v_mul_f32_e64 v224, |v216|, s101
	v_mul_f32_e64 v225, |v217|, s101
	v_mul_f32_e64 v226, |v218|, s101
	v_mul_f32_e64 v227, |v219|, s101
	v_exp_f32_e32 v224, v224
	v_exp_f32_e32 v225, v225
	v_exp_f32_e32 v226, v226
	v_exp_f32_e32 v227, v227
	v_max_f32_e64 v216, -v216, 0
	v_max_f32_e64 v217, -v217, 0
	v_max_f32_e64 v218, -v218, 0
	v_max_f32_e64 v219, -v219, 0
; __device__ __forceinline__ unsigned pk2(float lo, float hi) { unsigned r; asm("v_cvt_pk_bf16_f32 %0, %1, %2" : "=v"(r) : "v"(lo), "v"(hi)); return r; }
; __device__ __forceinline__ void p2_gate(const Params& p, const LAS float* aup, int t0, int lane) {
;     ...
;         *(u32x4*)(GG + (size_t)t * 512 + lane * 8) = __builtin_nontemporal_load((const u32x4*)(zg + 1024 + lane * 8));
;         const unsigned short araw = zg[1536 + (lane & 31)]; const int alo = (int)((unsigned)araw << 16);
;         f32x4 acc0 = ab0, acc1 = ab1;
; #pragma unroll
;         for (int r = 0; r < 16; ++r) { const float a0 = __int_as_float(__builtin_amdgcn_readlane(alo, r)), a1 = __int_as_float(__builtin_amdgcn_readlane(alo, 16 + r));
;             acc0 += a0 * *(const LAS f32x4*)(aup + r * 256 + 4 * lane); acc1 += a1 * *(const LAS f32x4*)(aup + (16 + r) * 256 + 4 * lane); }
;         float n0[4], n1[4];
; #pragma unroll
;         for (int j = 0; j < 4; ++j) { const float y0 = -acc0[j], y1 = -acc1[j];
;             n0[j] = (fmaxf(y0, 0.f) + __logf(1.0f + __expf(-fabsf(y0)))) * 0.0625f; n1[j] = (fmaxf(y1, 0.f) + __logf(1.0f + __expf(-fabsf(y1)))) * 0.0625f; }
;         u32x2 w; w.x = pk2(n0[0], n0[1]); w.y = pk2(n0[2], n0[3]); *(u32x2*)(GNL + (size_t)t * 512 + 4 * lane) = w;
;         w.x = pk2(n1[0], n1[1]); w.y = pk2(n1[2], n1[3]); *(u32x2*)(GNL + (size_t)t * 512 + 256 + 4 * lane) = w;
	v_add_f32_e32 v224, 1.0, v224
	v_add_f32_e32 v225, 1.0, v225
	v_add_f32_e32 v226, 1.0, v226
	v_add_f32_e32 v227, 1.0, v227
	v_log_f32_e32 v224, v224
	v_log_f32_e32 v225, v225
	v_log_f32_e32 v226, v226
	v_log_f32_e32 v227, v227
	s_nop 0
	v_fmac_f32_e32 v216, 0x3f317218, v224
	v_fmac_f32_e32 v217, 0x3f317218, v225
	v_fmac_f32_e32 v218, 0x3f317218, v226
	v_fmac_f32_e32 v219, 0x3f317218, v227
	v_mul_f32_e32 v216, 0x3d800000, v216
	v_mul_f32_e32 v217, 0x3d800000, v217
	v_mul_f32_e32 v218, 0x3d800000, v218
	v_mul_f32_e32 v219, 0x3d800000, v219
	v_mul_f32_e64 v224, |v220|, s101
	v_mul_f32_e64 v225, |v221|, s101
	v_mul_f32_e64 v226, |v222|, s101
	v_mul_f32_e64 v227, |v223|, s101
	v_exp_f32_e32 v224, v224
	v_exp_f32_e32 v225, v225
	v_exp_f32_e32 v226, v226
	v_exp_f32_e32 v227, v227
	v_max_f32_e64 v220, -v220, 0
	v_max_f32_e64 v221, -v221, 0
	v_max_f32_e64 v222, -v222, 0
	v_max_f32_e64 v223, -v223, 0
	v_add_f32_e32 v224, 1.0, v224
	v_add_f32_e32 v225, 1.0, v225
	v_add_f32_e32 v226, 1.0, v226
	v_add_f32_e32 v227, 1.0, v227
	v_log_f32_e32 v224, v224
	v_log_f32_e32 v225, v225
	v_log_f32_e32 v226, v226
	v_log_f32_e32 v227, v227
	s_nop 0
	v_fmac_f32_e32 v220, 0x3f317218, v224
	v_fmac_f32_e32 v221, 0x3f317218, v225
	v_fmac_f32_e32 v222, 0x3f317218, v226
	v_fmac_f32_e32 v223, 0x3f317218, v227
	v_mul_f32_e32 v220, 0x3d800000, v220
	v_mul_f32_e32 v221, 0x3d800000, v221
	v_mul_f32_e32 v222, 0x3d800000, v222
	v_mul_f32_e32 v223, 0x3d800000, v223
	v_cvt_pk_bf16_f32 v224, v216, v217
	v_cvt_pk_bf16_f32 v225, v218, v219
	v_cvt_pk_bf16_f32 v226, v220, v221
	v_cvt_pk_bf16_f32 v227, v222, v223
	global_store_dwordx2 v4, v[224:225], s[58:59] nt
	global_store_dwordx2 v4, v[226:227], s[58:59] offset:512 nt
	v_add_u32_e32 v5, 0x400, v5
	v_add_u32_e32 v4, 0x400, v4
	s_waitcnt vmcnt(34)
	global_store_dwordx4 v5, v[152:155], s[58:59] nt
	v_lshlrev_b32_e32 v204, 16, v204
	v_mov_b32_e32 v216, v228
	v_mov_b32_e32 v217, v229
	v_mov_b32_e32 v218, v230
	v_mov_b32_e32 v219, v231
	v_mov_b32_e32 v220, v232
	v_mov_b32_e32 v221, v233
	v_mov_b32_e32 v222, v234
	v_mov_b32_e32 v223, v235
	s_nop 0
	v_readlane_b32 s14, v204, 0
	v_readlane_b32 s15, v204, 1
	v_readlane_b32 s25, v204, 2
	v_readlane_b32 s26, v204, 3
	v_readlane_b32 s27, v204, 4
	v_readlane_b32 s36, v204, 5
	v_readlane_b32 s37, v204, 6
	v_readlane_b32 s42, v204, 7
	v_readlane_b32 s43, v204, 16
	v_readlane_b32 s63, v204, 17
	v_readlane_b32 s64, v204, 18
	v_readlane_b32 s65, v204, 19
	v_readlane_b32 s74, v204, 20
	v_readlane_b32 s75, v204, 21
	v_readlane_b32 s76, v204, 22
	v_readlane_b32 s77, v204, 23
	s_nop 1
	v_fmac_f32_e32 v216, s14, v8
	v_fmac_f32_e32 v217, s14, v9
	v_fmac_f32_e32 v218, s14, v10
	v_fmac_f32_e32 v219, s14, v11
	v_fmac_f32_e32 v220, s43, v72
	v_fmac_f32_e32 v221, s43, v73
	v_fmac_f32_e32 v222, s43, v74
	v_fmac_f32_e32 v223, s43, v75
	v_fmac_f32_e32 v216, s15, v12
	v_fmac_f32_e32 v217, s15, v13
	v_fmac_f32_e32 v218, s15, v14
	v_fmac_f32_e32 v219, s15, v15
	v_fmac_f32_e32 v220, s63, v76
	v_fmac_f32_e32 v221, s63, v77
	v_fmac_f32_e32 v222, s63, v78
	v_fmac_f32_e32 v223, s63, v79
	v_fmac_f32_e32 v216, s25, v16
	v_fmac_f32_e32 v217, s25, v17
	v_fmac_f32_e32 v218, s25, v18
	v_fmac_f32_e32 v219, s25, v19
	v_fmac_f32_e32 v220, s64, v80
	v_fmac_f32_e32 v221, s64, v81
	v_fmac_f32_e32 v222, s64, v82
	v_fmac_f32_e32 v223, s64, v83
	v_fmac_f32_e32 v216, s26, v20
	v_fmac_f32_e32 v217, s26, v21
	v_fmac_f32_e32 v218, s26, v22
	v_fmac_f32_e32 v219, s26, v23
	v_fmac_f32_e32 v220, s65, v84
	v_fmac_f32_e32 v221, s65, v85
	v_fmac_f32_e32 v222, s65, v86
	v_fmac_f32_e32 v223, s65, v87
	v_fmac_f32_e32 v216, s27, v24
	v_fmac_f32_e32 v217, s27, v25
	v_fmac_f32_e32 v218, s27, v26
	v_fmac_f32_e32 v219, s27, v27
	v_fmac_f32_e32 v220, s74, v88
	v_fmac_f32_e32 v221, s74, v89
	v_fmac_f32_e32 v222, s74, v90
	v_fmac_f32_e32 v223, s74, v91
	v_fmac_f32_e32 v216, s36, v28
	v_fmac_f32_e32 v217, s36, v29
	v_fmac_f32_e32 v218, s36, v30
	v_fmac_f32_e32 v219, s36, v31
	v_fmac_f32_e32 v220, s75, v92
	v_fmac_f32_e32 v221, s75, v93
	v_fmac_f32_e32 v222, s75, v94
	v_fmac_f32_e32 v223, s75, v95
	v_fmac_f32_e32 v216, s37, v32
	v_fmac_f32_e32 v217, s37, v33
	v_fmac_f32_e32 v218, s37, v34
	v_fmac_f32_e32 v219, s37, v35
	v_fmac_f32_e32 v220, s76, v96
	v_fmac_f32_e32 v221, s76, v97
	v_fmac_f32_e32 v222, s76, v98
	v_fmac_f32_e32 v223, s76, v99
	v_fmac_f32_e32 v216, s42, v36
	v_fmac_f32_e32 v217, s42, v37
	v_fmac_f32_e32 v218, s42, v38
	v_fmac_f32_e32 v219, s42, v39
	v_fmac_f32_e32 v220, s77, v100
	v_fmac_f32_e32 v221, s77, v101
	v_fmac_f32_e32 v222, s77, v102
	v_fmac_f32_e32 v223, s77, v103
	s_nop 0
	v_readlane_b32 s14, v204, 8
	v_readlane_b32 s15, v204, 9
	v_readlane_b32 s25, v204, 10
	v_readlane_b32 s26, v204, 11
	v_readlane_b32 s27, v204, 12
	v_readlane_b32 s36, v204, 13
	v_readlane_b32 s37, v204, 14
	v_readlane_b32 s42, v204, 15
	v_readlane_b32 s43, v204, 24
	v_readlane_b32 s63, v204, 25
	v_readlane_b32 s64, v204, 26
	v_readlane_b32 s65, v204, 27
	v_readlane_b32 s74, v204, 28
	v_readlane_b32 s75, v204, 29
	v_readlane_b32 s76, v204, 30
	v_readlane_b32 s77, v204, 31
	s_nop 1
	v_fmac_f32_e32 v216, s14, v40
	v_fmac_f32_e32 v217, s14, v41
	v_fmac_f32_e32 v218, s14, v42
	v_fmac_f32_e32 v219, s14, v43
	v_fmac_f32_e32 v220, s43, v104
	v_fmac_f32_e32 v221, s43, v105
	v_fmac_f32_e32 v222, s43, v106
	v_fmac_f32_e32 v223, s43, v107
	v_fmac_f32_e32 v216, s15, v44
	v_fmac_f32_e32 v217, s15, v45
	v_fmac_f32_e32 v218, s15, v46
	v_fmac_f32_e32 v219, s15, v47
	v_fmac_f32_e32 v220, s63, v108
	v_fmac_f32_e32 v221, s63, v109
	v_fmac_f32_e32 v222, s63, v110
	v_fmac_f32_e32 v223, s63, v111
	v_fmac_f32_e32 v216, s25, v48
	v_fmac_f32_e32 v217, s25, v49
	v_fmac_f32_e32 v218, s25, v50
; __device__ __forceinline__ unsigned pk2(float lo, float hi) { unsigned r; asm("v_cvt_pk_bf16_f32 %0, %1, %2" : "=v"(r) : "v"(lo), "v"(hi)); return r; }
; __device__ __forceinline__ void p2_gate(const Params& p, const LAS float* aup, int t0, int lane) {
;     ...
;         *(u32x4*)(GG + (size_t)t * 512 + lane * 8) = __builtin_nontemporal_load((const u32x4*)(zg + 1024 + lane * 8));
;         const unsigned short araw = zg[1536 + (lane & 31)]; const int alo = (int)((unsigned)araw << 16);
;         f32x4 acc0 = ab0, acc1 = ab1;
; #pragma unroll
;         for (int r = 0; r < 16; ++r) { const float a0 = __int_as_float(__builtin_amdgcn_readlane(alo, r)), a1 = __int_as_float(__builtin_amdgcn_readlane(alo, 16 + r));
;             acc0 += a0 * *(const LAS f32x4*)(aup + r * 256 + 4 * lane); acc1 += a1 * *(const LAS f32x4*)(aup + (16 + r) * 256 + 4 * lane); }
;         float n0[4], n1[4];
; #pragma unroll
;         for (int j = 0; j < 4; ++j) { const float y0 = -acc0[j], y1 = -acc1[j];
;             n0[j] = (fmaxf(y0, 0.f) + __logf(1.0f + __expf(-fabsf(y0)))) * 0.0625f; n1[j] = (fmaxf(y1, 0.f) + __logf(1.0f + __expf(-fabsf(y1)))) * 0.0625f; }
;         u32x2 w; w.x = pk2(n0[0], n0[1]); w.y = pk2(n0[2], n0[3]); *(u32x2*)(GNL + (size_t)t * 512 + 4 * lane) = w;
;         w.x = pk2(n1[0], n1[1]); w.y = pk2(n1[2], n1[3]); *(u32x2*)(GNL + (size_t)t * 512 + 256 + 4 * lane) = w;
	v_fmac_f32_e32 v219, s25, v51
	v_fmac_f32_e32 v220, s64, v112
	v_fmac_f32_e32 v221, s64, v113
	v_fmac_f32_e32 v222, s64, v114
	v_fmac_f32_e32 v223, s64, v115
	v_fmac_f32_e32 v216, s26, v52
	v_fmac_f32_e32 v217, s26, v53
	v_fmac_f32_e32 v218, s26, v54
	v_fmac_f32_e32 v219, s26, v55
	v_fmac_f32_e32 v220, s65, v116
	v_fmac_f32_e32 v221, s65, v117
	v_fmac_f32_e32 v222, s65, v118
	v_fmac_f32_e32 v223, s65, v119
	v_fmac_f32_e32 v216, s27, v56
	v_fmac_f32_e32 v217, s27, v57
	v_fmac_f32_e32 v218, s27, v58
	v_fmac_f32_e32 v219, s27, v59
	v_fmac_f32_e32 v220, s74, v120
	v_fmac_f32_e32 v221, s74, v121
	v_fmac_f32_e32 v222, s74, v122
	v_fmac_f32_e32 v223, s74, v123
	v_fmac_f32_e32 v216, s36, v60
	v_fmac_f32_e32 v217, s36, v61
	v_fmac_f32_e32 v218, s36, v62
	v_fmac_f32_e32 v219, s36, v63
	v_fmac_f32_e32 v220, s75, v124
	v_fmac_f32_e32 v221, s75, v125
	v_fmac_f32_e32 v222, s75, v126
	v_fmac_f32_e32 v223, s75, v127
	v_fmac_f32_e32 v216, s37, v64
	v_fmac_f32_e32 v217, s37, v65
	v_fmac_f32_e32 v218, s37, v66
	v_fmac_f32_e32 v219, s37, v67
	v_fmac_f32_e32 v220, s76, v128
	v_fmac_f32_e32 v221, s76, v129
	v_fmac_f32_e32 v222, s76, v130
	v_fmac_f32_e32 v223, s76, v131
	v_fmac_f32_e32 v216, s42, v68
	v_fmac_f32_e32 v217, s42, v69
	v_fmac_f32_e32 v218, s42, v70
	v_fmac_f32_e32 v219, s42, v71
	v_fmac_f32_e32 v220, s77, v132
	v_fmac_f32_e32 v221, s77, v133
	v_fmac_f32_e32 v222, s77, v134
	v_fmac_f32_e32 v223, s77, v135
	v_mul_f32_e64 v224, |v216|, s101
	v_mul_f32_e64 v225, |v217|, s101
	v_mul_f32_e64 v226, |v218|, s101
	v_mul_f32_e64 v227, |v219|, s101
	v_exp_f32_e32 v224, v224
	v_exp_f32_e32 v225, v225
	v_exp_f32_e32 v226, v226
	v_exp_f32_e32 v227, v227
	v_max_f32_e64 v216, -v216, 0
	v_max_f32_e64 v217, -v217, 0
	v_max_f32_e64 v218, -v218, 0
	v_max_f32_e64 v219, -v219, 0
	v_add_f32_e32 v224, 1.0, v224
	v_add_f32_e32 v225, 1.0, v225
	v_add_f32_e32 v226, 1.0, v226
	v_add_f32_e32 v227, 1.0, v227
	v_log_f32_e32 v224, v224
	v_log_f32_e32 v225, v225
	v_log_f32_e32 v226, v226
	v_log_f32_e32 v227, v227
	s_nop 0
	v_fmac_f32_e32 v216, 0x3f317218, v224
	v_fmac_f32_e32 v217, 0x3f317218, v225
	v_fmac_f32_e32 v218, 0x3f317218, v226
	v_fmac_f32_e32 v219, 0x3f317218, v227
	v_mul_f32_e32 v216, 0x3d800000, v216
	v_mul_f32_e32 v217, 0x3d800000, v217
	v_mul_f32_e32 v218, 0x3d800000, v218
	v_mul_f32_e32 v219, 0x3d800000, v219
	v_mul_f32_e64 v224, |v220|, s101
	v_mul_f32_e64 v225, |v221|, s101
	v_mul_f32_e64 v226, |v222|, s101
	v_mul_f32_e64 v227, |v223|, s101
	v_exp_f32_e32 v224, v224
	v_exp_f32_e32 v225, v225
	v_exp_f32_e32 v226, v226
	v_exp_f32_e32 v227, v227
	v_max_f32_e64 v220, -v220, 0
	v_max_f32_e64 v221, -v221, 0
	v_max_f32_e64 v222, -v222, 0
	v_max_f32_e64 v223, -v223, 0
	v_add_f32_e32 v224, 1.0, v224
	v_add_f32_e32 v225, 1.0, v225
	v_add_f32_e32 v226, 1.0, v226
	v_add_f32_e32 v227, 1.0, v227
	v_log_f32_e32 v224, v224
	v_log_f32_e32 v225, v225
	v_log_f32_e32 v226, v226
	v_log_f32_e32 v227, v227
	s_nop 0
	v_fmac_f32_e32 v220, 0x3f317218, v224
	v_fmac_f32_e32 v221, 0x3f317218, v225
	v_fmac_f32_e32 v222, 0x3f317218, v226
	v_fmac_f32_e32 v223, 0x3f317218, v227
	v_mul_f32_e32 v220, 0x3d800000, v220
	v_mul_f32_e32 v221, 0x3d800000, v221
	v_mul_f32_e32 v222, 0x3d800000, v222
	v_mul_f32_e32 v223, 0x3d800000, v223
	v_cvt_pk_bf16_f32 v224, v216, v217
	v_cvt_pk_bf16_f32 v225, v218, v219
	v_cvt_pk_bf16_f32 v226, v220, v221
	v_cvt_pk_bf16_f32 v227, v222, v223
	global_store_dwordx2 v4, v[224:225], s[58:59] nt
	global_store_dwordx2 v4, v[226:227], s[58:59] offset:512 nt
	v_add_u32_e32 v5, 0x400, v5
	v_add_u32_e32 v4, 0x400, v4
	s_waitcnt vmcnt(35)
	global_store_dwordx4 v5, v[156:159], s[58:59] nt
	v_lshlrev_b32_e32 v205, 16, v205
	v_mov_b32_e32 v216, v228
	v_mov_b32_e32 v217, v229
	v_mov_b32_e32 v218, v230
	v_mov_b32_e32 v219, v231
	v_mov_b32_e32 v220, v232
	v_mov_b32_e32 v221, v233
	v_mov_b32_e32 v222, v234
	v_mov_b32_e32 v223, v235
	s_nop 0
	v_readlane_b32 s14, v205, 0
	v_readlane_b32 s15, v205, 1
	v_readlane_b32 s25, v205, 2
	v_readlane_b32 s26, v205, 3
	v_readlane_b32 s27, v205, 4
	v_readlane_b32 s36, v205, 5
	v_readlane_b32 s37, v205, 6
	v_readlane_b32 s42, v205, 7
	v_readlane_b32 s43, v205, 16
	v_readlane_b32 s63, v205, 17
	v_readlane_b32 s64, v205, 18
	v_readlane_b32 s65, v205, 19
	v_readlane_b32 s74, v205, 20
	v_readlane_b32 s75, v205, 21
	v_readlane_b32 s76, v205, 22
	v_readlane_b32 s77, v205, 23
	s_nop 1
	v_fmac_f32_e32 v216, s14, v8
	v_fmac_f32_e32 v217, s14, v9
	v_fmac_f32_e32 v218, s14, v10
	v_fmac_f32_e32 v219, s14, v11
	v_fmac_f32_e32 v220, s43, v72
	v_fmac_f32_e32 v221, s43, v73
	v_fmac_f32_e32 v222, s43, v74
	v_fmac_f32_e32 v223, s43, v75
	v_fmac_f32_e32 v216, s15, v12
	v_fmac_f32_e32 v217, s15, v13
	v_fmac_f32_e32 v218, s15, v14
	v_fmac_f32_e32 v219, s15, v15
	v_fmac_f32_e32 v220, s63, v76
	v_fmac_f32_e32 v221, s63, v77
	v_fmac_f32_e32 v222, s63, v78
	v_fmac_f32_e32 v223, s63, v79
	v_fmac_f32_e32 v216, s25, v16
	v_fmac_f32_e32 v217, s25, v17
	v_fmac_f32_e32 v218, s25, v18
	v_fmac_f32_e32 v219, s25, v19
	v_fmac_f32_e32 v220, s64, v80
	v_fmac_f32_e32 v221, s64, v81
	v_fmac_f32_e32 v222, s64, v82
	v_fmac_f32_e32 v223, s64, v83
	v_fmac_f32_e32 v216, s26, v20
	v_fmac_f32_e32 v217, s26, v21
	v_fmac_f32_e32 v218, s26, v22
	v_fmac_f32_e32 v219, s26, v23
	v_fmac_f32_e32 v220, s65, v84
	v_fmac_f32_e32 v221, s65, v85
	v_fmac_f32_e32 v222, s65, v86
	v_fmac_f32_e32 v223, s65, v87
	v_fmac_f32_e32 v216, s27, v24
	v_fmac_f32_e32 v217, s27, v25
	v_fmac_f32_e32 v218, s27, v26
	v_fmac_f32_e32 v219, s27, v27
	v_fmac_f32_e32 v220, s74, v88
	v_fmac_f32_e32 v221, s74, v89
	v_fmac_f32_e32 v222, s74, v90
	v_fmac_f32_e32 v223, s74, v91
	v_fmac_f32_e32 v216, s36, v28
	v_fmac_f32_e32 v217, s36, v29
; __device__ __forceinline__ unsigned pk2(float lo, float hi) { unsigned r; asm("v_cvt_pk_bf16_f32 %0, %1, %2" : "=v"(r) : "v"(lo), "v"(hi)); return r; }
; __device__ __forceinline__ void p2_gate(const Params& p, const LAS float* aup, int t0, int lane) {
;     ...
;         for (int r = 0; r < 16; ++r) { const float a0 = __int_as_float(__builtin_amdgcn_readlane(alo, r)), a1 = __int_as_float(__builtin_amdgcn_readlane(alo, 16 + r));
;             acc0 += a0 * *(const LAS f32x4*)(aup + r * 256 + 4 * lane); acc1 += a1 * *(const LAS f32x4*)(aup + (16 + r) * 256 + 4 * lane); }
;         float n0[4], n1[4];
; #pragma unroll
;         for (int j = 0; j < 4; ++j) { const float y0 = -acc0[j], y1 = -acc1[j];
;             n0[j] = (fmaxf(y0, 0.f) + __logf(1.0f + __expf(-fabsf(y0)))) * 0.0625f; n1[j] = (fmaxf(y1, 0.f) + __logf(1.0f + __expf(-fabsf(y1)))) * 0.0625f; }
;         u32x2 w; w.x = pk2(n0[0], n0[1]); w.y = pk2(n0[2], n0[3]); *(u32x2*)(GNL + (size_t)t * 512 + 4 * lane) = w;
;         w.x = pk2(n1[0], n1[1]); w.y = pk2(n1[2], n1[3]); *(u32x2*)(GNL + (size_t)t * 512 + 256 + 4 * lane) = w;
	v_fmac_f32_e32 v218, s36, v30
	v_fmac_f32_e32 v219, s36, v31
	v_fmac_f32_e32 v220, s75, v92
	v_fmac_f32_e32 v221, s75, v93
	v_fmac_f32_e32 v222, s75, v94
	v_fmac_f32_e32 v223, s75, v95
	v_fmac_f32_e32 v216, s37, v32
	v_fmac_f32_e32 v217, s37, v33
	v_fmac_f32_e32 v218, s37, v34
	v_fmac_f32_e32 v219, s37, v35
	v_fmac_f32_e32 v220, s76, v96
	v_fmac_f32_e32 v221, s76, v97
	v_fmac_f32_e32 v222, s76, v98
	v_fmac_f32_e32 v223, s76, v99
	v_fmac_f32_e32 v216, s42, v36
	v_fmac_f32_e32 v217, s42, v37
	v_fmac_f32_e32 v218, s42, v38
	v_fmac_f32_e32 v219, s42, v39
	v_fmac_f32_e32 v220, s77, v100
	v_fmac_f32_e32 v221, s77, v101
	v_fmac_f32_e32 v222, s77, v102
	v_fmac_f32_e32 v223, s77, v103
	s_nop 0
	v_readlane_b32 s14, v205, 8
	v_readlane_b32 s15, v205, 9
	v_readlane_b32 s25, v205, 10
	v_readlane_b32 s26, v205, 11
	v_readlane_b32 s27, v205, 12
	v_readlane_b32 s36, v205, 13
	v_readlane_b32 s37, v205, 14
	v_readlane_b32 s42, v205, 15
	v_readlane_b32 s43, v205, 24
	v_readlane_b32 s63, v205, 25
	v_readlane_b32 s64, v205, 26
	v_readlane_b32 s65, v205, 27
	v_readlane_b32 s74, v205, 28
	v_readlane_b32 s75, v205, 29
	v_readlane_b32 s76, v205, 30
	v_readlane_b32 s77, v205, 31
	s_nop 1
	v_fmac_f32_e32 v216, s14, v40
	v_fmac_f32_e32 v217, s14, v41
	v_fmac_f32_e32 v218, s14, v42
	v_fmac_f32_e32 v219, s14, v43
	v_fmac_f32_e32 v220, s43, v104
	v_fmac_f32_e32 v221, s43, v105
	v_fmac_f32_e32 v222, s43, v106
	v_fmac_f32_e32 v223, s43, v107
	v_fmac_f32_e32 v216, s15, v44
	v_fmac_f32_e32 v217, s15, v45
	v_fmac_f32_e32 v218, s15, v46
	v_fmac_f32_e32 v219, s15, v47
	v_fmac_f32_e32 v220, s63, v108
	v_fmac_f32_e32 v221, s63, v109
	v_fmac_f32_e32 v222, s63, v110
	v_fmac_f32_e32 v223, s63, v111
	v_fmac_f32_e32 v216, s25, v48
	v_fmac_f32_e32 v217, s25, v49
	v_fmac_f32_e32 v218, s25, v50
	v_fmac_f32_e32 v219, s25, v51
	v_fmac_f32_e32 v220, s64, v112
	v_fmac_f32_e32 v221, s64, v113
	v_fmac_f32_e32 v222, s64, v114
	v_fmac_f32_e32 v223, s64, v115
	v_fmac_f32_e32 v216, s26, v52
	v_fmac_f32_e32 v217, s26, v53
	v_fmac_f32_e32 v218, s26, v54
	v_fmac_f32_e32 v219, s26, v55
	v_fmac_f32_e32 v220, s65, v116
	v_fmac_f32_e32 v221, s65, v117
	v_fmac_f32_e32 v222, s65, v118
	v_fmac_f32_e32 v223, s65, v119
	v_fmac_f32_e32 v216, s27, v56
	v_fmac_f32_e32 v217, s27, v57
	v_fmac_f32_e32 v218, s27, v58
	v_fmac_f32_e32 v219, s27, v59
	v_fmac_f32_e32 v220, s74, v120
	v_fmac_f32_e32 v221, s74, v121
	v_fmac_f32_e32 v222, s74, v122
	v_fmac_f32_e32 v223, s74, v123
	v_fmac_f32_e32 v216, s36, v60
	v_fmac_f32_e32 v217, s36, v61
	v_fmac_f32_e32 v218, s36, v62
	v_fmac_f32_e32 v219, s36, v63
	v_fmac_f32_e32 v220, s75, v124
	v_fmac_f32_e32 v221, s75, v125
	v_fmac_f32_e32 v222, s75, v126
	v_fmac_f32_e32 v223, s75, v127
	v_fmac_f32_e32 v216, s37, v64
	v_fmac_f32_e32 v217, s37, v65
	v_fmac_f32_e32 v218, s37, v66
	v_fmac_f32_e32 v219, s37, v67
	v_fmac_f32_e32 v220, s76, v128
	v_fmac_f32_e32 v221, s76, v129
	v_fmac_f32_e32 v222, s76, v130
	v_fmac_f32_e32 v223, s76, v131
	v_fmac_f32_e32 v216, s42, v68
	v_fmac_f32_e32 v217, s42, v69
	v_fmac_f32_e32 v218, s42, v70
	v_fmac_f32_e32 v219, s42, v71
	v_fmac_f32_e32 v220, s77, v132
	v_fmac_f32_e32 v221, s77, v133
	v_fmac_f32_e32 v222, s77, v134
	v_fmac_f32_e32 v223, s77, v135
	v_mul_f32_e64 v224, |v216|, s101
	v_mul_f32_e64 v225, |v217|, s101
	v_mul_f32_e64 v226, |v218|, s101
	v_mul_f32_e64 v227, |v219|, s101
	v_exp_f32_e32 v224, v224
	v_exp_f32_e32 v225, v225
	v_exp_f32_e32 v226, v226
	v_exp_f32_e32 v227, v227
	v_max_f32_e64 v216, -v216, 0
	v_max_f32_e64 v217, -v217, 0
	v_max_f32_e64 v218, -v218, 0
	v_max_f32_e64 v219, -v219, 0
	v_add_f32_e32 v224, 1.0, v224
	v_add_f32_e32 v225, 1.0, v225
	v_add_f32_e32 v226, 1.0, v226
	v_add_f32_e32 v227, 1.0, v227
	v_log_f32_e32 v224, v224
	v_log_f32_e32 v225, v225
	v_log_f32_e32 v226, v226
	v_log_f32_e32 v227, v227
	s_nop 0
	v_fmac_f32_e32 v216, 0x3f317218, v224
	v_fmac_f32_e32 v217, 0x3f317218, v225
	v_fmac_f32_e32 v218, 0x3f317218, v226
	v_fmac_f32_e32 v219, 0x3f317218, v227
	v_mul_f32_e32 v216, 0x3d800000, v216
	v_mul_f32_e32 v217, 0x3d800000, v217
	v_mul_f32_e32 v218, 0x3d800000, v218
	v_mul_f32_e32 v219, 0x3d800000, v219
	v_mul_f32_e64 v224, |v220|, s101
	v_mul_f32_e64 v225, |v221|, s101
	v_mul_f32_e64 v226, |v222|, s101
	v_mul_f32_e64 v227, |v223|, s101
	v_exp_f32_e32 v224, v224
	v_exp_f32_e32 v225, v225
	v_exp_f32_e32 v226, v226
	v_exp_f32_e32 v227, v227
	v_max_f32_e64 v220, -v220, 0
	v_max_f32_e64 v221, -v221, 0
	v_max_f32_e64 v222, -v222, 0
	v_max_f32_e64 v223, -v223, 0
	v_add_f32_e32 v224, 1.0, v224
	v_add_f32_e32 v225, 1.0, v225
	v_add_f32_e32 v226, 1.0, v226
	v_add_f32_e32 v227, 1.0, v227
	v_log_f32_e32 v224, v224
	v_log_f32_e32 v225, v225
	v_log_f32_e32 v226, v226
	v_log_f32_e32 v227, v227
	s_nop 0
	v_fmac_f32_e32 v220, 0x3f317218, v224
	v_fmac_f32_e32 v221, 0x3f317218, v225
	v_fmac_f32_e32 v222, 0x3f317218, v226
	v_fmac_f32_e32 v223, 0x3f317218, v227
	v_mul_f32_e32 v220, 0x3d800000, v220
	v_mul_f32_e32 v221, 0x3d800000, v221
	v_mul_f32_e32 v222, 0x3d800000, v222
	v_mul_f32_e32 v223, 0x3d800000, v223
	v_cvt_pk_bf16_f32 v224, v216, v217
	v_cvt_pk_bf16_f32 v225, v218, v219
	v_cvt_pk_bf16_f32 v226, v220, v221
	v_cvt_pk_bf16_f32 v227, v222, v223
	global_store_dwordx2 v4, v[224:225], s[58:59] nt
	global_store_dwordx2 v4, v[226:227], s[58:59] offset:512 nt
	v_add_u32_e32 v5, 0x400, v5
	v_add_u32_e32 v4, 0x400, v4
	s_waitcnt vmcnt(36)
; __device__ __forceinline__ void p2_gate(const Params& p, const LAS float* aup, int t0, int lane) {
;     ...
;         *(u32x4*)(GG + (size_t)t * 512 + lane * 8) = __builtin_nontemporal_load((const u32x4*)(zg + 1024 + lane * 8));
;         const unsigned short araw = zg[1536 + (lane & 31)]; const int alo = (int)((unsigned)araw << 16);
;         f32x4 acc0 = ab0, acc1 = ab1;
; #pragma unroll
;         for (int r = 0; r < 16; ++r) { const float a0 = __int_as_float(__builtin_amdgcn_readlane(alo, r)), a1 = __int_as_float(__builtin_amdgcn_readlane(alo, 16 + r));
;             acc0 += a0 * *(const LAS f32x4*)(aup + r * 256 + 4 * lane); acc1 += a1 * *(const LAS f32x4*)(aup + (16 + r) * 256 + 4 * lane); }
;         float n0[4], n1[4];
; #pragma unroll
;         for (int j = 0; j < 4; ++j) { const float y0 = -acc0[j], y1 = -acc1[j];
;             n0[j] = (fmaxf(y0, 0.f) + __logf(1.0f + __expf(-fabsf(y0)))) * 0.0625f; n1[j] = (fmaxf(y1, 0.f) + __logf(1.0f + __expf(-fabsf(y1)))) * 0.0625f; }
	global_store_dwordx4 v5, v[160:163], s[58:59] nt
	v_lshlrev_b32_e32 v206, 16, v206
	v_mov_b32_e32 v216, v228
	v_mov_b32_e32 v217, v229
	v_mov_b32_e32 v218, v230
	v_mov_b32_e32 v219, v231
	v_mov_b32_e32 v220, v232
	v_mov_b32_e32 v221, v233
	v_mov_b32_e32 v222, v234
	v_mov_b32_e32 v223, v235
	s_nop 0
	v_readlane_b32 s14, v206, 0
	v_readlane_b32 s15, v206, 1
	v_readlane_b32 s25, v206, 2
	v_readlane_b32 s26, v206, 3
	v_readlane_b32 s27, v206, 4
	v_readlane_b32 s36, v206, 5
	v_readlane_b32 s37, v206, 6
	v_readlane_b32 s42, v206, 7
	v_readlane_b32 s43, v206, 16
	v_readlane_b32 s63, v206, 17
	v_readlane_b32 s64, v206, 18
	v_readlane_b32 s65, v206, 19
	v_readlane_b32 s74, v206, 20
	v_readlane_b32 s75, v206, 21
	v_readlane_b32 s76, v206, 22
	v_readlane_b32 s77, v206, 23
	s_nop 1
	v_fmac_f32_e32 v216, s14, v8
	v_fmac_f32_e32 v217, s14, v9
	v_fmac_f32_e32 v218, s14, v10
	v_fmac_f32_e32 v219, s14, v11
	v_fmac_f32_e32 v220, s43, v72
	v_fmac_f32_e32 v221, s43, v73
	v_fmac_f32_e32 v222, s43, v74
	v_fmac_f32_e32 v223, s43, v75
	v_fmac_f32_e32 v216, s15, v12
	v_fmac_f32_e32 v217, s15, v13
	v_fmac_f32_e32 v218, s15, v14
	v_fmac_f32_e32 v219, s15, v15
	v_fmac_f32_e32 v220, s63, v76
	v_fmac_f32_e32 v221, s63, v77
	v_fmac_f32_e32 v222, s63, v78
	v_fmac_f32_e32 v223, s63, v79
	v_fmac_f32_e32 v216, s25, v16
	v_fmac_f32_e32 v217, s25, v17
	v_fmac_f32_e32 v218, s25, v18
	v_fmac_f32_e32 v219, s25, v19
	v_fmac_f32_e32 v220, s64, v80
	v_fmac_f32_e32 v221, s64, v81
	v_fmac_f32_e32 v222, s64, v82
	v_fmac_f32_e32 v223, s64, v83
	v_fmac_f32_e32 v216, s26, v20
	v_fmac_f32_e32 v217, s26, v21
	v_fmac_f32_e32 v218, s26, v22
	v_fmac_f32_e32 v219, s26, v23
	v_fmac_f32_e32 v220, s65, v84
	v_fmac_f32_e32 v221, s65, v85
	v_fmac_f32_e32 v222, s65, v86
	v_fmac_f32_e32 v223, s65, v87
	v_fmac_f32_e32 v216, s27, v24
	v_fmac_f32_e32 v217, s27, v25
	v_fmac_f32_e32 v218, s27, v26
	v_fmac_f32_e32 v219, s27, v27
	v_fmac_f32_e32 v220, s74, v88
	v_fmac_f32_e32 v221, s74, v89
	v_fmac_f32_e32 v222, s74, v90
	v_fmac_f32_e32 v223, s74, v91
	v_fmac_f32_e32 v216, s36, v28
	v_fmac_f32_e32 v217, s36, v29
	v_fmac_f32_e32 v218, s36, v30
	v_fmac_f32_e32 v219, s36, v31
	v_fmac_f32_e32 v220, s75, v92
	v_fmac_f32_e32 v221, s75, v93
	v_fmac_f32_e32 v222, s75, v94
	v_fmac_f32_e32 v223, s75, v95
	v_fmac_f32_e32 v216, s37, v32
	v_fmac_f32_e32 v217, s37, v33
	v_fmac_f32_e32 v218, s37, v34
	v_fmac_f32_e32 v219, s37, v35
	v_fmac_f32_e32 v220, s76, v96
	v_fmac_f32_e32 v221, s76, v97
	v_fmac_f32_e32 v222, s76, v98
	v_fmac_f32_e32 v223, s76, v99
	v_fmac_f32_e32 v216, s42, v36
	v_fmac_f32_e32 v217, s42, v37
	v_fmac_f32_e32 v218, s42, v38
	v_fmac_f32_e32 v219, s42, v39
	v_fmac_f32_e32 v220, s77, v100
	v_fmac_f32_e32 v221, s77, v101
	v_fmac_f32_e32 v222, s77, v102
	v_fmac_f32_e32 v223, s77, v103
	s_nop 0
	v_readlane_b32 s14, v206, 8
	v_readlane_b32 s15, v206, 9
	v_readlane_b32 s25, v206, 10
	v_readlane_b32 s26, v206, 11
	v_readlane_b32 s27, v206, 12
	v_readlane_b32 s36, v206, 13
	v_readlane_b32 s37, v206, 14
	v_readlane_b32 s42, v206, 15
	v_readlane_b32 s43, v206, 24
	v_readlane_b32 s63, v206, 25
	v_readlane_b32 s64, v206, 26
	v_readlane_b32 s65, v206, 27
	v_readlane_b32 s74, v206, 28
	v_readlane_b32 s75, v206, 29
	v_readlane_b32 s76, v206, 30
	v_readlane_b32 s77, v206, 31
	s_nop 1
	v_fmac_f32_e32 v216, s14, v40
	v_fmac_f32_e32 v217, s14, v41
	v_fmac_f32_e32 v218, s14, v42
	v_fmac_f32_e32 v219, s14, v43
	v_fmac_f32_e32 v220, s43, v104
	v_fmac_f32_e32 v221, s43, v105
	v_fmac_f32_e32 v222, s43, v106
	v_fmac_f32_e32 v223, s43, v107
	v_fmac_f32_e32 v216, s15, v44
	v_fmac_f32_e32 v217, s15, v45
	v_fmac_f32_e32 v218, s15, v46
	v_fmac_f32_e32 v219, s15, v47
	v_fmac_f32_e32 v220, s63, v108
	v_fmac_f32_e32 v221, s63, v109
	v_fmac_f32_e32 v222, s63, v110
	v_fmac_f32_e32 v223, s63, v111
	v_fmac_f32_e32 v216, s25, v48
	v_fmac_f32_e32 v217, s25, v49
	v_fmac_f32_e32 v218, s25, v50
	v_fmac_f32_e32 v219, s25, v51
	v_fmac_f32_e32 v220, s64, v112
	v_fmac_f32_e32 v221, s64, v113
	v_fmac_f32_e32 v222, s64, v114
	v_fmac_f32_e32 v223, s64, v115
	v_fmac_f32_e32 v216, s26, v52
	v_fmac_f32_e32 v217, s26, v53
	v_fmac_f32_e32 v218, s26, v54
	v_fmac_f32_e32 v219, s26, v55
	v_fmac_f32_e32 v220, s65, v116
	v_fmac_f32_e32 v221, s65, v117
	v_fmac_f32_e32 v222, s65, v118
	v_fmac_f32_e32 v223, s65, v119
	v_fmac_f32_e32 v216, s27, v56
	v_fmac_f32_e32 v217, s27, v57
	v_fmac_f32_e32 v218, s27, v58
	v_fmac_f32_e32 v219, s27, v59
	v_fmac_f32_e32 v220, s74, v120
	v_fmac_f32_e32 v221, s74, v121
	v_fmac_f32_e32 v222, s74, v122
	v_fmac_f32_e32 v223, s74, v123
	v_fmac_f32_e32 v216, s36, v60
	v_fmac_f32_e32 v217, s36, v61
	v_fmac_f32_e32 v218, s36, v62
	v_fmac_f32_e32 v219, s36, v63
	v_fmac_f32_e32 v220, s75, v124
	v_fmac_f32_e32 v221, s75, v125
	v_fmac_f32_e32 v222, s75, v126
	v_fmac_f32_e32 v223, s75, v127
	v_fmac_f32_e32 v216, s37, v64
	v_fmac_f32_e32 v217, s37, v65
	v_fmac_f32_e32 v218, s37, v66
	v_fmac_f32_e32 v219, s37, v67
	v_fmac_f32_e32 v220, s76, v128
	v_fmac_f32_e32 v221, s76, v129
	v_fmac_f32_e32 v222, s76, v130
	v_fmac_f32_e32 v223, s76, v131
	v_fmac_f32_e32 v216, s42, v68
	v_fmac_f32_e32 v217, s42, v69
	v_fmac_f32_e32 v218, s42, v70
	v_fmac_f32_e32 v219, s42, v71
	v_fmac_f32_e32 v220, s77, v132
	v_fmac_f32_e32 v221, s77, v133
	v_fmac_f32_e32 v222, s77, v134
	v_fmac_f32_e32 v223, s77, v135
	v_mul_f32_e64 v224, |v216|, s101
	v_mul_f32_e64 v225, |v217|, s101
	v_mul_f32_e64 v226, |v218|, s101
	v_mul_f32_e64 v227, |v219|, s101
	v_exp_f32_e32 v224, v224
	v_exp_f32_e32 v225, v225
	v_exp_f32_e32 v226, v226
	v_exp_f32_e32 v227, v227
	v_max_f32_e64 v216, -v216, 0
	v_max_f32_e64 v217, -v217, 0
	v_max_f32_e64 v218, -v218, 0
	v_max_f32_e64 v219, -v219, 0
; __device__ __forceinline__ unsigned pk2(float lo, float hi) { unsigned r; asm("v_cvt_pk_bf16_f32 %0, %1, %2" : "=v"(r) : "v"(lo), "v"(hi)); return r; }
; __device__ __forceinline__ void p2_gate(const Params& p, const LAS float* aup, int t0, int lane) {
;     ...
;         *(u32x4*)(GG + (size_t)t * 512 + lane * 8) = __builtin_nontemporal_load((const u32x4*)(zg + 1024 + lane * 8));
;         const unsigned short araw = zg[1536 + (lane & 31)]; const int alo = (int)((unsigned)araw << 16);
;         f32x4 acc0 = ab0, acc1 = ab1;
; #pragma unroll
;         for (int r = 0; r < 16; ++r) { const float a0 = __int_as_float(__builtin_amdgcn_readlane(alo, r)), a1 = __int_as_float(__builtin_amdgcn_readlane(alo, 16 + r));
;             acc0 += a0 * *(const LAS f32x4*)(aup + r * 256 + 4 * lane); acc1 += a1 * *(const LAS f32x4*)(aup + (16 + r) * 256 + 4 * lane); }
;         float n0[4], n1[4];
; #pragma unroll
;         for (int j = 0; j < 4; ++j) { const float y0 = -acc0[j], y1 = -acc1[j];
;             n0[j] = (fmaxf(y0, 0.f) + __logf(1.0f + __expf(-fabsf(y0)))) * 0.0625f; n1[j] = (fmaxf(y1, 0.f) + __logf(1.0f + __expf(-fabsf(y1)))) * 0.0625f; }
;         u32x2 w; w.x = pk2(n0[0], n0[1]); w.y = pk2(n0[2], n0[3]); *(u32x2*)(GNL + (size_t)t * 512 + 4 * lane) = w;
;         w.x = pk2(n1[0], n1[1]); w.y = pk2(n1[2], n1[3]); *(u32x2*)(GNL + (size_t)t * 512 + 256 + 4 * lane) = w;
	v_add_f32_e32 v224, 1.0, v224
	v_add_f32_e32 v225, 1.0, v225
	v_add_f32_e32 v226, 1.0, v226
	v_add_f32_e32 v227, 1.0, v227
	v_log_f32_e32 v224, v224
	v_log_f32_e32 v225, v225
	v_log_f32_e32 v226, v226
	v_log_f32_e32 v227, v227
	s_nop 0
	v_fmac_f32_e32 v216, 0x3f317218, v224
	v_fmac_f32_e32 v217, 0x3f317218, v225
	v_fmac_f32_e32 v218, 0x3f317218, v226
	v_fmac_f32_e32 v219, 0x3f317218, v227
	v_mul_f32_e32 v216, 0x3d800000, v216
	v_mul_f32_e32 v217, 0x3d800000, v217
	v_mul_f32_e32 v218, 0x3d800000, v218
	v_mul_f32_e32 v219, 0x3d800000, v219
	v_mul_f32_e64 v224, |v220|, s101
	v_mul_f32_e64 v225, |v221|, s101
	v_mul_f32_e64 v226, |v222|, s101
	v_mul_f32_e64 v227, |v223|, s101
	v_exp_f32_e32 v224, v224
	v_exp_f32_e32 v225, v225
	v_exp_f32_e32 v226, v226
	v_exp_f32_e32 v227, v227
	v_max_f32_e64 v220, -v220, 0
	v_max_f32_e64 v221, -v221, 0
	v_max_f32_e64 v222, -v222, 0
	v_max_f32_e64 v223, -v223, 0
	v_add_f32_e32 v224, 1.0, v224
	v_add_f32_e32 v225, 1.0, v225
	v_add_f32_e32 v226, 1.0, v226
	v_add_f32_e32 v227, 1.0, v227
	v_log_f32_e32 v224, v224
	v_log_f32_e32 v225, v225
	v_log_f32_e32 v226, v226
	v_log_f32_e32 v227, v227
	s_nop 0
	v_fmac_f32_e32 v220, 0x3f317218, v224
	v_fmac_f32_e32 v221, 0x3f317218, v225
	v_fmac_f32_e32 v222, 0x3f317218, v226
	v_fmac_f32_e32 v223, 0x3f317218, v227
	v_mul_f32_e32 v220, 0x3d800000, v220
	v_mul_f32_e32 v221, 0x3d800000, v221
	v_mul_f32_e32 v222, 0x3d800000, v222
	v_mul_f32_e32 v223, 0x3d800000, v223
	v_cvt_pk_bf16_f32 v224, v216, v217
	v_cvt_pk_bf16_f32 v225, v218, v219
	v_cvt_pk_bf16_f32 v226, v220, v221
	v_cvt_pk_bf16_f32 v227, v222, v223
	global_store_dwordx2 v4, v[224:225], s[58:59] nt
	global_store_dwordx2 v4, v[226:227], s[58:59] offset:512 nt
	v_add_u32_e32 v5, 0x400, v5
	v_add_u32_e32 v4, 0x400, v4
	s_waitcnt vmcnt(37)
	global_store_dwordx4 v5, v[164:167], s[58:59] nt
	v_lshlrev_b32_e32 v207, 16, v207
	v_mov_b32_e32 v216, v228
	v_mov_b32_e32 v217, v229
	v_mov_b32_e32 v218, v230
	v_mov_b32_e32 v219, v231
	v_mov_b32_e32 v220, v232
	v_mov_b32_e32 v221, v233
	v_mov_b32_e32 v222, v234
	v_mov_b32_e32 v223, v235
	s_nop 0
	v_readlane_b32 s14, v207, 0
	v_readlane_b32 s15, v207, 1
	v_readlane_b32 s25, v207, 2
	v_readlane_b32 s26, v207, 3
	v_readlane_b32 s27, v207, 4
	v_readlane_b32 s36, v207, 5
	v_readlane_b32 s37, v207, 6
	v_readlane_b32 s42, v207, 7
	v_readlane_b32 s43, v207, 16
	v_readlane_b32 s63, v207, 17
	v_readlane_b32 s64, v207, 18
	v_readlane_b32 s65, v207, 19
	v_readlane_b32 s74, v207, 20
	v_readlane_b32 s75, v207, 21
	v_readlane_b32 s76, v207, 22
	v_readlane_b32 s77, v207, 23
	s_nop 1
	v_fmac_f32_e32 v216, s14, v8
	v_fmac_f32_e32 v217, s14, v9
	v_fmac_f32_e32 v218, s14, v10
	v_fmac_f32_e32 v219, s14, v11
	v_fmac_f32_e32 v220, s43, v72
	v_fmac_f32_e32 v221, s43, v73
	v_fmac_f32_e32 v222, s43, v74
	v_fmac_f32_e32 v223, s43, v75
	v_fmac_f32_e32 v216, s15, v12
	v_fmac_f32_e32 v217, s15, v13
	v_fmac_f32_e32 v218, s15, v14
	v_fmac_f32_e32 v219, s15, v15
	v_fmac_f32_e32 v220, s63, v76
	v_fmac_f32_e32 v221, s63, v77
	v_fmac_f32_e32 v222, s63, v78
	v_fmac_f32_e32 v223, s63, v79
	v_fmac_f32_e32 v216, s25, v16
	v_fmac_f32_e32 v217, s25, v17
	v_fmac_f32_e32 v218, s25, v18
	v_fmac_f32_e32 v219, s25, v19
	v_fmac_f32_e32 v220, s64, v80
	v_fmac_f32_e32 v221, s64, v81
	v_fmac_f32_e32 v222, s64, v82
	v_fmac_f32_e32 v223, s64, v83
	v_fmac_f32_e32 v216, s26, v20
	v_fmac_f32_e32 v217, s26, v21
	v_fmac_f32_e32 v218, s26, v22
	v_fmac_f32_e32 v219, s26, v23
	v_fmac_f32_e32 v220, s65, v84
	v_fmac_f32_e32 v221, s65, v85
	v_fmac_f32_e32 v222, s65, v86
	v_fmac_f32_e32 v223, s65, v87
	v_fmac_f32_e32 v216, s27, v24
	v_fmac_f32_e32 v217, s27, v25
	v_fmac_f32_e32 v218, s27, v26
	v_fmac_f32_e32 v219, s27, v27
	v_fmac_f32_e32 v220, s74, v88
	v_fmac_f32_e32 v221, s74, v89
	v_fmac_f32_e32 v222, s74, v90
	v_fmac_f32_e32 v223, s74, v91
	v_fmac_f32_e32 v216, s36, v28
	v_fmac_f32_e32 v217, s36, v29
	v_fmac_f32_e32 v218, s36, v30
	v_fmac_f32_e32 v219, s36, v31
	v_fmac_f32_e32 v220, s75, v92
	v_fmac_f32_e32 v221, s75, v93
	v_fmac_f32_e32 v222, s75, v94
	v_fmac_f32_e32 v223, s75, v95
	v_fmac_f32_e32 v216, s37, v32
	v_fmac_f32_e32 v217, s37, v33
	v_fmac_f32_e32 v218, s37, v34
	v_fmac_f32_e32 v219, s37, v35
	v_fmac_f32_e32 v220, s76, v96
	v_fmac_f32_e32 v221, s76, v97
	v_fmac_f32_e32 v222, s76, v98
	v_fmac_f32_e32 v223, s76, v99
	v_fmac_f32_e32 v216, s42, v36
	v_fmac_f32_e32 v217, s42, v37
	v_fmac_f32_e32 v218, s42, v38
	v_fmac_f32_e32 v219, s42, v39
	v_fmac_f32_e32 v220, s77, v100
	v_fmac_f32_e32 v221, s77, v101
	v_fmac_f32_e32 v222, s77, v102
	v_fmac_f32_e32 v223, s77, v103
	s_nop 0
	v_readlane_b32 s14, v207, 8
	v_readlane_b32 s15, v207, 9
	v_readlane_b32 s25, v207, 10
	v_readlane_b32 s26, v207, 11
	v_readlane_b32 s27, v207, 12
	v_readlane_b32 s36, v207, 13
	v_readlane_b32 s37, v207, 14
	v_readlane_b32 s42, v207, 15
	v_readlane_b32 s43, v207, 24
	v_readlane_b32 s63, v207, 25
	v_readlane_b32 s64, v207, 26
	v_readlane_b32 s65, v207, 27
	v_readlane_b32 s74, v207, 28
	v_readlane_b32 s75, v207, 29
	v_readlane_b32 s76, v207, 30
	v_readlane_b32 s77, v207, 31
	s_nop 1
	v_fmac_f32_e32 v216, s14, v40
	v_fmac_f32_e32 v217, s14, v41
	v_fmac_f32_e32 v218, s14, v42
	v_fmac_f32_e32 v219, s14, v43
	v_fmac_f32_e32 v220, s43, v104
	v_fmac_f32_e32 v221, s43, v105
	v_fmac_f32_e32 v222, s43, v106
	v_fmac_f32_e32 v223, s43, v107
	v_fmac_f32_e32 v216, s15, v44
	v_fmac_f32_e32 v217, s15, v45
	v_fmac_f32_e32 v218, s15, v46
	v_fmac_f32_e32 v219, s15, v47
	v_fmac_f32_e32 v220, s63, v108
	v_fmac_f32_e32 v221, s63, v109
	v_fmac_f32_e32 v222, s63, v110
	v_fmac_f32_e32 v223, s63, v111
	v_fmac_f32_e32 v216, s25, v48
	v_fmac_f32_e32 v217, s25, v49
	v_fmac_f32_e32 v218, s25, v50
; __device__ __forceinline__ unsigned pk2(float lo, float hi) { unsigned r; asm("v_cvt_pk_bf16_f32 %0, %1, %2" : "=v"(r) : "v"(lo), "v"(hi)); return r; }
; __device__ __forceinline__ void p2_gate(const Params& p, const LAS float* aup, int t0, int lane) {
;     ...
;         *(u32x4*)(GG + (size_t)t * 512 + lane * 8) = __builtin_nontemporal_load((const u32x4*)(zg + 1024 + lane * 8));
;         const unsigned short araw = zg[1536 + (lane & 31)]; const int alo = (int)((unsigned)araw << 16);
;         f32x4 acc0 = ab0, acc1 = ab1;
; #pragma unroll
;         for (int r = 0; r < 16; ++r) { const float a0 = __int_as_float(__builtin_amdgcn_readlane(alo, r)), a1 = __int_as_float(__builtin_amdgcn_readlane(alo, 16 + r));
;             acc0 += a0 * *(const LAS f32x4*)(aup + r * 256 + 4 * lane); acc1 += a1 * *(const LAS f32x4*)(aup + (16 + r) * 256 + 4 * lane); }
;         float n0[4], n1[4];
; #pragma unroll
;         for (int j = 0; j < 4; ++j) { const float y0 = -acc0[j], y1 = -acc1[j];
;             n0[j] = (fmaxf(y0, 0.f) + __logf(1.0f + __expf(-fabsf(y0)))) * 0.0625f; n1[j] = (fmaxf(y1, 0.f) + __logf(1.0f + __expf(-fabsf(y1)))) * 0.0625f; }
;         u32x2 w; w.x = pk2(n0[0], n0[1]); w.y = pk2(n0[2], n0[3]); *(u32x2*)(GNL + (size_t)t * 512 + 4 * lane) = w;
;         w.x = pk2(n1[0], n1[1]); w.y = pk2(n1[2], n1[3]); *(u32x2*)(GNL + (size_t)t * 512 + 256 + 4 * lane) = w;
	v_fmac_f32_e32 v219, s25, v51
	v_fmac_f32_e32 v220, s64, v112
	v_fmac_f32_e32 v221, s64, v113
	v_fmac_f32_e32 v222, s64, v114
	v_fmac_f32_e32 v223, s64, v115
	v_fmac_f32_e32 v216, s26, v52
	v_fmac_f32_e32 v217, s26, v53
	v_fmac_f32_e32 v218, s26, v54
	v_fmac_f32_e32 v219, s26, v55
	v_fmac_f32_e32 v220, s65, v116
	v_fmac_f32_e32 v221, s65, v117
	v_fmac_f32_e32 v222, s65, v118
	v_fmac_f32_e32 v223, s65, v119
	v_fmac_f32_e32 v216, s27, v56
	v_fmac_f32_e32 v217, s27, v57
	v_fmac_f32_e32 v218, s27, v58
	v_fmac_f32_e32 v219, s27, v59
	v_fmac_f32_e32 v220, s74, v120
	v_fmac_f32_e32 v221, s74, v121
	v_fmac_f32_e32 v222, s74, v122
	v_fmac_f32_e32 v223, s74, v123
	v_fmac_f32_e32 v216, s36, v60
	v_fmac_f32_e32 v217, s36, v61
	v_fmac_f32_e32 v218, s36, v62
	v_fmac_f32_e32 v219, s36, v63
	v_fmac_f32_e32 v220, s75, v124
	v_fmac_f32_e32 v221, s75, v125
	v_fmac_f32_e32 v222, s75, v126
	v_fmac_f32_e32 v223, s75, v127
	v_fmac_f32_e32 v216, s37, v64
	v_fmac_f32_e32 v217, s37, v65
	v_fmac_f32_e32 v218, s37, v66
	v_fmac_f32_e32 v219, s37, v67
	v_fmac_f32_e32 v220, s76, v128
	v_fmac_f32_e32 v221, s76, v129
	v_fmac_f32_e32 v222, s76, v130
	v_fmac_f32_e32 v223, s76, v131
	v_fmac_f32_e32 v216, s42, v68
	v_fmac_f32_e32 v217, s42, v69
	v_fmac_f32_e32 v218, s42, v70
	v_fmac_f32_e32 v219, s42, v71
	v_fmac_f32_e32 v220, s77, v132
	v_fmac_f32_e32 v221, s77, v133
	v_fmac_f32_e32 v222, s77, v134
	v_fmac_f32_e32 v223, s77, v135
	v_mul_f32_e64 v224, |v216|, s101
	v_mul_f32_e64 v225, |v217|, s101
	v_mul_f32_e64 v226, |v218|, s101
	v_mul_f32_e64 v227, |v219|, s101
	v_exp_f32_e32 v224, v224
	v_exp_f32_e32 v225, v225
	v_exp_f32_e32 v226, v226
	v_exp_f32_e32 v227, v227
	v_max_f32_e64 v216, -v216, 0
	v_max_f32_e64 v217, -v217, 0
	v_max_f32_e64 v218, -v218, 0
	v_max_f32_e64 v219, -v219, 0
	v_add_f32_e32 v224, 1.0, v224
	v_add_f32_e32 v225, 1.0, v225
	v_add_f32_e32 v226, 1.0, v226
	v_add_f32_e32 v227, 1.0, v227
	v_log_f32_e32 v224, v224
	v_log_f32_e32 v225, v225
	v_log_f32_e32 v226, v226
	v_log_f32_e32 v227, v227
	s_nop 0
	v_fmac_f32_e32 v216, 0x3f317218, v224
	v_fmac_f32_e32 v217, 0x3f317218, v225
	v_fmac_f32_e32 v218, 0x3f317218, v226
	v_fmac_f32_e32 v219, 0x3f317218, v227
	v_mul_f32_e32 v216, 0x3d800000, v216
	v_mul_f32_e32 v217, 0x3d800000, v217
	v_mul_f32_e32 v218, 0x3d800000, v218
	v_mul_f32_e32 v219, 0x3d800000, v219
	v_mul_f32_e64 v224, |v220|, s101
	v_mul_f32_e64 v225, |v221|, s101
	v_mul_f32_e64 v226, |v222|, s101
	v_mul_f32_e64 v227, |v223|, s101
	v_exp_f32_e32 v224, v224
	v_exp_f32_e32 v225, v225
	v_exp_f32_e32 v226, v226
	v_exp_f32_e32 v227, v227
	v_max_f32_e64 v220, -v220, 0
	v_max_f32_e64 v221, -v221, 0
	v_max_f32_e64 v222, -v222, 0
	v_max_f32_e64 v223, -v223, 0
	v_add_f32_e32 v224, 1.0, v224
	v_add_f32_e32 v225, 1.0, v225
	v_add_f32_e32 v226, 1.0, v226
	v_add_f32_e32 v227, 1.0, v227
	v_log_f32_e32 v224, v224
	v_log_f32_e32 v225, v225
	v_log_f32_e32 v226, v226
	v_log_f32_e32 v227, v227
	s_nop 0
	v_fmac_f32_e32 v220, 0x3f317218, v224
	v_fmac_f32_e32 v221, 0x3f317218, v225
	v_fmac_f32_e32 v222, 0x3f317218, v226
	v_fmac_f32_e32 v223, 0x3f317218, v227
	v_mul_f32_e32 v220, 0x3d800000, v220
	v_mul_f32_e32 v221, 0x3d800000, v221
	v_mul_f32_e32 v222, 0x3d800000, v222
	v_mul_f32_e32 v223, 0x3d800000, v223
	v_cvt_pk_bf16_f32 v224, v216, v217
	v_cvt_pk_bf16_f32 v225, v218, v219
	v_cvt_pk_bf16_f32 v226, v220, v221
	v_cvt_pk_bf16_f32 v227, v222, v223
	global_store_dwordx2 v4, v[224:225], s[58:59] nt
	global_store_dwordx2 v4, v[226:227], s[58:59] offset:512 nt
	v_add_u32_e32 v5, 0x400, v5
	v_add_u32_e32 v4, 0x400, v4
	s_waitcnt vmcnt(38)
	global_store_dwordx4 v5, v[168:171], s[58:59] nt
	v_lshlrev_b32_e32 v208, 16, v208
	v_mov_b32_e32 v216, v228
	v_mov_b32_e32 v217, v229
	v_mov_b32_e32 v218, v230
	v_mov_b32_e32 v219, v231
	v_mov_b32_e32 v220, v232
	v_mov_b32_e32 v221, v233
	v_mov_b32_e32 v222, v234
	v_mov_b32_e32 v223, v235
	s_nop 0
	v_readlane_b32 s14, v208, 0
	v_readlane_b32 s15, v208, 1
	v_readlane_b32 s25, v208, 2
	v_readlane_b32 s26, v208, 3
	v_readlane_b32 s27, v208, 4
	v_readlane_b32 s36, v208, 5
	v_readlane_b32 s37, v208, 6
	v_readlane_b32 s42, v208, 7
	v_readlane_b32 s43, v208, 16
	v_readlane_b32 s63, v208, 17
	v_readlane_b32 s64, v208, 18
	v_readlane_b32 s65, v208, 19
	v_readlane_b32 s74, v208, 20
	v_readlane_b32 s75, v208, 21
	v_readlane_b32 s76, v208, 22
	v_readlane_b32 s77, v208, 23
	s_nop 1
	v_fmac_f32_e32 v216, s14, v8
	v_fmac_f32_e32 v217, s14, v9
	v_fmac_f32_e32 v218, s14, v10
	v_fmac_f32_e32 v219, s14, v11
	v_fmac_f32_e32 v220, s43, v72
	v_fmac_f32_e32 v221, s43, v73
	v_fmac_f32_e32 v222, s43, v74
	v_fmac_f32_e32 v223, s43, v75
	v_fmac_f32_e32 v216, s15, v12
	v_fmac_f32_e32 v217, s15, v13
	v_fmac_f32_e32 v218, s15, v14
	v_fmac_f32_e32 v219, s15, v15
	v_fmac_f32_e32 v220, s63, v76
	v_fmac_f32_e32 v221, s63, v77
	v_fmac_f32_e32 v222, s63, v78
	v_fmac_f32_e32 v223, s63, v79
	v_fmac_f32_e32 v216, s25, v16
	v_fmac_f32_e32 v217, s25, v17
	v_fmac_f32_e32 v218, s25, v18
	v_fmac_f32_e32 v219, s25, v19
	v_fmac_f32_e32 v220, s64, v80
	v_fmac_f32_e32 v221, s64, v81
	v_fmac_f32_e32 v222, s64, v82
	v_fmac_f32_e32 v223, s64, v83
	v_fmac_f32_e32 v216, s26, v20
	v_fmac_f32_e32 v217, s26, v21
	v_fmac_f32_e32 v218, s26, v22
	v_fmac_f32_e32 v219, s26, v23
	v_fmac_f32_e32 v220, s65, v84
	v_fmac_f32_e32 v221, s65, v85
	v_fmac_f32_e32 v222, s65, v86
	v_fmac_f32_e32 v223, s65, v87
	v_fmac_f32_e32 v216, s27, v24
	v_fmac_f32_e32 v217, s27, v25
	v_fmac_f32_e32 v218, s27, v26
	v_fmac_f32_e32 v219, s27, v27
	v_fmac_f32_e32 v220, s74, v88
	v_fmac_f32_e32 v221, s74, v89
	v_fmac_f32_e32 v222, s74, v90
	v_fmac_f32_e32 v223, s74, v91
	v_fmac_f32_e32 v216, s36, v28
	v_fmac_f32_e32 v217, s36, v29
; __device__ __forceinline__ unsigned pk2(float lo, float hi) { unsigned r; asm("v_cvt_pk_bf16_f32 %0, %1, %2" : "=v"(r) : "v"(lo), "v"(hi)); return r; }
; __device__ __forceinline__ void p2_gate(const Params& p, const LAS float* aup, int t0, int lane) {
;     ...
;         for (int r = 0; r < 16; ++r) { const float a0 = __int_as_float(__builtin_amdgcn_readlane(alo, r)), a1 = __int_as_float(__builtin_amdgcn_readlane(alo, 16 + r));
;             acc0 += a0 * *(const LAS f32x4*)(aup + r * 256 + 4 * lane); acc1 += a1 * *(const LAS f32x4*)(aup + (16 + r) * 256 + 4 * lane); }
;         float n0[4], n1[4];
; #pragma unroll
;         for (int j = 0; j < 4; ++j) { const float y0 = -acc0[j], y1 = -acc1[j];
;             n0[j] = (fmaxf(y0, 0.f) + __logf(1.0f + __expf(-fabsf(y0)))) * 0.0625f; n1[j] = (fmaxf(y1, 0.f) + __logf(1.0f + __expf(-fabsf(y1)))) * 0.0625f; }
;         u32x2 w; w.x = pk2(n0[0], n0[1]); w.y = pk2(n0[2], n0[3]); *(u32x2*)(GNL + (size_t)t * 512 + 4 * lane) = w;
;         w.x = pk2(n1[0], n1[1]); w.y = pk2(n1[2], n1[3]); *(u32x2*)(GNL + (size_t)t * 512 + 256 + 4 * lane) = w;
	v_fmac_f32_e32 v218, s36, v30
	v_fmac_f32_e32 v219, s36, v31
	v_fmac_f32_e32 v220, s75, v92
	v_fmac_f32_e32 v221, s75, v93
	v_fmac_f32_e32 v222, s75, v94
	v_fmac_f32_e32 v223, s75, v95
	v_fmac_f32_e32 v216, s37, v32
	v_fmac_f32_e32 v217, s37, v33
	v_fmac_f32_e32 v218, s37, v34
	v_fmac_f32_e32 v219, s37, v35
	v_fmac_f32_e32 v220, s76, v96
	v_fmac_f32_e32 v221, s76, v97
	v_fmac_f32_e32 v222, s76, v98
	v_fmac_f32_e32 v223, s76, v99
	v_fmac_f32_e32 v216, s42, v36
	v_fmac_f32_e32 v217, s42, v37
	v_fmac_f32_e32 v218, s42, v38
	v_fmac_f32_e32 v219, s42, v39
	v_fmac_f32_e32 v220, s77, v100
	v_fmac_f32_e32 v221, s77, v101
	v_fmac_f32_e32 v222, s77, v102
	v_fmac_f32_e32 v223, s77, v103
	s_nop 0
	v_readlane_b32 s14, v208, 8
	v_readlane_b32 s15, v208, 9
	v_readlane_b32 s25, v208, 10
	v_readlane_b32 s26, v208, 11
	v_readlane_b32 s27, v208, 12
	v_readlane_b32 s36, v208, 13
	v_readlane_b32 s37, v208, 14
	v_readlane_b32 s42, v208, 15
	v_readlane_b32 s43, v208, 24
	v_readlane_b32 s63, v208, 25
	v_readlane_b32 s64, v208, 26
	v_readlane_b32 s65, v208, 27
	v_readlane_b32 s74, v208, 28
	v_readlane_b32 s75, v208, 29
	v_readlane_b32 s76, v208, 30
	v_readlane_b32 s77, v208, 31
	s_nop 1
	v_fmac_f32_e32 v216, s14, v40
	v_fmac_f32_e32 v217, s14, v41
	v_fmac_f32_e32 v218, s14, v42
	v_fmac_f32_e32 v219, s14, v43
	v_fmac_f32_e32 v220, s43, v104
	v_fmac_f32_e32 v221, s43, v105
	v_fmac_f32_e32 v222, s43, v106
	v_fmac_f32_e32 v223, s43, v107
	v_fmac_f32_e32 v216, s15, v44
	v_fmac_f32_e32 v217, s15, v45
	v_fmac_f32_e32 v218, s15, v46
	v_fmac_f32_e32 v219, s15, v47
	v_fmac_f32_e32 v220, s63, v108
	v_fmac_f32_e32 v221, s63, v109
	v_fmac_f32_e32 v222, s63, v110
	v_fmac_f32_e32 v223, s63, v111
	v_fmac_f32_e32 v216, s25, v48
	v_fmac_f32_e32 v217, s25, v49
	v_fmac_f32_e32 v218, s25, v50
	v_fmac_f32_e32 v219, s25, v51
	v_fmac_f32_e32 v220, s64, v112
	v_fmac_f32_e32 v221, s64, v113
	v_fmac_f32_e32 v222, s64, v114
	v_fmac_f32_e32 v223, s64, v115
	v_fmac_f32_e32 v216, s26, v52
	v_fmac_f32_e32 v217, s26, v53
	v_fmac_f32_e32 v218, s26, v54
	v_fmac_f32_e32 v219, s26, v55
	v_fmac_f32_e32 v220, s65, v116
	v_fmac_f32_e32 v221, s65, v117
	v_fmac_f32_e32 v222, s65, v118
	v_fmac_f32_e32 v223, s65, v119
	v_fmac_f32_e32 v216, s27, v56
	v_fmac_f32_e32 v217, s27, v57
	v_fmac_f32_e32 v218, s27, v58
	v_fmac_f32_e32 v219, s27, v59
	v_fmac_f32_e32 v220, s74, v120
	v_fmac_f32_e32 v221, s74, v121
	v_fmac_f32_e32 v222, s74, v122
	v_fmac_f32_e32 v223, s74, v123
	v_fmac_f32_e32 v216, s36, v60
	v_fmac_f32_e32 v217, s36, v61
	v_fmac_f32_e32 v218, s36, v62
	v_fmac_f32_e32 v219, s36, v63
	v_fmac_f32_e32 v220, s75, v124
	v_fmac_f32_e32 v221, s75, v125
	v_fmac_f32_e32 v222, s75, v126
	v_fmac_f32_e32 v223, s75, v127
	v_fmac_f32_e32 v216, s37, v64
	v_fmac_f32_e32 v217, s37, v65
	v_fmac_f32_e32 v218, s37, v66
	v_fmac_f32_e32 v219, s37, v67
	v_fmac_f32_e32 v220, s76, v128
	v_fmac_f32_e32 v221, s76, v129
	v_fmac_f32_e32 v222, s76, v130
	v_fmac_f32_e32 v223, s76, v131
	v_fmac_f32_e32 v216, s42, v68
	v_fmac_f32_e32 v217, s42, v69
	v_fmac_f32_e32 v218, s42, v70
	v_fmac_f32_e32 v219, s42, v71
	v_fmac_f32_e32 v220, s77, v132
	v_fmac_f32_e32 v221, s77, v133
	v_fmac_f32_e32 v222, s77, v134
	v_fmac_f32_e32 v223, s77, v135
	v_mul_f32_e64 v224, |v216|, s101
	v_mul_f32_e64 v225, |v217|, s101
	v_mul_f32_e64 v226, |v218|, s101
	v_mul_f32_e64 v227, |v219|, s101
	v_exp_f32_e32 v224, v224
	v_exp_f32_e32 v225, v225
	v_exp_f32_e32 v226, v226
	v_exp_f32_e32 v227, v227
	v_max_f32_e64 v216, -v216, 0
	v_max_f32_e64 v217, -v217, 0
	v_max_f32_e64 v218, -v218, 0
	v_max_f32_e64 v219, -v219, 0
	v_add_f32_e32 v224, 1.0, v224
	v_add_f32_e32 v225, 1.0, v225
	v_add_f32_e32 v226, 1.0, v226
	v_add_f32_e32 v227, 1.0, v227
	v_log_f32_e32 v224, v224
	v_log_f32_e32 v225, v225
	v_log_f32_e32 v226, v226
	v_log_f32_e32 v227, v227
	s_nop 0
	v_fmac_f32_e32 v216, 0x3f317218, v224
	v_fmac_f32_e32 v217, 0x3f317218, v225
	v_fmac_f32_e32 v218, 0x3f317218, v226
	v_fmac_f32_e32 v219, 0x3f317218, v227
	v_mul_f32_e32 v216, 0x3d800000, v216
	v_mul_f32_e32 v217, 0x3d800000, v217
	v_mul_f32_e32 v218, 0x3d800000, v218
	v_mul_f32_e32 v219, 0x3d800000, v219
	v_mul_f32_e64 v224, |v220|, s101
	v_mul_f32_e64 v225, |v221|, s101
	v_mul_f32_e64 v226, |v222|, s101
	v_mul_f32_e64 v227, |v223|, s101
	v_exp_f32_e32 v224, v224
	v_exp_f32_e32 v225, v225
	v_exp_f32_e32 v226, v226
	v_exp_f32_e32 v227, v227
	v_max_f32_e64 v220, -v220, 0
	v_max_f32_e64 v221, -v221, 0
	v_max_f32_e64 v222, -v222, 0
	v_max_f32_e64 v223, -v223, 0
	v_add_f32_e32 v224, 1.0, v224
	v_add_f32_e32 v225, 1.0, v225
	v_add_f32_e32 v226, 1.0, v226
	v_add_f32_e32 v227, 1.0, v227
	v_log_f32_e32 v224, v224
	v_log_f32_e32 v225, v225
	v_log_f32_e32 v226, v226
	v_log_f32_e32 v227, v227
	s_nop 0
	v_fmac_f32_e32 v220, 0x3f317218, v224
	v_fmac_f32_e32 v221, 0x3f317218, v225
	v_fmac_f32_e32 v222, 0x3f317218, v226
	v_fmac_f32_e32 v223, 0x3f317218, v227
	v_mul_f32_e32 v220, 0x3d800000, v220
	v_mul_f32_e32 v221, 0x3d800000, v221
	v_mul_f32_e32 v222, 0x3d800000, v222
	v_mul_f32_e32 v223, 0x3d800000, v223
	v_cvt_pk_bf16_f32 v224, v216, v217
	v_cvt_pk_bf16_f32 v225, v218, v219
	v_cvt_pk_bf16_f32 v226, v220, v221
	v_cvt_pk_bf16_f32 v227, v222, v223
	global_store_dwordx2 v4, v[224:225], s[58:59] nt
	global_store_dwordx2 v4, v[226:227], s[58:59] offset:512 nt
	v_add_u32_e32 v5, 0x400, v5
	v_add_u32_e32 v4, 0x400, v4
	s_waitcnt vmcnt(39)
; __device__ __forceinline__ void p2_gate(const Params& p, const LAS float* aup, int t0, int lane) {
;     ...
;         *(u32x4*)(GG + (size_t)t * 512 + lane * 8) = __builtin_nontemporal_load((const u32x4*)(zg + 1024 + lane * 8));
;         const unsigned short araw = zg[1536 + (lane & 31)]; const int alo = (int)((unsigned)araw << 16);
;         f32x4 acc0 = ab0, acc1 = ab1;
; #pragma unroll
;         for (int r = 0; r < 16; ++r) { const float a0 = __int_as_float(__builtin_amdgcn_readlane(alo, r)), a1 = __int_as_float(__builtin_amdgcn_readlane(alo, 16 + r));
;             acc0 += a0 * *(const LAS f32x4*)(aup + r * 256 + 4 * lane); acc1 += a1 * *(const LAS f32x4*)(aup + (16 + r) * 256 + 4 * lane); }
;         float n0[4], n1[4];
; #pragma unroll
;         for (int j = 0; j < 4; ++j) { const float y0 = -acc0[j], y1 = -acc1[j];
;             n0[j] = (fmaxf(y0, 0.f) + __logf(1.0f + __expf(-fabsf(y0)))) * 0.0625f; n1[j] = (fmaxf(y1, 0.f) + __logf(1.0f + __expf(-fabsf(y1)))) * 0.0625f; }
	global_store_dwordx4 v5, v[172:175], s[58:59] nt
	v_lshlrev_b32_e32 v209, 16, v209
	v_mov_b32_e32 v216, v228
	v_mov_b32_e32 v217, v229
	v_mov_b32_e32 v218, v230
	v_mov_b32_e32 v219, v231
	v_mov_b32_e32 v220, v232
	v_mov_b32_e32 v221, v233
	v_mov_b32_e32 v222, v234
	v_mov_b32_e32 v223, v235
	s_nop 0
	v_readlane_b32 s14, v209, 0
	v_readlane_b32 s15, v209, 1
	v_readlane_b32 s25, v209, 2
	v_readlane_b32 s26, v209, 3
	v_readlane_b32 s27, v209, 4
	v_readlane_b32 s36, v209, 5
	v_readlane_b32 s37, v209, 6
	v_readlane_b32 s42, v209, 7
	v_readlane_b32 s43, v209, 16
	v_readlane_b32 s63, v209, 17
	v_readlane_b32 s64, v209, 18
	v_readlane_b32 s65, v209, 19
	v_readlane_b32 s74, v209, 20
	v_readlane_b32 s75, v209, 21
	v_readlane_b32 s76, v209, 22
	v_readlane_b32 s77, v209, 23
	s_nop 1
	v_fmac_f32_e32 v216, s14, v8
	v_fmac_f32_e32 v217, s14, v9
	v_fmac_f32_e32 v218, s14, v10
	v_fmac_f32_e32 v219, s14, v11
	v_fmac_f32_e32 v220, s43, v72
	v_fmac_f32_e32 v221, s43, v73
	v_fmac_f32_e32 v222, s43, v74
	v_fmac_f32_e32 v223, s43, v75
	v_fmac_f32_e32 v216, s15, v12
	v_fmac_f32_e32 v217, s15, v13
	v_fmac_f32_e32 v218, s15, v14
	v_fmac_f32_e32 v219, s15, v15
	v_fmac_f32_e32 v220, s63, v76
	v_fmac_f32_e32 v221, s63, v77
	v_fmac_f32_e32 v222, s63, v78
	v_fmac_f32_e32 v223, s63, v79
	v_fmac_f32_e32 v216, s25, v16
	v_fmac_f32_e32 v217, s25, v17
	v_fmac_f32_e32 v218, s25, v18
	v_fmac_f32_e32 v219, s25, v19
	v_fmac_f32_e32 v220, s64, v80
	v_fmac_f32_e32 v221, s64, v81
	v_fmac_f32_e32 v222, s64, v82
	v_fmac_f32_e32 v223, s64, v83
	v_fmac_f32_e32 v216, s26, v20
	v_fmac_f32_e32 v217, s26, v21
	v_fmac_f32_e32 v218, s26, v22
	v_fmac_f32_e32 v219, s26, v23
	v_fmac_f32_e32 v220, s65, v84
	v_fmac_f32_e32 v221, s65, v85
	v_fmac_f32_e32 v222, s65, v86
	v_fmac_f32_e32 v223, s65, v87
	v_fmac_f32_e32 v216, s27, v24
	v_fmac_f32_e32 v217, s27, v25
	v_fmac_f32_e32 v218, s27, v26
	v_fmac_f32_e32 v219, s27, v27
	v_fmac_f32_e32 v220, s74, v88
	v_fmac_f32_e32 v221, s74, v89
	v_fmac_f32_e32 v222, s74, v90
	v_fmac_f32_e32 v223, s74, v91
	v_fmac_f32_e32 v216, s36, v28
	v_fmac_f32_e32 v217, s36, v29
	v_fmac_f32_e32 v218, s36, v30
	v_fmac_f32_e32 v219, s36, v31
	v_fmac_f32_e32 v220, s75, v92
	v_fmac_f32_e32 v221, s75, v93
	v_fmac_f32_e32 v222, s75, v94
	v_fmac_f32_e32 v223, s75, v95
	v_fmac_f32_e32 v216, s37, v32
	v_fmac_f32_e32 v217, s37, v33
	v_fmac_f32_e32 v218, s37, v34
	v_fmac_f32_e32 v219, s37, v35
	v_fmac_f32_e32 v220, s76, v96
	v_fmac_f32_e32 v221, s76, v97
	v_fmac_f32_e32 v222, s76, v98
	v_fmac_f32_e32 v223, s76, v99
	v_fmac_f32_e32 v216, s42, v36
	v_fmac_f32_e32 v217, s42, v37
	v_fmac_f32_e32 v218, s42, v38
	v_fmac_f32_e32 v219, s42, v39
	v_fmac_f32_e32 v220, s77, v100
	v_fmac_f32_e32 v221, s77, v101
	v_fmac_f32_e32 v222, s77, v102
	v_fmac_f32_e32 v223, s77, v103
	s_nop 0
	v_readlane_b32 s14, v209, 8
	v_readlane_b32 s15, v209, 9
	v_readlane_b32 s25, v209, 10
	v_readlane_b32 s26, v209, 11
	v_readlane_b32 s27, v209, 12
	v_readlane_b32 s36, v209, 13
	v_readlane_b32 s37, v209, 14
	v_readlane_b32 s42, v209, 15
	v_readlane_b32 s43, v209, 24
	v_readlane_b32 s63, v209, 25
	v_readlane_b32 s64, v209, 26
	v_readlane_b32 s65, v209, 27
	v_readlane_b32 s74, v209, 28
	v_readlane_b32 s75, v209, 29
	v_readlane_b32 s76, v209, 30
	v_readlane_b32 s77, v209, 31
	s_nop 1
	v_fmac_f32_e32 v216, s14, v40
	v_fmac_f32_e32 v217, s14, v41
	v_fmac_f32_e32 v218, s14, v42
	v_fmac_f32_e32 v219, s14, v43
	v_fmac_f32_e32 v220, s43, v104
	v_fmac_f32_e32 v221, s43, v105
	v_fmac_f32_e32 v222, s43, v106
	v_fmac_f32_e32 v223, s43, v107
	v_fmac_f32_e32 v216, s15, v44
	v_fmac_f32_e32 v217, s15, v45
	v_fmac_f32_e32 v218, s15, v46
	v_fmac_f32_e32 v219, s15, v47
	v_fmac_f32_e32 v220, s63, v108
	v_fmac_f32_e32 v221, s63, v109
	v_fmac_f32_e32 v222, s63, v110
	v_fmac_f32_e32 v223, s63, v111
	v_fmac_f32_e32 v216, s25, v48
	v_fmac_f32_e32 v217, s25, v49
	v_fmac_f32_e32 v218, s25, v50
	v_fmac_f32_e32 v219, s25, v51
	v_fmac_f32_e32 v220, s64, v112
	v_fmac_f32_e32 v221, s64, v113
	v_fmac_f32_e32 v222, s64, v114
	v_fmac_f32_e32 v223, s64, v115
	v_fmac_f32_e32 v216, s26, v52
	v_fmac_f32_e32 v217, s26, v53
	v_fmac_f32_e32 v218, s26, v54
	v_fmac_f32_e32 v219, s26, v55
	v_fmac_f32_e32 v220, s65, v116
	v_fmac_f32_e32 v221, s65, v117
	v_fmac_f32_e32 v222, s65, v118
	v_fmac_f32_e32 v223, s65, v119
	v_fmac_f32_e32 v216, s27, v56
	v_fmac_f32_e32 v217, s27, v57
	v_fmac_f32_e32 v218, s27, v58
	v_fmac_f32_e32 v219, s27, v59
	v_fmac_f32_e32 v220, s74, v120
	v_fmac_f32_e32 v221, s74, v121
	v_fmac_f32_e32 v222, s74, v122
	v_fmac_f32_e32 v223, s74, v123
	v_fmac_f32_e32 v216, s36, v60
	v_fmac_f32_e32 v217, s36, v61
	v_fmac_f32_e32 v218, s36, v62
	v_fmac_f32_e32 v219, s36, v63
	v_fmac_f32_e32 v220, s75, v124
	v_fmac_f32_e32 v221, s75, v125
	v_fmac_f32_e32 v222, s75, v126
	v_fmac_f32_e32 v223, s75, v127
	v_fmac_f32_e32 v216, s37, v64
	v_fmac_f32_e32 v217, s37, v65
	v_fmac_f32_e32 v218, s37, v66
	v_fmac_f32_e32 v219, s37, v67
	v_fmac_f32_e32 v220, s76, v128
	v_fmac_f32_e32 v221, s76, v129
	v_fmac_f32_e32 v222, s76, v130
	v_fmac_f32_e32 v223, s76, v131
	v_fmac_f32_e32 v216, s42, v68
	v_fmac_f32_e32 v217, s42, v69
	v_fmac_f32_e32 v218, s42, v70
	v_fmac_f32_e32 v219, s42, v71
	v_fmac_f32_e32 v220, s77, v132
	v_fmac_f32_e32 v221, s77, v133
	v_fmac_f32_e32 v222, s77, v134
	v_fmac_f32_e32 v223, s77, v135
	v_mul_f32_e64 v224, |v216|, s101
	v_mul_f32_e64 v225, |v217|, s101
	v_mul_f32_e64 v226, |v218|, s101
	v_mul_f32_e64 v227, |v219|, s101
	v_exp_f32_e32 v224, v224
	v_exp_f32_e32 v225, v225
	v_exp_f32_e32 v226, v226
	v_exp_f32_e32 v227, v227
	v_max_f32_e64 v216, -v216, 0
	v_max_f32_e64 v217, -v217, 0
	v_max_f32_e64 v218, -v218, 0
	v_max_f32_e64 v219, -v219, 0
; __device__ __forceinline__ unsigned pk2(float lo, float hi) { unsigned r; asm("v_cvt_pk_bf16_f32 %0, %1, %2" : "=v"(r) : "v"(lo), "v"(hi)); return r; }
; __device__ __forceinline__ void p2_gate(const Params& p, const LAS float* aup, int t0, int lane) {
;     ...
;         *(u32x4*)(GG + (size_t)t * 512 + lane * 8) = __builtin_nontemporal_load((const u32x4*)(zg + 1024 + lane * 8));
;         const unsigned short araw = zg[1536 + (lane & 31)]; const int alo = (int)((unsigned)araw << 16);
;         f32x4 acc0 = ab0, acc1 = ab1;
; #pragma unroll
;         for (int r = 0; r < 16; ++r) { const float a0 = __int_as_float(__builtin_amdgcn_readlane(alo, r)), a1 = __int_as_float(__builtin_amdgcn_readlane(alo, 16 + r));
;             acc0 += a0 * *(const LAS f32x4*)(aup + r * 256 + 4 * lane); acc1 += a1 * *(const LAS f32x4*)(aup + (16 + r) * 256 + 4 * lane); }
;         float n0[4], n1[4];
; #pragma unroll
;         for (int j = 0; j < 4; ++j) { const float y0 = -acc0[j], y1 = -acc1[j];
;             n0[j] = (fmaxf(y0, 0.f) + __logf(1.0f + __expf(-fabsf(y0)))) * 0.0625f; n1[j] = (fmaxf(y1, 0.f) + __logf(1.0f + __expf(-fabsf(y1)))) * 0.0625f; }
;         u32x2 w; w.x = pk2(n0[0], n0[1]); w.y = pk2(n0[2], n0[3]); *(u32x2*)(GNL + (size_t)t * 512 + 4 * lane) = w;
;         w.x = pk2(n1[0], n1[1]); w.y = pk2(n1[2], n1[3]); *(u32x2*)(GNL + (size_t)t * 512 + 256 + 4 * lane) = w;
	v_add_f32_e32 v224, 1.0, v224
	v_add_f32_e32 v225, 1.0, v225
	v_add_f32_e32 v226, 1.0, v226
	v_add_f32_e32 v227, 1.0, v227
	v_log_f32_e32 v224, v224
	v_log_f32_e32 v225, v225
	v_log_f32_e32 v226, v226
	v_log_f32_e32 v227, v227
	s_nop 0
	v_fmac_f32_e32 v216, 0x3f317218, v224
	v_fmac_f32_e32 v217, 0x3f317218, v225
	v_fmac_f32_e32 v218, 0x3f317218, v226
	v_fmac_f32_e32 v219, 0x3f317218, v227
	v_mul_f32_e32 v216, 0x3d800000, v216
	v_mul_f32_e32 v217, 0x3d800000, v217
	v_mul_f32_e32 v218, 0x3d800000, v218
	v_mul_f32_e32 v219, 0x3d800000, v219
	v_mul_f32_e64 v224, |v220|, s101
	v_mul_f32_e64 v225, |v221|, s101
	v_mul_f32_e64 v226, |v222|, s101
	v_mul_f32_e64 v227, |v223|, s101
	v_exp_f32_e32 v224, v224
	v_exp_f32_e32 v225, v225
	v_exp_f32_e32 v226, v226
	v_exp_f32_e32 v227, v227
	v_max_f32_e64 v220, -v220, 0
	v_max_f32_e64 v221, -v221, 0
	v_max_f32_e64 v222, -v222, 0
	v_max_f32_e64 v223, -v223, 0
	v_add_f32_e32 v224, 1.0, v224
	v_add_f32_e32 v225, 1.0, v225
	v_add_f32_e32 v226, 1.0, v226
	v_add_f32_e32 v227, 1.0, v227
	v_log_f32_e32 v224, v224
	v_log_f32_e32 v225, v225
	v_log_f32_e32 v226, v226
	v_log_f32_e32 v227, v227
	s_nop 0
	v_fmac_f32_e32 v220, 0x3f317218, v224
	v_fmac_f32_e32 v221, 0x3f317218, v225
	v_fmac_f32_e32 v222, 0x3f317218, v226
	v_fmac_f32_e32 v223, 0x3f317218, v227
	v_mul_f32_e32 v220, 0x3d800000, v220
	v_mul_f32_e32 v221, 0x3d800000, v221
	v_mul_f32_e32 v222, 0x3d800000, v222
	v_mul_f32_e32 v223, 0x3d800000, v223
	v_cvt_pk_bf16_f32 v224, v216, v217
	v_cvt_pk_bf16_f32 v225, v218, v219
	v_cvt_pk_bf16_f32 v226, v220, v221
	v_cvt_pk_bf16_f32 v227, v222, v223
	global_store_dwordx2 v4, v[224:225], s[58:59] nt
	global_store_dwordx2 v4, v[226:227], s[58:59] offset:512 nt
	v_add_u32_e32 v5, 0x400, v5
	v_add_u32_e32 v4, 0x400, v4
	s_waitcnt vmcnt(40)
	global_store_dwordx4 v5, v[176:179], s[58:59] nt
	v_lshlrev_b32_e32 v210, 16, v210
	v_mov_b32_e32 v216, v228
	v_mov_b32_e32 v217, v229
	v_mov_b32_e32 v218, v230
	v_mov_b32_e32 v219, v231
	v_mov_b32_e32 v220, v232
	v_mov_b32_e32 v221, v233
	v_mov_b32_e32 v222, v234
	v_mov_b32_e32 v223, v235
	s_nop 0
	v_readlane_b32 s14, v210, 0
	v_readlane_b32 s15, v210, 1
	v_readlane_b32 s25, v210, 2
	v_readlane_b32 s26, v210, 3
	v_readlane_b32 s27, v210, 4
	v_readlane_b32 s36, v210, 5
	v_readlane_b32 s37, v210, 6
	v_readlane_b32 s42, v210, 7
	v_readlane_b32 s43, v210, 16
	v_readlane_b32 s63, v210, 17
	v_readlane_b32 s64, v210, 18
	v_readlane_b32 s65, v210, 19
	v_readlane_b32 s74, v210, 20
	v_readlane_b32 s75, v210, 21
	v_readlane_b32 s76, v210, 22
	v_readlane_b32 s77, v210, 23
	s_nop 1
	v_fmac_f32_e32 v216, s14, v8
	v_fmac_f32_e32 v217, s14, v9
	v_fmac_f32_e32 v218, s14, v10
	v_fmac_f32_e32 v219, s14, v11
	v_fmac_f32_e32 v220, s43, v72
	v_fmac_f32_e32 v221, s43, v73
	v_fmac_f32_e32 v222, s43, v74
	v_fmac_f32_e32 v223, s43, v75
	v_fmac_f32_e32 v216, s15, v12
	v_fmac_f32_e32 v217, s15, v13
	v_fmac_f32_e32 v218, s15, v14
	v_fmac_f32_e32 v219, s15, v15
	v_fmac_f32_e32 v220, s63, v76
	v_fmac_f32_e32 v221, s63, v77
	v_fmac_f32_e32 v222, s63, v78
	v_fmac_f32_e32 v223, s63, v79
	v_fmac_f32_e32 v216, s25, v16
	v_fmac_f32_e32 v217, s25, v17
	v_fmac_f32_e32 v218, s25, v18
	v_fmac_f32_e32 v219, s25, v19
	v_fmac_f32_e32 v220, s64, v80
	v_fmac_f32_e32 v221, s64, v81
	v_fmac_f32_e32 v222, s64, v82
	v_fmac_f32_e32 v223, s64, v83
	v_fmac_f32_e32 v216, s26, v20
	v_fmac_f32_e32 v217, s26, v21
	v_fmac_f32_e32 v218, s26, v22
	v_fmac_f32_e32 v219, s26, v23
	v_fmac_f32_e32 v220, s65, v84
	v_fmac_f32_e32 v221, s65, v85
	v_fmac_f32_e32 v222, s65, v86
	v_fmac_f32_e32 v223, s65, v87
	v_fmac_f32_e32 v216, s27, v24
	v_fmac_f32_e32 v217, s27, v25
	v_fmac_f32_e32 v218, s27, v26
	v_fmac_f32_e32 v219, s27, v27
	v_fmac_f32_e32 v220, s74, v88
	v_fmac_f32_e32 v221, s74, v89
	v_fmac_f32_e32 v222, s74, v90
	v_fmac_f32_e32 v223, s74, v91
	v_fmac_f32_e32 v216, s36, v28
	v_fmac_f32_e32 v217, s36, v29
	v_fmac_f32_e32 v218, s36, v30
	v_fmac_f32_e32 v219, s36, v31
	v_fmac_f32_e32 v220, s75, v92
	v_fmac_f32_e32 v221, s75, v93
	v_fmac_f32_e32 v222, s75, v94
	v_fmac_f32_e32 v223, s75, v95
	v_fmac_f32_e32 v216, s37, v32
	v_fmac_f32_e32 v217, s37, v33
	v_fmac_f32_e32 v218, s37, v34
	v_fmac_f32_e32 v219, s37, v35
	v_fmac_f32_e32 v220, s76, v96
	v_fmac_f32_e32 v221, s76, v97
	v_fmac_f32_e32 v222, s76, v98
	v_fmac_f32_e32 v223, s76, v99
	v_fmac_f32_e32 v216, s42, v36
	v_fmac_f32_e32 v217, s42, v37
	v_fmac_f32_e32 v218, s42, v38
	v_fmac_f32_e32 v219, s42, v39
	v_fmac_f32_e32 v220, s77, v100
	v_fmac_f32_e32 v221, s77, v101
	v_fmac_f32_e32 v222, s77, v102
	v_fmac_f32_e32 v223, s77, v103
	s_nop 0
	v_readlane_b32 s14, v210, 8
	v_readlane_b32 s15, v210, 9
	v_readlane_b32 s25, v210, 10
	v_readlane_b32 s26, v210, 11
	v_readlane_b32 s27, v210, 12
	v_readlane_b32 s36, v210, 13
	v_readlane_b32 s37, v210, 14
	v_readlane_b32 s42, v210, 15
	v_readlane_b32 s43, v210, 24
	v_readlane_b32 s63, v210, 25
	v_readlane_b32 s64, v210, 26
	v_readlane_b32 s65, v210, 27
	v_readlane_b32 s74, v210, 28
	v_readlane_b32 s75, v210, 29
	v_readlane_b32 s76, v210, 30
	v_readlane_b32 s77, v210, 31
	s_nop 1
	v_fmac_f32_e32 v216, s14, v40
	v_fmac_f32_e32 v217, s14, v41
	v_fmac_f32_e32 v218, s14, v42
	v_fmac_f32_e32 v219, s14, v43
	v_fmac_f32_e32 v220, s43, v104
	v_fmac_f32_e32 v221, s43, v105
	v_fmac_f32_e32 v222, s43, v106
	v_fmac_f32_e32 v223, s43, v107
	v_fmac_f32_e32 v216, s15, v44
	v_fmac_f32_e32 v217, s15, v45
	v_fmac_f32_e32 v218, s15, v46
	v_fmac_f32_e32 v219, s15, v47
	v_fmac_f32_e32 v220, s63, v108
	v_fmac_f32_e32 v221, s63, v109
	v_fmac_f32_e32 v222, s63, v110
	v_fmac_f32_e32 v223, s63, v111
	v_fmac_f32_e32 v216, s25, v48
	v_fmac_f32_e32 v217, s25, v49
	v_fmac_f32_e32 v218, s25, v50
; __device__ __forceinline__ unsigned pk2(float lo, float hi) { unsigned r; asm("v_cvt_pk_bf16_f32 %0, %1, %2" : "=v"(r) : "v"(lo), "v"(hi)); return r; }
; __device__ __forceinline__ void p2_gate(const Params& p, const LAS float* aup, int t0, int lane) {
;     ...
;         *(u32x4*)(GG + (size_t)t * 512 + lane * 8) = __builtin_nontemporal_load((const u32x4*)(zg + 1024 + lane * 8));
;         const unsigned short araw = zg[1536 + (lane & 31)]; const int alo = (int)((unsigned)araw << 16);
;         f32x4 acc0 = ab0, acc1 = ab1;
; #pragma unroll
;         for (int r = 0; r < 16; ++r) { const float a0 = __int_as_float(__builtin_amdgcn_readlane(alo, r)), a1 = __int_as_float(__builtin_amdgcn_readlane(alo, 16 + r));
;             acc0 += a0 * *(const LAS f32x4*)(aup + r * 256 + 4 * lane); acc1 += a1 * *(const LAS f32x4*)(aup + (16 + r) * 256 + 4 * lane); }
;         float n0[4], n1[4];
; #pragma unroll
;         for (int j = 0; j < 4; ++j) { const float y0 = -acc0[j], y1 = -acc1[j];
;             n0[j] = (fmaxf(y0, 0.f) + __logf(1.0f + __expf(-fabsf(y0)))) * 0.0625f; n1[j] = (fmaxf(y1, 0.f) + __logf(1.0f + __expf(-fabsf(y1)))) * 0.0625f; }
;         u32x2 w; w.x = pk2(n0[0], n0[1]); w.y = pk2(n0[2], n0[3]); *(u32x2*)(GNL + (size_t)t * 512 + 4 * lane) = w;
;         w.x = pk2(n1[0], n1[1]); w.y = pk2(n1[2], n1[3]); *(u32x2*)(GNL + (size_t)t * 512 + 256 + 4 * lane) = w;
	v_fmac_f32_e32 v219, s25, v51
	v_fmac_f32_e32 v220, s64, v112
	v_fmac_f32_e32 v221, s64, v113
	v_fmac_f32_e32 v222, s64, v114
	v_fmac_f32_e32 v223, s64, v115
	v_fmac_f32_e32 v216, s26, v52
	v_fmac_f32_e32 v217, s26, v53
	v_fmac_f32_e32 v218, s26, v54
	v_fmac_f32_e32 v219, s26, v55
	v_fmac_f32_e32 v220, s65, v116
	v_fmac_f32_e32 v221, s65, v117
	v_fmac_f32_e32 v222, s65, v118
	v_fmac_f32_e32 v223, s65, v119
	v_fmac_f32_e32 v216, s27, v56
	v_fmac_f32_e32 v217, s27, v57
	v_fmac_f32_e32 v218, s27, v58
	v_fmac_f32_e32 v219, s27, v59
	v_fmac_f32_e32 v220, s74, v120
	v_fmac_f32_e32 v221, s74, v121
	v_fmac_f32_e32 v222, s74, v122
	v_fmac_f32_e32 v223, s74, v123
	v_fmac_f32_e32 v216, s36, v60
	v_fmac_f32_e32 v217, s36, v61
	v_fmac_f32_e32 v218, s36, v62
	v_fmac_f32_e32 v219, s36, v63
	v_fmac_f32_e32 v220, s75, v124
	v_fmac_f32_e32 v221, s75, v125
	v_fmac_f32_e32 v222, s75, v126
	v_fmac_f32_e32 v223, s75, v127
	v_fmac_f32_e32 v216, s37, v64
	v_fmac_f32_e32 v217, s37, v65
	v_fmac_f32_e32 v218, s37, v66
	v_fmac_f32_e32 v219, s37, v67
	v_fmac_f32_e32 v220, s76, v128
	v_fmac_f32_e32 v221, s76, v129
	v_fmac_f32_e32 v222, s76, v130
	v_fmac_f32_e32 v223, s76, v131
	v_fmac_f32_e32 v216, s42, v68
	v_fmac_f32_e32 v217, s42, v69
	v_fmac_f32_e32 v218, s42, v70
	v_fmac_f32_e32 v219, s42, v71
	v_fmac_f32_e32 v220, s77, v132
	v_fmac_f32_e32 v221, s77, v133
	v_fmac_f32_e32 v222, s77, v134
	v_fmac_f32_e32 v223, s77, v135
	v_mul_f32_e64 v224, |v216|, s101
	v_mul_f32_e64 v225, |v217|, s101
	v_mul_f32_e64 v226, |v218|, s101
	v_mul_f32_e64 v227, |v219|, s101
	v_exp_f32_e32 v224, v224
	v_exp_f32_e32 v225, v225
	v_exp_f32_e32 v226, v226
	v_exp_f32_e32 v227, v227
	v_max_f32_e64 v216, -v216, 0
	v_max_f32_e64 v217, -v217, 0
	v_max_f32_e64 v218, -v218, 0
	v_max_f32_e64 v219, -v219, 0
	v_add_f32_e32 v224, 1.0, v224
	v_add_f32_e32 v225, 1.0, v225
	v_add_f32_e32 v226, 1.0, v226
	v_add_f32_e32 v227, 1.0, v227
	v_log_f32_e32 v224, v224
	v_log_f32_e32 v225, v225
	v_log_f32_e32 v226, v226
	v_log_f32_e32 v227, v227
	s_nop 0
	v_fmac_f32_e32 v216, 0x3f317218, v224
	v_fmac_f32_e32 v217, 0x3f317218, v225
	v_fmac_f32_e32 v218, 0x3f317218, v226
	v_fmac_f32_e32 v219, 0x3f317218, v227
	v_mul_f32_e32 v216, 0x3d800000, v216
	v_mul_f32_e32 v217, 0x3d800000, v217
	v_mul_f32_e32 v218, 0x3d800000, v218
	v_mul_f32_e32 v219, 0x3d800000, v219
	v_mul_f32_e64 v224, |v220|, s101
	v_mul_f32_e64 v225, |v221|, s101
	v_mul_f32_e64 v226, |v222|, s101
	v_mul_f32_e64 v227, |v223|, s101
	v_exp_f32_e32 v224, v224
	v_exp_f32_e32 v225, v225
	v_exp_f32_e32 v226, v226
	v_exp_f32_e32 v227, v227
	v_max_f32_e64 v220, -v220, 0
	v_max_f32_e64 v221, -v221, 0
	v_max_f32_e64 v222, -v222, 0
	v_max_f32_e64 v223, -v223, 0
	v_add_f32_e32 v224, 1.0, v224
	v_add_f32_e32 v225, 1.0, v225
	v_add_f32_e32 v226, 1.0, v226
	v_add_f32_e32 v227, 1.0, v227
	v_log_f32_e32 v224, v224
	v_log_f32_e32 v225, v225
	v_log_f32_e32 v226, v226
	v_log_f32_e32 v227, v227
	s_nop 0
	v_fmac_f32_e32 v220, 0x3f317218, v224
	v_fmac_f32_e32 v221, 0x3f317218, v225
	v_fmac_f32_e32 v222, 0x3f317218, v226
	v_fmac_f32_e32 v223, 0x3f317218, v227
	v_mul_f32_e32 v220, 0x3d800000, v220
	v_mul_f32_e32 v221, 0x3d800000, v221
	v_mul_f32_e32 v222, 0x3d800000, v222
	v_mul_f32_e32 v223, 0x3d800000, v223
	v_cvt_pk_bf16_f32 v224, v216, v217
	v_cvt_pk_bf16_f32 v225, v218, v219
	v_cvt_pk_bf16_f32 v226, v220, v221
	v_cvt_pk_bf16_f32 v227, v222, v223
	global_store_dwordx2 v4, v[224:225], s[58:59] nt
	global_store_dwordx2 v4, v[226:227], s[58:59] offset:512 nt
	v_add_u32_e32 v5, 0x400, v5
	v_add_u32_e32 v4, 0x400, v4
	s_waitcnt vmcnt(41)
	global_store_dwordx4 v5, v[180:183], s[58:59] nt
	v_lshlrev_b32_e32 v211, 16, v211
	v_mov_b32_e32 v216, v228
	v_mov_b32_e32 v217, v229
	v_mov_b32_e32 v218, v230
	v_mov_b32_e32 v219, v231
	v_mov_b32_e32 v220, v232
	v_mov_b32_e32 v221, v233
	v_mov_b32_e32 v222, v234
	v_mov_b32_e32 v223, v235
	s_nop 0
	v_readlane_b32 s14, v211, 0
	v_readlane_b32 s15, v211, 1
	v_readlane_b32 s25, v211, 2
	v_readlane_b32 s26, v211, 3
	v_readlane_b32 s27, v211, 4
	v_readlane_b32 s36, v211, 5
	v_readlane_b32 s37, v211, 6
	v_readlane_b32 s42, v211, 7
	v_readlane_b32 s43, v211, 16
	v_readlane_b32 s63, v211, 17
	v_readlane_b32 s64, v211, 18
	v_readlane_b32 s65, v211, 19
	v_readlane_b32 s74, v211, 20
	v_readlane_b32 s75, v211, 21
	v_readlane_b32 s76, v211, 22
	v_readlane_b32 s77, v211, 23
	s_nop 1
	v_fmac_f32_e32 v216, s14, v8
	v_fmac_f32_e32 v217, s14, v9
	v_fmac_f32_e32 v218, s14, v10
	v_fmac_f32_e32 v219, s14, v11
	v_fmac_f32_e32 v220, s43, v72
	v_fmac_f32_e32 v221, s43, v73
	v_fmac_f32_e32 v222, s43, v74
	v_fmac_f32_e32 v223, s43, v75
	v_fmac_f32_e32 v216, s15, v12
	v_fmac_f32_e32 v217, s15, v13
	v_fmac_f32_e32 v218, s15, v14
	v_fmac_f32_e32 v219, s15, v15
	v_fmac_f32_e32 v220, s63, v76
	v_fmac_f32_e32 v221, s63, v77
	v_fmac_f32_e32 v222, s63, v78
	v_fmac_f32_e32 v223, s63, v79
	v_fmac_f32_e32 v216, s25, v16
	v_fmac_f32_e32 v217, s25, v17
	v_fmac_f32_e32 v218, s25, v18
	v_fmac_f32_e32 v219, s25, v19
	v_fmac_f32_e32 v220, s64, v80
	v_fmac_f32_e32 v221, s64, v81
	v_fmac_f32_e32 v222, s64, v82
	v_fmac_f32_e32 v223, s64, v83
	v_fmac_f32_e32 v216, s26, v20
	v_fmac_f32_e32 v217, s26, v21
	v_fmac_f32_e32 v218, s26, v22
	v_fmac_f32_e32 v219, s26, v23
	v_fmac_f32_e32 v220, s65, v84
	v_fmac_f32_e32 v221, s65, v85
	v_fmac_f32_e32 v222, s65, v86
	v_fmac_f32_e32 v223, s65, v87
	v_fmac_f32_e32 v216, s27, v24
	v_fmac_f32_e32 v217, s27, v25
	v_fmac_f32_e32 v218, s27, v26
	v_fmac_f32_e32 v219, s27, v27
	v_fmac_f32_e32 v220, s74, v88
	v_fmac_f32_e32 v221, s74, v89
	v_fmac_f32_e32 v222, s74, v90
	v_fmac_f32_e32 v223, s74, v91
	v_fmac_f32_e32 v216, s36, v28
	v_fmac_f32_e32 v217, s36, v29
; __device__ __forceinline__ unsigned pk2(float lo, float hi) { unsigned r; asm("v_cvt_pk_bf16_f32 %0, %1, %2" : "=v"(r) : "v"(lo), "v"(hi)); return r; }
; __device__ __forceinline__ void p2_gate(const Params& p, const LAS float* aup, int t0, int lane) {
;     ...
;         for (int r = 0; r < 16; ++r) { const float a0 = __int_as_float(__builtin_amdgcn_readlane(alo, r)), a1 = __int_as_float(__builtin_amdgcn_readlane(alo, 16 + r));
;             acc0 += a0 * *(const LAS f32x4*)(aup + r * 256 + 4 * lane); acc1 += a1 * *(const LAS f32x4*)(aup + (16 + r) * 256 + 4 * lane); }
;         float n0[4], n1[4];
; #pragma unroll
;         for (int j = 0; j < 4; ++j) { const float y0 = -acc0[j], y1 = -acc1[j];
;             n0[j] = (fmaxf(y0, 0.f) + __logf(1.0f + __expf(-fabsf(y0)))) * 0.0625f; n1[j] = (fmaxf(y1, 0.f) + __logf(1.0f + __expf(-fabsf(y1)))) * 0.0625f; }
;         u32x2 w; w.x = pk2(n0[0], n0[1]); w.y = pk2(n0[2], n0[3]); *(u32x2*)(GNL + (size_t)t * 512 + 4 * lane) = w;
;         w.x = pk2(n1[0], n1[1]); w.y = pk2(n1[2], n1[3]); *(u32x2*)(GNL + (size_t)t * 512 + 256 + 4 * lane) = w;
	v_fmac_f32_e32 v218, s36, v30
	v_fmac_f32_e32 v219, s36, v31
	v_fmac_f32_e32 v220, s75, v92
	v_fmac_f32_e32 v221, s75, v93
	v_fmac_f32_e32 v222, s75, v94
	v_fmac_f32_e32 v223, s75, v95
	v_fmac_f32_e32 v216, s37, v32
	v_fmac_f32_e32 v217, s37, v33
	v_fmac_f32_e32 v218, s37, v34
	v_fmac_f32_e32 v219, s37, v35
	v_fmac_f32_e32 v220, s76, v96
	v_fmac_f32_e32 v221, s76, v97
	v_fmac_f32_e32 v222, s76, v98
	v_fmac_f32_e32 v223, s76, v99
	v_fmac_f32_e32 v216, s42, v36
	v_fmac_f32_e32 v217, s42, v37
	v_fmac_f32_e32 v218, s42, v38
	v_fmac_f32_e32 v219, s42, v39
	v_fmac_f32_e32 v220, s77, v100
	v_fmac_f32_e32 v221, s77, v101
	v_fmac_f32_e32 v222, s77, v102
	v_fmac_f32_e32 v223, s77, v103
	s_nop 0
	v_readlane_b32 s14, v211, 8
	v_readlane_b32 s15, v211, 9
	v_readlane_b32 s25, v211, 10
	v_readlane_b32 s26, v211, 11
	v_readlane_b32 s27, v211, 12
	v_readlane_b32 s36, v211, 13
	v_readlane_b32 s37, v211, 14
	v_readlane_b32 s42, v211, 15
	v_readlane_b32 s43, v211, 24
	v_readlane_b32 s63, v211, 25
	v_readlane_b32 s64, v211, 26
	v_readlane_b32 s65, v211, 27
	v_readlane_b32 s74, v211, 28
	v_readlane_b32 s75, v211, 29
	v_readlane_b32 s76, v211, 30
	v_readlane_b32 s77, v211, 31
	s_nop 1
	v_fmac_f32_e32 v216, s14, v40
	v_fmac_f32_e32 v217, s14, v41
	v_fmac_f32_e32 v218, s14, v42
	v_fmac_f32_e32 v219, s14, v43
	v_fmac_f32_e32 v220, s43, v104
	v_fmac_f32_e32 v221, s43, v105
	v_fmac_f32_e32 v222, s43, v106
	v_fmac_f32_e32 v223, s43, v107
	v_fmac_f32_e32 v216, s15, v44
	v_fmac_f32_e32 v217, s15, v45
	v_fmac_f32_e32 v218, s15, v46
	v_fmac_f32_e32 v219, s15, v47
	v_fmac_f32_e32 v220, s63, v108
	v_fmac_f32_e32 v221, s63, v109
	v_fmac_f32_e32 v222, s63, v110
	v_fmac_f32_e32 v223, s63, v111
	v_fmac_f32_e32 v216, s25, v48
	v_fmac_f32_e32 v217, s25, v49
	v_fmac_f32_e32 v218, s25, v50
	v_fmac_f32_e32 v219, s25, v51
	v_fmac_f32_e32 v220, s64, v112
	v_fmac_f32_e32 v221, s64, v113
	v_fmac_f32_e32 v222, s64, v114
	v_fmac_f32_e32 v223, s64, v115
	v_fmac_f32_e32 v216, s26, v52
	v_fmac_f32_e32 v217, s26, v53
	v_fmac_f32_e32 v218, s26, v54
	v_fmac_f32_e32 v219, s26, v55
	v_fmac_f32_e32 v220, s65, v116
	v_fmac_f32_e32 v221, s65, v117
	v_fmac_f32_e32 v222, s65, v118
	v_fmac_f32_e32 v223, s65, v119
	v_fmac_f32_e32 v216, s27, v56
	v_fmac_f32_e32 v217, s27, v57
	v_fmac_f32_e32 v218, s27, v58
	v_fmac_f32_e32 v219, s27, v59
	v_fmac_f32_e32 v220, s74, v120
	v_fmac_f32_e32 v221, s74, v121
	v_fmac_f32_e32 v222, s74, v122
	v_fmac_f32_e32 v223, s74, v123
	v_fmac_f32_e32 v216, s36, v60
	v_fmac_f32_e32 v217, s36, v61
	v_fmac_f32_e32 v218, s36, v62
	v_fmac_f32_e32 v219, s36, v63
	v_fmac_f32_e32 v220, s75, v124
	v_fmac_f32_e32 v221, s75, v125
	v_fmac_f32_e32 v222, s75, v126
	v_fmac_f32_e32 v223, s75, v127
	v_fmac_f32_e32 v216, s37, v64
	v_fmac_f32_e32 v217, s37, v65
	v_fmac_f32_e32 v218, s37, v66
	v_fmac_f32_e32 v219, s37, v67
	v_fmac_f32_e32 v220, s76, v128
	v_fmac_f32_e32 v221, s76, v129
	v_fmac_f32_e32 v222, s76, v130
	v_fmac_f32_e32 v223, s76, v131
	v_fmac_f32_e32 v216, s42, v68
	v_fmac_f32_e32 v217, s42, v69
	v_fmac_f32_e32 v218, s42, v70
	v_fmac_f32_e32 v219, s42, v71
	v_fmac_f32_e32 v220, s77, v132
	v_fmac_f32_e32 v221, s77, v133
	v_fmac_f32_e32 v222, s77, v134
	v_fmac_f32_e32 v223, s77, v135
	v_mul_f32_e64 v224, |v216|, s101
	v_mul_f32_e64 v225, |v217|, s101
	v_mul_f32_e64 v226, |v218|, s101
	v_mul_f32_e64 v227, |v219|, s101
	v_exp_f32_e32 v224, v224
	v_exp_f32_e32 v225, v225
	v_exp_f32_e32 v226, v226
	v_exp_f32_e32 v227, v227
	v_max_f32_e64 v216, -v216, 0
	v_max_f32_e64 v217, -v217, 0
	v_max_f32_e64 v218, -v218, 0
	v_max_f32_e64 v219, -v219, 0
	v_add_f32_e32 v224, 1.0, v224
	v_add_f32_e32 v225, 1.0, v225
	v_add_f32_e32 v226, 1.0, v226
	v_add_f32_e32 v227, 1.0, v227
	v_log_f32_e32 v224, v224
	v_log_f32_e32 v225, v225
	v_log_f32_e32 v226, v226
	v_log_f32_e32 v227, v227
	s_nop 0
	v_fmac_f32_e32 v216, 0x3f317218, v224
	v_fmac_f32_e32 v217, 0x3f317218, v225
	v_fmac_f32_e32 v218, 0x3f317218, v226
	v_fmac_f32_e32 v219, 0x3f317218, v227
	v_mul_f32_e32 v216, 0x3d800000, v216
	v_mul_f32_e32 v217, 0x3d800000, v217
	v_mul_f32_e32 v218, 0x3d800000, v218
	v_mul_f32_e32 v219, 0x3d800000, v219
	v_mul_f32_e64 v224, |v220|, s101
	v_mul_f32_e64 v225, |v221|, s101
	v_mul_f32_e64 v226, |v222|, s101
	v_mul_f32_e64 v227, |v223|, s101
	v_exp_f32_e32 v224, v224
	v_exp_f32_e32 v225, v225
	v_exp_f32_e32 v226, v226
	v_exp_f32_e32 v227, v227
	v_max_f32_e64 v220, -v220, 0
	v_max_f32_e64 v221, -v221, 0
	v_max_f32_e64 v222, -v222, 0
	v_max_f32_e64 v223, -v223, 0
	v_add_f32_e32 v224, 1.0, v224
	v_add_f32_e32 v225, 1.0, v225
	v_add_f32_e32 v226, 1.0, v226
	v_add_f32_e32 v227, 1.0, v227
	v_log_f32_e32 v224, v224
	v_log_f32_e32 v225, v225
	v_log_f32_e32 v226, v226
	v_log_f32_e32 v227, v227
	s_nop 0
	v_fmac_f32_e32 v220, 0x3f317218, v224
	v_fmac_f32_e32 v221, 0x3f317218, v225
	v_fmac_f32_e32 v222, 0x3f317218, v226
	v_fmac_f32_e32 v223, 0x3f317218, v227
	v_mul_f32_e32 v220, 0x3d800000, v220
	v_mul_f32_e32 v221, 0x3d800000, v221
	v_mul_f32_e32 v222, 0x3d800000, v222
	v_mul_f32_e32 v223, 0x3d800000, v223
	v_cvt_pk_bf16_f32 v224, v216, v217
	v_cvt_pk_bf16_f32 v225, v218, v219
	v_cvt_pk_bf16_f32 v226, v220, v221
	v_cvt_pk_bf16_f32 v227, v222, v223
	global_store_dwordx2 v4, v[224:225], s[58:59] nt
	global_store_dwordx2 v4, v[226:227], s[58:59] offset:512 nt
	v_add_u32_e32 v5, 0x400, v5
	v_add_u32_e32 v4, 0x400, v4
	s_waitcnt vmcnt(42)
; __device__ __forceinline__ unsigned pk2(float lo, float hi) { unsigned r; asm("v_cvt_pk_bf16_f32 %0, %1, %2" : "=v"(r) : "v"(lo), "v"(hi)); return r; }
; __device__ __forceinline__ void p2_gate(const Params& p, const LAS float* aup, int t0, int lane) {
;     ...
;         *(u32x4*)(GG + (size_t)t * 512 + lane * 8) = __builtin_nontemporal_load((const u32x4*)(zg + 1024 + lane * 8));
;         const unsigned short araw = zg[1536 + (lane & 31)]; const int alo = (int)((unsigned)araw << 16);
;         f32x4 acc0 = ab0, acc1 = ab1;
; #pragma unroll
;         for (int r = 0; r < 16; ++r) { const float a0 = __int_as_float(__builtin_amdgcn_readlane(alo, r)), a1 = __int_as_float(__builtin_amdgcn_readlane(alo, 16 + r));
;             acc0 += a0 * *(const LAS f32x4*)(aup + r * 256 + 4 * lane); acc1 += a1 * *(const LAS f32x4*)(aup + (16 + r) * 256 + 4 * lane); }
;         float n0[4], n1[4];
; #pragma unroll
;         for (int j = 0; j < 4; ++j) { const float y0 = -acc0[j], y1 = -acc1[j];
;             n0[j] = (fmaxf(y0, 0.f) + __logf(1.0f + __expf(-fabsf(y0)))) * 0.0625f; n1[j] = (fmaxf(y1, 0.f) + __logf(1.0f + __expf(-fabsf(y1)))) * 0.0625f; }
;         u32x2 w; w.x = pk2(n0[0], n0[1]); w.y = pk2(n0[2], n0[3]); *(u32x2*)(GNL + (size_t)t * 512 + 4 * lane) = w;
;         w.x = pk2(n1[0], n1[1]); w.y = pk2(n1[2], n1[3]); *(u32x2*)(GNL + (size_t)t * 512 + 256 + 4 * lane) = w;
	global_store_dwordx4 v5, v[184:187], s[58:59] nt
	v_lshlrev_b32_e32 v212, 16, v212
	v_mov_b32_e32 v216, v228
	v_mov_b32_e32 v217, v229
	v_mov_b32_e32 v218, v230
	v_mov_b32_e32 v219, v231
	v_mov_b32_e32 v220, v232
	v_mov_b32_e32 v221, v233
	v_mov_b32_e32 v222, v234
	v_mov_b32_e32 v223, v235
	s_nop 0
	v_readlane_b32 s14, v212, 0
	v_readlane_b32 s15, v212, 1
	v_readlane_b32 s25, v212, 2
	v_readlane_b32 s26, v212, 3
	v_readlane_b32 s27, v212, 4
	v_readlane_b32 s36, v212, 5
	v_readlane_b32 s37, v212, 6
	v_readlane_b32 s42, v212, 7
	v_readlane_b32 s43, v212, 16
	v_readlane_b32 s63, v212, 17
	v_readlane_b32 s64, v212, 18
	v_readlane_b32 s65, v212, 19
	v_readlane_b32 s74, v212, 20
	v_readlane_b32 s75, v212, 21
	v_readlane_b32 s76, v212, 22
	v_readlane_b32 s77, v212, 23
	s_nop 1
	v_fmac_f32_e32 v216, s14, v8
	v_fmac_f32_e32 v217, s14, v9
	v_fmac_f32_e32 v218, s14, v10
	v_fmac_f32_e32 v219, s14, v11
	v_fmac_f32_e32 v220, s43, v72
	v_fmac_f32_e32 v221, s43, v73
	v_fmac_f32_e32 v222, s43, v74
	v_fmac_f32_e32 v223, s43, v75
	v_fmac_f32_e32 v216, s15, v12
	v_fmac_f32_e32 v217, s15, v13
	v_fmac_f32_e32 v218, s15, v14
	v_fmac_f32_e32 v219, s15, v15
	v_fmac_f32_e32 v220, s63, v76
	v_fmac_f32_e32 v221, s63, v77
	v_fmac_f32_e32 v222, s63, v78
	v_fmac_f32_e32 v223, s63, v79
	v_fmac_f32_e32 v216, s25, v16
	v_fmac_f32_e32 v217, s25, v17
	v_fmac_f32_e32 v218, s25, v18
	v_fmac_f32_e32 v219, s25, v19
	v_fmac_f32_e32 v220, s64, v80
	v_fmac_f32_e32 v221, s64, v81
	v_fmac_f32_e32 v222, s64, v82
	v_fmac_f32_e32 v223, s64, v83
	v_fmac_f32_e32 v216, s26, v20
	v_fmac_f32_e32 v217, s26, v21
	v_fmac_f32_e32 v218, s26, v22
	v_fmac_f32_e32 v219, s26, v23
	v_fmac_f32_e32 v220, s65, v84
	v_fmac_f32_e32 v221, s65, v85
	v_fmac_f32_e32 v222, s65, v86
	v_fmac_f32_e32 v223, s65, v87
	v_fmac_f32_e32 v216, s27, v24
	v_fmac_f32_e32 v217, s27, v25
	v_fmac_f32_e32 v218, s27, v26
	v_fmac_f32_e32 v219, s27, v27
	v_fmac_f32_e32 v220, s74, v88
	v_fmac_f32_e32 v221, s74, v89
	v_fmac_f32_e32 v222, s74, v90
	v_fmac_f32_e32 v223, s74, v91
	v_fmac_f32_e32 v216, s36, v28
	v_fmac_f32_e32 v217, s36, v29
	v_fmac_f32_e32 v218, s36, v30
	v_fmac_f32_e32 v219, s36, v31
	v_fmac_f32_e32 v220, s75, v92
	v_fmac_f32_e32 v221, s75, v93
	v_fmac_f32_e32 v222, s75, v94
	v_fmac_f32_e32 v223, s75, v95
	v_fmac_f32_e32 v216, s37, v32
	v_fmac_f32_e32 v217, s37, v33
	v_fmac_f32_e32 v218, s37, v34
	v_fmac_f32_e32 v219, s37, v35
	v_fmac_f32_e32 v220, s76, v96
	v_fmac_f32_e32 v221, s76, v97
	v_fmac_f32_e32 v222, s76, v98
	v_fmac_f32_e32 v223, s76, v99
	v_fmac_f32_e32 v216, s42, v36
	v_fmac_f32_e32 v217, s42, v37
	v_fmac_f32_e32 v218, s42, v38
	v_fmac_f32_e32 v219, s42, v39
	v_fmac_f32_e32 v220, s77, v100
	v_fmac_f32_e32 v221, s77, v101
	v_fmac_f32_e32 v222, s77, v102
	v_fmac_f32_e32 v223, s77, v103
	s_nop 0
	v_readlane_b32 s14, v212, 8
	v_readlane_b32 s15, v212, 9
	v_readlane_b32 s25, v212, 10
	v_readlane_b32 s26, v212, 11
	v_readlane_b32 s27, v212, 12
	v_readlane_b32 s36, v212, 13
	v_readlane_b32 s37, v212, 14
	v_readlane_b32 s42, v212, 15
	v_readlane_b32 s43, v212, 24
	v_readlane_b32 s63, v212, 25
	v_readlane_b32 s64, v212, 26
	v_readlane_b32 s65, v212, 27
	v_readlane_b32 s74, v212, 28
	v_readlane_b32 s75, v212, 29
	v_readlane_b32 s76, v212, 30
	v_readlane_b32 s77, v212, 31
	s_nop 1
	v_fmac_f32_e32 v216, s14, v40
	v_fmac_f32_e32 v217, s14, v41
	v_fmac_f32_e32 v218, s14, v42
	v_fmac_f32_e32 v219, s14, v43
	v_fmac_f32_e32 v220, s43, v104
	v_fmac_f32_e32 v221, s43, v105
	v_fmac_f32_e32 v222, s43, v106
	v_fmac_f32_e32 v223, s43, v107
	v_fmac_f32_e32 v216, s15, v44
	v_fmac_f32_e32 v217, s15, v45
	v_fmac_f32_e32 v218, s15, v46
	v_fmac_f32_e32 v219, s15, v47
	v_fmac_f32_e32 v220, s63, v108
	v_fmac_f32_e32 v221, s63, v109
	v_fmac_f32_e32 v222, s63, v110
	v_fmac_f32_e32 v223, s63, v111
	v_fmac_f32_e32 v216, s25, v48
	v_fmac_f32_e32 v217, s25, v49
	v_fmac_f32_e32 v218, s25, v50
	v_fmac_f32_e32 v219, s25, v51
	v_fmac_f32_e32 v220, s64, v112
	v_fmac_f32_e32 v221, s64, v113
	v_fmac_f32_e32 v222, s64, v114
	v_fmac_f32_e32 v223, s64, v115
	v_fmac_f32_e32 v216, s26, v52
	v_fmac_f32_e32 v217, s26, v53
	v_fmac_f32_e32 v218, s26, v54
	v_fmac_f32_e32 v219, s26, v55
	v_fmac_f32_e32 v220, s65, v116
	v_fmac_f32_e32 v221, s65, v117
	v_fmac_f32_e32 v222, s65, v118
	v_fmac_f32_e32 v223, s65, v119
	v_fmac_f32_e32 v216, s27, v56
	v_fmac_f32_e32 v217, s27, v57
	v_fmac_f32_e32 v218, s27, v58
	v_fmac_f32_e32 v219, s27, v59
	v_fmac_f32_e32 v220, s74, v120
	v_fmac_f32_e32 v221, s74, v121
	v_fmac_f32_e32 v222, s74, v122
	v_fmac_f32_e32 v223, s74, v123
	v_fmac_f32_e32 v216, s36, v60
	v_fmac_f32_e32 v217, s36, v61
	v_fmac_f32_e32 v218, s36, v62
	v_fmac_f32_e32 v219, s36, v63
	v_fmac_f32_e32 v220, s75, v124
	v_fmac_f32_e32 v221, s75, v125
	v_fmac_f32_e32 v222, s75, v126
	v_fmac_f32_e32 v223, s75, v127
	v_fmac_f32_e32 v216, s37, v64
	v_fmac_f32_e32 v217, s37, v65
	v_fmac_f32_e32 v218, s37, v66
	v_fmac_f32_e32 v219, s37, v67
	v_fmac_f32_e32 v220, s76, v128
	v_fmac_f32_e32 v221, s76, v129
	v_fmac_f32_e32 v222, s76, v130
	v_fmac_f32_e32 v223, s76, v131
	v_fmac_f32_e32 v216, s42, v68
	v_fmac_f32_e32 v217, s42, v69
	v_fmac_f32_e32 v218, s42, v70
	v_fmac_f32_e32 v219, s42, v71
	v_fmac_f32_e32 v220, s77, v132
	v_fmac_f32_e32 v221, s77, v133
	v_fmac_f32_e32 v222, s77, v134
	v_fmac_f32_e32 v223, s77, v135
	v_mul_f32_e64 v224, |v216|, s101
	v_mul_f32_e64 v225, |v217|, s101
	v_mul_f32_e64 v226, |v218|, s101
	v_mul_f32_e64 v227, |v219|, s101
	v_exp_f32_e32 v224, v224
	v_exp_f32_e32 v225, v225
	v_exp_f32_e32 v226, v226
	v_exp_f32_e32 v227, v227
	v_max_f32_e64 v216, -v216, 0
	v_max_f32_e64 v217, -v217, 0
	v_max_f32_e64 v218, -v218, 0
	v_max_f32_e64 v219, -v219, 0
; __device__ __forceinline__ unsigned pk2(float lo, float hi) { unsigned r; asm("v_cvt_pk_bf16_f32 %0, %1, %2" : "=v"(r) : "v"(lo), "v"(hi)); return r; }
; __device__ __forceinline__ void p2_gate(const Params& p, const LAS float* aup, int t0, int lane) {
;     ...
;         for (int r = 0; r < 16; ++r) { const float a0 = __int_as_float(__builtin_amdgcn_readlane(alo, r)), a1 = __int_as_float(__builtin_amdgcn_readlane(alo, 16 + r));
;             acc0 += a0 * *(const LAS f32x4*)(aup + r * 256 + 4 * lane); acc1 += a1 * *(const LAS f32x4*)(aup + (16 + r) * 256 + 4 * lane); }
;         float n0[4], n1[4];
; #pragma unroll
;         for (int j = 0; j < 4; ++j) { const float y0 = -acc0[j], y1 = -acc1[j];
;             n0[j] = (fmaxf(y0, 0.f) + __logf(1.0f + __expf(-fabsf(y0)))) * 0.0625f; n1[j] = (fmaxf(y1, 0.f) + __logf(1.0f + __expf(-fabsf(y1)))) * 0.0625f; }
;         u32x2 w; w.x = pk2(n0[0], n0[1]); w.y = pk2(n0[2], n0[3]); *(u32x2*)(GNL + (size_t)t * 512 + 4 * lane) = w;
;         w.x = pk2(n1[0], n1[1]); w.y = pk2(n1[2], n1[3]); *(u32x2*)(GNL + (size_t)t * 512 + 256 + 4 * lane) = w;
	v_add_f32_e32 v224, 1.0, v224
	v_add_f32_e32 v225, 1.0, v225
	v_add_f32_e32 v226, 1.0, v226
	v_add_f32_e32 v227, 1.0, v227
	v_log_f32_e32 v224, v224
	v_log_f32_e32 v225, v225
	v_log_f32_e32 v226, v226
	v_log_f32_e32 v227, v227
	s_nop 0
	v_fmac_f32_e32 v216, 0x3f317218, v224
	v_fmac_f32_e32 v217, 0x3f317218, v225
	v_fmac_f32_e32 v218, 0x3f317218, v226
	v_fmac_f32_e32 v219, 0x3f317218, v227
	v_mul_f32_e32 v216, 0x3d800000, v216
	v_mul_f32_e32 v217, 0x3d800000, v217
	v_mul_f32_e32 v218, 0x3d800000, v218
	v_mul_f32_e32 v219, 0x3d800000, v219
	v_mul_f32_e64 v224, |v220|, s101
	v_mul_f32_e64 v225, |v221|, s101
	v_mul_f32_e64 v226, |v222|, s101
	v_mul_f32_e64 v227, |v223|, s101
	v_exp_f32_e32 v224, v224
	v_exp_f32_e32 v225, v225
	v_exp_f32_e32 v226, v226
	v_exp_f32_e32 v227, v227
	v_max_f32_e64 v220, -v220, 0
	v_max_f32_e64 v221, -v221, 0
	v_max_f32_e64 v222, -v222, 0
	v_max_f32_e64 v223, -v223, 0
	v_add_f32_e32 v224, 1.0, v224
	v_add_f32_e32 v225, 1.0, v225
	v_add_f32_e32 v226, 1.0, v226
	v_add_f32_e32 v227, 1.0, v227
	v_log_f32_e32 v224, v224
	v_log_f32_e32 v225, v225
	v_log_f32_e32 v226, v226
	v_log_f32_e32 v227, v227
	s_nop 0
	v_fmac_f32_e32 v220, 0x3f317218, v224
	v_fmac_f32_e32 v221, 0x3f317218, v225
	v_fmac_f32_e32 v222, 0x3f317218, v226
	v_fmac_f32_e32 v223, 0x3f317218, v227
	v_mul_f32_e32 v220, 0x3d800000, v220
	v_mul_f32_e32 v221, 0x3d800000, v221
	v_mul_f32_e32 v222, 0x3d800000, v222
	v_mul_f32_e32 v223, 0x3d800000, v223
	v_cvt_pk_bf16_f32 v224, v216, v217
	v_cvt_pk_bf16_f32 v225, v218, v219
	v_cvt_pk_bf16_f32 v226, v220, v221
	v_cvt_pk_bf16_f32 v227, v222, v223
	global_store_dwordx2 v4, v[224:225], s[58:59] nt
	global_store_dwordx2 v4, v[226:227], s[58:59] offset:512 nt
	v_add_u32_e32 v5, 0x400, v5
	v_add_u32_e32 v4, 0x400, v4
	s_waitcnt vmcnt(43)
	global_store_dwordx4 v5, v[188:191], s[58:59] nt
	v_lshlrev_b32_e32 v213, 16, v213
	v_mov_b32_e32 v216, v228
	v_mov_b32_e32 v217, v229
	v_mov_b32_e32 v218, v230
	v_mov_b32_e32 v219, v231
	v_mov_b32_e32 v220, v232
	v_mov_b32_e32 v221, v233
	v_mov_b32_e32 v222, v234
	v_mov_b32_e32 v223, v235
	s_nop 0
	v_readlane_b32 s14, v213, 0
	v_readlane_b32 s15, v213, 1
	v_readlane_b32 s25, v213, 2
	v_readlane_b32 s26, v213, 3
	v_readlane_b32 s27, v213, 4
	v_readlane_b32 s36, v213, 5
	v_readlane_b32 s37, v213, 6
	v_readlane_b32 s42, v213, 7
	v_readlane_b32 s43, v213, 16
	v_readlane_b32 s63, v213, 17
	v_readlane_b32 s64, v213, 18
	v_readlane_b32 s65, v213, 19
	v_readlane_b32 s74, v213, 20
	v_readlane_b32 s75, v213, 21
	v_readlane_b32 s76, v213, 22
	v_readlane_b32 s77, v213, 23
	s_nop 1
	v_fmac_f32_e32 v216, s14, v8
	v_fmac_f32_e32 v217, s14, v9
	v_fmac_f32_e32 v218, s14, v10
	v_fmac_f32_e32 v219, s14, v11
	v_fmac_f32_e32 v220, s43, v72
	v_fmac_f32_e32 v221, s43, v73
	v_fmac_f32_e32 v222, s43, v74
	v_fmac_f32_e32 v223, s43, v75
	v_fmac_f32_e32 v216, s15, v12
	v_fmac_f32_e32 v217, s15, v13
	v_fmac_f32_e32 v218, s15, v14
	v_fmac_f32_e32 v219, s15, v15
	v_fmac_f32_e32 v220, s63, v76
	v_fmac_f32_e32 v221, s63, v77
	v_fmac_f32_e32 v222, s63, v78
	v_fmac_f32_e32 v223, s63, v79
	v_fmac_f32_e32 v216, s25, v16
	v_fmac_f32_e32 v217, s25, v17
	v_fmac_f32_e32 v218, s25, v18
	v_fmac_f32_e32 v219, s25, v19
	v_fmac_f32_e32 v220, s64, v80
	v_fmac_f32_e32 v221, s64, v81
	v_fmac_f32_e32 v222, s64, v82
	v_fmac_f32_e32 v223, s64, v83
	v_fmac_f32_e32 v216, s26, v20
	v_fmac_f32_e32 v217, s26, v21
	v_fmac_f32_e32 v218, s26, v22
	v_fmac_f32_e32 v219, s26, v23
	v_fmac_f32_e32 v220, s65, v84
	v_fmac_f32_e32 v221, s65, v85
	v_fmac_f32_e32 v222, s65, v86
	v_fmac_f32_e32 v223, s65, v87
	v_fmac_f32_e32 v216, s27, v24
	v_fmac_f32_e32 v217, s27, v25
	v_fmac_f32_e32 v218, s27, v26
	v_fmac_f32_e32 v219, s27, v27
	v_fmac_f32_e32 v220, s74, v88
	v_fmac_f32_e32 v221, s74, v89
	v_fmac_f32_e32 v222, s74, v90
	v_fmac_f32_e32 v223, s74, v91
	v_fmac_f32_e32 v216, s36, v28
	v_fmac_f32_e32 v217, s36, v29
	v_fmac_f32_e32 v218, s36, v30
	v_fmac_f32_e32 v219, s36, v31
	v_fmac_f32_e32 v220, s75, v92
	v_fmac_f32_e32 v221, s75, v93
	v_fmac_f32_e32 v222, s75, v94
	v_fmac_f32_e32 v223, s75, v95
	v_fmac_f32_e32 v216, s37, v32
	v_fmac_f32_e32 v217, s37, v33
	v_fmac_f32_e32 v218, s37, v34
	v_fmac_f32_e32 v219, s37, v35
	v_fmac_f32_e32 v220, s76, v96
	v_fmac_f32_e32 v221, s76, v97
	v_fmac_f32_e32 v222, s76, v98
	v_fmac_f32_e32 v223, s76, v99
	v_fmac_f32_e32 v216, s42, v36
	v_fmac_f32_e32 v217, s42, v37
	v_fmac_f32_e32 v218, s42, v38
	v_fmac_f32_e32 v219, s42, v39
	v_fmac_f32_e32 v220, s77, v100
	v_fmac_f32_e32 v221, s77, v101
	v_fmac_f32_e32 v222, s77, v102
	v_fmac_f32_e32 v223, s77, v103
	s_nop 0
	v_readlane_b32 s14, v213, 8
	v_readlane_b32 s15, v213, 9
	v_readlane_b32 s25, v213, 10
	v_readlane_b32 s26, v213, 11
	v_readlane_b32 s27, v213, 12
	v_readlane_b32 s36, v213, 13
	v_readlane_b32 s37, v213, 14
	v_readlane_b32 s42, v213, 15
	v_readlane_b32 s43, v213, 24
	v_readlane_b32 s63, v213, 25
	v_readlane_b32 s64, v213, 26
	v_readlane_b32 s65, v213, 27
	v_readlane_b32 s74, v213, 28
	v_readlane_b32 s75, v213, 29
	v_readlane_b32 s76, v213, 30
	v_readlane_b32 s77, v213, 31
	s_nop 1
	v_fmac_f32_e32 v216, s14, v40
	v_fmac_f32_e32 v217, s14, v41
	v_fmac_f32_e32 v218, s14, v42
	v_fmac_f32_e32 v219, s14, v43
	v_fmac_f32_e32 v220, s43, v104
	v_fmac_f32_e32 v221, s43, v105
	v_fmac_f32_e32 v222, s43, v106
	v_fmac_f32_e32 v223, s43, v107
	v_fmac_f32_e32 v216, s15, v44
	v_fmac_f32_e32 v217, s15, v45
	v_fmac_f32_e32 v218, s15, v46
	v_fmac_f32_e32 v219, s15, v47
	v_fmac_f32_e32 v220, s63, v108
	v_fmac_f32_e32 v221, s63, v109
	v_fmac_f32_e32 v222, s63, v110
	v_fmac_f32_e32 v223, s63, v111
	v_fmac_f32_e32 v216, s25, v48
	v_fmac_f32_e32 v217, s25, v49
	v_fmac_f32_e32 v218, s25, v50
; __device__ __forceinline__ unsigned pk2(float lo, float hi) { unsigned r; asm("v_cvt_pk_bf16_f32 %0, %1, %2" : "=v"(r) : "v"(lo), "v"(hi)); return r; }
; __device__ __forceinline__ void p2_gate(const Params& p, const LAS float* aup, int t0, int lane) {
;     ...
;         for (int r = 0; r < 16; ++r) { const float a0 = __int_as_float(__builtin_amdgcn_readlane(alo, r)), a1 = __int_as_float(__builtin_amdgcn_readlane(alo, 16 + r));
;             acc0 += a0 * *(const LAS f32x4*)(aup + r * 256 + 4 * lane); acc1 += a1 * *(const LAS f32x4*)(aup + (16 + r) * 256 + 4 * lane); }
;         float n0[4], n1[4];
; #pragma unroll
;         for (int j = 0; j < 4; ++j) { const float y0 = -acc0[j], y1 = -acc1[j];
;             n0[j] = (fmaxf(y0, 0.f) + __logf(1.0f + __expf(-fabsf(y0)))) * 0.0625f; n1[j] = (fmaxf(y1, 0.f) + __logf(1.0f + __expf(-fabsf(y1)))) * 0.0625f; }
;         u32x2 w; w.x = pk2(n0[0], n0[1]); w.y = pk2(n0[2], n0[3]); *(u32x2*)(GNL + (size_t)t * 512 + 4 * lane) = w;
;         w.x = pk2(n1[0], n1[1]); w.y = pk2(n1[2], n1[3]); *(u32x2*)(GNL + (size_t)t * 512 + 256 + 4 * lane) = w;
	v_fmac_f32_e32 v219, s25, v51
	v_fmac_f32_e32 v220, s64, v112
	v_fmac_f32_e32 v221, s64, v113
	v_fmac_f32_e32 v222, s64, v114
	v_fmac_f32_e32 v223, s64, v115
	v_fmac_f32_e32 v216, s26, v52
	v_fmac_f32_e32 v217, s26, v53
	v_fmac_f32_e32 v218, s26, v54
	v_fmac_f32_e32 v219, s26, v55
	v_fmac_f32_e32 v220, s65, v116
	v_fmac_f32_e32 v221, s65, v117
	v_fmac_f32_e32 v222, s65, v118
	v_fmac_f32_e32 v223, s65, v119
	v_fmac_f32_e32 v216, s27, v56
	v_fmac_f32_e32 v217, s27, v57
	v_fmac_f32_e32 v218, s27, v58
	v_fmac_f32_e32 v219, s27, v59
	v_fmac_f32_e32 v220, s74, v120
	v_fmac_f32_e32 v221, s74, v121
	v_fmac_f32_e32 v222, s74, v122
	v_fmac_f32_e32 v223, s74, v123
	v_fmac_f32_e32 v216, s36, v60
	v_fmac_f32_e32 v217, s36, v61
	v_fmac_f32_e32 v218, s36, v62
	v_fmac_f32_e32 v219, s36, v63
	v_fmac_f32_e32 v220, s75, v124
	v_fmac_f32_e32 v221, s75, v125
	v_fmac_f32_e32 v222, s75, v126
	v_fmac_f32_e32 v223, s75, v127
	v_fmac_f32_e32 v216, s37, v64
	v_fmac_f32_e32 v217, s37, v65
	v_fmac_f32_e32 v218, s37, v66
	v_fmac_f32_e32 v219, s37, v67
	v_fmac_f32_e32 v220, s76, v128
	v_fmac_f32_e32 v221, s76, v129
	v_fmac_f32_e32 v222, s76, v130
	v_fmac_f32_e32 v223, s76, v131
	v_fmac_f32_e32 v216, s42, v68
	v_fmac_f32_e32 v217, s42, v69
	v_fmac_f32_e32 v218, s42, v70
	v_fmac_f32_e32 v219, s42, v71
	v_fmac_f32_e32 v220, s77, v132
	v_fmac_f32_e32 v221, s77, v133
	v_fmac_f32_e32 v222, s77, v134
	v_fmac_f32_e32 v223, s77, v135
	v_mul_f32_e64 v224, |v216|, s101
	v_mul_f32_e64 v225, |v217|, s101
	v_mul_f32_e64 v226, |v218|, s101
	v_mul_f32_e64 v227, |v219|, s101
	v_exp_f32_e32 v224, v224
	v_exp_f32_e32 v225, v225
	v_exp_f32_e32 v226, v226
	v_exp_f32_e32 v227, v227
	v_max_f32_e64 v216, -v216, 0
	v_max_f32_e64 v217, -v217, 0
	v_max_f32_e64 v218, -v218, 0
	v_max_f32_e64 v219, -v219, 0
	v_add_f32_e32 v224, 1.0, v224
	v_add_f32_e32 v225, 1.0, v225
	v_add_f32_e32 v226, 1.0, v226
	v_add_f32_e32 v227, 1.0, v227
	v_log_f32_e32 v224, v224
	v_log_f32_e32 v225, v225
	v_log_f32_e32 v226, v226
	v_log_f32_e32 v227, v227
	s_nop 0
	v_fmac_f32_e32 v216, 0x3f317218, v224
	v_fmac_f32_e32 v217, 0x3f317218, v225
	v_fmac_f32_e32 v218, 0x3f317218, v226
	v_fmac_f32_e32 v219, 0x3f317218, v227
	v_mul_f32_e32 v216, 0x3d800000, v216
	v_mul_f32_e32 v217, 0x3d800000, v217
	v_mul_f32_e32 v218, 0x3d800000, v218
	v_mul_f32_e32 v219, 0x3d800000, v219
	v_mul_f32_e64 v224, |v220|, s101
	v_mul_f32_e64 v225, |v221|, s101
	v_mul_f32_e64 v226, |v222|, s101
	v_mul_f32_e64 v227, |v223|, s101
	v_exp_f32_e32 v224, v224
	v_exp_f32_e32 v225, v225
	v_exp_f32_e32 v226, v226
	v_exp_f32_e32 v227, v227
	v_max_f32_e64 v220, -v220, 0
	v_max_f32_e64 v221, -v221, 0
	v_max_f32_e64 v222, -v222, 0
	v_max_f32_e64 v223, -v223, 0
	v_add_f32_e32 v224, 1.0, v224
	v_add_f32_e32 v225, 1.0, v225
	v_add_f32_e32 v226, 1.0, v226
	v_add_f32_e32 v227, 1.0, v227
	v_log_f32_e32 v224, v224
	v_log_f32_e32 v225, v225
	v_log_f32_e32 v226, v226
	v_log_f32_e32 v227, v227
	s_nop 0
	v_fmac_f32_e32 v220, 0x3f317218, v224
	v_fmac_f32_e32 v221, 0x3f317218, v225
	v_fmac_f32_e32 v222, 0x3f317218, v226
	v_fmac_f32_e32 v223, 0x3f317218, v227
	v_mul_f32_e32 v220, 0x3d800000, v220
	v_mul_f32_e32 v221, 0x3d800000, v221
	v_mul_f32_e32 v222, 0x3d800000, v222
	v_mul_f32_e32 v223, 0x3d800000, v223
	v_cvt_pk_bf16_f32 v224, v216, v217
	v_cvt_pk_bf16_f32 v225, v218, v219
	v_cvt_pk_bf16_f32 v226, v220, v221
	v_cvt_pk_bf16_f32 v227, v222, v223
	global_store_dwordx2 v4, v[224:225], s[58:59] nt
	global_store_dwordx2 v4, v[226:227], s[58:59] offset:512 nt
	v_add_u32_e32 v5, 0x400, v5
	v_add_u32_e32 v4, 0x400, v4
	s_waitcnt vmcnt(44)
	global_store_dwordx4 v5, v[192:195], s[58:59] nt
	v_lshlrev_b32_e32 v214, 16, v214
	v_mov_b32_e32 v216, v228
	v_mov_b32_e32 v217, v229
	v_mov_b32_e32 v218, v230
	v_mov_b32_e32 v219, v231
	v_mov_b32_e32 v220, v232
	v_mov_b32_e32 v221, v233
	v_mov_b32_e32 v222, v234
	v_mov_b32_e32 v223, v235
	s_nop 0
	v_readlane_b32 s14, v214, 0
	v_readlane_b32 s15, v214, 1
	v_readlane_b32 s25, v214, 2
	v_readlane_b32 s26, v214, 3
	v_readlane_b32 s27, v214, 4
	v_readlane_b32 s36, v214, 5
	v_readlane_b32 s37, v214, 6
	v_readlane_b32 s42, v214, 7
	v_readlane_b32 s43, v214, 16
	v_readlane_b32 s63, v214, 17
	v_readlane_b32 s64, v214, 18
	v_readlane_b32 s65, v214, 19
	v_readlane_b32 s74, v214, 20
	v_readlane_b32 s75, v214, 21
	v_readlane_b32 s76, v214, 22
	v_readlane_b32 s77, v214, 23
	s_nop 1
	v_fmac_f32_e32 v216, s14, v8
	v_fmac_f32_e32 v217, s14, v9
	v_fmac_f32_e32 v218, s14, v10
	v_fmac_f32_e32 v219, s14, v11
	v_fmac_f32_e32 v220, s43, v72
	v_fmac_f32_e32 v221, s43, v73
	v_fmac_f32_e32 v222, s43, v74
	v_fmac_f32_e32 v223, s43, v75
	v_fmac_f32_e32 v216, s15, v12
	v_fmac_f32_e32 v217, s15, v13
	v_fmac_f32_e32 v218, s15, v14
	v_fmac_f32_e32 v219, s15, v15
	v_fmac_f32_e32 v220, s63, v76
	v_fmac_f32_e32 v221, s63, v77
	v_fmac_f32_e32 v222, s63, v78
	v_fmac_f32_e32 v223, s63, v79
	v_fmac_f32_e32 v216, s25, v16
	v_fmac_f32_e32 v217, s25, v17
	v_fmac_f32_e32 v218, s25, v18
	v_fmac_f32_e32 v219, s25, v19
	v_fmac_f32_e32 v220, s64, v80
	v_fmac_f32_e32 v221, s64, v81
	v_fmac_f32_e32 v222, s64, v82
	v_fmac_f32_e32 v223, s64, v83
	v_fmac_f32_e32 v216, s26, v20
	v_fmac_f32_e32 v217, s26, v21
	v_fmac_f32_e32 v218, s26, v22
	v_fmac_f32_e32 v219, s26, v23
	v_fmac_f32_e32 v220, s65, v84
	v_fmac_f32_e32 v221, s65, v85
	v_fmac_f32_e32 v222, s65, v86
	v_fmac_f32_e32 v223, s65, v87
	v_fmac_f32_e32 v216, s27, v24
	v_fmac_f32_e32 v217, s27, v25
	v_fmac_f32_e32 v218, s27, v26
	v_fmac_f32_e32 v219, s27, v27
	v_fmac_f32_e32 v220, s74, v88
	v_fmac_f32_e32 v221, s74, v89
	v_fmac_f32_e32 v222, s74, v90
	v_fmac_f32_e32 v223, s74, v91
	v_fmac_f32_e32 v216, s36, v28
	v_fmac_f32_e32 v217, s36, v29
; __device__ __forceinline__ unsigned pk2(float lo, float hi) { unsigned r; asm("v_cvt_pk_bf16_f32 %0, %1, %2" : "=v"(r) : "v"(lo), "v"(hi)); return r; }
; __device__ __forceinline__ void p2_gate(const Params& p, const LAS float* aup, int t0, int lane) {
;     ...
;         for (int r = 0; r < 16; ++r) { const float a0 = __int_as_float(__builtin_amdgcn_readlane(alo, r)), a1 = __int_as_float(__builtin_amdgcn_readlane(alo, 16 + r));
;             acc0 += a0 * *(const LAS f32x4*)(aup + r * 256 + 4 * lane); acc1 += a1 * *(const LAS f32x4*)(aup + (16 + r) * 256 + 4 * lane); }
;         float n0[4], n1[4];
; #pragma unroll
;         for (int j = 0; j < 4; ++j) { const float y0 = -acc0[j], y1 = -acc1[j];
;             n0[j] = (fmaxf(y0, 0.f) + __logf(1.0f + __expf(-fabsf(y0)))) * 0.0625f; n1[j] = (fmaxf(y1, 0.f) + __logf(1.0f + __expf(-fabsf(y1)))) * 0.0625f; }
;         u32x2 w; w.x = pk2(n0[0], n0[1]); w.y = pk2(n0[2], n0[3]); *(u32x2*)(GNL + (size_t)t * 512 + 4 * lane) = w;
;         w.x = pk2(n1[0], n1[1]); w.y = pk2(n1[2], n1[3]); *(u32x2*)(GNL + (size_t)t * 512 + 256 + 4 * lane) = w;
	v_fmac_f32_e32 v218, s36, v30
	v_fmac_f32_e32 v219, s36, v31
	v_fmac_f32_e32 v220, s75, v92
	v_fmac_f32_e32 v221, s75, v93
	v_fmac_f32_e32 v222, s75, v94
	v_fmac_f32_e32 v223, s75, v95
	v_fmac_f32_e32 v216, s37, v32
	v_fmac_f32_e32 v217, s37, v33
	v_fmac_f32_e32 v218, s37, v34
	v_fmac_f32_e32 v219, s37, v35
	v_fmac_f32_e32 v220, s76, v96
	v_fmac_f32_e32 v221, s76, v97
	v_fmac_f32_e32 v222, s76, v98
	v_fmac_f32_e32 v223, s76, v99
	v_fmac_f32_e32 v216, s42, v36
	v_fmac_f32_e32 v217, s42, v37
	v_fmac_f32_e32 v218, s42, v38
	v_fmac_f32_e32 v219, s42, v39
	v_fmac_f32_e32 v220, s77, v100
	v_fmac_f32_e32 v221, s77, v101
	v_fmac_f32_e32 v222, s77, v102
	v_fmac_f32_e32 v223, s77, v103
	s_nop 0
	v_readlane_b32 s14, v214, 8
	v_readlane_b32 s15, v214, 9
	v_readlane_b32 s25, v214, 10
	v_readlane_b32 s26, v214, 11
	v_readlane_b32 s27, v214, 12
	v_readlane_b32 s36, v214, 13
	v_readlane_b32 s37, v214, 14
	v_readlane_b32 s42, v214, 15
	v_readlane_b32 s43, v214, 24
	v_readlane_b32 s63, v214, 25
	v_readlane_b32 s64, v214, 26
	v_readlane_b32 s65, v214, 27
	v_readlane_b32 s74, v214, 28
	v_readlane_b32 s75, v214, 29
	v_readlane_b32 s76, v214, 30
	v_readlane_b32 s77, v214, 31
	s_nop 1
	v_fmac_f32_e32 v216, s14, v40
	v_fmac_f32_e32 v217, s14, v41
	v_fmac_f32_e32 v218, s14, v42
	v_fmac_f32_e32 v219, s14, v43
	v_fmac_f32_e32 v220, s43, v104
	v_fmac_f32_e32 v221, s43, v105
	v_fmac_f32_e32 v222, s43, v106
	v_fmac_f32_e32 v223, s43, v107
	v_fmac_f32_e32 v216, s15, v44
	v_fmac_f32_e32 v217, s15, v45
	v_fmac_f32_e32 v218, s15, v46
	v_fmac_f32_e32 v219, s15, v47
	v_fmac_f32_e32 v220, s63, v108
	v_fmac_f32_e32 v221, s63, v109
	v_fmac_f32_e32 v222, s63, v110
	v_fmac_f32_e32 v223, s63, v111
	v_fmac_f32_e32 v216, s25, v48
	v_fmac_f32_e32 v217, s25, v49
	v_fmac_f32_e32 v218, s25, v50
	v_fmac_f32_e32 v219, s25, v51
	v_fmac_f32_e32 v220, s64, v112
	v_fmac_f32_e32 v221, s64, v113
	v_fmac_f32_e32 v222, s64, v114
	v_fmac_f32_e32 v223, s64, v115
	v_fmac_f32_e32 v216, s26, v52
	v_fmac_f32_e32 v217, s26, v53
	v_fmac_f32_e32 v218, s26, v54
	v_fmac_f32_e32 v219, s26, v55
	v_fmac_f32_e32 v220, s65, v116
	v_fmac_f32_e32 v221, s65, v117
	v_fmac_f32_e32 v222, s65, v118
	v_fmac_f32_e32 v223, s65, v119
	v_fmac_f32_e32 v216, s27, v56
	v_fmac_f32_e32 v217, s27, v57
	v_fmac_f32_e32 v218, s27, v58
	v_fmac_f32_e32 v219, s27, v59
	v_fmac_f32_e32 v220, s74, v120
	v_fmac_f32_e32 v221, s74, v121
	v_fmac_f32_e32 v222, s74, v122
	v_fmac_f32_e32 v223, s74, v123
	v_fmac_f32_e32 v216, s36, v60
	v_fmac_f32_e32 v217, s36, v61
	v_fmac_f32_e32 v218, s36, v62
	v_fmac_f32_e32 v219, s36, v63
	v_fmac_f32_e32 v220, s75, v124
	v_fmac_f32_e32 v221, s75, v125
	v_fmac_f32_e32 v222, s75, v126
	v_fmac_f32_e32 v223, s75, v127
	v_fmac_f32_e32 v216, s37, v64
	v_fmac_f32_e32 v217, s37, v65
	v_fmac_f32_e32 v218, s37, v66
	v_fmac_f32_e32 v219, s37, v67
	v_fmac_f32_e32 v220, s76, v128
	v_fmac_f32_e32 v221, s76, v129
	v_fmac_f32_e32 v222, s76, v130
	v_fmac_f32_e32 v223, s76, v131
	v_fmac_f32_e32 v216, s42, v68
	v_fmac_f32_e32 v217, s42, v69
	v_fmac_f32_e32 v218, s42, v70
	v_fmac_f32_e32 v219, s42, v71
	v_fmac_f32_e32 v220, s77, v132
	v_fmac_f32_e32 v221, s77, v133
	v_fmac_f32_e32 v222, s77, v134
	v_fmac_f32_e32 v223, s77, v135
	v_mul_f32_e64 v224, |v216|, s101
	v_mul_f32_e64 v225, |v217|, s101
	v_mul_f32_e64 v226, |v218|, s101
	v_mul_f32_e64 v227, |v219|, s101
	v_exp_f32_e32 v224, v224
	v_exp_f32_e32 v225, v225
	v_exp_f32_e32 v226, v226
	v_exp_f32_e32 v227, v227
	v_max_f32_e64 v216, -v216, 0
	v_max_f32_e64 v217, -v217, 0
	v_max_f32_e64 v218, -v218, 0
	v_max_f32_e64 v219, -v219, 0
	v_add_f32_e32 v224, 1.0, v224
	v_add_f32_e32 v225, 1.0, v225
	v_add_f32_e32 v226, 1.0, v226
	v_add_f32_e32 v227, 1.0, v227
	v_log_f32_e32 v224, v224
	v_log_f32_e32 v225, v225
	v_log_f32_e32 v226, v226
	v_log_f32_e32 v227, v227
	s_nop 0
	v_fmac_f32_e32 v216, 0x3f317218, v224
	v_fmac_f32_e32 v217, 0x3f317218, v225
	v_fmac_f32_e32 v218, 0x3f317218, v226
	v_fmac_f32_e32 v219, 0x3f317218, v227
	v_mul_f32_e32 v216, 0x3d800000, v216
	v_mul_f32_e32 v217, 0x3d800000, v217
	v_mul_f32_e32 v218, 0x3d800000, v218
	v_mul_f32_e32 v219, 0x3d800000, v219
	v_mul_f32_e64 v224, |v220|, s101
	v_mul_f32_e64 v225, |v221|, s101
	v_mul_f32_e64 v226, |v222|, s101
	v_mul_f32_e64 v227, |v223|, s101
	v_exp_f32_e32 v224, v224
	v_exp_f32_e32 v225, v225
	v_exp_f32_e32 v226, v226
	v_exp_f32_e32 v227, v227
	v_max_f32_e64 v220, -v220, 0
	v_max_f32_e64 v221, -v221, 0
	v_max_f32_e64 v222, -v222, 0
	v_max_f32_e64 v223, -v223, 0
	v_add_f32_e32 v224, 1.0, v224
	v_add_f32_e32 v225, 1.0, v225
	v_add_f32_e32 v226, 1.0, v226
	v_add_f32_e32 v227, 1.0, v227
	v_log_f32_e32 v224, v224
	v_log_f32_e32 v225, v225
	v_log_f32_e32 v226, v226
	v_log_f32_e32 v227, v227
	s_nop 0
	v_fmac_f32_e32 v220, 0x3f317218, v224
	v_fmac_f32_e32 v221, 0x3f317218, v225
	v_fmac_f32_e32 v222, 0x3f317218, v226
	v_fmac_f32_e32 v223, 0x3f317218, v227
	v_mul_f32_e32 v220, 0x3d800000, v220
	v_mul_f32_e32 v221, 0x3d800000, v221
	v_mul_f32_e32 v222, 0x3d800000, v222
	v_mul_f32_e32 v223, 0x3d800000, v223
	v_cvt_pk_bf16_f32 v224, v216, v217
	v_cvt_pk_bf16_f32 v225, v218, v219
	v_cvt_pk_bf16_f32 v226, v220, v221
	v_cvt_pk_bf16_f32 v227, v222, v223
	global_store_dwordx2 v4, v[224:225], s[58:59] nt
	global_store_dwordx2 v4, v[226:227], s[58:59] offset:512 nt
	v_add_u32_e32 v5, 0x400, v5
	v_add_u32_e32 v4, 0x400, v4
	s_waitcnt vmcnt(45)
; __device__ __forceinline__ void p2_gate(const Params& p, const LAS float* aup, int t0, int lane) {
;     ...
;         *(u32x4*)(GG + (size_t)t * 512 + lane * 8) = __builtin_nontemporal_load((const u32x4*)(zg + 1024 + lane * 8));
;         const unsigned short araw = zg[1536 + (lane & 31)]; const int alo = (int)((unsigned)araw << 16);
;         f32x4 acc0 = ab0, acc1 = ab1;
; #pragma unroll
;         for (int r = 0; r < 16; ++r) { const float a0 = __int_as_float(__builtin_amdgcn_readlane(alo, r)), a1 = __int_as_float(__builtin_amdgcn_readlane(alo, 16 + r));
;             acc0 += a0 * *(const LAS f32x4*)(aup + r * 256 + 4 * lane); acc1 += a1 * *(const LAS f32x4*)(aup + (16 + r) * 256 + 4 * lane); }
	global_store_dwordx4 v5, v[196:199], s[58:59] nt
	v_lshlrev_b32_e32 v215, 16, v215
	v_mov_b32_e32 v216, v228
	v_mov_b32_e32 v217, v229
	v_mov_b32_e32 v218, v230
	v_mov_b32_e32 v219, v231
	v_mov_b32_e32 v220, v232
	v_mov_b32_e32 v221, v233
	v_mov_b32_e32 v222, v234
	v_mov_b32_e32 v223, v235
	s_nop 0
	v_readlane_b32 s14, v215, 0
	v_readlane_b32 s15, v215, 1
	v_readlane_b32 s25, v215, 2
	v_readlane_b32 s26, v215, 3
	v_readlane_b32 s27, v215, 4
	v_readlane_b32 s36, v215, 5
	v_readlane_b32 s37, v215, 6
	v_readlane_b32 s42, v215, 7
	v_readlane_b32 s43, v215, 16
	v_readlane_b32 s63, v215, 17
	v_readlane_b32 s64, v215, 18
	v_readlane_b32 s65, v215, 19
	v_readlane_b32 s74, v215, 20
	v_readlane_b32 s75, v215, 21
	v_readlane_b32 s76, v215, 22
	v_readlane_b32 s77, v215, 23
	s_nop 1
	v_fmac_f32_e32 v216, s14, v8
	v_fmac_f32_e32 v217, s14, v9
	v_fmac_f32_e32 v218, s14, v10
	v_fmac_f32_e32 v219, s14, v11
	v_fmac_f32_e32 v220, s43, v72
	v_fmac_f32_e32 v221, s43, v73
	v_fmac_f32_e32 v222, s43, v74
	v_fmac_f32_e32 v223, s43, v75
	v_fmac_f32_e32 v216, s15, v12
	v_fmac_f32_e32 v217, s15, v13
	v_fmac_f32_e32 v218, s15, v14
	v_fmac_f32_e32 v219, s15, v15
	v_fmac_f32_e32 v220, s63, v76
	v_fmac_f32_e32 v221, s63, v77
	v_fmac_f32_e32 v222, s63, v78
	v_fmac_f32_e32 v223, s63, v79
	v_fmac_f32_e32 v216, s25, v16
	v_fmac_f32_e32 v217, s25, v17
	v_fmac_f32_e32 v218, s25, v18
	v_fmac_f32_e32 v219, s25, v19
	v_fmac_f32_e32 v220, s64, v80
	v_fmac_f32_e32 v221, s64, v81
	v_fmac_f32_e32 v222, s64, v82
	v_fmac_f32_e32 v223, s64, v83
	v_fmac_f32_e32 v216, s26, v20
	v_fmac_f32_e32 v217, s26, v21
	v_fmac_f32_e32 v218, s26, v22
	v_fmac_f32_e32 v219, s26, v23
	v_fmac_f32_e32 v220, s65, v84
	v_fmac_f32_e32 v221, s65, v85
	v_fmac_f32_e32 v222, s65, v86
	v_fmac_f32_e32 v223, s65, v87
	v_fmac_f32_e32 v216, s27, v24
	v_fmac_f32_e32 v217, s27, v25
	v_fmac_f32_e32 v218, s27, v26
	v_fmac_f32_e32 v219, s27, v27
	v_fmac_f32_e32 v220, s74, v88
	v_fmac_f32_e32 v221, s74, v89
	v_fmac_f32_e32 v222, s74, v90
	v_fmac_f32_e32 v223, s74, v91
	v_fmac_f32_e32 v216, s36, v28
	v_fmac_f32_e32 v217, s36, v29
	v_fmac_f32_e32 v218, s36, v30
	v_fmac_f32_e32 v219, s36, v31
	v_fmac_f32_e32 v220, s75, v92
	v_fmac_f32_e32 v221, s75, v93
	v_fmac_f32_e32 v222, s75, v94
	v_fmac_f32_e32 v223, s75, v95
	v_fmac_f32_e32 v216, s37, v32
	v_fmac_f32_e32 v217, s37, v33
	v_fmac_f32_e32 v218, s37, v34
	v_fmac_f32_e32 v219, s37, v35
	v_fmac_f32_e32 v220, s76, v96
	v_fmac_f32_e32 v221, s76, v97
	v_fmac_f32_e32 v222, s76, v98
	v_fmac_f32_e32 v223, s76, v99
	v_fmac_f32_e32 v216, s42, v36
	v_fmac_f32_e32 v217, s42, v37
	v_fmac_f32_e32 v218, s42, v38
	v_fmac_f32_e32 v219, s42, v39
	v_fmac_f32_e32 v220, s77, v100
	v_fmac_f32_e32 v221, s77, v101
	v_fmac_f32_e32 v222, s77, v102
	v_fmac_f32_e32 v223, s77, v103
	s_nop 0
	v_readlane_b32 s14, v215, 8
	v_readlane_b32 s15, v215, 9
	v_readlane_b32 s25, v215, 10
	v_readlane_b32 s26, v215, 11
	v_readlane_b32 s27, v215, 12
	v_readlane_b32 s36, v215, 13
	v_readlane_b32 s37, v215, 14
	v_readlane_b32 s42, v215, 15
	v_readlane_b32 s43, v215, 24
	v_readlane_b32 s63, v215, 25
	v_readlane_b32 s64, v215, 26
	v_readlane_b32 s65, v215, 27
	v_readlane_b32 s74, v215, 28
	v_readlane_b32 s75, v215, 29
	v_readlane_b32 s76, v215, 30
	v_readlane_b32 s77, v215, 31
	s_nop 1
	v_fmac_f32_e32 v216, s14, v40
	v_fmac_f32_e32 v217, s14, v41
	v_fmac_f32_e32 v218, s14, v42
	v_fmac_f32_e32 v219, s14, v43
	v_fmac_f32_e32 v220, s43, v104
	v_fmac_f32_e32 v221, s43, v105
	v_fmac_f32_e32 v222, s43, v106
	v_fmac_f32_e32 v223, s43, v107
	v_fmac_f32_e32 v216, s15, v44
	v_fmac_f32_e32 v217, s15, v45
	v_fmac_f32_e32 v218, s15, v46
	v_fmac_f32_e32 v219, s15, v47
	v_fmac_f32_e32 v220, s63, v108
	v_fmac_f32_e32 v221, s63, v109
	v_fmac_f32_e32 v222, s63, v110
	v_fmac_f32_e32 v223, s63, v111
	v_fmac_f32_e32 v216, s25, v48
	v_fmac_f32_e32 v217, s25, v49
	v_fmac_f32_e32 v218, s25, v50
	v_fmac_f32_e32 v219, s25, v51
	v_fmac_f32_e32 v220, s64, v112
	v_fmac_f32_e32 v221, s64, v113
	v_fmac_f32_e32 v222, s64, v114
	v_fmac_f32_e32 v223, s64, v115
	v_fmac_f32_e32 v216, s26, v52
	v_fmac_f32_e32 v217, s26, v53
	v_fmac_f32_e32 v218, s26, v54
	v_fmac_f32_e32 v219, s26, v55
	v_fmac_f32_e32 v220, s65, v116
	v_fmac_f32_e32 v221, s65, v117
	v_fmac_f32_e32 v222, s65, v118
	v_fmac_f32_e32 v223, s65, v119
	v_fmac_f32_e32 v216, s27, v56
	v_fmac_f32_e32 v217, s27, v57
	v_fmac_f32_e32 v218, s27, v58
	v_fmac_f32_e32 v219, s27, v59
	v_fmac_f32_e32 v220, s74, v120
	v_fmac_f32_e32 v221, s74, v121
	v_fmac_f32_e32 v222, s74, v122
; __device__ __forceinline__ unsigned pk2(float lo, float hi) { unsigned r; asm("v_cvt_pk_bf16_f32 %0, %1, %2" : "=v"(r) : "v"(lo), "v"(hi)); return r; }
; __device__ __forceinline__ void xcd_barrier(const XcdBarrier& b) {
;     asm volatile("s_waitcnt vmcnt(0)" ::: "memory");
;     __syncthreads();
;     if (threadIdx.x == 0) {
;         unsigned* bar = b.bar;
;         __builtin_amdgcn_s_waitcnt(0);
;         unsigned nloc = b.st[0], nx = b.st[1];
;         if (nloc == 0u) { xcd_barrier_complete(bar, b.x, nloc, nx); b.st[0] = nloc; b.st[1] = nx; }
; __device__ __forceinline__ void p2_gate(const Params& p, const LAS float* aup, int t0, int lane) {
;     ...
;         for (int r = 0; r < 16; ++r) { const float a0 = __int_as_float(__builtin_amdgcn_readlane(alo, r)), a1 = __int_as_float(__builtin_amdgcn_readlane(alo, 16 + r));
;             acc0 += a0 * *(const LAS f32x4*)(aup + r * 256 + 4 * lane); acc1 += a1 * *(const LAS f32x4*)(aup + (16 + r) * 256 + 4 * lane); }
;         float n0[4], n1[4];
; #pragma unroll
;         for (int j = 0; j < 4; ++j) { const float y0 = -acc0[j], y1 = -acc1[j];
;             n0[j] = (fmaxf(y0, 0.f) + __logf(1.0f + __expf(-fabsf(y0)))) * 0.0625f; n1[j] = (fmaxf(y1, 0.f) + __logf(1.0f + __expf(-fabsf(y1)))) * 0.0625f; }
;         u32x2 w; w.x = pk2(n0[0], n0[1]); w.y = pk2(n0[2], n0[3]); *(u32x2*)(GNL + (size_t)t * 512 + 4 * lane) = w;
;         w.x = pk2(n1[0], n1[1]); w.y = pk2(n1[2], n1[3]); *(u32x2*)(GNL + (size_t)t * 512 + 256 + 4 * lane) = w;
	v_fmac_f32_e32 v223, s74, v123
	v_fmac_f32_e32 v216, s36, v60
	v_fmac_f32_e32 v217, s36, v61
	v_fmac_f32_e32 v218, s36, v62
	v_fmac_f32_e32 v219, s36, v63
	v_fmac_f32_e32 v220, s75, v124
	v_fmac_f32_e32 v221, s75, v125
	v_fmac_f32_e32 v222, s75, v126
	v_fmac_f32_e32 v223, s75, v127
	v_fmac_f32_e32 v216, s37, v64
	v_fmac_f32_e32 v217, s37, v65
	v_fmac_f32_e32 v218, s37, v66
	v_fmac_f32_e32 v219, s37, v67
	v_fmac_f32_e32 v220, s76, v128
	v_fmac_f32_e32 v221, s76, v129
	v_fmac_f32_e32 v222, s76, v130
	v_fmac_f32_e32 v223, s76, v131
	v_fmac_f32_e32 v216, s42, v68
	v_fmac_f32_e32 v217, s42, v69
	v_fmac_f32_e32 v218, s42, v70
	v_fmac_f32_e32 v219, s42, v71
	v_fmac_f32_e32 v220, s77, v132
	v_fmac_f32_e32 v221, s77, v133
	v_fmac_f32_e32 v222, s77, v134
	v_fmac_f32_e32 v223, s77, v135
	v_mul_f32_e64 v224, |v216|, s101
	v_mul_f32_e64 v225, |v217|, s101
	v_mul_f32_e64 v226, |v218|, s101
	v_mul_f32_e64 v227, |v219|, s101
	v_exp_f32_e32 v224, v224
	v_exp_f32_e32 v225, v225
	v_exp_f32_e32 v226, v226
	v_exp_f32_e32 v227, v227
	v_max_f32_e64 v216, -v216, 0
	v_max_f32_e64 v217, -v217, 0
	v_max_f32_e64 v218, -v218, 0
	v_max_f32_e64 v219, -v219, 0
	v_add_f32_e32 v224, 1.0, v224
	v_add_f32_e32 v225, 1.0, v225
	v_add_f32_e32 v226, 1.0, v226
	v_add_f32_e32 v227, 1.0, v227
	v_log_f32_e32 v224, v224
	v_log_f32_e32 v225, v225
	v_log_f32_e32 v226, v226
	v_log_f32_e32 v227, v227
	s_nop 0
	v_fmac_f32_e32 v216, 0x3f317218, v224
	v_fmac_f32_e32 v217, 0x3f317218, v225
	v_fmac_f32_e32 v218, 0x3f317218, v226
	v_fmac_f32_e32 v219, 0x3f317218, v227
	v_mul_f32_e32 v216, 0x3d800000, v216
	v_mul_f32_e32 v217, 0x3d800000, v217
	v_mul_f32_e32 v218, 0x3d800000, v218
	v_mul_f32_e32 v219, 0x3d800000, v219
	v_mul_f32_e64 v224, |v220|, s101
	v_mul_f32_e64 v225, |v221|, s101
	v_mul_f32_e64 v226, |v222|, s101
	v_mul_f32_e64 v227, |v223|, s101
	v_exp_f32_e32 v224, v224
	v_exp_f32_e32 v225, v225
	v_exp_f32_e32 v226, v226
	v_exp_f32_e32 v227, v227
	v_max_f32_e64 v220, -v220, 0
	v_max_f32_e64 v221, -v221, 0
	v_max_f32_e64 v222, -v222, 0
	v_max_f32_e64 v223, -v223, 0
	v_add_f32_e32 v224, 1.0, v224
	v_add_f32_e32 v225, 1.0, v225
	v_add_f32_e32 v226, 1.0, v226
	v_add_f32_e32 v227, 1.0, v227
	v_log_f32_e32 v224, v224
	v_log_f32_e32 v225, v225
	v_log_f32_e32 v226, v226
	v_log_f32_e32 v227, v227
	s_nop 0
	v_fmac_f32_e32 v220, 0x3f317218, v224
	v_fmac_f32_e32 v221, 0x3f317218, v225
	v_fmac_f32_e32 v222, 0x3f317218, v226
	v_fmac_f32_e32 v223, 0x3f317218, v227
	v_mul_f32_e32 v220, 0x3d800000, v220
	v_mul_f32_e32 v221, 0x3d800000, v221
	v_mul_f32_e32 v222, 0x3d800000, v222
	v_mul_f32_e32 v223, 0x3d800000, v223
	v_cvt_pk_bf16_f32 v224, v216, v217
	v_cvt_pk_bf16_f32 v225, v218, v219
	v_cvt_pk_bf16_f32 v226, v220, v221
	v_cvt_pk_bf16_f32 v227, v222, v223
	global_store_dwordx2 v4, v[224:225], s[58:59] nt
	global_store_dwordx2 v4, v[226:227], s[58:59] offset:512 nt
	v_add_u32_e32 v5, 0x400, v5
	v_add_u32_e32 v4, 0x400, v4
	s_add_i32 s60, s60, s61
	s_branch .Lp2_grp_1
.Lp2_done_2:
.LBB0_379:
	s_waitcnt vmcnt(0)
	s_barrier
	s_mov_b64 s[0:1], exec
	v_readlane_b32 s4, v254, 1
	v_readlane_b32 s5, v254, 2
	s_and_b64 s[4:5], s[0:1], s[4:5]
	s_mov_b64 exec, s[4:5]
	s_cbranch_execz .LBB0_431
	s_add_i32 s3, 0, 0x20000
	v_mov_b32_e32 v0, s3
	s_waitcnt vmcnt(0) expcnt(0) lgkmcnt(0)
	ds_read_b32 v2, v0
	s_add_i32 s3, 0, 0x20004
	v_mov_b32_e32 v0, s3
	ds_read_b32 v0, v0
	s_waitcnt lgkmcnt(1)
	v_cmp_ne_u32_e32 vcc, 0, v2
	s_cbranch_vccnz .LBB0_395
	s_add_u32 s4, s58, 0x2f80200
	s_addc_u32 s5, s59, 0
	s_add_u32 s6, s58, 0x2f80400
	s_addc_u32 s7, s59, 0
	s_add_u32 s8, s58, 0x2f80500
	s_addc_u32 s9, s59, 0
	s_add_u32 s10, s58, 0x2f80600
	s_addc_u32 s11, s59, 0
	s_add_u32 s12, s58, 0x2f80700
	s_addc_u32 s13, s59, 0
	s_add_u32 s14, s58, 0x2f80800
	s_addc_u32 s15, s59, 0
	s_add_u32 s16, s58, 0x2f80900
	s_addc_u32 s17, s59, 0
	s_add_u32 s20, s58, 0x2f80a00
	s_addc_u32 s21, s59, 0
	s_add_u32 s24, s58, 0x2f80b00
	s_addc_u32 s25, s59, 0
	s_add_u32 s26, s58, 0x2f80c00
	s_addc_u32 s27, s59, 0
	s_add_u32 s36, s58, 0x2f80d00
	s_addc_u32 s37, s59, 0
	s_add_u32 s38, s58, 0x2f80e00
	s_addc_u32 s39, s59, 0
	s_add_u32 s40, s58, 0x2f80f00
	s_addc_u32 s41, s59, 0
	s_add_u32 s42, s58, 0x2f81000
	s_addc_u32 s43, s59, 0
	s_add_u32 s48, s58, 0x2f81100
	s_addc_u32 s49, s59, 0
	s_add_u32 s52, s58, 0x2f81200
	v_readlane_b32 s3, v254, 0
	s_addc_u32 s53, s59, 0
	s_mul_i32 s3, s97, s3
	s_add_u32 s60, s58, 0x2f81300
	s_mul_i32 s3, s3, s96
	s_addc_u32 s61, s59, 0
	s_mov_b32 s68, 1
	v_mov_b32_e32 v16, 0
	s_branch .LBB0_383
